# combined: stack9 + row-load hoist + EpiFfn dead v_mov removal + merged row-stat atomics
# speedup vs baseline: 1.0100x; 1.0038x over previous
; DEVI unsigned pk2(float lo, float hi) { unsigned r; asm("v_cvt_pk_bf16_f32 %0, %1, %2" : "=v"(r) : "v"(lo), "v"(hi)); return r; }
; DEVI void row_stats(const float* stats, int row, float& mu, float& rs) {
;     if (stats) { const float2 st = *(const float2*)(stats + 2 * (size_t)row); mu = st.x * (1.0f / 1024.0f); const float var = st.y * (1.0f / 1024.0f) - mu * mu; rs = rsqrtf(fmaxf(var, 0.f) + LN_EPS); }
;     else { mu = 0.f; rs = 1.f; }
; }
;     DEVI void operator()(const f32x4 (&acc)[2][2][4][2], const pg8::Unit& u, int wr, int wc, int fr, int fq) const {
;     ...
;             for (int m = 0; m < 4; ++m) {
;                 const int row = row0 + ai * 128 + m * 16; float mu, rs; row_stats(stin, row, mu, rs);
;                 float sum = 0.f, sq = 0.f;
; #pragma unroll
;                 for (int bj = 0; bj < 2; ++bj) {
;                     f32x4 z[2];
; #pragma unroll
;                     for (int n = 0; n < 2; ++n) {
;                         const int col = colb + bj * 128 + 4 * n;
;                         f32x4 xv = *(const f32x4*)(zsrc + (size_t)row * DM + col);
;                         if (stin) { const f32x4 gv = *(const f32x4*)(gin + col), bv = *(const f32x4*)(bin + col); xv = (xv - mu) * rs * gv + bv; }
;                         f32x4 zz = ALPHA * xv + acc[ai][bj][m][n];
;                         if (bias) zz += *(const f32x4*)(bias + col);
;                         *(f32x4*)(zdst + (size_t)row * DM + col) = zz;
;                         sum += zz[0] + zz[1] + zz[2] + zz[3]; sq += zz[0] * zz[0] + zz[1] * zz[1] + zz[2] * zz[2] + zz[3] * zz[3];
;                         z[n] = zz;
;                     }
;                     u32x4 o; o.x = pk2(z[0][0], z[0][1]); o.y = pk2(z[0][2], z[0][3]); o.z = pk2(z[1][0], z[1][1]); o.w = pk2(z[1][2], z[1][3]);
;                     if (zb) *(u32x4*)(zb + (size_t)row * DM + colb + bj * 128) = o;
;                 }
;                 sum += __shfl_xor(sum, 16); sq += __shfl_xor(sq, 16);
;                 sum += __shfl_xor(sum, 32); sq += __shfl_xor(sq, 32);
;                 if (fq == 0) { atomicAdd(stout + 2 * (size_t)row, sum); atomicAdd(stout + 2 * (size_t)row + 1, sq); }
.LBB0_1331:
	s_or_b64 exec, exec, s[30:31]
	v_or_b32_e32 v126, 16, v150
	v_ashrrev_i32_e32 v127, 31, v126
	v_lshlrev_b64 v[112:113], 3, v[126:127]
	s_waitcnt lgkmcnt(0)
	v_lshl_add_u64 v[114:115], s[6:7], 0, v[112:113]
	flat_load_dwordx2 v[160:161], v[114:115]
	v_lshlrev_b64 v[114:115], 12, v[126:127]
	v_lshl_add_u64 v[114:115], s[46:47], 0, v[114:115]
	v_lshl_add_u64 v[114:115], v[148:149], 2, v[114:115]
	global_load_dwordx4 v[122:125], v[114:115], off
	global_load_dwordx4 v[156:159], v[144:145], off
	global_load_dwordx4 v[170:173], v[146:147], off
	global_load_dwordx4 v[174:177], v[152:153], off
	global_load_dwordx4 v[178:181], v[114:115], off offset:16
	v_lshlrev_b64 v[126:127], 11, v[126:127]
	v_lshl_add_u64 v[126:127], s[10:11], 0, v[126:127]
	v_lshl_add_u64 v[126:127], v[148:149], 1, v[126:127]
	global_load_dwordx4 v[196:199], v[144:145], off offset:16
	global_load_dwordx4 v[200:203], v[146:147], off offset:16
	global_load_dwordx4 v[204:207], v[154:155], off
	global_load_dwordx4 v[208:211], v[114:115], off offset:512
	global_load_dwordx4 v[212:215], v[114:115], off offset:528
	s_waitcnt vmcnt(0) lgkmcnt(0)
	v_pk_mul_f32 v[160:161], v[160:161], s[18:19] op_sel:[1,0] op_sel_hi:[0,0]
	v_fma_f32 v151, -v161, v161, v160
	v_max_f32_e32 v151, 0, v151
	v_add_f32_e32 v151, 0x3727c5ac, v151
	v_mul_f32_e32 v160, 0x4b800000, v151
	v_cmp_gt_f32_e32 vcc, s64, v151
	v_sub_f32_e32 v125, v125, v161
	v_sub_f32_e32 v124, v124, v161
	v_cndmask_b32_e32 v151, v151, v160, vcc
	v_rsq_f32_e32 v151, v151
	v_sub_f32_e32 v123, v123, v161
	v_sub_f32_e32 v122, v122, v161
	v_mul_f32_e32 v160, 0x45800000, v151
	v_cndmask_b32_e32 v160, v151, v160, vcc
	v_pk_mul_f32 v[122:123], v[122:123], v[160:161] op_sel_hi:[1,0]
	v_pk_mul_f32 v[124:125], v[124:125], v[160:161] op_sel_hi:[1,0]
	v_pk_fma_f32 v[122:123], v[156:157], v[122:123], v[170:171]
	v_pk_fma_f32 v[124:125], v[158:159], v[124:125], v[172:173]
	v_pk_fma_f32 v[108:109], v[122:123], s[20:21], v[108:109] op_sel_hi:[1,0,1]
	v_pk_fma_f32 v[110:111], v[124:125], s[20:21], v[110:111] op_sel_hi:[1,0,1]
	v_pk_add_f32 v[108:109], v[174:175], v[108:109]
	v_pk_add_f32 v[110:111], v[176:177], v[110:111]
	global_store_dwordx4 v[114:115], v[108:111], off
	v_sub_f32_e32 v175, v181, v161
	v_sub_f32_e32 v174, v180, v161
	v_sub_f32_e32 v177, v179, v161
	v_sub_f32_e32 v176, v178, v161
	v_pk_mul_f32 v[176:177], v[176:177], v[160:161] op_sel_hi:[1,0]
	v_pk_mul_f32 v[178:179], v[174:175], v[160:161] op_sel_hi:[1,0]
	v_cvt_pk_bf16_f32 v174, v108, v109
	v_cvt_pk_bf16_f32 v175, v110, v111
	v_add_f32_e32 v151, v108, v109
	v_mul_f32_e32 v109, v109, v109
	v_fmac_f32_e32 v109, v108, v108
	v_add_f32_e32 v151, v110, v151
	v_fmac_f32_e32 v109, v110, v110
	v_add_f32_e32 v108, v111, v151
	v_add_f32_e32 v108, 0, v108
	v_fmac_f32_e32 v109, v111, v111
	v_pk_fma_f32 v[124:125], v[198:199], v[178:179], v[202:203]
	v_pk_fma_f32 v[122:123], v[196:197], v[176:177], v[200:201]
	v_pk_fma_f32 v[106:107], v[124:125], s[20:21], v[106:107] op_sel_hi:[1,0,1]
	v_pk_fma_f32 v[104:105], v[122:123], s[20:21], v[104:105] op_sel_hi:[1,0,1]
	v_pk_add_f32 v[106:107], v[206:207], v[106:107]
	v_pk_add_f32 v[104:105], v[204:205], v[104:105]
	global_store_dwordx4 v[114:115], v[104:107], off offset:16
	v_cvt_pk_bf16_f32 v176, v104, v105
	v_cvt_pk_bf16_f32 v177, v106, v107
	flat_store_dwordx4 v[126:127], v[174:177]
	global_load_dwordx4 v[156:159], v[144:145], off offset:512
	global_load_dwordx4 v[170:173], v[146:147], off offset:512
	s_nop 0
	global_load_dwordx4 v[174:177], v[120:121], off
	v_add_f32_e32 v110, v104, v105
	v_mul_f32_e32 v105, v105, v105
	v_fmac_f32_e32 v105, v104, v104
	v_add_f32_e32 v110, v106, v110
	v_fmac_f32_e32 v105, v106, v106
	v_add_f32_e32 v104, v107, v110
	v_fmac_f32_e32 v105, v107, v107
	v_add_f32_e32 v108, v104, v108
	v_add_f32_e32 v109, v109, v105
	global_load_dwordx4 v[196:199], v[144:145], off offset:528
	global_load_dwordx4 v[200:203], v[146:147], off offset:528
	global_load_dwordx4 v[204:207], v[116:117], off
	s_waitcnt vmcnt(0)
	v_sub_f32_e32 v125, v211, v161
	v_sub_f32_e32 v124, v210, v161
	v_sub_f32_e32 v123, v209, v161
	v_sub_f32_e32 v122, v208, v161
	v_pk_mul_f32 v[122:123], v[160:161], v[122:123] op_sel_hi:[0,1]
	v_pk_mul_f32 v[124:125], v[160:161], v[124:125] op_sel_hi:[0,1]
	v_pk_fma_f32 v[124:125], v[158:159], v[124:125], v[172:173]
	v_pk_fma_f32 v[122:123], v[156:157], v[122:123], v[170:171]
	v_pk_fma_f32 v[102:103], v[124:125], s[20:21], v[102:103] op_sel_hi:[1,0,1]
	v_pk_fma_f32 v[100:101], v[122:123], s[20:21], v[100:101] op_sel_hi:[1,0,1]
	v_pk_add_f32 v[102:103], v[176:177], v[102:103]
	v_pk_add_f32 v[100:101], v[174:175], v[100:101]
	global_store_dwordx4 v[114:115], v[100:103], off offset:512
	v_sub_f32_e32 v107, v213, v161
	v_sub_f32_e32 v106, v212, v161
	v_sub_f32_e32 v105, v215, v161
	v_sub_f32_e32 v104, v214, v161
	v_pk_mul_f32 v[106:107], v[160:161], v[106:107] op_sel_hi:[0,1]
	v_pk_mul_f32 v[104:105], v[160:161], v[104:105] op_sel_hi:[0,1]
	v_mul_f32_e32 v111, v101, v101
	v_add_f32_e32 v110, v100, v101
	v_fmac_f32_e32 v111, v100, v100
	v_add_f32_e32 v110, v102, v110
	v_fmac_f32_e32 v111, v102, v102
	v_add_f32_e32 v110, v103, v110
	v_fmac_f32_e32 v111, v103, v103
	v_add_f32_e32 v108, v108, v110
	v_add_f32_e32 v109, v109, v111
	v_cvt_pk_bf16_f32 v100, v100, v101
	v_cvt_pk_bf16_f32 v101, v102, v103
	v_pk_fma_f32 v[106:107], v[196:197], v[106:107], v[200:201]
	v_pk_fma_f32 v[104:105], v[198:199], v[104:105], v[202:203]
	v_pk_fma_f32 v[96:97], v[106:107], s[20:21], v[96:97] op_sel_hi:[1,0,1]
	v_pk_fma_f32 v[98:99], v[104:105], s[20:21], v[98:99] op_sel_hi:[1,0,1]
	v_pk_add_f32 v[104:105], v[204:205], v[96:97]
	v_pk_add_f32 v[106:107], v[206:207], v[98:99]
	v_mul_f32_e32 v97, v105, v105
	v_add_f32_e32 v96, v104, v105
	v_fmac_f32_e32 v97, v104, v104
	v_add_f32_e32 v96, v106, v96
	v_fmac_f32_e32 v97, v106, v106
	v_add_f32_e32 v96, v107, v96
	v_fmac_f32_e32 v97, v107, v107
	v_add_f32_e32 v96, v108, v96
	v_add_f32_e32 v97, v109, v97
	ds_bpermute_b32 v98, v118, v96
	ds_bpermute_b32 v99, v118, v97
	global_store_dwordx4 v[114:115], v[104:107], off offset:528
	v_cvt_pk_bf16_f32 v102, v104, v105
	v_cvt_pk_bf16_f32 v103, v106, v107
	s_waitcnt lgkmcnt(0)
	v_add_f32_e32 v96, v96, v98
	v_add_f32_e32 v97, v97, v99
	ds_bpermute_b32 v98, v119, v96
	ds_bpermute_b32 v99, v119, v97
	flat_store_dwordx4 v[126:127], v[100:103] offset:256
	s_mov_b32 s100, -1
	s_mov_b32 s101, 0
	s_mov_b32 s98, 0xffff0000
	s_mov_b32 s99, 0
	s_and_saveexec_b64 s[30:31], s[100:101]
	s_cbranch_execz .LBB0_1333
	v_lshl_add_u64 v[100:101], s[8:9], 0, v[112:113]
	s_waitcnt lgkmcnt(0)
	v_add_f32_e32 v96, v96, v98
	v_add_f32_e32 v97, v97, v99
	v_cndmask_b32_e64 v96, v96, v97, s[98:99]
	v_cndmask_b32_e64 v97, 0, 4, s[98:99]
	v_or_b32_e32 v100, v100, v97
	flat_atomic_add_f32 v[100:101], v96
; DEVI unsigned pk2(float lo, float hi) { unsigned r; asm("v_cvt_pk_bf16_f32 %0, %1, %2" : "=v"(r) : "v"(lo), "v"(hi)); return r; }
; DEVI void row_stats(const float* stats, int row, float& mu, float& rs) {
;     if (stats) { const float2 st = *(const float2*)(stats + 2 * (size_t)row); mu = st.x * (1.0f / 1024.0f); const float var = st.y * (1.0f / 1024.0f) - mu * mu; rs = rsqrtf(fmaxf(var, 0.f) + LN_EPS); }
;     else { mu = 0.f; rs = 1.f; }
; }
;     DEVI void operator()(const f32x4 (&acc)[2][2][4][2], const pg8::Unit& u, int wr, int wc, int fr, int fq) const {
;     ...
;             for (int m = 0; m < 4; ++m) {
;                 const int row = row0 + ai * 128 + m * 16; float mu, rs; row_stats(stin, row, mu, rs);
;                 float sum = 0.f, sq = 0.f;
; #pragma unroll
;                 for (int bj = 0; bj < 2; ++bj) {
;                     f32x4 z[2];
; #pragma unroll
;                     for (int n = 0; n < 2; ++n) {
;                         const int col = colb + bj * 128 + 4 * n;
;                         f32x4 xv = *(const f32x4*)(zsrc + (size_t)row * DM + col);
;                         if (stin) { const f32x4 gv = *(const f32x4*)(gin + col), bv = *(const f32x4*)(bin + col); xv = (xv - mu) * rs * gv + bv; }
;                         f32x4 zz = ALPHA * xv + acc[ai][bj][m][n];
;                         if (bias) zz += *(const f32x4*)(bias + col);
;                         *(f32x4*)(zdst + (size_t)row * DM + col) = zz;
;                         sum += zz[0] + zz[1] + zz[2] + zz[3]; sq += zz[0] * zz[0] + zz[1] * zz[1] + zz[2] * zz[2] + zz[3] * zz[3];
;                         z[n] = zz;
;                     }
;                     u32x4 o; o.x = pk2(z[0][0], z[0][1]); o.y = pk2(z[0][2], z[0][3]); o.z = pk2(z[1][0], z[1][1]); o.w = pk2(z[1][2], z[1][3]);
;                     if (zb) *(u32x4*)(zb + (size_t)row * DM + colb + bj * 128) = o;
;                 }
;                 sum += __shfl_xor(sum, 16); sq += __shfl_xor(sq, 16);
;                 sum += __shfl_xor(sum, 32); sq += __shfl_xor(sq, 32);
;                 if (fq == 0) { atomicAdd(stout + 2 * (size_t)row, sum); atomicAdd(stout + 2 * (size_t)row + 1, sq); }
.LBB0_1333:
	s_or_b64 exec, exec, s[30:31]
	v_or_b32_e32 v126, 32, v150
	v_ashrrev_i32_e32 v127, 31, v126
	v_lshlrev_b64 v[96:97], 3, v[126:127]
	s_waitcnt lgkmcnt(0)
	v_lshl_add_u64 v[98:99], s[6:7], 0, v[96:97]
	flat_load_dwordx2 v[156:157], v[98:99]
	v_lshlrev_b64 v[98:99], 12, v[126:127]
	v_lshl_add_u64 v[98:99], s[46:47], 0, v[98:99]
	v_lshl_add_u64 v[98:99], v[148:149], 2, v[98:99]
	global_load_dwordx4 v[100:103], v[98:99], off
	global_load_dwordx4 v[104:107], v[144:145], off
	global_load_dwordx4 v[108:111], v[146:147], off
	global_load_dwordx4 v[112:115], v[152:153], off
	global_load_dwordx4 v[122:125], v[98:99], off offset:16
	global_load_dwordx4 v[196:199], v[144:145], off offset:16
	global_load_dwordx4 v[200:203], v[146:147], off offset:16
	global_load_dwordx4 v[204:207], v[154:155], off
	global_load_dwordx4 v[208:211], v[98:99], off offset:512
	global_load_dwordx4 v[212:215], v[98:99], off offset:528
	s_waitcnt vmcnt(0) lgkmcnt(0)
	v_pk_mul_f32 v[156:157], v[156:157], s[18:19] op_sel:[1,0] op_sel_hi:[0,0]
	v_fma_f32 v151, -v157, v157, v156
	v_max_f32_e32 v151, 0, v151
	v_add_f32_e32 v151, 0x3727c5ac, v151
	v_mul_f32_e32 v156, 0x4b800000, v151
	v_cmp_gt_f32_e32 vcc, s64, v151
	v_sub_f32_e32 v103, v103, v157
	v_sub_f32_e32 v102, v102, v157
	v_cndmask_b32_e32 v151, v151, v156, vcc
	v_rsq_f32_e32 v151, v151
	v_sub_f32_e32 v101, v101, v157
	v_sub_f32_e32 v100, v100, v157
	v_mul_f32_e32 v156, 0x45800000, v151
	v_cndmask_b32_e32 v156, v151, v156, vcc
	v_pk_mul_f32 v[100:101], v[100:101], v[156:157] op_sel_hi:[1,0]
	v_pk_mul_f32 v[102:103], v[102:103], v[156:157] op_sel_hi:[1,0]
	v_pk_fma_f32 v[100:101], v[104:105], v[100:101], v[108:109]
	v_pk_fma_f32 v[102:103], v[106:107], v[102:103], v[110:111]
	v_pk_fma_f32 v[92:93], v[100:101], s[20:21], v[92:93] op_sel_hi:[1,0,1]
	v_pk_fma_f32 v[94:95], v[102:103], s[20:21], v[94:95] op_sel_hi:[1,0,1]
	v_pk_add_f32 v[92:93], v[112:113], v[92:93]
	v_pk_add_f32 v[94:95], v[114:115], v[94:95]
	global_store_dwordx4 v[98:99], v[92:95], off
	v_lshlrev_b64 v[112:113], 11, v[126:127]
	v_lshl_add_u64 v[112:113], s[10:11], 0, v[112:113]
	v_lshl_add_u64 v[126:127], v[148:149], 1, v[112:113]
	v_sub_f32_e32 v113, v125, v157
	v_sub_f32_e32 v112, v124, v157
	v_sub_f32_e32 v115, v123, v157
	v_sub_f32_e32 v114, v122, v157
	v_pk_mul_f32 v[114:115], v[114:115], v[156:157] op_sel_hi:[1,0]
	v_pk_mul_f32 v[122:123], v[112:113], v[156:157] op_sel_hi:[1,0]
	v_cvt_pk_bf16_f32 v112, v92, v93
	v_cvt_pk_bf16_f32 v113, v94, v95
	v_pk_fma_f32 v[100:101], v[196:197], v[114:115], v[200:201]
	v_pk_fma_f32 v[102:103], v[198:199], v[122:123], v[202:203]
	v_pk_fma_f32 v[88:89], v[100:101], s[20:21], v[88:89] op_sel_hi:[1,0,1]
	v_pk_fma_f32 v[90:91], v[102:103], s[20:21], v[90:91] op_sel_hi:[1,0,1]
	v_pk_add_f32 v[88:89], v[204:205], v[88:89]
	v_pk_add_f32 v[90:91], v[206:207], v[90:91]
	global_store_dwordx4 v[98:99], v[88:91], off offset:16
	v_cvt_pk_bf16_f32 v114, v88, v89
	v_cvt_pk_bf16_f32 v115, v90, v91
	flat_store_dwordx4 v[126:127], v[112:115]
	global_load_dwordx4 v[104:107], v[144:145], off offset:512
	global_load_dwordx4 v[108:111], v[146:147], off offset:512
	s_nop 0
	global_load_dwordx4 v[112:115], v[120:121], off
	global_load_dwordx4 v[196:199], v[144:145], off offset:528
	global_load_dwordx4 v[200:203], v[146:147], off offset:528
	global_load_dwordx4 v[204:207], v[116:117], off
	s_waitcnt vmcnt(0)
	v_sub_f32_e32 v103, v211, v157
	v_sub_f32_e32 v102, v210, v157
	v_sub_f32_e32 v101, v209, v157
	v_sub_f32_e32 v100, v208, v157
	v_pk_mul_f32 v[100:101], v[156:157], v[100:101] op_sel_hi:[0,1]
	v_pk_mul_f32 v[102:103], v[156:157], v[102:103] op_sel_hi:[0,1]
	v_pk_fma_f32 v[102:103], v[106:107], v[102:103], v[110:111]
	v_pk_fma_f32 v[100:101], v[104:105], v[100:101], v[108:109]
	v_pk_fma_f32 v[86:87], v[102:103], s[20:21], v[86:87] op_sel_hi:[1,0,1]
	v_pk_fma_f32 v[84:85], v[100:101], s[20:21], v[84:85] op_sel_hi:[1,0,1]
	v_pk_add_f32 v[86:87], v[114:115], v[86:87]
	v_pk_add_f32 v[84:85], v[112:113], v[84:85]
	global_store_dwordx4 v[98:99], v[84:87], off offset:512
	v_add_f32_e32 v112, v92, v93
	v_mul_f32_e32 v93, v93, v93
	v_fmac_f32_e32 v93, v92, v92
	v_add_f32_e32 v112, v94, v112
	v_fmac_f32_e32 v93, v94, v94
	v_add_f32_e32 v94, v88, v89
	v_mul_f32_e32 v89, v89, v89
	v_fmac_f32_e32 v89, v88, v88
	v_add_f32_e32 v92, v95, v112
	v_add_f32_e32 v94, v90, v94
	v_fmac_f32_e32 v89, v90, v90
	v_add_f32_e32 v92, 0, v92
	v_fmac_f32_e32 v93, v95, v95
	v_add_f32_e32 v88, v91, v94
	v_fmac_f32_e32 v89, v91, v91
	v_sub_f32_e32 v91, v213, v157
	v_sub_f32_e32 v90, v212, v157
	v_add_f32_e32 v92, v88, v92
	v_add_f32_e32 v93, v93, v89
	v_sub_f32_e32 v89, v215, v157
	v_sub_f32_e32 v88, v214, v157
	v_pk_mul_f32 v[90:91], v[156:157], v[90:91] op_sel_hi:[0,1]
	v_pk_mul_f32 v[88:89], v[156:157], v[88:89] op_sel_hi:[0,1]
	v_mul_f32_e32 v95, v85, v85
	v_add_f32_e32 v94, v84, v85
	v_fmac_f32_e32 v95, v84, v84
	v_add_f32_e32 v94, v86, v94
	v_fmac_f32_e32 v95, v86, v86
	v_add_f32_e32 v94, v87, v94
	v_fmac_f32_e32 v95, v87, v87
	v_add_f32_e32 v92, v92, v94
	v_add_f32_e32 v93, v93, v95
	v_cvt_pk_bf16_f32 v84, v84, v85
	v_cvt_pk_bf16_f32 v85, v86, v87
	v_pk_fma_f32 v[90:91], v[196:197], v[90:91], v[200:201]
	v_pk_fma_f32 v[88:89], v[198:199], v[88:89], v[202:203]
	v_pk_fma_f32 v[80:81], v[90:91], s[20:21], v[80:81] op_sel_hi:[1,0,1]
	v_pk_fma_f32 v[82:83], v[88:89], s[20:21], v[82:83] op_sel_hi:[1,0,1]
	v_pk_add_f32 v[88:89], v[204:205], v[80:81]
	v_pk_add_f32 v[90:91], v[206:207], v[82:83]
	v_mul_f32_e32 v81, v89, v89
	v_add_f32_e32 v80, v88, v89
	v_fmac_f32_e32 v81, v88, v88
	v_add_f32_e32 v80, v90, v80
	v_fmac_f32_e32 v81, v90, v90
	v_add_f32_e32 v80, v91, v80
	v_fmac_f32_e32 v81, v91, v91
	v_add_f32_e32 v80, v92, v80
	v_add_f32_e32 v81, v93, v81
	ds_bpermute_b32 v82, v118, v80
	ds_bpermute_b32 v83, v118, v81
	global_store_dwordx4 v[98:99], v[88:91], off offset:528
	v_cvt_pk_bf16_f32 v86, v88, v89
	v_cvt_pk_bf16_f32 v87, v90, v91
	s_waitcnt lgkmcnt(0)
	v_add_f32_e32 v80, v80, v82
	v_add_f32_e32 v81, v81, v83
	ds_bpermute_b32 v82, v119, v80
	ds_bpermute_b32 v83, v119, v81
	flat_store_dwordx4 v[126:127], v[84:87] offset:256
	s_mov_b32 s100, -1
	s_mov_b32 s101, 0
	s_mov_b32 s98, 0xffff0000
	s_mov_b32 s99, 0
	s_and_saveexec_b64 s[30:31], s[100:101]
	s_cbranch_execz .LBB0_1335
	v_lshl_add_u64 v[84:85], s[8:9], 0, v[96:97]
	s_waitcnt lgkmcnt(0)
	v_add_f32_e32 v80, v80, v82
	v_add_f32_e32 v81, v81, v83
	v_cndmask_b32_e64 v80, v80, v81, s[98:99]
	v_cndmask_b32_e64 v81, 0, 4, s[98:99]
	v_or_b32_e32 v84, v84, v81
	flat_atomic_add_f32 v[84:85], v80
; DEVI unsigned pk2(float lo, float hi) { unsigned r; asm("v_cvt_pk_bf16_f32 %0, %1, %2" : "=v"(r) : "v"(lo), "v"(hi)); return r; }
; DEVI void row_stats(const float* stats, int row, float& mu, float& rs) {
;     if (stats) { const float2 st = *(const float2*)(stats + 2 * (size_t)row); mu = st.x * (1.0f / 1024.0f); const float var = st.y * (1.0f / 1024.0f) - mu * mu; rs = rsqrtf(fmaxf(var, 0.f) + LN_EPS); }
;     else { mu = 0.f; rs = 1.f; }
; }
;     DEVI void operator()(const f32x4 (&acc)[2][2][4][2], const pg8::Unit& u, int wr, int wc, int fr, int fq) const {
;     ...
;             for (int m = 0; m < 4; ++m) {
;                 const int row = row0 + ai * 128 + m * 16; float mu, rs; row_stats(stin, row, mu, rs);
;                 float sum = 0.f, sq = 0.f;
; #pragma unroll
;                 for (int bj = 0; bj < 2; ++bj) {
;                     f32x4 z[2];
; #pragma unroll
;                     for (int n = 0; n < 2; ++n) {
;                         const int col = colb + bj * 128 + 4 * n;
;                         f32x4 xv = *(const f32x4*)(zsrc + (size_t)row * DM + col);
;                         if (stin) { const f32x4 gv = *(const f32x4*)(gin + col), bv = *(const f32x4*)(bin + col); xv = (xv - mu) * rs * gv + bv; }
;                         f32x4 zz = ALPHA * xv + acc[ai][bj][m][n];
;                         if (bias) zz += *(const f32x4*)(bias + col);
;                         *(f32x4*)(zdst + (size_t)row * DM + col) = zz;
;                         sum += zz[0] + zz[1] + zz[2] + zz[3]; sq += zz[0] * zz[0] + zz[1] * zz[1] + zz[2] * zz[2] + zz[3] * zz[3];
;                         z[n] = zz;
;                     }
;                     u32x4 o; o.x = pk2(z[0][0], z[0][1]); o.y = pk2(z[0][2], z[0][3]); o.z = pk2(z[1][0], z[1][1]); o.w = pk2(z[1][2], z[1][3]);
;                     if (zb) *(u32x4*)(zb + (size_t)row * DM + colb + bj * 128) = o;
;                 }
;                 sum += __shfl_xor(sum, 16); sq += __shfl_xor(sq, 16);
;                 sum += __shfl_xor(sum, 32); sq += __shfl_xor(sq, 32);
;                 if (fq == 0) { atomicAdd(stout + 2 * (size_t)row, sum); atomicAdd(stout + 2 * (size_t)row + 1, sq); }
.LBB0_1335:
	s_or_b64 exec, exec, s[30:31]
	v_or_b32_e32 v104, 48, v150
	v_ashrrev_i32_e32 v105, 31, v104
	v_lshlrev_b64 v[80:81], 3, v[104:105]
	s_waitcnt lgkmcnt(0)
	v_lshl_add_u64 v[82:83], s[6:7], 0, v[80:81]
	flat_load_dwordx2 v[106:107], v[82:83]
	v_lshlrev_b64 v[82:83], 12, v[104:105]
	v_lshl_add_u64 v[82:83], s[46:47], 0, v[82:83]
	v_lshl_add_u64 v[82:83], v[148:149], 2, v[82:83]
	global_load_dwordx4 v[84:87], v[82:83], off
	global_load_dwordx4 v[88:91], v[144:145], off
	global_load_dwordx4 v[92:95], v[146:147], off
	global_load_dwordx4 v[96:99], v[152:153], off
	global_load_dwordx4 v[100:103], v[82:83], off offset:16
	global_load_dwordx4 v[196:199], v[144:145], off offset:16
	global_load_dwordx4 v[200:203], v[146:147], off offset:16
	global_load_dwordx4 v[204:207], v[154:155], off
	global_load_dwordx4 v[208:211], v[82:83], off offset:512
	global_load_dwordx4 v[212:215], v[82:83], off offset:528
	s_waitcnt vmcnt(0) lgkmcnt(0)
	v_pk_mul_f32 v[106:107], v[106:107], s[18:19] op_sel:[1,0] op_sel_hi:[0,0]
	v_fma_f32 v106, -v107, v107, v106
	v_max_f32_e32 v106, 0, v106
	v_add_f32_e32 v106, 0x3727c5ac, v106
	v_mul_f32_e32 v108, 0x4b800000, v106
	v_cmp_gt_f32_e32 vcc, s64, v106
	v_sub_f32_e32 v87, v87, v107
	v_sub_f32_e32 v86, v86, v107
	v_cndmask_b32_e32 v106, v106, v108, vcc
	v_rsq_f32_e32 v106, v106
	v_sub_f32_e32 v85, v85, v107
	v_sub_f32_e32 v84, v84, v107
	v_mul_f32_e32 v108, 0x45800000, v106
	v_cndmask_b32_e32 v106, v106, v108, vcc
	v_pk_mul_f32 v[84:85], v[84:85], v[106:107] op_sel_hi:[1,0]
	v_pk_mul_f32 v[86:87], v[86:87], v[106:107] op_sel_hi:[1,0]
	v_pk_fma_f32 v[84:85], v[88:89], v[84:85], v[92:93]
	v_pk_fma_f32 v[86:87], v[90:91], v[86:87], v[94:95]
	v_pk_fma_f32 v[76:77], v[84:85], s[20:21], v[76:77] op_sel_hi:[1,0,1]
	v_pk_fma_f32 v[78:79], v[86:87], s[20:21], v[78:79] op_sel_hi:[1,0,1]
	v_pk_add_f32 v[76:77], v[96:97], v[76:77]
	v_pk_add_f32 v[78:79], v[98:99], v[78:79]
	global_store_dwordx4 v[82:83], v[76:79], off
	v_lshlrev_b64 v[96:97], 11, v[104:105]
	v_lshl_add_u64 v[96:97], s[10:11], 0, v[96:97]
	v_lshl_add_u64 v[104:105], v[148:149], 1, v[96:97]
	v_sub_f32_e32 v97, v103, v107
	v_sub_f32_e32 v96, v102, v107
	v_sub_f32_e32 v99, v101, v107
	v_sub_f32_e32 v98, v100, v107
	v_pk_mul_f32 v[98:99], v[98:99], v[106:107] op_sel_hi:[1,0]
	v_pk_mul_f32 v[100:101], v[96:97], v[106:107] op_sel_hi:[1,0]
	v_cvt_pk_bf16_f32 v96, v76, v77
	v_cvt_pk_bf16_f32 v97, v78, v79
	v_pk_fma_f32 v[84:85], v[196:197], v[98:99], v[200:201]
	v_pk_fma_f32 v[86:87], v[198:199], v[100:101], v[202:203]
	v_pk_fma_f32 v[72:73], v[84:85], s[20:21], v[72:73] op_sel_hi:[1,0,1]
	v_pk_fma_f32 v[74:75], v[86:87], s[20:21], v[74:75] op_sel_hi:[1,0,1]
	v_pk_add_f32 v[72:73], v[204:205], v[72:73]
	v_pk_add_f32 v[74:75], v[206:207], v[74:75]
	global_store_dwordx4 v[82:83], v[72:75], off offset:16
	v_cvt_pk_bf16_f32 v98, v72, v73
	v_cvt_pk_bf16_f32 v99, v74, v75
	flat_store_dwordx4 v[104:105], v[96:99]
	global_load_dwordx4 v[88:91], v[144:145], off offset:512
	global_load_dwordx4 v[92:95], v[146:147], off offset:512
	s_nop 0
	global_load_dwordx4 v[96:99], v[120:121], off
	global_load_dwordx4 v[196:199], v[144:145], off offset:528
	global_load_dwordx4 v[200:203], v[146:147], off offset:528
	global_load_dwordx4 v[204:207], v[116:117], off
	s_waitcnt vmcnt(0)
	v_sub_f32_e32 v87, v211, v107
	v_sub_f32_e32 v86, v210, v107
	v_sub_f32_e32 v85, v209, v107
	v_sub_f32_e32 v84, v208, v107
	v_pk_mul_f32 v[84:85], v[106:107], v[84:85] op_sel_hi:[0,1]
	v_pk_mul_f32 v[86:87], v[106:107], v[86:87] op_sel_hi:[0,1]
	v_pk_fma_f32 v[86:87], v[90:91], v[86:87], v[94:95]
	v_pk_fma_f32 v[84:85], v[88:89], v[84:85], v[92:93]
	v_pk_fma_f32 v[70:71], v[86:87], s[20:21], v[70:71] op_sel_hi:[1,0,1]
	v_pk_fma_f32 v[68:69], v[84:85], s[20:21], v[68:69] op_sel_hi:[1,0,1]
	v_pk_add_f32 v[70:71], v[98:99], v[70:71]
	v_pk_add_f32 v[68:69], v[96:97], v[68:69]
	global_store_dwordx4 v[82:83], v[68:71], off offset:512
	v_add_f32_e32 v96, v76, v77
	v_mul_f32_e32 v77, v77, v77
	v_fmac_f32_e32 v77, v76, v76
	v_add_f32_e32 v96, v78, v96
	v_fmac_f32_e32 v77, v78, v78
	v_add_f32_e32 v78, v72, v73
	v_mul_f32_e32 v73, v73, v73
	v_fmac_f32_e32 v73, v72, v72
	v_add_f32_e32 v76, v79, v96
	v_add_f32_e32 v78, v74, v78
	v_fmac_f32_e32 v73, v74, v74
	v_add_f32_e32 v76, 0, v76
	v_fmac_f32_e32 v77, v79, v79
	v_add_f32_e32 v72, v75, v78
	v_fmac_f32_e32 v73, v75, v75
	v_sub_f32_e32 v75, v213, v107
	v_sub_f32_e32 v74, v212, v107
	v_add_f32_e32 v76, v72, v76
	v_add_f32_e32 v77, v77, v73
	v_sub_f32_e32 v73, v215, v107
	v_sub_f32_e32 v72, v214, v107
	v_pk_mul_f32 v[74:75], v[106:107], v[74:75] op_sel_hi:[0,1]
	v_pk_mul_f32 v[72:73], v[106:107], v[72:73] op_sel_hi:[0,1]
	v_mul_f32_e32 v79, v69, v69
	v_add_f32_e32 v78, v68, v69
	v_fmac_f32_e32 v79, v68, v68
	v_add_f32_e32 v78, v70, v78
	v_fmac_f32_e32 v79, v70, v70
	v_add_f32_e32 v78, v71, v78
	v_fmac_f32_e32 v79, v71, v71
	v_add_f32_e32 v76, v76, v78
	v_add_f32_e32 v77, v77, v79
	v_cvt_pk_bf16_f32 v68, v68, v69
	v_cvt_pk_bf16_f32 v69, v70, v71
	v_pk_fma_f32 v[74:75], v[196:197], v[74:75], v[200:201]
	v_pk_fma_f32 v[72:73], v[198:199], v[72:73], v[202:203]
	v_pk_fma_f32 v[64:65], v[74:75], s[20:21], v[64:65] op_sel_hi:[1,0,1]
	v_pk_fma_f32 v[66:67], v[72:73], s[20:21], v[66:67] op_sel_hi:[1,0,1]
	v_pk_add_f32 v[72:73], v[204:205], v[64:65]
	v_pk_add_f32 v[74:75], v[206:207], v[66:67]
	v_mul_f32_e32 v65, v73, v73
	v_add_f32_e32 v64, v72, v73
	v_fmac_f32_e32 v65, v72, v72
	v_add_f32_e32 v64, v74, v64
	v_fmac_f32_e32 v65, v74, v74
	v_add_f32_e32 v64, v75, v64
	v_fmac_f32_e32 v65, v75, v75
	v_add_f32_e32 v64, v76, v64
	v_add_f32_e32 v65, v77, v65
	ds_bpermute_b32 v66, v118, v64
	ds_bpermute_b32 v67, v118, v65
	global_store_dwordx4 v[82:83], v[72:75], off offset:528
	v_cvt_pk_bf16_f32 v70, v72, v73
	v_cvt_pk_bf16_f32 v71, v74, v75
	s_waitcnt lgkmcnt(0)
	v_add_f32_e32 v64, v64, v66
	v_add_f32_e32 v65, v65, v67
	ds_bpermute_b32 v66, v119, v64
	ds_bpermute_b32 v67, v119, v65
	flat_store_dwordx4 v[104:105], v[68:71] offset:256
	s_mov_b32 s100, -1
	s_mov_b32 s101, 0
	s_mov_b32 s98, 0xffff0000
	s_mov_b32 s99, 0
	s_and_saveexec_b64 s[30:31], s[100:101]
	s_cbranch_execz .LBB0_1337
	v_lshl_add_u64 v[68:69], s[8:9], 0, v[80:81]
	s_waitcnt lgkmcnt(0)
	v_add_f32_e32 v64, v64, v66
	v_add_f32_e32 v65, v65, v67
	v_cndmask_b32_e64 v64, v64, v65, s[98:99]
	v_cndmask_b32_e64 v65, 0, 4, s[98:99]
	v_or_b32_e32 v68, v68, v65
	flat_atomic_add_f32 v[68:69], v64
; DEVI unsigned pk2(float lo, float hi) { unsigned r; asm("v_cvt_pk_bf16_f32 %0, %1, %2" : "=v"(r) : "v"(lo), "v"(hi)); return r; }
; DEVI void row_stats(const float* stats, int row, float& mu, float& rs) {
;     if (stats) { const float2 st = *(const float2*)(stats + 2 * (size_t)row); mu = st.x * (1.0f / 1024.0f); const float var = st.y * (1.0f / 1024.0f) - mu * mu; rs = rsqrtf(fmaxf(var, 0.f) + LN_EPS); }
;     else { mu = 0.f; rs = 1.f; }
; }
;     DEVI void operator()(const f32x4 (&acc)[2][2][4][2], const pg8::Unit& u, int wr, int wc, int fr, int fq) const {
;     ...
;             for (int m = 0; m < 4; ++m) {
;                 const int row = row0 + ai * 128 + m * 16; float mu, rs; row_stats(stin, row, mu, rs);
;                 float sum = 0.f, sq = 0.f;
; #pragma unroll
;                 for (int bj = 0; bj < 2; ++bj) {
;                     f32x4 z[2];
; #pragma unroll
;                     for (int n = 0; n < 2; ++n) {
;                         const int col = colb + bj * 128 + 4 * n;
;                         f32x4 xv = *(const f32x4*)(zsrc + (size_t)row * DM + col);
;                         if (stin) { const f32x4 gv = *(const f32x4*)(gin + col), bv = *(const f32x4*)(bin + col); xv = (xv - mu) * rs * gv + bv; }
;                         f32x4 zz = ALPHA * xv + acc[ai][bj][m][n];
;                         if (bias) zz += *(const f32x4*)(bias + col);
;                         *(f32x4*)(zdst + (size_t)row * DM + col) = zz;
;                         sum += zz[0] + zz[1] + zz[2] + zz[3]; sq += zz[0] * zz[0] + zz[1] * zz[1] + zz[2] * zz[2] + zz[3] * zz[3];
;                         z[n] = zz;
;                     }
;                     u32x4 o; o.x = pk2(z[0][0], z[0][1]); o.y = pk2(z[0][2], z[0][3]); o.z = pk2(z[1][0], z[1][1]); o.w = pk2(z[1][2], z[1][3]);
;                     if (zb) *(u32x4*)(zb + (size_t)row * DM + colb + bj * 128) = o;
;                 }
;                 sum += __shfl_xor(sum, 16); sq += __shfl_xor(sq, 16);
;                 sum += __shfl_xor(sum, 32); sq += __shfl_xor(sq, 32);
;                 if (fq == 0) { atomicAdd(stout + 2 * (size_t)row, sum); atomicAdd(stout + 2 * (size_t)row + 1, sq); }
.LBB0_1337:
	s_or_b64 exec, exec, s[30:31]
	v_add_u32_e32 v88, 0x80, v150
	v_ashrrev_i32_e32 v89, 31, v88
	v_lshlrev_b64 v[64:65], 3, v[88:89]
	s_waitcnt lgkmcnt(0)
	v_lshl_add_u64 v[66:67], s[6:7], 0, v[64:65]
	flat_load_dwordx2 v[90:91], v[66:67]
	v_lshlrev_b64 v[66:67], 12, v[88:89]
	v_lshl_add_u64 v[66:67], s[46:47], 0, v[66:67]
	v_lshl_add_u64 v[66:67], v[148:149], 2, v[66:67]
	global_load_dwordx4 v[68:71], v[66:67], off
	global_load_dwordx4 v[72:75], v[144:145], off
	global_load_dwordx4 v[76:79], v[146:147], off
	global_load_dwordx4 v[80:83], v[152:153], off
	global_load_dwordx4 v[84:87], v[66:67], off offset:16
	global_load_dwordx4 v[196:199], v[144:145], off offset:16
	global_load_dwordx4 v[200:203], v[146:147], off offset:16
	global_load_dwordx4 v[204:207], v[154:155], off
	global_load_dwordx4 v[208:211], v[66:67], off offset:512
	global_load_dwordx4 v[212:215], v[66:67], off offset:528
	s_waitcnt vmcnt(0) lgkmcnt(0)
	v_pk_mul_f32 v[90:91], v[90:91], s[18:19] op_sel:[1,0] op_sel_hi:[0,0]
	v_fma_f32 v90, -v91, v91, v90
	v_max_f32_e32 v90, 0, v90
	v_add_f32_e32 v90, 0x3727c5ac, v90
	v_mul_f32_e32 v92, 0x4b800000, v90
	v_cmp_gt_f32_e32 vcc, s64, v90
	v_sub_f32_e32 v71, v71, v91
	v_sub_f32_e32 v70, v70, v91
	v_cndmask_b32_e32 v90, v90, v92, vcc
	v_rsq_f32_e32 v90, v90
	v_sub_f32_e32 v69, v69, v91
	v_sub_f32_e32 v68, v68, v91
	v_mul_f32_e32 v92, 0x45800000, v90
	v_cndmask_b32_e32 v90, v90, v92, vcc
	v_pk_mul_f32 v[68:69], v[68:69], v[90:91] op_sel_hi:[1,0]
	v_pk_mul_f32 v[70:71], v[70:71], v[90:91] op_sel_hi:[1,0]
	v_pk_fma_f32 v[68:69], v[72:73], v[68:69], v[76:77]
	v_pk_fma_f32 v[70:71], v[74:75], v[70:71], v[78:79]
	v_pk_fma_f32 v[60:61], v[68:69], s[20:21], v[60:61] op_sel_hi:[1,0,1]
	v_pk_fma_f32 v[62:63], v[70:71], s[20:21], v[62:63] op_sel_hi:[1,0,1]
	v_pk_add_f32 v[60:61], v[80:81], v[60:61]
	v_pk_add_f32 v[62:63], v[82:83], v[62:63]
	global_store_dwordx4 v[66:67], v[60:63], off
	v_lshlrev_b64 v[80:81], 11, v[88:89]
	v_lshl_add_u64 v[80:81], s[10:11], 0, v[80:81]
	v_lshl_add_u64 v[88:89], v[148:149], 1, v[80:81]
	v_sub_f32_e32 v81, v87, v91
	v_sub_f32_e32 v80, v86, v91
	v_sub_f32_e32 v83, v85, v91
	v_sub_f32_e32 v82, v84, v91
	v_pk_mul_f32 v[82:83], v[82:83], v[90:91] op_sel_hi:[1,0]
	v_pk_mul_f32 v[84:85], v[80:81], v[90:91] op_sel_hi:[1,0]
	v_cvt_pk_bf16_f32 v80, v60, v61
	v_cvt_pk_bf16_f32 v81, v62, v63
	v_pk_fma_f32 v[68:69], v[196:197], v[82:83], v[200:201]
	v_pk_fma_f32 v[70:71], v[198:199], v[84:85], v[202:203]
	v_pk_fma_f32 v[56:57], v[68:69], s[20:21], v[56:57] op_sel_hi:[1,0,1]
	v_pk_fma_f32 v[58:59], v[70:71], s[20:21], v[58:59] op_sel_hi:[1,0,1]
	v_pk_add_f32 v[56:57], v[204:205], v[56:57]
	v_pk_add_f32 v[58:59], v[206:207], v[58:59]
	global_store_dwordx4 v[66:67], v[56:59], off offset:16
	v_cvt_pk_bf16_f32 v82, v56, v57
	v_cvt_pk_bf16_f32 v83, v58, v59
	flat_store_dwordx4 v[88:89], v[80:83]
	global_load_dwordx4 v[72:75], v[144:145], off offset:512
	global_load_dwordx4 v[76:79], v[146:147], off offset:512
	s_nop 0
	global_load_dwordx4 v[80:83], v[120:121], off
	global_load_dwordx4 v[196:199], v[144:145], off offset:528
	global_load_dwordx4 v[200:203], v[146:147], off offset:528
	global_load_dwordx4 v[204:207], v[116:117], off
	s_waitcnt vmcnt(0)
	v_sub_f32_e32 v71, v211, v91
	v_sub_f32_e32 v70, v210, v91
	v_sub_f32_e32 v69, v209, v91
	v_sub_f32_e32 v68, v208, v91
	v_pk_mul_f32 v[68:69], v[90:91], v[68:69] op_sel_hi:[0,1]
	v_pk_mul_f32 v[70:71], v[90:91], v[70:71] op_sel_hi:[0,1]
	v_pk_fma_f32 v[70:71], v[74:75], v[70:71], v[78:79]
	v_pk_fma_f32 v[68:69], v[72:73], v[68:69], v[76:77]
	v_pk_fma_f32 v[54:55], v[70:71], s[20:21], v[54:55] op_sel_hi:[1,0,1]
	v_pk_fma_f32 v[52:53], v[68:69], s[20:21], v[52:53] op_sel_hi:[1,0,1]
	v_pk_add_f32 v[54:55], v[82:83], v[54:55]
	v_pk_add_f32 v[52:53], v[80:81], v[52:53]
	global_store_dwordx4 v[66:67], v[52:55], off offset:512
	v_add_f32_e32 v80, v60, v61
	v_mul_f32_e32 v61, v61, v61
	v_fmac_f32_e32 v61, v60, v60
	v_add_f32_e32 v80, v62, v80
	v_fmac_f32_e32 v61, v62, v62
	v_add_f32_e32 v62, v56, v57
	v_mul_f32_e32 v57, v57, v57
	v_fmac_f32_e32 v57, v56, v56
	v_add_f32_e32 v60, v63, v80
	v_add_f32_e32 v62, v58, v62
	v_fmac_f32_e32 v57, v58, v58
	v_add_f32_e32 v60, 0, v60
	v_fmac_f32_e32 v61, v63, v63
	v_add_f32_e32 v56, v59, v62
	v_fmac_f32_e32 v57, v59, v59
	v_sub_f32_e32 v59, v213, v91
	v_sub_f32_e32 v58, v212, v91
	v_add_f32_e32 v60, v56, v60
	v_add_f32_e32 v61, v61, v57
	v_sub_f32_e32 v57, v215, v91
	v_sub_f32_e32 v56, v214, v91
	v_pk_mul_f32 v[58:59], v[90:91], v[58:59] op_sel_hi:[0,1]
	v_pk_mul_f32 v[56:57], v[90:91], v[56:57] op_sel_hi:[0,1]
	v_mul_f32_e32 v63, v53, v53
	v_add_f32_e32 v62, v52, v53
	v_fmac_f32_e32 v63, v52, v52
	v_add_f32_e32 v62, v54, v62
	v_fmac_f32_e32 v63, v54, v54
	v_add_f32_e32 v62, v55, v62
	v_fmac_f32_e32 v63, v55, v55
	v_add_f32_e32 v60, v60, v62
	v_add_f32_e32 v61, v61, v63
	v_cvt_pk_bf16_f32 v52, v52, v53
	v_cvt_pk_bf16_f32 v53, v54, v55
	v_pk_fma_f32 v[58:59], v[196:197], v[58:59], v[200:201]
	v_pk_fma_f32 v[56:57], v[198:199], v[56:57], v[202:203]
	v_pk_fma_f32 v[48:49], v[58:59], s[20:21], v[48:49] op_sel_hi:[1,0,1]
	v_pk_fma_f32 v[50:51], v[56:57], s[20:21], v[50:51] op_sel_hi:[1,0,1]
	v_pk_add_f32 v[56:57], v[204:205], v[48:49]
	v_pk_add_f32 v[58:59], v[206:207], v[50:51]
	v_mul_f32_e32 v49, v57, v57
	v_add_f32_e32 v48, v56, v57
	v_fmac_f32_e32 v49, v56, v56
	v_add_f32_e32 v48, v58, v48
	v_fmac_f32_e32 v49, v58, v58
	v_add_f32_e32 v48, v59, v48
	v_fmac_f32_e32 v49, v59, v59
	v_add_f32_e32 v48, v60, v48
	v_add_f32_e32 v49, v61, v49
	ds_bpermute_b32 v50, v118, v48
	ds_bpermute_b32 v51, v118, v49
	global_store_dwordx4 v[66:67], v[56:59], off offset:528
	v_cvt_pk_bf16_f32 v54, v56, v57
	v_cvt_pk_bf16_f32 v55, v58, v59
	s_waitcnt lgkmcnt(0)
	v_add_f32_e32 v48, v48, v50
	v_add_f32_e32 v49, v49, v51
	ds_bpermute_b32 v50, v119, v48
	ds_bpermute_b32 v51, v119, v49
	flat_store_dwordx4 v[88:89], v[52:55] offset:256
	s_mov_b32 s100, -1
	s_mov_b32 s101, 0
	s_mov_b32 s98, 0xffff0000
	s_mov_b32 s99, 0
	s_and_saveexec_b64 s[30:31], s[100:101]
	s_cbranch_execz .LBB0_1339
	v_lshl_add_u64 v[52:53], s[8:9], 0, v[64:65]
	s_waitcnt lgkmcnt(0)
	v_add_f32_e32 v48, v48, v50
	v_add_f32_e32 v49, v49, v51
	v_cndmask_b32_e64 v48, v48, v49, s[98:99]
	v_cndmask_b32_e64 v49, 0, 4, s[98:99]
	v_or_b32_e32 v52, v52, v49
	flat_atomic_add_f32 v[52:53], v48
; DEVI unsigned pk2(float lo, float hi) { unsigned r; asm("v_cvt_pk_bf16_f32 %0, %1, %2" : "=v"(r) : "v"(lo), "v"(hi)); return r; }
; DEVI void row_stats(const float* stats, int row, float& mu, float& rs) {
;     if (stats) { const float2 st = *(const float2*)(stats + 2 * (size_t)row); mu = st.x * (1.0f / 1024.0f); const float var = st.y * (1.0f / 1024.0f) - mu * mu; rs = rsqrtf(fmaxf(var, 0.f) + LN_EPS); }
;     else { mu = 0.f; rs = 1.f; }
; }
;     DEVI void operator()(const f32x4 (&acc)[2][2][4][2], const pg8::Unit& u, int wr, int wc, int fr, int fq) const {
;     ...
;             for (int m = 0; m < 4; ++m) {
;                 const int row = row0 + ai * 128 + m * 16; float mu, rs; row_stats(stin, row, mu, rs);
;                 float sum = 0.f, sq = 0.f;
; #pragma unroll
;                 for (int bj = 0; bj < 2; ++bj) {
;                     f32x4 z[2];
; #pragma unroll
;                     for (int n = 0; n < 2; ++n) {
;                         const int col = colb + bj * 128 + 4 * n;
;                         f32x4 xv = *(const f32x4*)(zsrc + (size_t)row * DM + col);
;                         if (stin) { const f32x4 gv = *(const f32x4*)(gin + col), bv = *(const f32x4*)(bin + col); xv = (xv - mu) * rs * gv + bv; }
;                         f32x4 zz = ALPHA * xv + acc[ai][bj][m][n];
;                         if (bias) zz += *(const f32x4*)(bias + col);
;                         *(f32x4*)(zdst + (size_t)row * DM + col) = zz;
;                         sum += zz[0] + zz[1] + zz[2] + zz[3]; sq += zz[0] * zz[0] + zz[1] * zz[1] + zz[2] * zz[2] + zz[3] * zz[3];
;                         z[n] = zz;
;                     }
;                     u32x4 o; o.x = pk2(z[0][0], z[0][1]); o.y = pk2(z[0][2], z[0][3]); o.z = pk2(z[1][0], z[1][1]); o.w = pk2(z[1][2], z[1][3]);
;                     if (zb) *(u32x4*)(zb + (size_t)row * DM + colb + bj * 128) = o;
;                 }
;                 sum += __shfl_xor(sum, 16); sq += __shfl_xor(sq, 16);
;                 sum += __shfl_xor(sum, 32); sq += __shfl_xor(sq, 32);
;                 if (fq == 0) { atomicAdd(stout + 2 * (size_t)row, sum); atomicAdd(stout + 2 * (size_t)row + 1, sq); }
.LBB0_1339:
	s_or_b64 exec, exec, s[30:31]
	v_add_u32_e32 v72, 0x90, v150
	v_ashrrev_i32_e32 v73, 31, v72
	v_lshlrev_b64 v[48:49], 3, v[72:73]
	s_waitcnt lgkmcnt(0)
	v_lshl_add_u64 v[50:51], s[6:7], 0, v[48:49]
	flat_load_dwordx2 v[74:75], v[50:51]
	v_lshlrev_b64 v[50:51], 12, v[72:73]
	v_lshl_add_u64 v[50:51], s[46:47], 0, v[50:51]
	v_lshl_add_u64 v[50:51], v[148:149], 2, v[50:51]
	global_load_dwordx4 v[52:55], v[50:51], off
	global_load_dwordx4 v[56:59], v[144:145], off
	global_load_dwordx4 v[60:63], v[146:147], off
	global_load_dwordx4 v[64:67], v[152:153], off
	global_load_dwordx4 v[68:71], v[50:51], off offset:16
	global_load_dwordx4 v[196:199], v[144:145], off offset:16
	global_load_dwordx4 v[200:203], v[146:147], off offset:16
	global_load_dwordx4 v[204:207], v[154:155], off
	global_load_dwordx4 v[208:211], v[50:51], off offset:512
	global_load_dwordx4 v[212:215], v[50:51], off offset:528
	s_waitcnt vmcnt(0) lgkmcnt(0)
	v_pk_mul_f32 v[74:75], v[74:75], s[18:19] op_sel:[1,0] op_sel_hi:[0,0]
	v_fma_f32 v74, -v75, v75, v74
	v_max_f32_e32 v74, 0, v74
	v_add_f32_e32 v74, 0x3727c5ac, v74
	v_mul_f32_e32 v76, 0x4b800000, v74
	v_cmp_gt_f32_e32 vcc, s64, v74
	v_sub_f32_e32 v55, v55, v75
	v_sub_f32_e32 v54, v54, v75
	v_cndmask_b32_e32 v74, v74, v76, vcc
	v_rsq_f32_e32 v74, v74
	v_sub_f32_e32 v53, v53, v75
	v_sub_f32_e32 v52, v52, v75
	v_mul_f32_e32 v76, 0x45800000, v74
	v_cndmask_b32_e32 v74, v74, v76, vcc
	v_pk_mul_f32 v[52:53], v[52:53], v[74:75] op_sel_hi:[1,0]
	v_pk_mul_f32 v[54:55], v[54:55], v[74:75] op_sel_hi:[1,0]
	v_pk_fma_f32 v[52:53], v[56:57], v[52:53], v[60:61]
	v_pk_fma_f32 v[54:55], v[58:59], v[54:55], v[62:63]
	v_pk_fma_f32 v[44:45], v[52:53], s[20:21], v[44:45] op_sel_hi:[1,0,1]
	v_pk_fma_f32 v[46:47], v[54:55], s[20:21], v[46:47] op_sel_hi:[1,0,1]
	v_pk_add_f32 v[44:45], v[64:65], v[44:45]
	v_pk_add_f32 v[46:47], v[66:67], v[46:47]
	global_store_dwordx4 v[50:51], v[44:47], off
	v_lshlrev_b64 v[64:65], 11, v[72:73]
	v_lshl_add_u64 v[64:65], s[10:11], 0, v[64:65]
	v_lshl_add_u64 v[72:73], v[148:149], 1, v[64:65]
	v_sub_f32_e32 v65, v71, v75
	v_sub_f32_e32 v64, v70, v75
	v_sub_f32_e32 v67, v69, v75
	v_sub_f32_e32 v66, v68, v75
	v_pk_mul_f32 v[66:67], v[66:67], v[74:75] op_sel_hi:[1,0]
	v_pk_mul_f32 v[68:69], v[64:65], v[74:75] op_sel_hi:[1,0]
	v_cvt_pk_bf16_f32 v64, v44, v45
	v_cvt_pk_bf16_f32 v65, v46, v47
	v_pk_fma_f32 v[52:53], v[196:197], v[66:67], v[200:201]
	v_pk_fma_f32 v[54:55], v[198:199], v[68:69], v[202:203]
	v_pk_fma_f32 v[40:41], v[52:53], s[20:21], v[40:41] op_sel_hi:[1,0,1]
	v_pk_fma_f32 v[42:43], v[54:55], s[20:21], v[42:43] op_sel_hi:[1,0,1]
	v_pk_add_f32 v[40:41], v[204:205], v[40:41]
	v_pk_add_f32 v[42:43], v[206:207], v[42:43]
	global_store_dwordx4 v[50:51], v[40:43], off offset:16
	v_cvt_pk_bf16_f32 v66, v40, v41
	v_cvt_pk_bf16_f32 v67, v42, v43
	flat_store_dwordx4 v[72:73], v[64:67]
	global_load_dwordx4 v[56:59], v[144:145], off offset:512
	global_load_dwordx4 v[60:63], v[146:147], off offset:512
	s_nop 0
	global_load_dwordx4 v[64:67], v[120:121], off
	global_load_dwordx4 v[196:199], v[144:145], off offset:528
	global_load_dwordx4 v[200:203], v[146:147], off offset:528
	global_load_dwordx4 v[204:207], v[116:117], off
	s_waitcnt vmcnt(0)
	v_sub_f32_e32 v55, v211, v75
	v_sub_f32_e32 v54, v210, v75
	v_sub_f32_e32 v53, v209, v75
	v_sub_f32_e32 v52, v208, v75
	v_pk_mul_f32 v[52:53], v[74:75], v[52:53] op_sel_hi:[0,1]
	v_pk_mul_f32 v[54:55], v[74:75], v[54:55] op_sel_hi:[0,1]
	v_pk_fma_f32 v[54:55], v[58:59], v[54:55], v[62:63]
	v_pk_fma_f32 v[52:53], v[56:57], v[52:53], v[60:61]
	v_pk_fma_f32 v[38:39], v[54:55], s[20:21], v[38:39] op_sel_hi:[1,0,1]
	v_pk_fma_f32 v[36:37], v[52:53], s[20:21], v[36:37] op_sel_hi:[1,0,1]
	v_pk_add_f32 v[38:39], v[66:67], v[38:39]
	v_pk_add_f32 v[36:37], v[64:65], v[36:37]
	global_store_dwordx4 v[50:51], v[36:39], off offset:512
	v_add_f32_e32 v64, v44, v45
	v_mul_f32_e32 v45, v45, v45
	v_fmac_f32_e32 v45, v44, v44
	v_add_f32_e32 v64, v46, v64
	v_fmac_f32_e32 v45, v46, v46
	v_add_f32_e32 v46, v40, v41
	v_mul_f32_e32 v41, v41, v41
	v_fmac_f32_e32 v41, v40, v40
	v_add_f32_e32 v44, v47, v64
	v_add_f32_e32 v46, v42, v46
	v_fmac_f32_e32 v41, v42, v42
	v_add_f32_e32 v44, 0, v44
	v_fmac_f32_e32 v45, v47, v47
	v_add_f32_e32 v40, v43, v46
	v_fmac_f32_e32 v41, v43, v43
	v_sub_f32_e32 v43, v213, v75
	v_sub_f32_e32 v42, v212, v75
	v_add_f32_e32 v44, v40, v44
	v_add_f32_e32 v45, v45, v41
	v_sub_f32_e32 v41, v215, v75
	v_sub_f32_e32 v40, v214, v75
	v_pk_mul_f32 v[42:43], v[74:75], v[42:43] op_sel_hi:[0,1]
	v_pk_mul_f32 v[40:41], v[74:75], v[40:41] op_sel_hi:[0,1]
	v_mul_f32_e32 v47, v37, v37
	v_add_f32_e32 v46, v36, v37
	v_fmac_f32_e32 v47, v36, v36
	v_add_f32_e32 v46, v38, v46
	v_fmac_f32_e32 v47, v38, v38
	v_add_f32_e32 v46, v39, v46
	v_fmac_f32_e32 v47, v39, v39
	v_add_f32_e32 v44, v44, v46
	v_add_f32_e32 v45, v45, v47
	v_cvt_pk_bf16_f32 v36, v36, v37
	v_cvt_pk_bf16_f32 v37, v38, v39
	v_pk_fma_f32 v[42:43], v[196:197], v[42:43], v[200:201]
	v_pk_fma_f32 v[40:41], v[198:199], v[40:41], v[202:203]
	v_pk_fma_f32 v[32:33], v[42:43], s[20:21], v[32:33] op_sel_hi:[1,0,1]
	v_pk_fma_f32 v[34:35], v[40:41], s[20:21], v[34:35] op_sel_hi:[1,0,1]
	v_pk_add_f32 v[40:41], v[204:205], v[32:33]
	v_pk_add_f32 v[42:43], v[206:207], v[34:35]
	v_mul_f32_e32 v33, v41, v41
	v_add_f32_e32 v32, v40, v41
	v_fmac_f32_e32 v33, v40, v40
	v_add_f32_e32 v32, v42, v32
	v_fmac_f32_e32 v33, v42, v42
	v_add_f32_e32 v32, v43, v32
	v_fmac_f32_e32 v33, v43, v43
	v_add_f32_e32 v32, v44, v32
	v_add_f32_e32 v33, v45, v33
	ds_bpermute_b32 v34, v118, v32
	ds_bpermute_b32 v35, v118, v33
	global_store_dwordx4 v[50:51], v[40:43], off offset:528
	v_cvt_pk_bf16_f32 v38, v40, v41
	v_cvt_pk_bf16_f32 v39, v42, v43
	s_waitcnt lgkmcnt(0)
	v_add_f32_e32 v32, v32, v34
	v_add_f32_e32 v33, v33, v35
	ds_bpermute_b32 v34, v119, v32
	ds_bpermute_b32 v35, v119, v33
	flat_store_dwordx4 v[72:73], v[36:39] offset:256
	s_mov_b32 s100, -1
	s_mov_b32 s101, 0
	s_mov_b32 s98, 0xffff0000
	s_mov_b32 s99, 0
	s_and_saveexec_b64 s[30:31], s[100:101]
	s_cbranch_execz .LBB0_1341
	v_lshl_add_u64 v[36:37], s[8:9], 0, v[48:49]
	s_waitcnt lgkmcnt(0)
	v_add_f32_e32 v32, v32, v34
	v_add_f32_e32 v33, v33, v35
	v_cndmask_b32_e64 v32, v32, v33, s[98:99]
	v_cndmask_b32_e64 v33, 0, 4, s[98:99]
	v_or_b32_e32 v36, v36, v33
	flat_atomic_add_f32 v[36:37], v32
; DEVI unsigned pk2(float lo, float hi) { unsigned r; asm("v_cvt_pk_bf16_f32 %0, %1, %2" : "=v"(r) : "v"(lo), "v"(hi)); return r; }
; DEVI void row_stats(const float* stats, int row, float& mu, float& rs) {
;     if (stats) { const float2 st = *(const float2*)(stats + 2 * (size_t)row); mu = st.x * (1.0f / 1024.0f); const float var = st.y * (1.0f / 1024.0f) - mu * mu; rs = rsqrtf(fmaxf(var, 0.f) + LN_EPS); }
;     else { mu = 0.f; rs = 1.f; }
; }
;     DEVI void operator()(const f32x4 (&acc)[2][2][4][2], const pg8::Unit& u, int wr, int wc, int fr, int fq) const {
;     ...
;             for (int m = 0; m < 4; ++m) {
;                 const int row = row0 + ai * 128 + m * 16; float mu, rs; row_stats(stin, row, mu, rs);
;                 float sum = 0.f, sq = 0.f;
; #pragma unroll
;                 for (int bj = 0; bj < 2; ++bj) {
;                     f32x4 z[2];
; #pragma unroll
;                     for (int n = 0; n < 2; ++n) {
;                         const int col = colb + bj * 128 + 4 * n;
;                         f32x4 xv = *(const f32x4*)(zsrc + (size_t)row * DM + col);
;                         if (stin) { const f32x4 gv = *(const f32x4*)(gin + col), bv = *(const f32x4*)(bin + col); xv = (xv - mu) * rs * gv + bv; }
;                         f32x4 zz = ALPHA * xv + acc[ai][bj][m][n];
;                         if (bias) zz += *(const f32x4*)(bias + col);
;                         *(f32x4*)(zdst + (size_t)row * DM + col) = zz;
;                         sum += zz[0] + zz[1] + zz[2] + zz[3]; sq += zz[0] * zz[0] + zz[1] * zz[1] + zz[2] * zz[2] + zz[3] * zz[3];
;                         z[n] = zz;
;                     }
;                     u32x4 o; o.x = pk2(z[0][0], z[0][1]); o.y = pk2(z[0][2], z[0][3]); o.z = pk2(z[1][0], z[1][1]); o.w = pk2(z[1][2], z[1][3]);
;                     if (zb) *(u32x4*)(zb + (size_t)row * DM + colb + bj * 128) = o;
;                 }
;                 sum += __shfl_xor(sum, 16); sq += __shfl_xor(sq, 16);
;                 sum += __shfl_xor(sum, 32); sq += __shfl_xor(sq, 32);
;                 if (fq == 0) { atomicAdd(stout + 2 * (size_t)row, sum); atomicAdd(stout + 2 * (size_t)row + 1, sq); }
.LBB0_1341:
	s_or_b64 exec, exec, s[30:31]
	v_add_u32_e32 v56, 0xa0, v150
	v_ashrrev_i32_e32 v57, 31, v56
	v_lshlrev_b64 v[32:33], 3, v[56:57]
	s_waitcnt lgkmcnt(0)
	v_lshl_add_u64 v[34:35], s[6:7], 0, v[32:33]
	flat_load_dwordx2 v[58:59], v[34:35]
	v_lshlrev_b64 v[34:35], 12, v[56:57]
	v_lshl_add_u64 v[34:35], s[46:47], 0, v[34:35]
	v_lshl_add_u64 v[34:35], v[148:149], 2, v[34:35]
	global_load_dwordx4 v[36:39], v[34:35], off
	global_load_dwordx4 v[40:43], v[144:145], off
	global_load_dwordx4 v[44:47], v[146:147], off
	global_load_dwordx4 v[48:51], v[152:153], off
	global_load_dwordx4 v[52:55], v[34:35], off offset:16
	global_load_dwordx4 v[196:199], v[144:145], off offset:16
	global_load_dwordx4 v[200:203], v[146:147], off offset:16
	global_load_dwordx4 v[204:207], v[154:155], off
	global_load_dwordx4 v[208:211], v[34:35], off offset:512
	global_load_dwordx4 v[212:215], v[34:35], off offset:528
	s_waitcnt vmcnt(0) lgkmcnt(0)
	v_pk_mul_f32 v[58:59], v[58:59], s[18:19] op_sel:[1,0] op_sel_hi:[0,0]
	v_fma_f32 v58, -v59, v59, v58
	v_max_f32_e32 v58, 0, v58
	v_add_f32_e32 v58, 0x3727c5ac, v58
	v_mul_f32_e32 v60, 0x4b800000, v58
	v_cmp_gt_f32_e32 vcc, s64, v58
	v_sub_f32_e32 v39, v39, v59
	v_sub_f32_e32 v38, v38, v59
	v_cndmask_b32_e32 v58, v58, v60, vcc
	v_rsq_f32_e32 v58, v58
	v_sub_f32_e32 v37, v37, v59
	v_sub_f32_e32 v36, v36, v59
	v_mul_f32_e32 v60, 0x45800000, v58
	v_cndmask_b32_e32 v58, v58, v60, vcc
	v_pk_mul_f32 v[36:37], v[36:37], v[58:59] op_sel_hi:[1,0]
	v_pk_mul_f32 v[38:39], v[38:39], v[58:59] op_sel_hi:[1,0]
	v_pk_fma_f32 v[36:37], v[40:41], v[36:37], v[44:45]
	v_pk_fma_f32 v[38:39], v[42:43], v[38:39], v[46:47]
	v_pk_fma_f32 v[28:29], v[36:37], s[20:21], v[28:29] op_sel_hi:[1,0,1]
	v_pk_fma_f32 v[30:31], v[38:39], s[20:21], v[30:31] op_sel_hi:[1,0,1]
	v_pk_add_f32 v[28:29], v[48:49], v[28:29]
	v_pk_add_f32 v[30:31], v[50:51], v[30:31]
	global_store_dwordx4 v[34:35], v[28:31], off
	v_lshlrev_b64 v[48:49], 11, v[56:57]
	v_lshl_add_u64 v[48:49], s[10:11], 0, v[48:49]
	v_lshl_add_u64 v[56:57], v[148:149], 1, v[48:49]
	v_sub_f32_e32 v49, v55, v59
	v_sub_f32_e32 v48, v54, v59
	v_sub_f32_e32 v51, v53, v59
	v_sub_f32_e32 v50, v52, v59
	v_pk_mul_f32 v[50:51], v[50:51], v[58:59] op_sel_hi:[1,0]
	v_pk_mul_f32 v[52:53], v[48:49], v[58:59] op_sel_hi:[1,0]
	v_cvt_pk_bf16_f32 v48, v28, v29
	v_cvt_pk_bf16_f32 v49, v30, v31
	v_pk_fma_f32 v[36:37], v[196:197], v[50:51], v[200:201]
	v_pk_fma_f32 v[38:39], v[198:199], v[52:53], v[202:203]
	v_pk_fma_f32 v[24:25], v[36:37], s[20:21], v[24:25] op_sel_hi:[1,0,1]
	v_pk_fma_f32 v[26:27], v[38:39], s[20:21], v[26:27] op_sel_hi:[1,0,1]
	v_pk_add_f32 v[24:25], v[204:205], v[24:25]
	v_pk_add_f32 v[26:27], v[206:207], v[26:27]
	global_store_dwordx4 v[34:35], v[24:27], off offset:16
	v_cvt_pk_bf16_f32 v50, v24, v25
	v_cvt_pk_bf16_f32 v51, v26, v27
	flat_store_dwordx4 v[56:57], v[48:51]
	global_load_dwordx4 v[40:43], v[144:145], off offset:512
	global_load_dwordx4 v[44:47], v[146:147], off offset:512
	s_nop 0
	global_load_dwordx4 v[48:51], v[120:121], off
	global_load_dwordx4 v[196:199], v[144:145], off offset:528
	global_load_dwordx4 v[200:203], v[146:147], off offset:528
	global_load_dwordx4 v[204:207], v[116:117], off
	s_waitcnt vmcnt(0)
	v_sub_f32_e32 v39, v211, v59
	v_sub_f32_e32 v38, v210, v59
	v_sub_f32_e32 v37, v209, v59
	v_sub_f32_e32 v36, v208, v59
	v_pk_mul_f32 v[36:37], v[58:59], v[36:37] op_sel_hi:[0,1]
	v_pk_mul_f32 v[38:39], v[58:59], v[38:39] op_sel_hi:[0,1]
	v_pk_fma_f32 v[38:39], v[42:43], v[38:39], v[46:47]
	v_pk_fma_f32 v[36:37], v[40:41], v[36:37], v[44:45]
	v_pk_fma_f32 v[22:23], v[38:39], s[20:21], v[22:23] op_sel_hi:[1,0,1]
	v_pk_fma_f32 v[20:21], v[36:37], s[20:21], v[20:21] op_sel_hi:[1,0,1]
	v_pk_add_f32 v[22:23], v[50:51], v[22:23]
	v_pk_add_f32 v[20:21], v[48:49], v[20:21]
	global_store_dwordx4 v[34:35], v[20:23], off offset:512
	v_add_f32_e32 v48, v28, v29
	v_mul_f32_e32 v29, v29, v29
	v_fmac_f32_e32 v29, v28, v28
	v_add_f32_e32 v48, v30, v48
	v_fmac_f32_e32 v29, v30, v30
	v_add_f32_e32 v30, v24, v25
	v_mul_f32_e32 v25, v25, v25
	v_fmac_f32_e32 v25, v24, v24
	v_add_f32_e32 v28, v31, v48
	v_add_f32_e32 v30, v26, v30
	v_fmac_f32_e32 v25, v26, v26
	v_add_f32_e32 v28, 0, v28
	v_fmac_f32_e32 v29, v31, v31
	v_add_f32_e32 v24, v27, v30
	v_fmac_f32_e32 v25, v27, v27
	v_sub_f32_e32 v27, v213, v59
	v_sub_f32_e32 v26, v212, v59
	v_add_f32_e32 v28, v24, v28
	v_add_f32_e32 v29, v29, v25
	v_sub_f32_e32 v25, v215, v59
	v_sub_f32_e32 v24, v214, v59
	v_pk_mul_f32 v[26:27], v[58:59], v[26:27] op_sel_hi:[0,1]
	v_pk_mul_f32 v[24:25], v[58:59], v[24:25] op_sel_hi:[0,1]
	v_mul_f32_e32 v31, v21, v21
	v_add_f32_e32 v30, v20, v21
	v_fmac_f32_e32 v31, v20, v20
	v_add_f32_e32 v30, v22, v30
	v_fmac_f32_e32 v31, v22, v22
	v_add_f32_e32 v30, v23, v30
	v_fmac_f32_e32 v31, v23, v23
	v_add_f32_e32 v28, v28, v30
	v_add_f32_e32 v29, v29, v31
	v_cvt_pk_bf16_f32 v20, v20, v21
	v_cvt_pk_bf16_f32 v21, v22, v23
	v_pk_fma_f32 v[26:27], v[196:197], v[26:27], v[200:201]
	v_pk_fma_f32 v[24:25], v[198:199], v[24:25], v[202:203]
	v_pk_fma_f32 v[16:17], v[26:27], s[20:21], v[16:17] op_sel_hi:[1,0,1]
	v_pk_fma_f32 v[18:19], v[24:25], s[20:21], v[18:19] op_sel_hi:[1,0,1]
	v_pk_add_f32 v[24:25], v[204:205], v[16:17]
	v_pk_add_f32 v[26:27], v[206:207], v[18:19]
	v_mul_f32_e32 v17, v25, v25
	v_add_f32_e32 v16, v24, v25
	v_fmac_f32_e32 v17, v24, v24
	v_add_f32_e32 v16, v26, v16
	v_fmac_f32_e32 v17, v26, v26
	v_add_f32_e32 v16, v27, v16
	v_fmac_f32_e32 v17, v27, v27
	v_add_f32_e32 v16, v28, v16
	v_add_f32_e32 v17, v29, v17
	ds_bpermute_b32 v18, v118, v16
	ds_bpermute_b32 v19, v118, v17
	global_store_dwordx4 v[34:35], v[24:27], off offset:528
	v_cvt_pk_bf16_f32 v22, v24, v25
	v_cvt_pk_bf16_f32 v23, v26, v27
	s_waitcnt lgkmcnt(0)
	v_add_f32_e32 v16, v16, v18
	v_add_f32_e32 v17, v17, v19
	ds_bpermute_b32 v18, v119, v16
	ds_bpermute_b32 v19, v119, v17
	flat_store_dwordx4 v[56:57], v[20:23] offset:256
	s_mov_b32 s100, -1
	s_mov_b32 s101, 0
	s_mov_b32 s98, 0xffff0000
	s_mov_b32 s99, 0
	s_and_saveexec_b64 s[30:31], s[100:101]
	s_cbranch_execz .LBB0_1343
	v_lshl_add_u64 v[20:21], s[8:9], 0, v[32:33]
	s_waitcnt lgkmcnt(0)
	v_add_f32_e32 v16, v16, v18
	v_add_f32_e32 v17, v17, v19
	v_cndmask_b32_e64 v16, v16, v17, s[98:99]
	v_cndmask_b32_e64 v17, 0, 4, s[98:99]
	v_or_b32_e32 v20, v20, v17
	flat_atomic_add_f32 v[20:21], v16
; DEVI unsigned pk2(float lo, float hi) { unsigned r; asm("v_cvt_pk_bf16_f32 %0, %1, %2" : "=v"(r) : "v"(lo), "v"(hi)); return r; }
; DEVI void row_stats(const float* stats, int row, float& mu, float& rs) {
;     if (stats) { const float2 st = *(const float2*)(stats + 2 * (size_t)row); mu = st.x * (1.0f / 1024.0f); const float var = st.y * (1.0f / 1024.0f) - mu * mu; rs = rsqrtf(fmaxf(var, 0.f) + LN_EPS); }
;     else { mu = 0.f; rs = 1.f; }
; }
;     DEVI void operator()(const f32x4 (&acc)[2][2][4][2], const pg8::Unit& u, int wr, int wc, int fr, int fq) const {
;     ...
;             for (int m = 0; m < 4; ++m) {
;                 const int row = row0 + ai * 128 + m * 16; float mu, rs; row_stats(stin, row, mu, rs);
;                 float sum = 0.f, sq = 0.f;
; #pragma unroll
;                 for (int bj = 0; bj < 2; ++bj) {
;                     f32x4 z[2];
; #pragma unroll
;                     for (int n = 0; n < 2; ++n) {
;                         const int col = colb + bj * 128 + 4 * n;
;                         f32x4 xv = *(const f32x4*)(zsrc + (size_t)row * DM + col);
;                         if (stin) { const f32x4 gv = *(const f32x4*)(gin + col), bv = *(const f32x4*)(bin + col); xv = (xv - mu) * rs * gv + bv; }
;                         f32x4 zz = ALPHA * xv + acc[ai][bj][m][n];
;                         if (bias) zz += *(const f32x4*)(bias + col);
;                         *(f32x4*)(zdst + (size_t)row * DM + col) = zz;
;                         sum += zz[0] + zz[1] + zz[2] + zz[3]; sq += zz[0] * zz[0] + zz[1] * zz[1] + zz[2] * zz[2] + zz[3] * zz[3];
;                         z[n] = zz;
;                     }
;                     u32x4 o; o.x = pk2(z[0][0], z[0][1]); o.y = pk2(z[0][2], z[0][3]); o.z = pk2(z[1][0], z[1][1]); o.w = pk2(z[1][2], z[1][3]);
;                     if (zb) *(u32x4*)(zb + (size_t)row * DM + colb + bj * 128) = o;
;                 }
;                 sum += __shfl_xor(sum, 16); sq += __shfl_xor(sq, 16);
;                 sum += __shfl_xor(sum, 32); sq += __shfl_xor(sq, 32);
;                 if (fq == 0) { atomicAdd(stout + 2 * (size_t)row, sum); atomicAdd(stout + 2 * (size_t)row + 1, sq); }
.LBB0_1343:
	s_or_b64 exec, exec, s[30:31]
	v_add_u32_e32 v40, 0xb0, v150
	v_ashrrev_i32_e32 v41, 31, v40
	v_lshlrev_b64 v[16:17], 3, v[40:41]
	s_waitcnt lgkmcnt(0)
	v_lshl_add_u64 v[18:19], s[6:7], 0, v[16:17]
	flat_load_dwordx2 v[42:43], v[18:19]
	v_lshlrev_b64 v[18:19], 12, v[40:41]
	v_lshl_add_u64 v[18:19], s[46:47], 0, v[18:19]
	v_lshl_add_u64 v[18:19], v[148:149], 2, v[18:19]
	global_load_dwordx4 v[20:23], v[18:19], off
	global_load_dwordx4 v[24:27], v[144:145], off
	global_load_dwordx4 v[28:31], v[146:147], off
	global_load_dwordx4 v[32:35], v[152:153], off
	global_load_dwordx4 v[36:39], v[18:19], off offset:16
	global_load_dwordx4 v[196:199], v[144:145], off offset:16
	global_load_dwordx4 v[200:203], v[146:147], off offset:16
	global_load_dwordx4 v[204:207], v[154:155], off
	global_load_dwordx4 v[208:211], v[18:19], off offset:512
	global_load_dwordx4 v[212:215], v[18:19], off offset:528
	s_waitcnt vmcnt(0) lgkmcnt(0)
	v_pk_mul_f32 v[42:43], v[42:43], s[18:19] op_sel:[1,0] op_sel_hi:[0,0]
	v_fma_f32 v42, -v43, v43, v42
	v_max_f32_e32 v42, 0, v42
	v_add_f32_e32 v42, 0x3727c5ac, v42
	v_mul_f32_e32 v44, 0x4b800000, v42
	v_cmp_gt_f32_e32 vcc, s64, v42
	v_sub_f32_e32 v23, v23, v43
	v_sub_f32_e32 v22, v22, v43
	v_cndmask_b32_e32 v42, v42, v44, vcc
	v_rsq_f32_e32 v42, v42
	v_sub_f32_e32 v21, v21, v43
	v_sub_f32_e32 v20, v20, v43
	v_mul_f32_e32 v44, 0x45800000, v42
	v_cndmask_b32_e32 v42, v42, v44, vcc
	v_pk_mul_f32 v[20:21], v[20:21], v[42:43] op_sel_hi:[1,0]
	v_pk_mul_f32 v[22:23], v[22:23], v[42:43] op_sel_hi:[1,0]
	v_pk_fma_f32 v[20:21], v[24:25], v[20:21], v[28:29]
	v_pk_fma_f32 v[22:23], v[26:27], v[22:23], v[30:31]
	v_pk_fma_f32 v[12:13], v[20:21], s[20:21], v[12:13] op_sel_hi:[1,0,1]
	v_pk_fma_f32 v[14:15], v[22:23], s[20:21], v[14:15] op_sel_hi:[1,0,1]
	v_pk_add_f32 v[12:13], v[32:33], v[12:13]
	v_pk_add_f32 v[14:15], v[34:35], v[14:15]
	global_store_dwordx4 v[18:19], v[12:15], off
	v_lshlrev_b64 v[32:33], 11, v[40:41]
	v_lshl_add_u64 v[32:33], s[10:11], 0, v[32:33]
	v_lshl_add_u64 v[40:41], v[148:149], 1, v[32:33]
	v_sub_f32_e32 v33, v39, v43
	v_sub_f32_e32 v32, v38, v43
	v_sub_f32_e32 v35, v37, v43
	v_sub_f32_e32 v34, v36, v43
	v_pk_mul_f32 v[34:35], v[34:35], v[42:43] op_sel_hi:[1,0]
	v_pk_mul_f32 v[36:37], v[32:33], v[42:43] op_sel_hi:[1,0]
	v_cvt_pk_bf16_f32 v32, v12, v13
	v_cvt_pk_bf16_f32 v33, v14, v15
	v_pk_fma_f32 v[20:21], v[196:197], v[34:35], v[200:201]
	v_pk_fma_f32 v[22:23], v[198:199], v[36:37], v[202:203]
	v_pk_fma_f32 v[8:9], v[20:21], s[20:21], v[8:9] op_sel_hi:[1,0,1]
	v_pk_fma_f32 v[10:11], v[22:23], s[20:21], v[10:11] op_sel_hi:[1,0,1]
	v_pk_add_f32 v[8:9], v[204:205], v[8:9]
	v_pk_add_f32 v[10:11], v[206:207], v[10:11]
	global_store_dwordx4 v[18:19], v[8:11], off offset:16
	v_cvt_pk_bf16_f32 v34, v8, v9
	v_cvt_pk_bf16_f32 v35, v10, v11
	flat_store_dwordx4 v[40:41], v[32:35]
	global_load_dwordx4 v[24:27], v[144:145], off offset:512
	global_load_dwordx4 v[28:31], v[146:147], off offset:512
	s_nop 0
	global_load_dwordx4 v[32:35], v[120:121], off
	global_load_dwordx4 v[196:199], v[144:145], off offset:528
	global_load_dwordx4 v[200:203], v[146:147], off offset:528
	global_load_dwordx4 v[204:207], v[116:117], off
	s_waitcnt vmcnt(0)
	v_sub_f32_e32 v23, v211, v43
	v_sub_f32_e32 v22, v210, v43
	v_sub_f32_e32 v21, v209, v43
	v_sub_f32_e32 v20, v208, v43
	v_pk_mul_f32 v[20:21], v[42:43], v[20:21] op_sel_hi:[0,1]
	v_pk_mul_f32 v[22:23], v[42:43], v[22:23] op_sel_hi:[0,1]
	v_pk_fma_f32 v[22:23], v[26:27], v[22:23], v[30:31]
	v_pk_fma_f32 v[20:21], v[24:25], v[20:21], v[28:29]
	v_pk_fma_f32 v[6:7], v[22:23], s[20:21], v[6:7] op_sel_hi:[1,0,1]
	v_pk_fma_f32 v[4:5], v[20:21], s[20:21], v[4:5] op_sel_hi:[1,0,1]
	v_pk_add_f32 v[6:7], v[34:35], v[6:7]
	v_pk_add_f32 v[4:5], v[32:33], v[4:5]
	global_store_dwordx4 v[18:19], v[4:7], off offset:512
	v_add_f32_e32 v32, v12, v13
	v_mul_f32_e32 v13, v13, v13
	v_fmac_f32_e32 v13, v12, v12
	v_add_f32_e32 v32, v14, v32
	v_fmac_f32_e32 v13, v14, v14
	v_add_f32_e32 v14, v8, v9
	v_mul_f32_e32 v9, v9, v9
	v_fmac_f32_e32 v9, v8, v8
	v_add_f32_e32 v12, v15, v32
	v_add_f32_e32 v14, v10, v14
	v_fmac_f32_e32 v9, v10, v10
	v_add_f32_e32 v12, 0, v12
	v_fmac_f32_e32 v13, v15, v15
	v_add_f32_e32 v8, v11, v14
	v_fmac_f32_e32 v9, v11, v11
	v_sub_f32_e32 v11, v213, v43
	v_sub_f32_e32 v10, v212, v43
	v_add_f32_e32 v12, v8, v12
	v_add_f32_e32 v13, v13, v9
	v_sub_f32_e32 v9, v215, v43
	v_sub_f32_e32 v8, v214, v43
	v_pk_mul_f32 v[10:11], v[42:43], v[10:11] op_sel_hi:[0,1]
	v_pk_mul_f32 v[8:9], v[42:43], v[8:9] op_sel_hi:[0,1]
	v_mul_f32_e32 v15, v5, v5
	v_add_f32_e32 v14, v4, v5
	v_fmac_f32_e32 v15, v4, v4
	v_add_f32_e32 v14, v6, v14
	v_fmac_f32_e32 v15, v6, v6
	v_add_f32_e32 v14, v7, v14
	v_fmac_f32_e32 v15, v7, v7
	v_add_f32_e32 v12, v12, v14
	v_add_f32_e32 v13, v13, v15
	v_cvt_pk_bf16_f32 v4, v4, v5
	v_cvt_pk_bf16_f32 v5, v6, v7
	v_pk_fma_f32 v[10:11], v[196:197], v[10:11], v[200:201]
	v_pk_fma_f32 v[8:9], v[198:199], v[8:9], v[202:203]
	v_pk_fma_f32 v[0:1], v[10:11], s[20:21], v[0:1] op_sel_hi:[1,0,1]
	v_pk_fma_f32 v[2:3], v[8:9], s[20:21], v[2:3] op_sel_hi:[1,0,1]
	v_pk_add_f32 v[8:9], v[204:205], v[0:1]
	v_pk_add_f32 v[10:11], v[206:207], v[2:3]
	v_mul_f32_e32 v1, v9, v9
	v_add_f32_e32 v0, v8, v9
	v_fmac_f32_e32 v1, v8, v8
	v_add_f32_e32 v0, v10, v0
	v_fmac_f32_e32 v1, v10, v10
	v_add_f32_e32 v0, v11, v0
	v_fmac_f32_e32 v1, v11, v11
	v_add_f32_e32 v0, v12, v0
	v_add_f32_e32 v1, v13, v1
	ds_bpermute_b32 v2, v118, v0
	ds_bpermute_b32 v3, v118, v1
	global_store_dwordx4 v[18:19], v[8:11], off offset:528
	v_cvt_pk_bf16_f32 v6, v8, v9
	v_cvt_pk_bf16_f32 v7, v10, v11
	s_waitcnt lgkmcnt(0)
	v_add_f32_e32 v0, v0, v2
	v_add_f32_e32 v1, v1, v3
	ds_bpermute_b32 v2, v119, v0
	ds_bpermute_b32 v3, v119, v1
	flat_store_dwordx4 v[40:41], v[4:7] offset:256
	s_mov_b32 s100, -1
	s_mov_b32 s101, 0
	s_mov_b32 s98, 0xffff0000
	s_mov_b32 s99, 0
	s_and_saveexec_b64 s[30:31], s[100:101]
	s_cbranch_execz .LBB0_1345
	v_lshl_add_u64 v[4:5], s[8:9], 0, v[16:17]
	s_waitcnt lgkmcnt(0)
	v_add_f32_e32 v0, v0, v2
	v_add_f32_e32 v1, v1, v3
	v_cndmask_b32_e64 v0, v0, v1, s[98:99]
	v_cndmask_b32_e64 v1, 0, 4, s[98:99]
	v_or_b32_e32 v4, v4, v1
	flat_atomic_add_f32 v[4:5], v0

; DEVI unsigned pk2(float lo, float hi) { unsigned r; asm("v_cvt_pk_bf16_f32 %0, %1, %2" : "=v"(r) : "v"(lo), "v"(hi)); return r; }
; DEVI void row_stats(const float* stats, int row, float& mu, float& rs) {
;     if (stats) { const float2 st = *(const float2*)(stats + 2 * (size_t)row); mu = st.x * (1.0f / 1024.0f); const float var = st.y * (1.0f / 1024.0f) - mu * mu; rs = rsqrtf(fmaxf(var, 0.f) + LN_EPS); }
;     else { mu = 0.f; rs = 1.f; }
; }
;     DEVI void operator()(const f32x4 (&acc)[2][2][4][2], const pg8::Unit& u, int wr, int wc, int fr, int fq) const {
;     ...
;             for (int m = 0; m < 4; ++m) {
;                 const int row = row0 + ai * 128 + m * 16; float mu, rs; row_stats(stin, row, mu, rs);
;                 float sum = 0.f, sq = 0.f;
; #pragma unroll
;                 for (int bj = 0; bj < 2; ++bj) {
;                     f32x4 z[2];
; #pragma unroll
;                     for (int n = 0; n < 2; ++n) {
;                         const int col = colb + bj * 128 + 4 * n;
;                         f32x4 xv = *(const f32x4*)(zsrc + (size_t)row * DM + col);
;                         if (stin) { const f32x4 gv = *(const f32x4*)(gin + col), bv = *(const f32x4*)(bin + col); xv = (xv - mu) * rs * gv + bv; }
;                         f32x4 zz = ALPHA * xv + acc[ai][bj][m][n];
;                         if (bias) zz += *(const f32x4*)(bias + col);
;                         *(f32x4*)(zdst + (size_t)row * DM + col) = zz;
;                         sum += zz[0] + zz[1] + zz[2] + zz[3]; sq += zz[0] * zz[0] + zz[1] * zz[1] + zz[2] * zz[2] + zz[3] * zz[3];
;                         z[n] = zz;
;                     }
;                     u32x4 o; o.x = pk2(z[0][0], z[0][1]); o.y = pk2(z[0][2], z[0][3]); o.z = pk2(z[1][0], z[1][1]); o.w = pk2(z[1][2], z[1][3]);
;                     if (zb) *(u32x4*)(zb + (size_t)row * DM + colb + bj * 128) = o;
;                 }
;                 sum += __shfl_xor(sum, 16); sq += __shfl_xor(sq, 16);
;                 sum += __shfl_xor(sum, 32); sq += __shfl_xor(sq, 32);
;                 if (fq == 0) { atomicAdd(stout + 2 * (size_t)row, sum); atomicAdd(stout + 2 * (size_t)row + 1, sq); }
.LBB0_1540:
	s_or_b64 exec, exec, s[30:31]
	v_or_b32_e32 v118, 16, v154
	v_ashrrev_i32_e32 v119, 31, v118
	v_lshlrev_b64 v[112:113], 3, v[118:119]
	s_waitcnt lgkmcnt(0)
	v_lshl_add_u64 v[114:115], s[12:13], 0, v[112:113]
	flat_load_dwordx2 v[160:161], v[114:115]
	v_lshlrev_b64 v[114:115], 12, v[118:119]
	v_lshl_add_u64 v[114:115], s[46:47], 0, v[114:115]
	v_lshl_add_u64 v[114:115], v[144:145], 2, v[114:115]
	global_load_dwordx4 v[156:159], v[114:115], off
	global_load_dwordx4 v[170:173], v[150:151], off
	global_load_dwordx4 v[174:177], v[152:153], off
	global_load_dwordx4 v[178:181], v[114:115], off offset:16
	v_lshlrev_b64 v[118:119], 11, v[118:119]
	v_lshl_add_u64 v[118:119], s[14:15], 0, v[118:119]
	v_lshl_add_u64 v[118:119], v[144:145], 1, v[118:119]
	global_load_dwordx4 v[196:199], v[146:147], off
	global_load_dwordx4 v[200:203], v[148:149], off
	global_load_dwordx4 v[204:207], v[114:115], off offset:512
	global_load_dwordx4 v[208:211], v[114:115], off offset:528
	s_waitcnt vmcnt(0) lgkmcnt(0)
	v_pk_mul_f32 v[160:161], v[160:161], s[24:25] op_sel:[1,0] op_sel_hi:[0,0]
	v_fma_f32 v155, -v161, v161, v160
	v_max_f32_e32 v155, 0, v155
	v_add_f32_e32 v155, 0x3727c5ac, v155
	v_mul_f32_e32 v160, 0x4b800000, v155
	v_cmp_gt_f32_e32 vcc, s61, v155
	v_sub_f32_e32 v157, v157, v161
	v_sub_f32_e32 v156, v156, v161
	v_cndmask_b32_e32 v155, v155, v160, vcc
	v_rsq_f32_e32 v155, v155
	v_sub_f32_e32 v159, v159, v161
	v_sub_f32_e32 v158, v158, v161
	v_mul_f32_e32 v160, 0x45800000, v155
	v_cndmask_b32_e32 v160, v155, v160, vcc
	v_pk_mul_f32 v[158:159], v[158:159], v[160:161] op_sel_hi:[1,0]
	v_pk_mul_f32 v[156:157], v[156:157], v[160:161] op_sel_hi:[1,0]
	v_pk_fma_f32 v[158:159], v[172:173], v[158:159], v[176:177]
	v_pk_fma_f32 v[156:157], v[170:171], v[156:157], v[174:175]
	v_pk_fma_f32 v[110:111], v[158:159], s[26:27], v[110:111] op_sel_hi:[1,0,1]
	v_pk_fma_f32 v[108:109], v[156:157], s[26:27], v[108:109] op_sel_hi:[1,0,1]
	global_store_dwordx4 v[114:115], v[108:111], off
	v_sub_f32_e32 v175, v179, v161
	v_sub_f32_e32 v174, v178, v161
	v_sub_f32_e32 v177, v181, v161
	v_sub_f32_e32 v176, v180, v161
	v_pk_mul_f32 v[176:177], v[176:177], v[160:161] op_sel_hi:[1,0]
	v_pk_mul_f32 v[178:179], v[174:175], v[160:161] op_sel_hi:[1,0]
	v_cvt_pk_bf16_f32 v174, v108, v109
	v_cvt_pk_bf16_f32 v175, v110, v111
	v_add_f32_e32 v155, v108, v109
	v_mul_f32_e32 v109, v109, v109
	v_fmac_f32_e32 v109, v108, v108
	v_add_f32_e32 v155, v110, v155
	v_fmac_f32_e32 v109, v110, v110
	v_add_f32_e32 v108, v111, v155
	v_add_f32_e32 v108, 0, v108
	v_fmac_f32_e32 v109, v111, v111
	v_pk_fma_f32 v[156:157], v[196:197], v[178:179], v[200:201]
	v_pk_fma_f32 v[158:159], v[198:199], v[176:177], v[202:203]
	v_pk_fma_f32 v[104:105], v[156:157], s[26:27], v[104:105] op_sel_hi:[1,0,1]
	v_pk_fma_f32 v[106:107], v[158:159], s[26:27], v[106:107] op_sel_hi:[1,0,1]
	global_store_dwordx4 v[114:115], v[104:107], off offset:16
	v_cvt_pk_bf16_f32 v176, v104, v105
	v_cvt_pk_bf16_f32 v177, v106, v107
	flat_store_dwordx4 v[118:119], v[174:177]
	global_load_dwordx4 v[170:173], v[120:121], off
	s_nop 0
	global_load_dwordx4 v[174:177], v[122:123], off
	v_add_f32_e32 v110, v104, v105
	v_mul_f32_e32 v105, v105, v105
	v_fmac_f32_e32 v105, v104, v104
	v_add_f32_e32 v110, v106, v110
	v_fmac_f32_e32 v105, v106, v106
	v_add_f32_e32 v104, v107, v110
	v_fmac_f32_e32 v105, v107, v107
	v_add_f32_e32 v108, v104, v108
	v_add_f32_e32 v109, v109, v105
	global_load_dwordx4 v[196:199], v[124:125], off
	global_load_dwordx4 v[200:203], v[126:127], off
	s_waitcnt vmcnt(0)
	v_sub_f32_e32 v157, v205, v161
	v_sub_f32_e32 v156, v204, v161
	v_sub_f32_e32 v159, v207, v161
	v_sub_f32_e32 v158, v206, v161
	v_pk_mul_f32 v[158:159], v[160:161], v[158:159] op_sel_hi:[0,1]
	v_pk_mul_f32 v[156:157], v[160:161], v[156:157] op_sel_hi:[0,1]
	v_pk_fma_f32 v[156:157], v[170:171], v[156:157], v[174:175]
	v_pk_fma_f32 v[158:159], v[172:173], v[158:159], v[176:177]
	v_pk_fma_f32 v[100:101], v[156:157], s[26:27], v[100:101] op_sel_hi:[1,0,1]
	v_pk_fma_f32 v[102:103], v[158:159], s[26:27], v[102:103] op_sel_hi:[1,0,1]
	global_store_dwordx4 v[114:115], v[100:103], off offset:512
	v_sub_f32_e32 v105, v209, v161
	v_sub_f32_e32 v104, v208, v161
	v_pk_mul_f32 v[104:105], v[160:161], v[104:105] op_sel_hi:[0,1]
	v_sub_f32_e32 v107, v211, v161
	v_sub_f32_e32 v106, v210, v161
	v_pk_mul_f32 v[106:107], v[160:161], v[106:107] op_sel_hi:[0,1]
	v_mul_f32_e32 v111, v101, v101
	v_add_f32_e32 v110, v100, v101
	v_fmac_f32_e32 v111, v100, v100
	v_add_f32_e32 v110, v102, v110
	v_fmac_f32_e32 v111, v102, v102
	v_add_f32_e32 v110, v103, v110
	v_fmac_f32_e32 v111, v103, v103
	v_add_f32_e32 v108, v108, v110
	v_add_f32_e32 v109, v109, v111
	v_cvt_pk_bf16_f32 v100, v100, v101
	v_cvt_pk_bf16_f32 v101, v102, v103
	v_pk_fma_f32 v[104:105], v[196:197], v[104:105], v[200:201]
	s_nop 0
	v_pk_fma_f32 v[104:105], v[104:105], s[26:27], v[96:97] op_sel_hi:[1,0,1]
	v_pk_fma_f32 v[106:107], v[198:199], v[106:107], v[202:203]
	v_mul_f32_e32 v97, v105, v105
	v_pk_fma_f32 v[106:107], v[106:107], s[26:27], v[98:99] op_sel_hi:[1,0,1]
	v_add_f32_e32 v96, v104, v105
	v_fmac_f32_e32 v97, v104, v104
	v_add_f32_e32 v96, v106, v96
	v_fmac_f32_e32 v97, v106, v106
	v_add_f32_e32 v96, v107, v96
	v_fmac_f32_e32 v97, v107, v107
	v_add_f32_e32 v96, v108, v96
	v_add_f32_e32 v97, v109, v97
	ds_bpermute_b32 v98, v116, v96
	ds_bpermute_b32 v99, v116, v97
	global_store_dwordx4 v[114:115], v[104:107], off offset:528
	v_cvt_pk_bf16_f32 v102, v104, v105
	v_cvt_pk_bf16_f32 v103, v106, v107
	s_waitcnt lgkmcnt(0)
	v_add_f32_e32 v96, v96, v98
	v_add_f32_e32 v97, v97, v99
	ds_bpermute_b32 v98, v117, v96
	ds_bpermute_b32 v99, v117, v97
	flat_store_dwordx4 v[118:119], v[100:103] offset:256
	s_mov_b32 s100, -1
	s_mov_b32 s101, 0
	s_mov_b32 s98, 0xffff0000
	s_mov_b32 s99, 0
	s_and_saveexec_b64 s[30:31], s[100:101]
	s_cbranch_execz .LBB0_1542
	v_lshl_add_u64 v[100:101], s[10:11], 0, v[112:113]
	s_waitcnt lgkmcnt(0)
	v_add_f32_e32 v96, v96, v98
	v_add_f32_e32 v97, v97, v99
	v_cndmask_b32_e64 v96, v96, v97, s[98:99]
	v_cndmask_b32_e64 v97, 0, 4, s[98:99]
	v_or_b32_e32 v100, v100, v97
	flat_atomic_add_f32 v[100:101], v96
; DEVI unsigned pk2(float lo, float hi) { unsigned r; asm("v_cvt_pk_bf16_f32 %0, %1, %2" : "=v"(r) : "v"(lo), "v"(hi)); return r; }
; DEVI void row_stats(const float* stats, int row, float& mu, float& rs) {
;     if (stats) { const float2 st = *(const float2*)(stats + 2 * (size_t)row); mu = st.x * (1.0f / 1024.0f); const float var = st.y * (1.0f / 1024.0f) - mu * mu; rs = rsqrtf(fmaxf(var, 0.f) + LN_EPS); }
;     else { mu = 0.f; rs = 1.f; }
; }
;     DEVI void operator()(const f32x4 (&acc)[2][2][4][2], const pg8::Unit& u, int wr, int wc, int fr, int fq) const {
;     ...
;             for (int m = 0; m < 4; ++m) {
;                 const int row = row0 + ai * 128 + m * 16; float mu, rs; row_stats(stin, row, mu, rs);
;                 float sum = 0.f, sq = 0.f;
; #pragma unroll
;                 for (int bj = 0; bj < 2; ++bj) {
;                     f32x4 z[2];
; #pragma unroll
;                     for (int n = 0; n < 2; ++n) {
;                         const int col = colb + bj * 128 + 4 * n;
;                         f32x4 xv = *(const f32x4*)(zsrc + (size_t)row * DM + col);
;                         if (stin) { const f32x4 gv = *(const f32x4*)(gin + col), bv = *(const f32x4*)(bin + col); xv = (xv - mu) * rs * gv + bv; }
;                         f32x4 zz = ALPHA * xv + acc[ai][bj][m][n];
;                         if (bias) zz += *(const f32x4*)(bias + col);
;                         *(f32x4*)(zdst + (size_t)row * DM + col) = zz;
;                         sum += zz[0] + zz[1] + zz[2] + zz[3]; sq += zz[0] * zz[0] + zz[1] * zz[1] + zz[2] * zz[2] + zz[3] * zz[3];
;                         z[n] = zz;
;                     }
;                     u32x4 o; o.x = pk2(z[0][0], z[0][1]); o.y = pk2(z[0][2], z[0][3]); o.z = pk2(z[1][0], z[1][1]); o.w = pk2(z[1][2], z[1][3]);
;                     if (zb) *(u32x4*)(zb + (size_t)row * DM + colb + bj * 128) = o;
;                 }
;                 sum += __shfl_xor(sum, 16); sq += __shfl_xor(sq, 16);
;                 sum += __shfl_xor(sum, 32); sq += __shfl_xor(sq, 32);
;                 if (fq == 0) { atomicAdd(stout + 2 * (size_t)row, sum); atomicAdd(stout + 2 * (size_t)row + 1, sq); }
.LBB0_1542:
	s_or_b64 exec, exec, s[30:31]
	v_or_b32_e32 v118, 32, v154
	v_ashrrev_i32_e32 v119, 31, v118
	v_lshlrev_b64 v[96:97], 3, v[118:119]
	s_waitcnt lgkmcnt(0)
	v_lshl_add_u64 v[98:99], s[12:13], 0, v[96:97]
	flat_load_dwordx2 v[156:157], v[98:99]
	v_lshlrev_b64 v[98:99], 12, v[118:119]
	v_lshl_add_u64 v[98:99], s[46:47], 0, v[98:99]
	v_lshl_add_u64 v[98:99], v[144:145], 2, v[98:99]
	global_load_dwordx4 v[100:103], v[98:99], off
	global_load_dwordx4 v[104:107], v[150:151], off
	global_load_dwordx4 v[108:111], v[152:153], off
	global_load_dwordx4 v[112:115], v[98:99], off offset:16
	global_load_dwordx4 v[196:199], v[146:147], off
	global_load_dwordx4 v[200:203], v[148:149], off
	global_load_dwordx4 v[204:207], v[98:99], off offset:512
	global_load_dwordx4 v[208:211], v[98:99], off offset:528
	s_waitcnt vmcnt(0) lgkmcnt(0)
	v_pk_mul_f32 v[156:157], v[156:157], s[24:25] op_sel:[1,0] op_sel_hi:[0,0]
	v_fma_f32 v155, -v157, v157, v156
	v_max_f32_e32 v155, 0, v155
	v_add_f32_e32 v155, 0x3727c5ac, v155
	v_mul_f32_e32 v156, 0x4b800000, v155
	v_cmp_gt_f32_e32 vcc, s61, v155
	v_sub_f32_e32 v101, v101, v157
	v_sub_f32_e32 v100, v100, v157
	v_cndmask_b32_e32 v155, v155, v156, vcc
	v_rsq_f32_e32 v155, v155
	v_sub_f32_e32 v103, v103, v157
	v_sub_f32_e32 v102, v102, v157
	v_mul_f32_e32 v156, 0x45800000, v155
	v_cndmask_b32_e32 v156, v155, v156, vcc
	v_pk_mul_f32 v[102:103], v[102:103], v[156:157] op_sel_hi:[1,0]
	v_pk_mul_f32 v[100:101], v[100:101], v[156:157] op_sel_hi:[1,0]
	v_pk_fma_f32 v[102:103], v[106:107], v[102:103], v[110:111]
	v_pk_fma_f32 v[100:101], v[104:105], v[100:101], v[108:109]
	v_pk_fma_f32 v[94:95], v[102:103], s[26:27], v[94:95] op_sel_hi:[1,0,1]
	v_pk_fma_f32 v[92:93], v[100:101], s[26:27], v[92:93] op_sel_hi:[1,0,1]
	global_store_dwordx4 v[98:99], v[92:95], off
	v_lshlrev_b64 v[108:109], 11, v[118:119]
	v_lshl_add_u64 v[108:109], s[14:15], 0, v[108:109]
	v_lshl_add_u64 v[118:119], v[144:145], 1, v[108:109]
	v_sub_f32_e32 v109, v113, v157
	v_sub_f32_e32 v108, v112, v157
	v_sub_f32_e32 v111, v115, v157
	v_sub_f32_e32 v110, v114, v157
	v_pk_mul_f32 v[110:111], v[110:111], v[156:157] op_sel_hi:[1,0]
	v_pk_mul_f32 v[112:113], v[108:109], v[156:157] op_sel_hi:[1,0]
	v_cvt_pk_bf16_f32 v108, v92, v93
	v_cvt_pk_bf16_f32 v109, v94, v95
	v_pk_fma_f32 v[102:103], v[198:199], v[110:111], v[202:203]
	v_pk_fma_f32 v[100:101], v[196:197], v[112:113], v[200:201]
	v_pk_fma_f32 v[90:91], v[102:103], s[26:27], v[90:91] op_sel_hi:[1,0,1]
	v_pk_fma_f32 v[88:89], v[100:101], s[26:27], v[88:89] op_sel_hi:[1,0,1]
	global_store_dwordx4 v[98:99], v[88:91], off offset:16
	v_cvt_pk_bf16_f32 v110, v88, v89
	v_cvt_pk_bf16_f32 v111, v90, v91
	flat_store_dwordx4 v[118:119], v[108:111]
	global_load_dwordx4 v[104:107], v[120:121], off
	s_nop 0
	global_load_dwordx4 v[108:111], v[122:123], off
	global_load_dwordx4 v[196:199], v[124:125], off
	global_load_dwordx4 v[200:203], v[126:127], off
	s_waitcnt vmcnt(0)
	v_sub_f32_e32 v101, v205, v157
	v_sub_f32_e32 v100, v204, v157
	v_sub_f32_e32 v103, v207, v157
	v_sub_f32_e32 v102, v206, v157
	v_pk_mul_f32 v[102:103], v[156:157], v[102:103] op_sel_hi:[0,1]
	v_pk_mul_f32 v[100:101], v[156:157], v[100:101] op_sel_hi:[0,1]
	v_pk_fma_f32 v[100:101], v[104:105], v[100:101], v[108:109]
	v_pk_fma_f32 v[102:103], v[106:107], v[102:103], v[110:111]
	v_pk_fma_f32 v[84:85], v[100:101], s[26:27], v[84:85] op_sel_hi:[1,0,1]
	v_pk_fma_f32 v[86:87], v[102:103], s[26:27], v[86:87] op_sel_hi:[1,0,1]
	global_store_dwordx4 v[98:99], v[84:87], off offset:512
	v_add_f32_e32 v108, v92, v93
	v_mul_f32_e32 v93, v93, v93
	v_fmac_f32_e32 v93, v92, v92
	v_add_f32_e32 v108, v94, v108
	v_fmac_f32_e32 v93, v94, v94
	v_add_f32_e32 v94, v88, v89
	v_mul_f32_e32 v89, v89, v89
	v_fmac_f32_e32 v89, v88, v88
	v_add_f32_e32 v92, v95, v108
	v_add_f32_e32 v94, v90, v94
	v_fmac_f32_e32 v89, v90, v90
	v_add_f32_e32 v92, 0, v92
	v_fmac_f32_e32 v93, v95, v95
	v_add_f32_e32 v88, v91, v94
	v_fmac_f32_e32 v89, v91, v91
	v_add_f32_e32 v92, v88, v92
	v_add_f32_e32 v93, v93, v89
	v_sub_f32_e32 v89, v209, v157
	v_sub_f32_e32 v88, v208, v157
	v_pk_mul_f32 v[88:89], v[156:157], v[88:89] op_sel_hi:[0,1]
	v_sub_f32_e32 v91, v211, v157
	v_sub_f32_e32 v90, v210, v157
	v_pk_mul_f32 v[90:91], v[156:157], v[90:91] op_sel_hi:[0,1]
	v_mul_f32_e32 v95, v85, v85
	v_add_f32_e32 v94, v84, v85
	v_fmac_f32_e32 v95, v84, v84
	v_add_f32_e32 v94, v86, v94
	v_fmac_f32_e32 v95, v86, v86
	v_add_f32_e32 v94, v87, v94
	v_fmac_f32_e32 v95, v87, v87
	v_add_f32_e32 v92, v92, v94
	v_add_f32_e32 v93, v93, v95
	v_cvt_pk_bf16_f32 v84, v84, v85
	v_cvt_pk_bf16_f32 v85, v86, v87
	v_pk_fma_f32 v[88:89], v[196:197], v[88:89], v[200:201]
	s_nop 0
	v_pk_fma_f32 v[88:89], v[88:89], s[26:27], v[80:81] op_sel_hi:[1,0,1]
	v_pk_fma_f32 v[90:91], v[198:199], v[90:91], v[202:203]
	v_mul_f32_e32 v81, v89, v89
	v_pk_fma_f32 v[90:91], v[90:91], s[26:27], v[82:83] op_sel_hi:[1,0,1]
	v_add_f32_e32 v80, v88, v89
	v_fmac_f32_e32 v81, v88, v88
	v_add_f32_e32 v80, v90, v80
	v_fmac_f32_e32 v81, v90, v90
	v_add_f32_e32 v80, v91, v80
	v_fmac_f32_e32 v81, v91, v91
	v_add_f32_e32 v80, v92, v80
	v_add_f32_e32 v81, v93, v81
	ds_bpermute_b32 v82, v116, v80
	ds_bpermute_b32 v83, v116, v81
	global_store_dwordx4 v[98:99], v[88:91], off offset:528
	v_cvt_pk_bf16_f32 v86, v88, v89
	v_cvt_pk_bf16_f32 v87, v90, v91
	s_waitcnt lgkmcnt(0)
	v_add_f32_e32 v80, v80, v82
	v_add_f32_e32 v81, v81, v83
	ds_bpermute_b32 v82, v117, v80
	ds_bpermute_b32 v83, v117, v81
	flat_store_dwordx4 v[118:119], v[84:87] offset:256
	s_mov_b32 s100, -1
	s_mov_b32 s101, 0
	s_mov_b32 s98, 0xffff0000
	s_mov_b32 s99, 0
	s_and_saveexec_b64 s[30:31], s[100:101]
	s_cbranch_execz .LBB0_1544
	v_lshl_add_u64 v[84:85], s[10:11], 0, v[96:97]
	s_waitcnt lgkmcnt(0)
	v_add_f32_e32 v80, v80, v82
	v_add_f32_e32 v81, v81, v83
	v_cndmask_b32_e64 v80, v80, v81, s[98:99]
	v_cndmask_b32_e64 v81, 0, 4, s[98:99]
	v_or_b32_e32 v84, v84, v81
	flat_atomic_add_f32 v[84:85], v80
; DEVI unsigned pk2(float lo, float hi) { unsigned r; asm("v_cvt_pk_bf16_f32 %0, %1, %2" : "=v"(r) : "v"(lo), "v"(hi)); return r; }
; DEVI void row_stats(const float* stats, int row, float& mu, float& rs) {
;     if (stats) { const float2 st = *(const float2*)(stats + 2 * (size_t)row); mu = st.x * (1.0f / 1024.0f); const float var = st.y * (1.0f / 1024.0f) - mu * mu; rs = rsqrtf(fmaxf(var, 0.f) + LN_EPS); }
;     else { mu = 0.f; rs = 1.f; }
; }
;     DEVI void operator()(const f32x4 (&acc)[2][2][4][2], const pg8::Unit& u, int wr, int wc, int fr, int fq) const {
;     ...
;             for (int m = 0; m < 4; ++m) {
;                 const int row = row0 + ai * 128 + m * 16; float mu, rs; row_stats(stin, row, mu, rs);
;                 float sum = 0.f, sq = 0.f;
; #pragma unroll
;                 for (int bj = 0; bj < 2; ++bj) {
;                     f32x4 z[2];
; #pragma unroll
;                     for (int n = 0; n < 2; ++n) {
;                         const int col = colb + bj * 128 + 4 * n;
;                         f32x4 xv = *(const f32x4*)(zsrc + (size_t)row * DM + col);
;                         if (stin) { const f32x4 gv = *(const f32x4*)(gin + col), bv = *(const f32x4*)(bin + col); xv = (xv - mu) * rs * gv + bv; }
;                         f32x4 zz = ALPHA * xv + acc[ai][bj][m][n];
;                         if (bias) zz += *(const f32x4*)(bias + col);
;                         *(f32x4*)(zdst + (size_t)row * DM + col) = zz;
;                         sum += zz[0] + zz[1] + zz[2] + zz[3]; sq += zz[0] * zz[0] + zz[1] * zz[1] + zz[2] * zz[2] + zz[3] * zz[3];
;                         z[n] = zz;
;                     }
;                     u32x4 o; o.x = pk2(z[0][0], z[0][1]); o.y = pk2(z[0][2], z[0][3]); o.z = pk2(z[1][0], z[1][1]); o.w = pk2(z[1][2], z[1][3]);
;                     if (zb) *(u32x4*)(zb + (size_t)row * DM + colb + bj * 128) = o;
;                 }
;                 sum += __shfl_xor(sum, 16); sq += __shfl_xor(sq, 16);
;                 sum += __shfl_xor(sum, 32); sq += __shfl_xor(sq, 32);
;                 if (fq == 0) { atomicAdd(stout + 2 * (size_t)row, sum); atomicAdd(stout + 2 * (size_t)row + 1, sq); }
.LBB0_1544:
	s_or_b64 exec, exec, s[30:31]
	v_or_b32_e32 v100, 48, v154
	v_ashrrev_i32_e32 v101, 31, v100
	v_lshlrev_b64 v[80:81], 3, v[100:101]
	s_waitcnt lgkmcnt(0)
	v_lshl_add_u64 v[82:83], s[12:13], 0, v[80:81]
	flat_load_dwordx2 v[102:103], v[82:83]
	v_lshlrev_b64 v[82:83], 12, v[100:101]
	v_lshl_add_u64 v[82:83], s[46:47], 0, v[82:83]
	v_lshl_add_u64 v[82:83], v[144:145], 2, v[82:83]
	global_load_dwordx4 v[84:87], v[82:83], off
	global_load_dwordx4 v[88:91], v[150:151], off
	global_load_dwordx4 v[92:95], v[152:153], off
	global_load_dwordx4 v[96:99], v[82:83], off offset:16
	global_load_dwordx4 v[196:199], v[146:147], off
	global_load_dwordx4 v[200:203], v[148:149], off
	global_load_dwordx4 v[204:207], v[82:83], off offset:512
	global_load_dwordx4 v[208:211], v[82:83], off offset:528
	s_waitcnt vmcnt(0) lgkmcnt(0)
	v_pk_mul_f32 v[102:103], v[102:103], s[24:25] op_sel:[1,0] op_sel_hi:[0,0]
	v_fma_f32 v102, -v103, v103, v102
	v_max_f32_e32 v102, 0, v102
	v_add_f32_e32 v102, 0x3727c5ac, v102
	v_mul_f32_e32 v104, 0x4b800000, v102
	v_cmp_gt_f32_e32 vcc, s61, v102
	v_sub_f32_e32 v85, v85, v103
	v_sub_f32_e32 v84, v84, v103
	v_cndmask_b32_e32 v102, v102, v104, vcc
	v_rsq_f32_e32 v102, v102
	v_sub_f32_e32 v87, v87, v103
	v_sub_f32_e32 v86, v86, v103
	v_mul_f32_e32 v104, 0x45800000, v102
	v_cndmask_b32_e32 v102, v102, v104, vcc
	v_pk_mul_f32 v[86:87], v[86:87], v[102:103] op_sel_hi:[1,0]
	v_pk_mul_f32 v[84:85], v[84:85], v[102:103] op_sel_hi:[1,0]
	v_pk_fma_f32 v[86:87], v[90:91], v[86:87], v[94:95]
	v_pk_fma_f32 v[84:85], v[88:89], v[84:85], v[92:93]
	v_pk_fma_f32 v[78:79], v[86:87], s[26:27], v[78:79] op_sel_hi:[1,0,1]
	v_pk_fma_f32 v[76:77], v[84:85], s[26:27], v[76:77] op_sel_hi:[1,0,1]
	global_store_dwordx4 v[82:83], v[76:79], off
	v_lshlrev_b64 v[92:93], 11, v[100:101]
	v_lshl_add_u64 v[92:93], s[14:15], 0, v[92:93]
	v_lshl_add_u64 v[100:101], v[144:145], 1, v[92:93]
	v_sub_f32_e32 v93, v97, v103
	v_sub_f32_e32 v92, v96, v103
	v_sub_f32_e32 v95, v99, v103
	v_sub_f32_e32 v94, v98, v103
	v_pk_mul_f32 v[94:95], v[94:95], v[102:103] op_sel_hi:[1,0]
	v_pk_mul_f32 v[96:97], v[92:93], v[102:103] op_sel_hi:[1,0]
	v_cvt_pk_bf16_f32 v92, v76, v77
	v_cvt_pk_bf16_f32 v93, v78, v79
	v_pk_fma_f32 v[86:87], v[198:199], v[94:95], v[202:203]
	v_pk_fma_f32 v[84:85], v[196:197], v[96:97], v[200:201]
	v_pk_fma_f32 v[74:75], v[86:87], s[26:27], v[74:75] op_sel_hi:[1,0,1]
	v_pk_fma_f32 v[72:73], v[84:85], s[26:27], v[72:73] op_sel_hi:[1,0,1]
	global_store_dwordx4 v[82:83], v[72:75], off offset:16
	v_cvt_pk_bf16_f32 v94, v72, v73
	v_cvt_pk_bf16_f32 v95, v74, v75
	flat_store_dwordx4 v[100:101], v[92:95]
	global_load_dwordx4 v[88:91], v[120:121], off
	s_nop 0
	global_load_dwordx4 v[92:95], v[122:123], off
	global_load_dwordx4 v[196:199], v[124:125], off
	global_load_dwordx4 v[200:203], v[126:127], off
	s_waitcnt vmcnt(0)
	v_sub_f32_e32 v85, v205, v103
	v_sub_f32_e32 v84, v204, v103
	v_sub_f32_e32 v87, v207, v103
	v_sub_f32_e32 v86, v206, v103
	v_pk_mul_f32 v[86:87], v[102:103], v[86:87] op_sel_hi:[0,1]
	v_pk_mul_f32 v[84:85], v[102:103], v[84:85] op_sel_hi:[0,1]
	v_pk_fma_f32 v[84:85], v[88:89], v[84:85], v[92:93]
	v_pk_fma_f32 v[86:87], v[90:91], v[86:87], v[94:95]
	v_pk_fma_f32 v[68:69], v[84:85], s[26:27], v[68:69] op_sel_hi:[1,0,1]
	v_pk_fma_f32 v[70:71], v[86:87], s[26:27], v[70:71] op_sel_hi:[1,0,1]
	global_store_dwordx4 v[82:83], v[68:71], off offset:512
	v_add_f32_e32 v92, v76, v77
	v_mul_f32_e32 v77, v77, v77
	v_fmac_f32_e32 v77, v76, v76
	v_add_f32_e32 v92, v78, v92
	v_fmac_f32_e32 v77, v78, v78
	v_add_f32_e32 v78, v72, v73
	v_mul_f32_e32 v73, v73, v73
	v_fmac_f32_e32 v73, v72, v72
	v_add_f32_e32 v76, v79, v92
	v_add_f32_e32 v78, v74, v78
	v_fmac_f32_e32 v73, v74, v74
	v_add_f32_e32 v76, 0, v76
	v_fmac_f32_e32 v77, v79, v79
	v_add_f32_e32 v72, v75, v78
	v_fmac_f32_e32 v73, v75, v75
	v_add_f32_e32 v76, v72, v76
	v_add_f32_e32 v77, v77, v73
	v_sub_f32_e32 v73, v209, v103
	v_sub_f32_e32 v72, v208, v103
	v_pk_mul_f32 v[72:73], v[102:103], v[72:73] op_sel_hi:[0,1]
	v_sub_f32_e32 v75, v211, v103
	v_sub_f32_e32 v74, v210, v103
	v_pk_mul_f32 v[74:75], v[102:103], v[74:75] op_sel_hi:[0,1]
	v_mul_f32_e32 v79, v69, v69
	v_add_f32_e32 v78, v68, v69
	v_fmac_f32_e32 v79, v68, v68
	v_add_f32_e32 v78, v70, v78
	v_fmac_f32_e32 v79, v70, v70
	v_add_f32_e32 v78, v71, v78
	v_fmac_f32_e32 v79, v71, v71
	v_add_f32_e32 v76, v76, v78
	v_add_f32_e32 v77, v77, v79
	v_cvt_pk_bf16_f32 v68, v68, v69
	v_cvt_pk_bf16_f32 v69, v70, v71
	v_pk_fma_f32 v[72:73], v[196:197], v[72:73], v[200:201]
	s_nop 0
	v_pk_fma_f32 v[72:73], v[72:73], s[26:27], v[64:65] op_sel_hi:[1,0,1]
	v_pk_fma_f32 v[74:75], v[198:199], v[74:75], v[202:203]
	v_mul_f32_e32 v65, v73, v73
	v_pk_fma_f32 v[74:75], v[74:75], s[26:27], v[66:67] op_sel_hi:[1,0,1]
	v_add_f32_e32 v64, v72, v73
	v_fmac_f32_e32 v65, v72, v72
	v_add_f32_e32 v64, v74, v64
	v_fmac_f32_e32 v65, v74, v74
	v_add_f32_e32 v64, v75, v64
	v_fmac_f32_e32 v65, v75, v75
	v_add_f32_e32 v64, v76, v64
	v_add_f32_e32 v65, v77, v65
	ds_bpermute_b32 v66, v116, v64
	ds_bpermute_b32 v67, v116, v65
	global_store_dwordx4 v[82:83], v[72:75], off offset:528
	v_cvt_pk_bf16_f32 v70, v72, v73
	v_cvt_pk_bf16_f32 v71, v74, v75
	s_waitcnt lgkmcnt(0)
	v_add_f32_e32 v64, v64, v66
	v_add_f32_e32 v65, v65, v67
	ds_bpermute_b32 v66, v117, v64
	ds_bpermute_b32 v67, v117, v65
	flat_store_dwordx4 v[100:101], v[68:71] offset:256
	s_mov_b32 s100, -1
	s_mov_b32 s101, 0
	s_mov_b32 s98, 0xffff0000
	s_mov_b32 s99, 0
	s_and_saveexec_b64 s[30:31], s[100:101]
	s_cbranch_execz .LBB0_1546
	v_lshl_add_u64 v[68:69], s[10:11], 0, v[80:81]
	s_waitcnt lgkmcnt(0)
	v_add_f32_e32 v64, v64, v66
	v_add_f32_e32 v65, v65, v67
	v_cndmask_b32_e64 v64, v64, v65, s[98:99]
	v_cndmask_b32_e64 v65, 0, 4, s[98:99]
	v_or_b32_e32 v68, v68, v65
	flat_atomic_add_f32 v[68:69], v64
; DEVI unsigned pk2(float lo, float hi) { unsigned r; asm("v_cvt_pk_bf16_f32 %0, %1, %2" : "=v"(r) : "v"(lo), "v"(hi)); return r; }
; DEVI void row_stats(const float* stats, int row, float& mu, float& rs) {
;     if (stats) { const float2 st = *(const float2*)(stats + 2 * (size_t)row); mu = st.x * (1.0f / 1024.0f); const float var = st.y * (1.0f / 1024.0f) - mu * mu; rs = rsqrtf(fmaxf(var, 0.f) + LN_EPS); }
;     else { mu = 0.f; rs = 1.f; }
; }
;     DEVI void operator()(const f32x4 (&acc)[2][2][4][2], const pg8::Unit& u, int wr, int wc, int fr, int fq) const {
;     ...
;             for (int m = 0; m < 4; ++m) {
;                 const int row = row0 + ai * 128 + m * 16; float mu, rs; row_stats(stin, row, mu, rs);
;                 float sum = 0.f, sq = 0.f;
; #pragma unroll
;                 for (int bj = 0; bj < 2; ++bj) {
;                     f32x4 z[2];
; #pragma unroll
;                     for (int n = 0; n < 2; ++n) {
;                         const int col = colb + bj * 128 + 4 * n;
;                         f32x4 xv = *(const f32x4*)(zsrc + (size_t)row * DM + col);
;                         if (stin) { const f32x4 gv = *(const f32x4*)(gin + col), bv = *(const f32x4*)(bin + col); xv = (xv - mu) * rs * gv + bv; }
;                         f32x4 zz = ALPHA * xv + acc[ai][bj][m][n];
;                         if (bias) zz += *(const f32x4*)(bias + col);
;                         *(f32x4*)(zdst + (size_t)row * DM + col) = zz;
;                         sum += zz[0] + zz[1] + zz[2] + zz[3]; sq += zz[0] * zz[0] + zz[1] * zz[1] + zz[2] * zz[2] + zz[3] * zz[3];
;                         z[n] = zz;
;                     }
;                     u32x4 o; o.x = pk2(z[0][0], z[0][1]); o.y = pk2(z[0][2], z[0][3]); o.z = pk2(z[1][0], z[1][1]); o.w = pk2(z[1][2], z[1][3]);
;                     if (zb) *(u32x4*)(zb + (size_t)row * DM + colb + bj * 128) = o;
;                 }
;                 sum += __shfl_xor(sum, 16); sq += __shfl_xor(sq, 16);
;                 sum += __shfl_xor(sum, 32); sq += __shfl_xor(sq, 32);
;                 if (fq == 0) { atomicAdd(stout + 2 * (size_t)row, sum); atomicAdd(stout + 2 * (size_t)row + 1, sq); }
.LBB0_1546:
	s_or_b64 exec, exec, s[30:31]
	v_add_u32_e32 v84, 0x80, v154
	v_ashrrev_i32_e32 v85, 31, v84
	v_lshlrev_b64 v[64:65], 3, v[84:85]
	s_waitcnt lgkmcnt(0)
	v_lshl_add_u64 v[66:67], s[12:13], 0, v[64:65]
	flat_load_dwordx2 v[86:87], v[66:67]
	v_lshlrev_b64 v[66:67], 12, v[84:85]
	v_lshl_add_u64 v[66:67], s[46:47], 0, v[66:67]
	v_lshl_add_u64 v[66:67], v[144:145], 2, v[66:67]
	global_load_dwordx4 v[68:71], v[66:67], off
	global_load_dwordx4 v[72:75], v[150:151], off
	global_load_dwordx4 v[76:79], v[152:153], off
	global_load_dwordx4 v[80:83], v[66:67], off offset:16
	global_load_dwordx4 v[196:199], v[146:147], off
	global_load_dwordx4 v[200:203], v[148:149], off
	global_load_dwordx4 v[204:207], v[66:67], off offset:512
	global_load_dwordx4 v[208:211], v[66:67], off offset:528
	s_waitcnt vmcnt(0) lgkmcnt(0)
	v_pk_mul_f32 v[86:87], v[86:87], s[24:25] op_sel:[1,0] op_sel_hi:[0,0]
	v_fma_f32 v86, -v87, v87, v86
	v_max_f32_e32 v86, 0, v86
	v_add_f32_e32 v86, 0x3727c5ac, v86
	v_mul_f32_e32 v88, 0x4b800000, v86
	v_cmp_gt_f32_e32 vcc, s61, v86
	v_sub_f32_e32 v69, v69, v87
	v_sub_f32_e32 v68, v68, v87
	v_cndmask_b32_e32 v86, v86, v88, vcc
	v_rsq_f32_e32 v86, v86
	v_sub_f32_e32 v71, v71, v87
	v_sub_f32_e32 v70, v70, v87
	v_mul_f32_e32 v88, 0x45800000, v86
	v_cndmask_b32_e32 v86, v86, v88, vcc
	v_pk_mul_f32 v[70:71], v[70:71], v[86:87] op_sel_hi:[1,0]
	v_pk_mul_f32 v[68:69], v[68:69], v[86:87] op_sel_hi:[1,0]
	v_pk_fma_f32 v[70:71], v[74:75], v[70:71], v[78:79]
	v_pk_fma_f32 v[68:69], v[72:73], v[68:69], v[76:77]
	v_pk_fma_f32 v[62:63], v[70:71], s[26:27], v[62:63] op_sel_hi:[1,0,1]
	v_pk_fma_f32 v[60:61], v[68:69], s[26:27], v[60:61] op_sel_hi:[1,0,1]
	global_store_dwordx4 v[66:67], v[60:63], off
	v_lshlrev_b64 v[76:77], 11, v[84:85]
	v_lshl_add_u64 v[76:77], s[14:15], 0, v[76:77]
	v_lshl_add_u64 v[84:85], v[144:145], 1, v[76:77]
	v_sub_f32_e32 v77, v81, v87
	v_sub_f32_e32 v76, v80, v87
	v_sub_f32_e32 v79, v83, v87
	v_sub_f32_e32 v78, v82, v87
	v_pk_mul_f32 v[78:79], v[78:79], v[86:87] op_sel_hi:[1,0]
	v_pk_mul_f32 v[80:81], v[76:77], v[86:87] op_sel_hi:[1,0]
	v_cvt_pk_bf16_f32 v76, v60, v61
	v_cvt_pk_bf16_f32 v77, v62, v63
	v_pk_fma_f32 v[70:71], v[198:199], v[78:79], v[202:203]
	v_pk_fma_f32 v[68:69], v[196:197], v[80:81], v[200:201]
	v_pk_fma_f32 v[58:59], v[70:71], s[26:27], v[58:59] op_sel_hi:[1,0,1]
	v_pk_fma_f32 v[56:57], v[68:69], s[26:27], v[56:57] op_sel_hi:[1,0,1]
	global_store_dwordx4 v[66:67], v[56:59], off offset:16
	v_cvt_pk_bf16_f32 v78, v56, v57
	v_cvt_pk_bf16_f32 v79, v58, v59
	flat_store_dwordx4 v[84:85], v[76:79]
	global_load_dwordx4 v[72:75], v[120:121], off
	s_nop 0
	global_load_dwordx4 v[76:79], v[122:123], off
	global_load_dwordx4 v[196:199], v[124:125], off
	global_load_dwordx4 v[200:203], v[126:127], off
	s_waitcnt vmcnt(0)
	v_sub_f32_e32 v69, v205, v87
	v_sub_f32_e32 v68, v204, v87
	v_sub_f32_e32 v71, v207, v87
	v_sub_f32_e32 v70, v206, v87
	v_pk_mul_f32 v[70:71], v[86:87], v[70:71] op_sel_hi:[0,1]
	v_pk_mul_f32 v[68:69], v[86:87], v[68:69] op_sel_hi:[0,1]
	v_pk_fma_f32 v[68:69], v[72:73], v[68:69], v[76:77]
	v_pk_fma_f32 v[70:71], v[74:75], v[70:71], v[78:79]
	v_pk_fma_f32 v[52:53], v[68:69], s[26:27], v[52:53] op_sel_hi:[1,0,1]
	v_pk_fma_f32 v[54:55], v[70:71], s[26:27], v[54:55] op_sel_hi:[1,0,1]
	global_store_dwordx4 v[66:67], v[52:55], off offset:512
	v_add_f32_e32 v76, v60, v61
	v_mul_f32_e32 v61, v61, v61
	v_fmac_f32_e32 v61, v60, v60
	v_add_f32_e32 v76, v62, v76
	v_fmac_f32_e32 v61, v62, v62
	v_add_f32_e32 v62, v56, v57
	v_mul_f32_e32 v57, v57, v57
	v_fmac_f32_e32 v57, v56, v56
	v_add_f32_e32 v60, v63, v76
	v_add_f32_e32 v62, v58, v62
	v_fmac_f32_e32 v57, v58, v58
	v_add_f32_e32 v60, 0, v60
	v_fmac_f32_e32 v61, v63, v63
	v_add_f32_e32 v56, v59, v62
	v_fmac_f32_e32 v57, v59, v59
	v_add_f32_e32 v60, v56, v60
	v_add_f32_e32 v61, v61, v57
	v_sub_f32_e32 v57, v209, v87
	v_sub_f32_e32 v56, v208, v87
	v_pk_mul_f32 v[56:57], v[86:87], v[56:57] op_sel_hi:[0,1]
	v_sub_f32_e32 v59, v211, v87
	v_sub_f32_e32 v58, v210, v87
	v_pk_mul_f32 v[58:59], v[86:87], v[58:59] op_sel_hi:[0,1]
	v_mul_f32_e32 v63, v53, v53
	v_add_f32_e32 v62, v52, v53
	v_fmac_f32_e32 v63, v52, v52
	v_add_f32_e32 v62, v54, v62
	v_fmac_f32_e32 v63, v54, v54
	v_add_f32_e32 v62, v55, v62
	v_fmac_f32_e32 v63, v55, v55
	v_add_f32_e32 v60, v60, v62
	v_add_f32_e32 v61, v61, v63
	v_cvt_pk_bf16_f32 v52, v52, v53
	v_cvt_pk_bf16_f32 v53, v54, v55
	v_pk_fma_f32 v[56:57], v[196:197], v[56:57], v[200:201]
	s_nop 0
	v_pk_fma_f32 v[56:57], v[56:57], s[26:27], v[48:49] op_sel_hi:[1,0,1]
	v_pk_fma_f32 v[58:59], v[198:199], v[58:59], v[202:203]
	v_mul_f32_e32 v49, v57, v57
	v_pk_fma_f32 v[58:59], v[58:59], s[26:27], v[50:51] op_sel_hi:[1,0,1]
	v_add_f32_e32 v48, v56, v57
	v_fmac_f32_e32 v49, v56, v56
	v_add_f32_e32 v48, v58, v48
	v_fmac_f32_e32 v49, v58, v58
	v_add_f32_e32 v48, v59, v48
	v_fmac_f32_e32 v49, v59, v59
	v_add_f32_e32 v48, v60, v48
	v_add_f32_e32 v49, v61, v49
	ds_bpermute_b32 v50, v116, v48
	ds_bpermute_b32 v51, v116, v49
	global_store_dwordx4 v[66:67], v[56:59], off offset:528
	v_cvt_pk_bf16_f32 v54, v56, v57
	v_cvt_pk_bf16_f32 v55, v58, v59
	s_waitcnt lgkmcnt(0)
	v_add_f32_e32 v48, v48, v50
	v_add_f32_e32 v49, v49, v51
	ds_bpermute_b32 v50, v117, v48
	ds_bpermute_b32 v51, v117, v49
	flat_store_dwordx4 v[84:85], v[52:55] offset:256
	s_mov_b32 s100, -1
	s_mov_b32 s101, 0
	s_mov_b32 s98, 0xffff0000
	s_mov_b32 s99, 0
	s_and_saveexec_b64 s[30:31], s[100:101]
	s_cbranch_execz .LBB0_1548
	v_lshl_add_u64 v[52:53], s[10:11], 0, v[64:65]
	s_waitcnt lgkmcnt(0)
	v_add_f32_e32 v48, v48, v50
	v_add_f32_e32 v49, v49, v51
	v_cndmask_b32_e64 v48, v48, v49, s[98:99]
	v_cndmask_b32_e64 v49, 0, 4, s[98:99]
	v_or_b32_e32 v52, v52, v49
	flat_atomic_add_f32 v[52:53], v48
; DEVI unsigned pk2(float lo, float hi) { unsigned r; asm("v_cvt_pk_bf16_f32 %0, %1, %2" : "=v"(r) : "v"(lo), "v"(hi)); return r; }
; DEVI void row_stats(const float* stats, int row, float& mu, float& rs) {
;     if (stats) { const float2 st = *(const float2*)(stats + 2 * (size_t)row); mu = st.x * (1.0f / 1024.0f); const float var = st.y * (1.0f / 1024.0f) - mu * mu; rs = rsqrtf(fmaxf(var, 0.f) + LN_EPS); }
;     else { mu = 0.f; rs = 1.f; }
; }
;     DEVI void operator()(const f32x4 (&acc)[2][2][4][2], const pg8::Unit& u, int wr, int wc, int fr, int fq) const {
;     ...
;             for (int m = 0; m < 4; ++m) {
;                 const int row = row0 + ai * 128 + m * 16; float mu, rs; row_stats(stin, row, mu, rs);
;                 float sum = 0.f, sq = 0.f;
; #pragma unroll
;                 for (int bj = 0; bj < 2; ++bj) {
;                     f32x4 z[2];
; #pragma unroll
;                     for (int n = 0; n < 2; ++n) {
;                         const int col = colb + bj * 128 + 4 * n;
;                         f32x4 xv = *(const f32x4*)(zsrc + (size_t)row * DM + col);
;                         if (stin) { const f32x4 gv = *(const f32x4*)(gin + col), bv = *(const f32x4*)(bin + col); xv = (xv - mu) * rs * gv + bv; }
;                         f32x4 zz = ALPHA * xv + acc[ai][bj][m][n];
;                         if (bias) zz += *(const f32x4*)(bias + col);
;                         *(f32x4*)(zdst + (size_t)row * DM + col) = zz;
;                         sum += zz[0] + zz[1] + zz[2] + zz[3]; sq += zz[0] * zz[0] + zz[1] * zz[1] + zz[2] * zz[2] + zz[3] * zz[3];
;                         z[n] = zz;
;                     }
;                     u32x4 o; o.x = pk2(z[0][0], z[0][1]); o.y = pk2(z[0][2], z[0][3]); o.z = pk2(z[1][0], z[1][1]); o.w = pk2(z[1][2], z[1][3]);
;                     if (zb) *(u32x4*)(zb + (size_t)row * DM + colb + bj * 128) = o;
;                 }
;                 sum += __shfl_xor(sum, 16); sq += __shfl_xor(sq, 16);
;                 sum += __shfl_xor(sum, 32); sq += __shfl_xor(sq, 32);
;                 if (fq == 0) { atomicAdd(stout + 2 * (size_t)row, sum); atomicAdd(stout + 2 * (size_t)row + 1, sq); }
.LBB0_1548:
	s_or_b64 exec, exec, s[30:31]
	v_add_u32_e32 v68, 0x90, v154
	v_ashrrev_i32_e32 v69, 31, v68
	v_lshlrev_b64 v[48:49], 3, v[68:69]
	s_waitcnt lgkmcnt(0)
	v_lshl_add_u64 v[50:51], s[12:13], 0, v[48:49]
	flat_load_dwordx2 v[70:71], v[50:51]
	v_lshlrev_b64 v[50:51], 12, v[68:69]
	v_lshl_add_u64 v[50:51], s[46:47], 0, v[50:51]
	v_lshl_add_u64 v[50:51], v[144:145], 2, v[50:51]
	global_load_dwordx4 v[52:55], v[50:51], off
	global_load_dwordx4 v[56:59], v[150:151], off
	global_load_dwordx4 v[60:63], v[152:153], off
	global_load_dwordx4 v[64:67], v[50:51], off offset:16
	global_load_dwordx4 v[196:199], v[146:147], off
	global_load_dwordx4 v[200:203], v[148:149], off
	global_load_dwordx4 v[204:207], v[50:51], off offset:512
	global_load_dwordx4 v[208:211], v[50:51], off offset:528
	s_waitcnt vmcnt(0) lgkmcnt(0)
	v_pk_mul_f32 v[70:71], v[70:71], s[24:25] op_sel:[1,0] op_sel_hi:[0,0]
	v_fma_f32 v70, -v71, v71, v70
	v_max_f32_e32 v70, 0, v70
	v_add_f32_e32 v70, 0x3727c5ac, v70
	v_mul_f32_e32 v72, 0x4b800000, v70
	v_cmp_gt_f32_e32 vcc, s61, v70
	v_sub_f32_e32 v53, v53, v71
	v_sub_f32_e32 v52, v52, v71
	v_cndmask_b32_e32 v70, v70, v72, vcc
	v_rsq_f32_e32 v70, v70
	v_sub_f32_e32 v55, v55, v71
	v_sub_f32_e32 v54, v54, v71
	v_mul_f32_e32 v72, 0x45800000, v70
	v_cndmask_b32_e32 v70, v70, v72, vcc
	v_pk_mul_f32 v[54:55], v[54:55], v[70:71] op_sel_hi:[1,0]
	v_pk_mul_f32 v[52:53], v[52:53], v[70:71] op_sel_hi:[1,0]
	v_pk_fma_f32 v[54:55], v[58:59], v[54:55], v[62:63]
	v_pk_fma_f32 v[52:53], v[56:57], v[52:53], v[60:61]
	v_pk_fma_f32 v[46:47], v[54:55], s[26:27], v[46:47] op_sel_hi:[1,0,1]
	v_pk_fma_f32 v[44:45], v[52:53], s[26:27], v[44:45] op_sel_hi:[1,0,1]
	global_store_dwordx4 v[50:51], v[44:47], off
	v_lshlrev_b64 v[60:61], 11, v[68:69]
	v_lshl_add_u64 v[60:61], s[14:15], 0, v[60:61]
	v_lshl_add_u64 v[68:69], v[144:145], 1, v[60:61]
	v_sub_f32_e32 v61, v65, v71
	v_sub_f32_e32 v60, v64, v71
	v_sub_f32_e32 v63, v67, v71
	v_sub_f32_e32 v62, v66, v71
	v_pk_mul_f32 v[62:63], v[62:63], v[70:71] op_sel_hi:[1,0]
	v_pk_mul_f32 v[64:65], v[60:61], v[70:71] op_sel_hi:[1,0]
	v_cvt_pk_bf16_f32 v60, v44, v45
	v_cvt_pk_bf16_f32 v61, v46, v47
	v_pk_fma_f32 v[54:55], v[198:199], v[62:63], v[202:203]
	v_pk_fma_f32 v[52:53], v[196:197], v[64:65], v[200:201]
	v_pk_fma_f32 v[42:43], v[54:55], s[26:27], v[42:43] op_sel_hi:[1,0,1]
	v_pk_fma_f32 v[40:41], v[52:53], s[26:27], v[40:41] op_sel_hi:[1,0,1]
	global_store_dwordx4 v[50:51], v[40:43], off offset:16
	v_cvt_pk_bf16_f32 v62, v40, v41
	v_cvt_pk_bf16_f32 v63, v42, v43
	flat_store_dwordx4 v[68:69], v[60:63]
	global_load_dwordx4 v[56:59], v[120:121], off
	s_nop 0
	global_load_dwordx4 v[60:63], v[122:123], off
	global_load_dwordx4 v[196:199], v[124:125], off
	global_load_dwordx4 v[200:203], v[126:127], off
	s_waitcnt vmcnt(0)
	v_sub_f32_e32 v53, v205, v71
	v_sub_f32_e32 v52, v204, v71
	v_sub_f32_e32 v55, v207, v71
	v_sub_f32_e32 v54, v206, v71
	v_pk_mul_f32 v[54:55], v[70:71], v[54:55] op_sel_hi:[0,1]
	v_pk_mul_f32 v[52:53], v[70:71], v[52:53] op_sel_hi:[0,1]
	v_pk_fma_f32 v[52:53], v[56:57], v[52:53], v[60:61]
	v_pk_fma_f32 v[54:55], v[58:59], v[54:55], v[62:63]
	v_pk_fma_f32 v[36:37], v[52:53], s[26:27], v[36:37] op_sel_hi:[1,0,1]
	v_pk_fma_f32 v[38:39], v[54:55], s[26:27], v[38:39] op_sel_hi:[1,0,1]
	global_store_dwordx4 v[50:51], v[36:39], off offset:512
	v_add_f32_e32 v60, v44, v45
	v_mul_f32_e32 v45, v45, v45
	v_fmac_f32_e32 v45, v44, v44
	v_add_f32_e32 v60, v46, v60
	v_fmac_f32_e32 v45, v46, v46
	v_add_f32_e32 v46, v40, v41
	v_mul_f32_e32 v41, v41, v41
	v_fmac_f32_e32 v41, v40, v40
	v_add_f32_e32 v44, v47, v60
	v_add_f32_e32 v46, v42, v46
	v_fmac_f32_e32 v41, v42, v42
	v_add_f32_e32 v44, 0, v44
	v_fmac_f32_e32 v45, v47, v47
	v_add_f32_e32 v40, v43, v46
	v_fmac_f32_e32 v41, v43, v43
	v_add_f32_e32 v44, v40, v44
	v_add_f32_e32 v45, v45, v41
	v_sub_f32_e32 v41, v209, v71
	v_sub_f32_e32 v40, v208, v71
	v_pk_mul_f32 v[40:41], v[70:71], v[40:41] op_sel_hi:[0,1]
	v_sub_f32_e32 v43, v211, v71
	v_sub_f32_e32 v42, v210, v71
	v_pk_mul_f32 v[42:43], v[70:71], v[42:43] op_sel_hi:[0,1]
	v_mul_f32_e32 v47, v37, v37
	v_add_f32_e32 v46, v36, v37
	v_fmac_f32_e32 v47, v36, v36
	v_add_f32_e32 v46, v38, v46
	v_fmac_f32_e32 v47, v38, v38
	v_add_f32_e32 v46, v39, v46
	v_fmac_f32_e32 v47, v39, v39
	v_add_f32_e32 v44, v44, v46
	v_add_f32_e32 v45, v45, v47
	v_cvt_pk_bf16_f32 v36, v36, v37
	v_cvt_pk_bf16_f32 v37, v38, v39
	v_pk_fma_f32 v[40:41], v[196:197], v[40:41], v[200:201]
	s_nop 0
	v_pk_fma_f32 v[40:41], v[40:41], s[26:27], v[32:33] op_sel_hi:[1,0,1]
	v_pk_fma_f32 v[42:43], v[198:199], v[42:43], v[202:203]
	v_mul_f32_e32 v33, v41, v41
	v_pk_fma_f32 v[42:43], v[42:43], s[26:27], v[34:35] op_sel_hi:[1,0,1]
	v_add_f32_e32 v32, v40, v41
	v_fmac_f32_e32 v33, v40, v40
	v_add_f32_e32 v32, v42, v32
	v_fmac_f32_e32 v33, v42, v42
	v_add_f32_e32 v32, v43, v32
	v_fmac_f32_e32 v33, v43, v43
	v_add_f32_e32 v32, v44, v32
	v_add_f32_e32 v33, v45, v33
	ds_bpermute_b32 v34, v116, v32
	ds_bpermute_b32 v35, v116, v33
	global_store_dwordx4 v[50:51], v[40:43], off offset:528
	v_cvt_pk_bf16_f32 v38, v40, v41
	v_cvt_pk_bf16_f32 v39, v42, v43
	s_waitcnt lgkmcnt(0)
	v_add_f32_e32 v32, v32, v34
	v_add_f32_e32 v33, v33, v35
	ds_bpermute_b32 v34, v117, v32
	ds_bpermute_b32 v35, v117, v33
	flat_store_dwordx4 v[68:69], v[36:39] offset:256
	s_mov_b32 s100, -1
	s_mov_b32 s101, 0
	s_mov_b32 s98, 0xffff0000
	s_mov_b32 s99, 0
	s_and_saveexec_b64 s[30:31], s[100:101]
	s_cbranch_execz .LBB0_1550
	v_lshl_add_u64 v[36:37], s[10:11], 0, v[48:49]
	s_waitcnt lgkmcnt(0)
	v_add_f32_e32 v32, v32, v34
	v_add_f32_e32 v33, v33, v35
	v_cndmask_b32_e64 v32, v32, v33, s[98:99]
	v_cndmask_b32_e64 v33, 0, 4, s[98:99]
	v_or_b32_e32 v36, v36, v33
	flat_atomic_add_f32 v[36:37], v32
; DEVI unsigned pk2(float lo, float hi) { unsigned r; asm("v_cvt_pk_bf16_f32 %0, %1, %2" : "=v"(r) : "v"(lo), "v"(hi)); return r; }
;     DEVI void operator()(const f32x4 (&acc)[2][2][4][2], const pg8::Unit& u, int wr, int wc, int fr, int fq) const {
;     ...
;                 const int row = row0 + ai * 128 + m * 16; float mu, rs; row_stats(stin, row, mu, rs);
;                 float sum = 0.f, sq = 0.f;
; #pragma unroll
;                 for (int bj = 0; bj < 2; ++bj) {
;                     f32x4 z[2];
; #pragma unroll
;                     for (int n = 0; n < 2; ++n) {
;                         const int col = colb + bj * 128 + 4 * n;
;                         f32x4 xv = *(const f32x4*)(zsrc + (size_t)row * DM + col);
;                         if (stin) { const f32x4 gv = *(const f32x4*)(gin + col), bv = *(const f32x4*)(bin + col); xv = (xv - mu) * rs * gv + bv; }
;                         f32x4 zz = ALPHA * xv + acc[ai][bj][m][n];
;                         if (bias) zz += *(const f32x4*)(bias + col);
;                         *(f32x4*)(zdst + (size_t)row * DM + col) = zz;
;                         sum += zz[0] + zz[1] + zz[2] + zz[3]; sq += zz[0] * zz[0] + zz[1] * zz[1] + zz[2] * zz[2] + zz[3] * zz[3];
;                         z[n] = zz;
;                     }
;                     u32x4 o; o.x = pk2(z[0][0], z[0][1]); o.y = pk2(z[0][2], z[0][3]); o.z = pk2(z[1][0], z[1][1]); o.w = pk2(z[1][2], z[1][3]);
;                     if (zb) *(u32x4*)(zb + (size_t)row * DM + colb + bj * 128) = o;
;                 }
;                 sum += __shfl_xor(sum, 16); sq += __shfl_xor(sq, 16);
;                 sum += __shfl_xor(sum, 32); sq += __shfl_xor(sq, 32);
;                 if (fq == 0) { atomicAdd(stout + 2 * (size_t)row, sum); atomicAdd(stout + 2 * (size_t)row + 1, sq); }
.LBB0_1550:
	s_or_b64 exec, exec, s[30:31]
	v_add_u32_e32 v52, 0xa0, v154
	v_ashrrev_i32_e32 v53, 31, v52
	v_lshlrev_b64 v[32:33], 3, v[52:53]
	s_waitcnt lgkmcnt(0)
	v_lshl_add_u64 v[34:35], s[12:13], 0, v[32:33]
	flat_load_dwordx2 v[54:55], v[34:35]
	v_lshlrev_b64 v[34:35], 12, v[52:53]
	v_lshl_add_u64 v[34:35], s[46:47], 0, v[34:35]
	v_lshl_add_u64 v[34:35], v[144:145], 2, v[34:35]
	global_load_dwordx4 v[36:39], v[34:35], off
	global_load_dwordx4 v[40:43], v[150:151], off
	global_load_dwordx4 v[44:47], v[152:153], off
	global_load_dwordx4 v[48:51], v[34:35], off offset:16
	global_load_dwordx4 v[196:199], v[146:147], off
	global_load_dwordx4 v[200:203], v[148:149], off
	global_load_dwordx4 v[204:207], v[34:35], off offset:512
	global_load_dwordx4 v[208:211], v[34:35], off offset:528
	s_waitcnt vmcnt(0) lgkmcnt(0)
	v_pk_mul_f32 v[54:55], v[54:55], s[24:25] op_sel:[1,0] op_sel_hi:[0,0]
	v_fma_f32 v54, -v55, v55, v54
	v_max_f32_e32 v54, 0, v54
	v_add_f32_e32 v54, 0x3727c5ac, v54
	v_mul_f32_e32 v56, 0x4b800000, v54
	v_cmp_gt_f32_e32 vcc, s61, v54
	v_sub_f32_e32 v37, v37, v55
	v_sub_f32_e32 v36, v36, v55
	v_cndmask_b32_e32 v54, v54, v56, vcc
	v_rsq_f32_e32 v54, v54
	v_sub_f32_e32 v39, v39, v55
	v_sub_f32_e32 v38, v38, v55
	v_mul_f32_e32 v56, 0x45800000, v54
	v_cndmask_b32_e32 v54, v54, v56, vcc
	v_pk_mul_f32 v[38:39], v[38:39], v[54:55] op_sel_hi:[1,0]
	v_pk_mul_f32 v[36:37], v[36:37], v[54:55] op_sel_hi:[1,0]
	v_pk_fma_f32 v[38:39], v[42:43], v[38:39], v[46:47]
	v_pk_fma_f32 v[36:37], v[40:41], v[36:37], v[44:45]
	v_pk_fma_f32 v[30:31], v[38:39], s[26:27], v[30:31] op_sel_hi:[1,0,1]
	v_pk_fma_f32 v[28:29], v[36:37], s[26:27], v[28:29] op_sel_hi:[1,0,1]
	global_store_dwordx4 v[34:35], v[28:31], off
	v_lshlrev_b64 v[44:45], 11, v[52:53]
	v_lshl_add_u64 v[44:45], s[14:15], 0, v[44:45]
	v_lshl_add_u64 v[52:53], v[144:145], 1, v[44:45]
	v_sub_f32_e32 v45, v49, v55
	v_sub_f32_e32 v44, v48, v55
	v_sub_f32_e32 v47, v51, v55
	v_sub_f32_e32 v46, v50, v55
	v_pk_mul_f32 v[46:47], v[46:47], v[54:55] op_sel_hi:[1,0]
	v_pk_mul_f32 v[48:49], v[44:45], v[54:55] op_sel_hi:[1,0]
	v_cvt_pk_bf16_f32 v44, v28, v29
	v_cvt_pk_bf16_f32 v45, v30, v31
	v_pk_fma_f32 v[38:39], v[198:199], v[46:47], v[202:203]
	v_pk_fma_f32 v[36:37], v[196:197], v[48:49], v[200:201]
	v_pk_fma_f32 v[26:27], v[38:39], s[26:27], v[26:27] op_sel_hi:[1,0,1]
	v_pk_fma_f32 v[24:25], v[36:37], s[26:27], v[24:25] op_sel_hi:[1,0,1]
	global_store_dwordx4 v[34:35], v[24:27], off offset:16
	v_cvt_pk_bf16_f32 v46, v24, v25
	v_cvt_pk_bf16_f32 v47, v26, v27
	flat_store_dwordx4 v[52:53], v[44:47]
	global_load_dwordx4 v[40:43], v[120:121], off
	s_nop 0
	global_load_dwordx4 v[44:47], v[122:123], off
	global_load_dwordx4 v[196:199], v[124:125], off
	global_load_dwordx4 v[200:203], v[126:127], off
	s_waitcnt vmcnt(0)
	v_sub_f32_e32 v37, v205, v55
	v_sub_f32_e32 v36, v204, v55
	v_sub_f32_e32 v39, v207, v55
	v_sub_f32_e32 v38, v206, v55
	v_pk_mul_f32 v[38:39], v[54:55], v[38:39] op_sel_hi:[0,1]
	v_pk_mul_f32 v[36:37], v[54:55], v[36:37] op_sel_hi:[0,1]
	v_pk_fma_f32 v[36:37], v[40:41], v[36:37], v[44:45]
	v_pk_fma_f32 v[38:39], v[42:43], v[38:39], v[46:47]
	v_pk_fma_f32 v[20:21], v[36:37], s[26:27], v[20:21] op_sel_hi:[1,0,1]
	v_pk_fma_f32 v[22:23], v[38:39], s[26:27], v[22:23] op_sel_hi:[1,0,1]
	global_store_dwordx4 v[34:35], v[20:23], off offset:512
	v_add_f32_e32 v44, v28, v29
	v_mul_f32_e32 v29, v29, v29
	v_fmac_f32_e32 v29, v28, v28
	v_add_f32_e32 v44, v30, v44
	v_fmac_f32_e32 v29, v30, v30
	v_add_f32_e32 v30, v24, v25
	v_mul_f32_e32 v25, v25, v25
	v_fmac_f32_e32 v25, v24, v24
	v_add_f32_e32 v28, v31, v44
	v_add_f32_e32 v30, v26, v30
	v_fmac_f32_e32 v25, v26, v26
	v_add_f32_e32 v28, 0, v28
	v_fmac_f32_e32 v29, v31, v31
	v_add_f32_e32 v24, v27, v30
	v_fmac_f32_e32 v25, v27, v27
	v_add_f32_e32 v28, v24, v28
	v_add_f32_e32 v29, v29, v25
	v_sub_f32_e32 v25, v209, v55
	v_sub_f32_e32 v24, v208, v55
	v_pk_mul_f32 v[24:25], v[54:55], v[24:25] op_sel_hi:[0,1]
	v_sub_f32_e32 v27, v211, v55
	v_sub_f32_e32 v26, v210, v55
	v_pk_mul_f32 v[26:27], v[54:55], v[26:27] op_sel_hi:[0,1]
	v_mul_f32_e32 v31, v21, v21
	v_add_f32_e32 v30, v20, v21
	v_fmac_f32_e32 v31, v20, v20
	v_add_f32_e32 v30, v22, v30
	v_fmac_f32_e32 v31, v22, v22
	v_add_f32_e32 v30, v23, v30
	v_fmac_f32_e32 v31, v23, v23
	v_add_f32_e32 v28, v28, v30
	v_add_f32_e32 v29, v29, v31
	v_cvt_pk_bf16_f32 v20, v20, v21
	v_cvt_pk_bf16_f32 v21, v22, v23
	v_pk_fma_f32 v[24:25], v[196:197], v[24:25], v[200:201]
	s_nop 0
	v_pk_fma_f32 v[24:25], v[24:25], s[26:27], v[16:17] op_sel_hi:[1,0,1]
	v_pk_fma_f32 v[26:27], v[198:199], v[26:27], v[202:203]
	v_mul_f32_e32 v17, v25, v25
	v_pk_fma_f32 v[26:27], v[26:27], s[26:27], v[18:19] op_sel_hi:[1,0,1]
	v_add_f32_e32 v16, v24, v25
	v_fmac_f32_e32 v17, v24, v24
	v_add_f32_e32 v16, v26, v16
	v_fmac_f32_e32 v17, v26, v26
	v_add_f32_e32 v16, v27, v16
	v_fmac_f32_e32 v17, v27, v27
	v_add_f32_e32 v16, v28, v16
	v_add_f32_e32 v17, v29, v17
	ds_bpermute_b32 v18, v116, v16
	ds_bpermute_b32 v19, v116, v17
	global_store_dwordx4 v[34:35], v[24:27], off offset:528
	v_cvt_pk_bf16_f32 v22, v24, v25
	v_cvt_pk_bf16_f32 v23, v26, v27
	s_waitcnt lgkmcnt(0)
	v_add_f32_e32 v16, v16, v18
	v_add_f32_e32 v17, v17, v19
	ds_bpermute_b32 v18, v117, v16
	ds_bpermute_b32 v19, v117, v17
	flat_store_dwordx4 v[52:53], v[20:23] offset:256
	s_mov_b32 s100, -1
	s_mov_b32 s101, 0
	s_mov_b32 s98, 0xffff0000
	s_mov_b32 s99, 0
	s_and_saveexec_b64 s[30:31], s[100:101]
	s_cbranch_execz .LBB0_1552
	v_lshl_add_u64 v[20:21], s[10:11], 0, v[32:33]
	s_waitcnt lgkmcnt(0)
	v_add_f32_e32 v16, v16, v18
	v_add_f32_e32 v17, v17, v19
	v_cndmask_b32_e64 v16, v16, v17, s[98:99]
	v_cndmask_b32_e64 v17, 0, 4, s[98:99]
	v_or_b32_e32 v20, v20, v17
	flat_atomic_add_f32 v[20:21], v16
; DEVI unsigned pk2(float lo, float hi) { unsigned r; asm("v_cvt_pk_bf16_f32 %0, %1, %2" : "=v"(r) : "v"(lo), "v"(hi)); return r; }
;     DEVI void operator()(const f32x4 (&acc)[2][2][4][2], const pg8::Unit& u, int wr, int wc, int fr, int fq) const {
;     ...
;                 const int row = row0 + ai * 128 + m * 16; float mu, rs; row_stats(stin, row, mu, rs);
;                 float sum = 0.f, sq = 0.f;
; #pragma unroll
;                 for (int bj = 0; bj < 2; ++bj) {
;                     f32x4 z[2];
; #pragma unroll
;                     for (int n = 0; n < 2; ++n) {
;                         const int col = colb + bj * 128 + 4 * n;
;                         f32x4 xv = *(const f32x4*)(zsrc + (size_t)row * DM + col);
;                         if (stin) { const f32x4 gv = *(const f32x4*)(gin + col), bv = *(const f32x4*)(bin + col); xv = (xv - mu) * rs * gv + bv; }
;                         f32x4 zz = ALPHA * xv + acc[ai][bj][m][n];
;                         if (bias) zz += *(const f32x4*)(bias + col);
;                         *(f32x4*)(zdst + (size_t)row * DM + col) = zz;
;                         sum += zz[0] + zz[1] + zz[2] + zz[3]; sq += zz[0] * zz[0] + zz[1] * zz[1] + zz[2] * zz[2] + zz[3] * zz[3];
;                         z[n] = zz;
;                     }
;                     u32x4 o; o.x = pk2(z[0][0], z[0][1]); o.y = pk2(z[0][2], z[0][3]); o.z = pk2(z[1][0], z[1][1]); o.w = pk2(z[1][2], z[1][3]);
;                     if (zb) *(u32x4*)(zb + (size_t)row * DM + colb + bj * 128) = o;
;                 }
;                 sum += __shfl_xor(sum, 16); sq += __shfl_xor(sq, 16);
;                 sum += __shfl_xor(sum, 32); sq += __shfl_xor(sq, 32);
;                 if (fq == 0) { atomicAdd(stout + 2 * (size_t)row, sum); atomicAdd(stout + 2 * (size_t)row + 1, sq); }
.LBB0_1552:
	s_or_b64 exec, exec, s[30:31]
	v_add_u32_e32 v36, 0xb0, v154
	v_ashrrev_i32_e32 v37, 31, v36
	v_lshlrev_b64 v[16:17], 3, v[36:37]
	s_waitcnt lgkmcnt(0)
	v_lshl_add_u64 v[18:19], s[12:13], 0, v[16:17]
	flat_load_dwordx2 v[38:39], v[18:19]
	v_lshlrev_b64 v[18:19], 12, v[36:37]
	v_lshl_add_u64 v[18:19], s[46:47], 0, v[18:19]
	v_lshl_add_u64 v[18:19], v[144:145], 2, v[18:19]
	global_load_dwordx4 v[20:23], v[18:19], off
	global_load_dwordx4 v[24:27], v[150:151], off
	global_load_dwordx4 v[28:31], v[152:153], off
	global_load_dwordx4 v[32:35], v[18:19], off offset:16
	global_load_dwordx4 v[196:199], v[146:147], off
	global_load_dwordx4 v[200:203], v[148:149], off
	global_load_dwordx4 v[204:207], v[18:19], off offset:512
	global_load_dwordx4 v[208:211], v[18:19], off offset:528
	s_waitcnt vmcnt(0) lgkmcnt(0)
	v_pk_mul_f32 v[38:39], v[38:39], s[24:25] op_sel:[1,0] op_sel_hi:[0,0]
	v_fma_f32 v38, -v39, v39, v38
	v_max_f32_e32 v38, 0, v38
	v_add_f32_e32 v38, 0x3727c5ac, v38
	v_mul_f32_e32 v40, 0x4b800000, v38
	v_cmp_gt_f32_e32 vcc, s61, v38
	v_sub_f32_e32 v21, v21, v39
	v_sub_f32_e32 v20, v20, v39
	v_cndmask_b32_e32 v38, v38, v40, vcc
	v_rsq_f32_e32 v38, v38
	v_sub_f32_e32 v23, v23, v39
	v_sub_f32_e32 v22, v22, v39
	v_mul_f32_e32 v40, 0x45800000, v38
	v_cndmask_b32_e32 v38, v38, v40, vcc
	v_pk_mul_f32 v[22:23], v[22:23], v[38:39] op_sel_hi:[1,0]
	v_pk_mul_f32 v[20:21], v[20:21], v[38:39] op_sel_hi:[1,0]
	v_pk_fma_f32 v[22:23], v[26:27], v[22:23], v[30:31]
	v_pk_fma_f32 v[20:21], v[24:25], v[20:21], v[28:29]
	v_pk_fma_f32 v[14:15], v[22:23], s[26:27], v[14:15] op_sel_hi:[1,0,1]
	v_pk_fma_f32 v[12:13], v[20:21], s[26:27], v[12:13] op_sel_hi:[1,0,1]
	global_store_dwordx4 v[18:19], v[12:15], off
	v_lshlrev_b64 v[28:29], 11, v[36:37]
	v_lshl_add_u64 v[28:29], s[14:15], 0, v[28:29]
	v_lshl_add_u64 v[36:37], v[144:145], 1, v[28:29]
	v_sub_f32_e32 v29, v33, v39
	v_sub_f32_e32 v28, v32, v39
	v_sub_f32_e32 v31, v35, v39
	v_sub_f32_e32 v30, v34, v39
	v_pk_mul_f32 v[30:31], v[30:31], v[38:39] op_sel_hi:[1,0]
	v_pk_mul_f32 v[32:33], v[28:29], v[38:39] op_sel_hi:[1,0]
	v_cvt_pk_bf16_f32 v28, v12, v13
	v_cvt_pk_bf16_f32 v29, v14, v15
	v_pk_fma_f32 v[22:23], v[198:199], v[30:31], v[202:203]
	v_pk_fma_f32 v[20:21], v[196:197], v[32:33], v[200:201]
	v_pk_fma_f32 v[10:11], v[22:23], s[26:27], v[10:11] op_sel_hi:[1,0,1]
	v_pk_fma_f32 v[8:9], v[20:21], s[26:27], v[8:9] op_sel_hi:[1,0,1]
	global_store_dwordx4 v[18:19], v[8:11], off offset:16
	v_cvt_pk_bf16_f32 v30, v8, v9
	v_cvt_pk_bf16_f32 v31, v10, v11
	flat_store_dwordx4 v[36:37], v[28:31]
	global_load_dwordx4 v[24:27], v[120:121], off
	s_nop 0
	global_load_dwordx4 v[28:31], v[122:123], off
	global_load_dwordx4 v[196:199], v[124:125], off
	global_load_dwordx4 v[200:203], v[126:127], off
	s_waitcnt vmcnt(0)
	v_sub_f32_e32 v21, v205, v39
	v_sub_f32_e32 v20, v204, v39
	v_sub_f32_e32 v23, v207, v39
	v_sub_f32_e32 v22, v206, v39
	v_pk_mul_f32 v[22:23], v[38:39], v[22:23] op_sel_hi:[0,1]
	v_pk_mul_f32 v[20:21], v[38:39], v[20:21] op_sel_hi:[0,1]
	v_pk_fma_f32 v[20:21], v[24:25], v[20:21], v[28:29]
	v_pk_fma_f32 v[22:23], v[26:27], v[22:23], v[30:31]
	v_pk_fma_f32 v[4:5], v[20:21], s[26:27], v[4:5] op_sel_hi:[1,0,1]
	v_pk_fma_f32 v[6:7], v[22:23], s[26:27], v[6:7] op_sel_hi:[1,0,1]
	global_store_dwordx4 v[18:19], v[4:7], off offset:512
	v_add_f32_e32 v28, v12, v13
	v_mul_f32_e32 v13, v13, v13
	v_fmac_f32_e32 v13, v12, v12
	v_add_f32_e32 v28, v14, v28
	v_fmac_f32_e32 v13, v14, v14
	v_add_f32_e32 v14, v8, v9
	v_mul_f32_e32 v9, v9, v9
	v_fmac_f32_e32 v9, v8, v8
	v_add_f32_e32 v12, v15, v28
	v_add_f32_e32 v14, v10, v14
	v_fmac_f32_e32 v9, v10, v10
	v_add_f32_e32 v12, 0, v12
	v_fmac_f32_e32 v13, v15, v15
	v_add_f32_e32 v8, v11, v14
	v_fmac_f32_e32 v9, v11, v11
	v_add_f32_e32 v12, v8, v12
	v_add_f32_e32 v13, v13, v9
	v_sub_f32_e32 v9, v209, v39
	v_sub_f32_e32 v8, v208, v39
	v_pk_mul_f32 v[8:9], v[38:39], v[8:9] op_sel_hi:[0,1]
	v_sub_f32_e32 v11, v211, v39
	v_sub_f32_e32 v10, v210, v39
	v_pk_mul_f32 v[10:11], v[38:39], v[10:11] op_sel_hi:[0,1]
	v_mul_f32_e32 v15, v5, v5
	v_add_f32_e32 v14, v4, v5
	v_fmac_f32_e32 v15, v4, v4
	v_add_f32_e32 v14, v6, v14
	v_fmac_f32_e32 v15, v6, v6
	v_add_f32_e32 v14, v7, v14
	v_fmac_f32_e32 v15, v7, v7
	v_add_f32_e32 v12, v12, v14
	v_add_f32_e32 v13, v13, v15
	v_cvt_pk_bf16_f32 v4, v4, v5
	v_cvt_pk_bf16_f32 v5, v6, v7
	v_pk_fma_f32 v[8:9], v[196:197], v[8:9], v[200:201]
	s_nop 0
	v_pk_fma_f32 v[8:9], v[8:9], s[26:27], v[0:1] op_sel_hi:[1,0,1]
	v_pk_fma_f32 v[10:11], v[198:199], v[10:11], v[202:203]
	v_mul_f32_e32 v1, v9, v9
	v_pk_fma_f32 v[10:11], v[10:11], s[26:27], v[2:3] op_sel_hi:[1,0,1]
	v_add_f32_e32 v0, v8, v9
	v_fmac_f32_e32 v1, v8, v8
	v_add_f32_e32 v0, v10, v0
	v_fmac_f32_e32 v1, v10, v10
	v_add_f32_e32 v0, v11, v0
	v_fmac_f32_e32 v1, v11, v11
	v_add_f32_e32 v0, v12, v0
	v_add_f32_e32 v1, v13, v1
	ds_bpermute_b32 v2, v116, v0
	ds_bpermute_b32 v3, v116, v1
	global_store_dwordx4 v[18:19], v[8:11], off offset:528
	v_cvt_pk_bf16_f32 v6, v8, v9
	v_cvt_pk_bf16_f32 v7, v10, v11
	s_waitcnt lgkmcnt(0)
	v_add_f32_e32 v0, v0, v2
	v_add_f32_e32 v1, v1, v3
	ds_bpermute_b32 v2, v117, v0
	ds_bpermute_b32 v3, v117, v1
	flat_store_dwordx4 v[36:37], v[4:7] offset:256
	s_mov_b32 s100, -1
	s_mov_b32 s101, 0
	s_mov_b32 s98, 0xffff0000
	s_mov_b32 s99, 0
	s_and_saveexec_b64 s[30:31], s[100:101]
	s_cbranch_execz .LBB0_1554
	v_lshl_add_u64 v[4:5], s[10:11], 0, v[16:17]
	s_waitcnt lgkmcnt(0)
	v_add_f32_e32 v0, v0, v2
	v_add_f32_e32 v1, v1, v3
	v_cndmask_b32_e64 v0, v0, v1, s[98:99]
	v_cndmask_b32_e64 v1, 0, 4, s[98:99]
	v_or_b32_e32 v4, v4, v1
	flat_atomic_add_f32 v[4:5], v0

; DEVI unsigned pk2(float lo, float hi) { unsigned r; asm("v_cvt_pk_bf16_f32 %0, %1, %2" : "=v"(r) : "v"(lo), "v"(hi)); return r; }
;     DEVI void operator()(const f32x4 (&acc)[2][2][4][2], const pg8::Unit& u, int wr, int wc, int fr, int fq) const {
;     ...
;                 const int row = row0 + ai * 128 + m * 16; float mu, rs; row_stats(stin, row, mu, rs);
;                 float sum = 0.f, sq = 0.f;
; #pragma unroll
;                 for (int bj = 0; bj < 2; ++bj) {
;                     f32x4 z[2];
; #pragma unroll
;                     for (int n = 0; n < 2; ++n) {
;                         const int col = colb + bj * 128 + 4 * n;
;                         f32x4 xv = *(const f32x4*)(zsrc + (size_t)row * DM + col);
;                         if (stin) { const f32x4 gv = *(const f32x4*)(gin + col), bv = *(const f32x4*)(bin + col); xv = (xv - mu) * rs * gv + bv; }
;                         f32x4 zz = ALPHA * xv + acc[ai][bj][m][n];
;                         if (bias) zz += *(const f32x4*)(bias + col);
;                         *(f32x4*)(zdst + (size_t)row * DM + col) = zz;
;                         sum += zz[0] + zz[1] + zz[2] + zz[3]; sq += zz[0] * zz[0] + zz[1] * zz[1] + zz[2] * zz[2] + zz[3] * zz[3];
;                         z[n] = zz;
;                     }
;                     u32x4 o; o.x = pk2(z[0][0], z[0][1]); o.y = pk2(z[0][2], z[0][3]); o.z = pk2(z[1][0], z[1][1]); o.w = pk2(z[1][2], z[1][3]);
;                     if (zb) *(u32x4*)(zb + (size_t)row * DM + colb + bj * 128) = o;
;                 }
;                 sum += __shfl_xor(sum, 16); sq += __shfl_xor(sq, 16);
;                 sum += __shfl_xor(sum, 32); sq += __shfl_xor(sq, 32);
;                 if (fq == 0) { atomicAdd(stout + 2 * (size_t)row, sum); atomicAdd(stout + 2 * (size_t)row + 1, sq); }
.LBB0_1985:
	s_or_b64 exec, exec, s[36:37]
	v_or_b32_e32 v166, 16, v154
	v_ashrrev_i32_e32 v167, 31, v166
	v_lshlrev_b64 v[112:113], 3, v[166:167]
	s_waitcnt lgkmcnt(0)
	v_lshl_add_u64 v[114:115], s[6:7], 0, v[112:113]
	flat_load_dwordx2 v[192:193], v[114:115]
	v_lshlrev_b64 v[114:115], 12, v[166:167]
	v_lshl_add_u64 v[114:115], s[46:47], 0, v[114:115]
	v_lshl_add_u64 v[114:115], v[144:145], 2, v[114:115]
	global_load_dwordx4 v[162:165], v[114:115], off
	global_load_dwordx4 v[176:179], v[150:151], off
	global_load_dwordx4 v[180:183], v[152:153], off
	global_load_dwordx4 v[184:187], v[156:157], off
	global_load_dwordx4 v[188:191], v[114:115], off offset:16
	v_lshlrev_b64 v[166:167], 11, v[166:167]
	v_lshl_add_u64 v[166:167], s[10:11], 0, v[166:167]
	v_lshl_add_u64 v[166:167], v[144:145], 1, v[166:167]
	global_load_dwordx4 v[208:211], v[146:147], off
	global_load_dwordx4 v[212:215], v[148:149], off
	global_load_dwordx4 v[250:253], v[124:125], off
	s_waitcnt vmcnt(0) lgkmcnt(0)
	v_pk_mul_f32 v[192:193], v[192:193], s[22:23] op_sel:[1,0] op_sel_hi:[0,0]
	v_fma_f32 v155, -v193, v193, v192
	v_max_f32_e32 v155, 0, v155
	v_add_f32_e32 v155, 0x3727c5ac, v155
	v_mul_f32_e32 v175, 0x4b800000, v155
	v_cmp_gt_f32_e32 vcc, s72, v155
	v_sub_f32_e32 v165, v165, v193
	v_sub_f32_e32 v164, v164, v193
	v_cndmask_b32_e32 v155, v155, v175, vcc
	v_rsq_f32_e32 v155, v155
	v_sub_f32_e32 v163, v163, v193
	v_sub_f32_e32 v162, v162, v193
	v_mul_f32_e32 v175, 0x45800000, v155
	v_cndmask_b32_e32 v192, v155, v175, vcc
	v_pk_mul_f32 v[162:163], v[162:163], v[192:193] op_sel_hi:[1,0]
	v_pk_mul_f32 v[164:165], v[164:165], v[192:193] op_sel_hi:[1,0]
	v_pk_fma_f32 v[162:163], v[176:177], v[162:163], v[180:181]
	v_pk_fma_f32 v[164:165], v[178:179], v[164:165], v[182:183]
	v_pk_fma_f32 v[108:109], v[162:163], s[24:25], v[108:109] op_sel_hi:[1,0,1]
	v_pk_fma_f32 v[110:111], v[164:165], s[24:25], v[110:111] op_sel_hi:[1,0,1]
	v_pk_add_f32 v[108:109], v[184:185], v[108:109]
	v_pk_add_f32 v[110:111], v[186:187], v[110:111]
	global_store_dwordx4 v[114:115], v[108:111], off
	v_sub_f32_e32 v185, v191, v193
	v_sub_f32_e32 v184, v190, v193
	v_sub_f32_e32 v187, v189, v193
	v_sub_f32_e32 v186, v188, v193
	v_pk_mul_f32 v[186:187], v[186:187], v[192:193] op_sel_hi:[1,0]
	v_pk_mul_f32 v[188:189], v[184:185], v[192:193] op_sel_hi:[1,0]
	v_cvt_pk_bf16_f32 v184, v108, v109
	v_cvt_pk_bf16_f32 v185, v110, v111
	v_add_f32_e32 v155, v108, v109
	v_mul_f32_e32 v109, v109, v109
	v_fmac_f32_e32 v109, v108, v108
	v_add_f32_e32 v155, v110, v155
	v_fmac_f32_e32 v109, v110, v110
	v_add_f32_e32 v108, v111, v155
	v_add_f32_e32 v108, 0, v108
	v_fmac_f32_e32 v109, v111, v111
	v_pk_fma_f32 v[164:165], v[210:211], v[188:189], v[214:215]
	v_pk_fma_f32 v[162:163], v[208:209], v[186:187], v[212:213]
	v_pk_fma_f32 v[106:107], v[164:165], s[24:25], v[106:107] op_sel_hi:[1,0,1]
	v_pk_fma_f32 v[104:105], v[162:163], s[24:25], v[104:105] op_sel_hi:[1,0,1]
	v_pk_add_f32 v[106:107], v[252:253], v[106:107]
	v_pk_add_f32 v[104:105], v[250:251], v[104:105]
	global_store_dwordx4 v[114:115], v[104:107], off offset:16
	v_cvt_pk_bf16_f32 v186, v104, v105
	v_cvt_pk_bf16_f32 v187, v106, v107
	flat_store_dwordx4 v[166:167], v[184:187]
	global_load_dwordx4 v[162:165], v[114:115], off offset:512
	global_load_dwordx4 v[176:179], v[126:127], off
	global_load_dwordx4 v[180:183], v[158:159], off
	s_nop 0
	global_load_dwordx4 v[184:187], v[160:161], off
	global_load_dwordx4 v[188:191], v[114:115], off offset:528
	v_add_f32_e32 v110, v104, v105
	v_mul_f32_e32 v105, v105, v105
	v_fmac_f32_e32 v105, v104, v104
	v_add_f32_e32 v110, v106, v110
	v_fmac_f32_e32 v105, v106, v106
	v_add_f32_e32 v104, v107, v110
	v_fmac_f32_e32 v105, v107, v107
	v_add_f32_e32 v108, v104, v108
	v_add_f32_e32 v109, v109, v105
	global_load_dwordx4 v[208:211], v[120:121], off
	global_load_dwordx4 v[212:215], v[122:123], off
	global_load_dwordx4 v[250:253], v[116:117], off
	s_waitcnt vmcnt(0)
	v_sub_f32_e32 v165, v165, v193
	v_sub_f32_e32 v164, v164, v193
	v_sub_f32_e32 v163, v163, v193
	v_sub_f32_e32 v162, v162, v193
	v_pk_mul_f32 v[162:163], v[192:193], v[162:163] op_sel_hi:[0,1]
	v_pk_mul_f32 v[164:165], v[192:193], v[164:165] op_sel_hi:[0,1]
	v_pk_fma_f32 v[164:165], v[178:179], v[164:165], v[182:183]
	v_pk_fma_f32 v[162:163], v[176:177], v[162:163], v[180:181]
	v_pk_fma_f32 v[102:103], v[164:165], s[24:25], v[102:103] op_sel_hi:[1,0,1]
	v_pk_fma_f32 v[100:101], v[162:163], s[24:25], v[100:101] op_sel_hi:[1,0,1]
	v_pk_add_f32 v[102:103], v[186:187], v[102:103]
	v_pk_add_f32 v[100:101], v[184:185], v[100:101]
	global_store_dwordx4 v[114:115], v[100:103], off offset:512
	v_sub_f32_e32 v107, v189, v193
	v_sub_f32_e32 v106, v188, v193
	v_sub_f32_e32 v105, v191, v193
	v_sub_f32_e32 v104, v190, v193
	v_pk_mul_f32 v[106:107], v[192:193], v[106:107] op_sel_hi:[0,1]
	v_pk_mul_f32 v[104:105], v[192:193], v[104:105] op_sel_hi:[0,1]
	v_mul_f32_e32 v111, v101, v101
	v_add_f32_e32 v110, v100, v101
	v_fmac_f32_e32 v111, v100, v100
	v_add_f32_e32 v110, v102, v110
	v_fmac_f32_e32 v111, v102, v102
	v_add_f32_e32 v110, v103, v110
	v_fmac_f32_e32 v111, v103, v103
	v_add_f32_e32 v108, v108, v110
	v_add_f32_e32 v109, v109, v111
	v_cvt_pk_bf16_f32 v100, v100, v101
	v_cvt_pk_bf16_f32 v101, v102, v103
	v_pk_fma_f32 v[106:107], v[208:209], v[106:107], v[212:213]
	v_pk_fma_f32 v[104:105], v[210:211], v[104:105], v[214:215]
	v_pk_fma_f32 v[96:97], v[106:107], s[24:25], v[96:97] op_sel_hi:[1,0,1]
	v_pk_fma_f32 v[98:99], v[104:105], s[24:25], v[98:99] op_sel_hi:[1,0,1]
	v_pk_add_f32 v[104:105], v[250:251], v[96:97]
	v_pk_add_f32 v[106:107], v[252:253], v[98:99]
	v_mul_f32_e32 v97, v105, v105
	v_add_f32_e32 v96, v104, v105
	v_fmac_f32_e32 v97, v104, v104
	v_add_f32_e32 v96, v106, v96
	v_fmac_f32_e32 v97, v106, v106
	v_add_f32_e32 v96, v107, v96
	v_fmac_f32_e32 v97, v107, v107
	v_add_f32_e32 v96, v108, v96
	v_add_f32_e32 v97, v109, v97
	ds_bpermute_b32 v98, v118, v96
	ds_bpermute_b32 v99, v118, v97
	global_store_dwordx4 v[114:115], v[104:107], off offset:528
	v_cvt_pk_bf16_f32 v102, v104, v105
	v_cvt_pk_bf16_f32 v103, v106, v107
	s_waitcnt lgkmcnt(0)
	v_add_f32_e32 v96, v96, v98
	v_add_f32_e32 v97, v97, v99
	ds_bpermute_b32 v98, v119, v96
	ds_bpermute_b32 v99, v119, v97
	flat_store_dwordx4 v[166:167], v[100:103] offset:256
	s_mov_b32 s100, -1
	s_mov_b32 s101, 0
	s_mov_b32 s98, 0xffff0000
	s_mov_b32 s99, 0
	s_and_saveexec_b64 s[36:37], s[100:101]
	s_cbranch_execz .LBB0_1987
	s_waitcnt lgkmcnt(0)
	v_add_f32_e32 v99, v97, v99
	v_add_f32_e32 v98, v96, v98
	v_lshl_add_u64 v[96:97], s[8:9], 0, v[112:113]
	v_cndmask_b32_e64 v98, v98, v99, s[98:99]
	v_cndmask_b32_e64 v99, 0, 4, s[98:99]
	v_or_b32_e32 v96, v96, v99
	flat_atomic_add_f32 v[96:97], v98
; DEVI unsigned pk2(float lo, float hi) { unsigned r; asm("v_cvt_pk_bf16_f32 %0, %1, %2" : "=v"(r) : "v"(lo), "v"(hi)); return r; }
;     DEVI void operator()(const f32x4 (&acc)[2][2][4][2], const pg8::Unit& u, int wr, int wc, int fr, int fq) const {
;     ...
;                 const int row = row0 + ai * 128 + m * 16; float mu, rs; row_stats(stin, row, mu, rs);
;                 float sum = 0.f, sq = 0.f;
; #pragma unroll
;                 for (int bj = 0; bj < 2; ++bj) {
;                     f32x4 z[2];
; #pragma unroll
;                     for (int n = 0; n < 2; ++n) {
;                         const int col = colb + bj * 128 + 4 * n;
;                         f32x4 xv = *(const f32x4*)(zsrc + (size_t)row * DM + col);
;                         if (stin) { const f32x4 gv = *(const f32x4*)(gin + col), bv = *(const f32x4*)(bin + col); xv = (xv - mu) * rs * gv + bv; }
;                         f32x4 zz = ALPHA * xv + acc[ai][bj][m][n];
;                         if (bias) zz += *(const f32x4*)(bias + col);
;                         *(f32x4*)(zdst + (size_t)row * DM + col) = zz;
;                         sum += zz[0] + zz[1] + zz[2] + zz[3]; sq += zz[0] * zz[0] + zz[1] * zz[1] + zz[2] * zz[2] + zz[3] * zz[3];
;                         z[n] = zz;
;                     }
;                     u32x4 o; o.x = pk2(z[0][0], z[0][1]); o.y = pk2(z[0][2], z[0][3]); o.z = pk2(z[1][0], z[1][1]); o.w = pk2(z[1][2], z[1][3]);
;                     if (zb) *(u32x4*)(zb + (size_t)row * DM + colb + bj * 128) = o;
;                 }
;                 sum += __shfl_xor(sum, 16); sq += __shfl_xor(sq, 16);
;                 sum += __shfl_xor(sum, 32); sq += __shfl_xor(sq, 32);
;                 if (fq == 0) { atomicAdd(stout + 2 * (size_t)row, sum); atomicAdd(stout + 2 * (size_t)row + 1, sq); }
.LBB0_1987:
	s_or_b64 exec, exec, s[36:37]
	v_or_b32_e32 v166, 32, v154
	v_ashrrev_i32_e32 v167, 31, v166
	v_lshlrev_b64 v[96:97], 3, v[166:167]
	s_waitcnt lgkmcnt(0)
	v_lshl_add_u64 v[98:99], s[6:7], 0, v[96:97]
	flat_load_dwordx2 v[176:177], v[98:99]
	v_lshlrev_b64 v[98:99], 12, v[166:167]
	v_lshl_add_u64 v[98:99], s[46:47], 0, v[98:99]
	v_lshl_add_u64 v[98:99], v[144:145], 2, v[98:99]
	global_load_dwordx4 v[100:103], v[98:99], off
	global_load_dwordx4 v[104:107], v[150:151], off
	global_load_dwordx4 v[108:111], v[152:153], off
	global_load_dwordx4 v[112:115], v[156:157], off
	global_load_dwordx4 v[162:165], v[98:99], off offset:16
	global_load_dwordx4 v[208:211], v[146:147], off
	global_load_dwordx4 v[212:215], v[148:149], off
	global_load_dwordx4 v[250:253], v[124:125], off
	s_waitcnt vmcnt(0) lgkmcnt(0)
	v_pk_mul_f32 v[176:177], v[176:177], s[22:23] op_sel:[1,0] op_sel_hi:[0,0]
	v_fma_f32 v155, -v177, v177, v176
	v_max_f32_e32 v155, 0, v155
	v_add_f32_e32 v155, 0x3727c5ac, v155
	v_mul_f32_e32 v175, 0x4b800000, v155
	v_cmp_gt_f32_e32 vcc, s72, v155
	v_sub_f32_e32 v103, v103, v177
	v_sub_f32_e32 v102, v102, v177
	v_cndmask_b32_e32 v155, v155, v175, vcc
	v_rsq_f32_e32 v155, v155
	v_sub_f32_e32 v101, v101, v177
	v_sub_f32_e32 v100, v100, v177
	v_mul_f32_e32 v175, 0x45800000, v155
	v_cndmask_b32_e32 v176, v155, v175, vcc
	v_pk_mul_f32 v[100:101], v[100:101], v[176:177] op_sel_hi:[1,0]
	v_pk_mul_f32 v[102:103], v[102:103], v[176:177] op_sel_hi:[1,0]
	v_pk_fma_f32 v[100:101], v[104:105], v[100:101], v[108:109]
	v_pk_fma_f32 v[102:103], v[106:107], v[102:103], v[110:111]
	v_pk_fma_f32 v[92:93], v[100:101], s[24:25], v[92:93] op_sel_hi:[1,0,1]
	v_pk_fma_f32 v[94:95], v[102:103], s[24:25], v[94:95] op_sel_hi:[1,0,1]
	v_pk_add_f32 v[92:93], v[112:113], v[92:93]
	v_pk_add_f32 v[94:95], v[114:115], v[94:95]
	global_store_dwordx4 v[98:99], v[92:95], off
	v_lshlrev_b64 v[112:113], 11, v[166:167]
	v_lshl_add_u64 v[112:113], s[10:11], 0, v[112:113]
	v_lshl_add_u64 v[166:167], v[144:145], 1, v[112:113]
	v_sub_f32_e32 v113, v165, v177
	v_sub_f32_e32 v112, v164, v177
	v_sub_f32_e32 v115, v163, v177
	v_sub_f32_e32 v114, v162, v177
	v_pk_mul_f32 v[114:115], v[114:115], v[176:177] op_sel_hi:[1,0]
	v_pk_mul_f32 v[162:163], v[112:113], v[176:177] op_sel_hi:[1,0]
	v_cvt_pk_bf16_f32 v112, v92, v93
	v_cvt_pk_bf16_f32 v113, v94, v95
	v_pk_fma_f32 v[100:101], v[208:209], v[114:115], v[212:213]
	v_pk_fma_f32 v[102:103], v[210:211], v[162:163], v[214:215]
	v_pk_fma_f32 v[88:89], v[100:101], s[24:25], v[88:89] op_sel_hi:[1,0,1]
	v_pk_fma_f32 v[90:91], v[102:103], s[24:25], v[90:91] op_sel_hi:[1,0,1]
	v_pk_add_f32 v[88:89], v[250:251], v[88:89]
	v_pk_add_f32 v[90:91], v[252:253], v[90:91]
	global_store_dwordx4 v[98:99], v[88:91], off offset:16
	v_cvt_pk_bf16_f32 v114, v88, v89
	v_cvt_pk_bf16_f32 v115, v90, v91
	flat_store_dwordx4 v[166:167], v[112:115]
	global_load_dwordx4 v[100:103], v[98:99], off offset:512
	global_load_dwordx4 v[104:107], v[126:127], off
	global_load_dwordx4 v[108:111], v[158:159], off
	s_nop 0
	global_load_dwordx4 v[112:115], v[160:161], off
	global_load_dwordx4 v[162:165], v[98:99], off offset:528
	global_load_dwordx4 v[208:211], v[120:121], off
	global_load_dwordx4 v[212:215], v[122:123], off
	global_load_dwordx4 v[250:253], v[116:117], off
	s_waitcnt vmcnt(0)
	v_sub_f32_e32 v103, v103, v177
	v_sub_f32_e32 v102, v102, v177
	v_sub_f32_e32 v101, v101, v177
	v_sub_f32_e32 v100, v100, v177
	v_pk_mul_f32 v[100:101], v[176:177], v[100:101] op_sel_hi:[0,1]
	v_pk_mul_f32 v[102:103], v[176:177], v[102:103] op_sel_hi:[0,1]
	v_pk_fma_f32 v[102:103], v[106:107], v[102:103], v[110:111]
	v_pk_fma_f32 v[100:101], v[104:105], v[100:101], v[108:109]
	v_pk_fma_f32 v[86:87], v[102:103], s[24:25], v[86:87] op_sel_hi:[1,0,1]
	v_pk_fma_f32 v[84:85], v[100:101], s[24:25], v[84:85] op_sel_hi:[1,0,1]
	v_pk_add_f32 v[86:87], v[114:115], v[86:87]
	v_pk_add_f32 v[84:85], v[112:113], v[84:85]
	global_store_dwordx4 v[98:99], v[84:87], off offset:512
	v_add_f32_e32 v112, v92, v93
	v_mul_f32_e32 v93, v93, v93
	v_fmac_f32_e32 v93, v92, v92
	v_add_f32_e32 v112, v94, v112
	v_fmac_f32_e32 v93, v94, v94
	v_add_f32_e32 v94, v88, v89
	v_mul_f32_e32 v89, v89, v89
	v_fmac_f32_e32 v89, v88, v88
	v_add_f32_e32 v92, v95, v112
	v_add_f32_e32 v94, v90, v94
	v_fmac_f32_e32 v89, v90, v90
	v_add_f32_e32 v92, 0, v92
	v_fmac_f32_e32 v93, v95, v95
	v_add_f32_e32 v88, v91, v94
	v_fmac_f32_e32 v89, v91, v91
	v_sub_f32_e32 v91, v163, v177
	v_sub_f32_e32 v90, v162, v177
	v_add_f32_e32 v92, v88, v92
	v_add_f32_e32 v93, v93, v89
	v_sub_f32_e32 v89, v165, v177
	v_sub_f32_e32 v88, v164, v177
	v_pk_mul_f32 v[90:91], v[176:177], v[90:91] op_sel_hi:[0,1]
	v_pk_mul_f32 v[88:89], v[176:177], v[88:89] op_sel_hi:[0,1]
	v_mul_f32_e32 v95, v85, v85
	v_add_f32_e32 v94, v84, v85
	v_fmac_f32_e32 v95, v84, v84
	v_add_f32_e32 v94, v86, v94
	v_fmac_f32_e32 v95, v86, v86
	v_add_f32_e32 v94, v87, v94
	v_fmac_f32_e32 v95, v87, v87
	v_add_f32_e32 v92, v92, v94
	v_add_f32_e32 v93, v93, v95
	v_cvt_pk_bf16_f32 v84, v84, v85
	v_cvt_pk_bf16_f32 v85, v86, v87
	v_pk_fma_f32 v[90:91], v[208:209], v[90:91], v[212:213]
	v_pk_fma_f32 v[88:89], v[210:211], v[88:89], v[214:215]
	v_pk_fma_f32 v[80:81], v[90:91], s[24:25], v[80:81] op_sel_hi:[1,0,1]
	v_pk_fma_f32 v[82:83], v[88:89], s[24:25], v[82:83] op_sel_hi:[1,0,1]
	v_pk_add_f32 v[88:89], v[250:251], v[80:81]
	v_pk_add_f32 v[90:91], v[252:253], v[82:83]
	v_mul_f32_e32 v81, v89, v89
	v_add_f32_e32 v80, v88, v89
	v_fmac_f32_e32 v81, v88, v88
	v_add_f32_e32 v80, v90, v80
	v_fmac_f32_e32 v81, v90, v90
	v_add_f32_e32 v80, v91, v80
	v_fmac_f32_e32 v81, v91, v91
	v_add_f32_e32 v80, v92, v80
	v_add_f32_e32 v81, v93, v81
	ds_bpermute_b32 v82, v118, v80
	ds_bpermute_b32 v83, v118, v81
	global_store_dwordx4 v[98:99], v[88:91], off offset:528
	v_cvt_pk_bf16_f32 v86, v88, v89
	v_cvt_pk_bf16_f32 v87, v90, v91
	s_waitcnt lgkmcnt(0)
	v_add_f32_e32 v80, v80, v82
	v_add_f32_e32 v81, v81, v83
	ds_bpermute_b32 v82, v119, v80
	ds_bpermute_b32 v83, v119, v81
	flat_store_dwordx4 v[166:167], v[84:87] offset:256
	s_mov_b32 s100, -1
	s_mov_b32 s101, 0
	s_mov_b32 s98, 0xffff0000
	s_mov_b32 s99, 0
	s_and_saveexec_b64 s[36:37], s[100:101]
	s_cbranch_execz .LBB0_1989
	s_waitcnt lgkmcnt(0)
	v_add_f32_e32 v83, v81, v83
	v_add_f32_e32 v82, v80, v82
	v_lshl_add_u64 v[80:81], s[8:9], 0, v[96:97]
	v_cndmask_b32_e64 v82, v82, v83, s[98:99]
	v_cndmask_b32_e64 v83, 0, 4, s[98:99]
	v_or_b32_e32 v80, v80, v83
	flat_atomic_add_f32 v[80:81], v82
; DEVI unsigned pk2(float lo, float hi) { unsigned r; asm("v_cvt_pk_bf16_f32 %0, %1, %2" : "=v"(r) : "v"(lo), "v"(hi)); return r; }
;     DEVI void operator()(const f32x4 (&acc)[2][2][4][2], const pg8::Unit& u, int wr, int wc, int fr, int fq) const {
;     ...
;                 const int row = row0 + ai * 128 + m * 16; float mu, rs; row_stats(stin, row, mu, rs);
;                 float sum = 0.f, sq = 0.f;
; #pragma unroll
;                 for (int bj = 0; bj < 2; ++bj) {
;                     f32x4 z[2];
; #pragma unroll
;                     for (int n = 0; n < 2; ++n) {
;                         const int col = colb + bj * 128 + 4 * n;
;                         f32x4 xv = *(const f32x4*)(zsrc + (size_t)row * DM + col);
;                         if (stin) { const f32x4 gv = *(const f32x4*)(gin + col), bv = *(const f32x4*)(bin + col); xv = (xv - mu) * rs * gv + bv; }
;                         f32x4 zz = ALPHA * xv + acc[ai][bj][m][n];
;                         if (bias) zz += *(const f32x4*)(bias + col);
;                         *(f32x4*)(zdst + (size_t)row * DM + col) = zz;
;                         sum += zz[0] + zz[1] + zz[2] + zz[3]; sq += zz[0] * zz[0] + zz[1] * zz[1] + zz[2] * zz[2] + zz[3] * zz[3];
;                         z[n] = zz;
;                     }
;                     u32x4 o; o.x = pk2(z[0][0], z[0][1]); o.y = pk2(z[0][2], z[0][3]); o.z = pk2(z[1][0], z[1][1]); o.w = pk2(z[1][2], z[1][3]);
;                     if (zb) *(u32x4*)(zb + (size_t)row * DM + colb + bj * 128) = o;
;                 }
;                 sum += __shfl_xor(sum, 16); sq += __shfl_xor(sq, 16);
;                 sum += __shfl_xor(sum, 32); sq += __shfl_xor(sq, 32);
;                 if (fq == 0) { atomicAdd(stout + 2 * (size_t)row, sum); atomicAdd(stout + 2 * (size_t)row + 1, sq); }
.LBB0_1989:
	s_or_b64 exec, exec, s[36:37]
	v_or_b32_e32 v104, 48, v154
	v_ashrrev_i32_e32 v105, 31, v104
	v_lshlrev_b64 v[80:81], 3, v[104:105]
	s_waitcnt lgkmcnt(0)
	v_lshl_add_u64 v[82:83], s[6:7], 0, v[80:81]
	flat_load_dwordx2 v[106:107], v[82:83]
	v_lshlrev_b64 v[82:83], 12, v[104:105]
	v_lshl_add_u64 v[82:83], s[46:47], 0, v[82:83]
	v_lshl_add_u64 v[82:83], v[144:145], 2, v[82:83]
	global_load_dwordx4 v[84:87], v[82:83], off
	global_load_dwordx4 v[88:91], v[150:151], off
	global_load_dwordx4 v[92:95], v[152:153], off
	global_load_dwordx4 v[96:99], v[156:157], off
	global_load_dwordx4 v[100:103], v[82:83], off offset:16
	global_load_dwordx4 v[208:211], v[146:147], off
	global_load_dwordx4 v[212:215], v[148:149], off
	global_load_dwordx4 v[250:253], v[124:125], off
	s_waitcnt vmcnt(0) lgkmcnt(0)
	v_pk_mul_f32 v[106:107], v[106:107], s[22:23] op_sel:[1,0] op_sel_hi:[0,0]
	v_fma_f32 v106, -v107, v107, v106
	v_max_f32_e32 v106, 0, v106
	v_add_f32_e32 v106, 0x3727c5ac, v106
	v_mul_f32_e32 v108, 0x4b800000, v106
	v_cmp_gt_f32_e32 vcc, s72, v106
	v_sub_f32_e32 v87, v87, v107
	v_sub_f32_e32 v86, v86, v107
	v_cndmask_b32_e32 v106, v106, v108, vcc
	v_rsq_f32_e32 v106, v106
	v_sub_f32_e32 v85, v85, v107
	v_sub_f32_e32 v84, v84, v107
	v_mul_f32_e32 v108, 0x45800000, v106
	v_cndmask_b32_e32 v106, v106, v108, vcc
	v_pk_mul_f32 v[84:85], v[84:85], v[106:107] op_sel_hi:[1,0]
	v_pk_mul_f32 v[86:87], v[86:87], v[106:107] op_sel_hi:[1,0]
	v_pk_fma_f32 v[84:85], v[88:89], v[84:85], v[92:93]
	v_pk_fma_f32 v[86:87], v[90:91], v[86:87], v[94:95]
	v_pk_fma_f32 v[76:77], v[84:85], s[24:25], v[76:77] op_sel_hi:[1,0,1]
	v_pk_fma_f32 v[78:79], v[86:87], s[24:25], v[78:79] op_sel_hi:[1,0,1]
	v_pk_add_f32 v[76:77], v[96:97], v[76:77]
	v_pk_add_f32 v[78:79], v[98:99], v[78:79]
	global_store_dwordx4 v[82:83], v[76:79], off
	v_lshlrev_b64 v[96:97], 11, v[104:105]
	v_lshl_add_u64 v[96:97], s[10:11], 0, v[96:97]
	v_lshl_add_u64 v[104:105], v[144:145], 1, v[96:97]
	v_sub_f32_e32 v97, v103, v107
	v_sub_f32_e32 v96, v102, v107
	v_sub_f32_e32 v99, v101, v107
	v_sub_f32_e32 v98, v100, v107
	v_pk_mul_f32 v[98:99], v[98:99], v[106:107] op_sel_hi:[1,0]
	v_pk_mul_f32 v[100:101], v[96:97], v[106:107] op_sel_hi:[1,0]
	v_cvt_pk_bf16_f32 v96, v76, v77
	v_cvt_pk_bf16_f32 v97, v78, v79
	v_pk_fma_f32 v[84:85], v[208:209], v[98:99], v[212:213]
	v_pk_fma_f32 v[86:87], v[210:211], v[100:101], v[214:215]
	v_pk_fma_f32 v[72:73], v[84:85], s[24:25], v[72:73] op_sel_hi:[1,0,1]
	v_pk_fma_f32 v[74:75], v[86:87], s[24:25], v[74:75] op_sel_hi:[1,0,1]
	v_pk_add_f32 v[72:73], v[250:251], v[72:73]
	v_pk_add_f32 v[74:75], v[252:253], v[74:75]
	global_store_dwordx4 v[82:83], v[72:75], off offset:16
	v_cvt_pk_bf16_f32 v98, v72, v73
	v_cvt_pk_bf16_f32 v99, v74, v75
	flat_store_dwordx4 v[104:105], v[96:99]
	global_load_dwordx4 v[84:87], v[82:83], off offset:512
	global_load_dwordx4 v[88:91], v[126:127], off
	global_load_dwordx4 v[92:95], v[158:159], off
	s_nop 0
	global_load_dwordx4 v[96:99], v[160:161], off
	global_load_dwordx4 v[100:103], v[82:83], off offset:528
	global_load_dwordx4 v[208:211], v[120:121], off
	global_load_dwordx4 v[212:215], v[122:123], off
	global_load_dwordx4 v[250:253], v[116:117], off
	s_waitcnt vmcnt(0)
	v_sub_f32_e32 v87, v87, v107
	v_sub_f32_e32 v86, v86, v107
	v_sub_f32_e32 v85, v85, v107
	v_sub_f32_e32 v84, v84, v107
	v_pk_mul_f32 v[84:85], v[106:107], v[84:85] op_sel_hi:[0,1]
	v_pk_mul_f32 v[86:87], v[106:107], v[86:87] op_sel_hi:[0,1]
	v_pk_fma_f32 v[86:87], v[90:91], v[86:87], v[94:95]
	v_pk_fma_f32 v[84:85], v[88:89], v[84:85], v[92:93]
	v_pk_fma_f32 v[70:71], v[86:87], s[24:25], v[70:71] op_sel_hi:[1,0,1]
	v_pk_fma_f32 v[68:69], v[84:85], s[24:25], v[68:69] op_sel_hi:[1,0,1]
	v_pk_add_f32 v[70:71], v[98:99], v[70:71]
	v_pk_add_f32 v[68:69], v[96:97], v[68:69]
	global_store_dwordx4 v[82:83], v[68:71], off offset:512
	v_add_f32_e32 v96, v76, v77
	v_mul_f32_e32 v77, v77, v77
	v_fmac_f32_e32 v77, v76, v76
	v_add_f32_e32 v96, v78, v96
	v_fmac_f32_e32 v77, v78, v78
	v_add_f32_e32 v78, v72, v73
	v_mul_f32_e32 v73, v73, v73
	v_fmac_f32_e32 v73, v72, v72
	v_add_f32_e32 v76, v79, v96
	v_add_f32_e32 v78, v74, v78
	v_fmac_f32_e32 v73, v74, v74
	v_add_f32_e32 v76, 0, v76
	v_fmac_f32_e32 v77, v79, v79
	v_add_f32_e32 v72, v75, v78
	v_fmac_f32_e32 v73, v75, v75
	v_sub_f32_e32 v75, v101, v107
	v_sub_f32_e32 v74, v100, v107
	v_add_f32_e32 v76, v72, v76
	v_add_f32_e32 v77, v77, v73
	v_sub_f32_e32 v73, v103, v107
	v_sub_f32_e32 v72, v102, v107
	v_pk_mul_f32 v[74:75], v[106:107], v[74:75] op_sel_hi:[0,1]
	v_pk_mul_f32 v[72:73], v[106:107], v[72:73] op_sel_hi:[0,1]
	v_mul_f32_e32 v79, v69, v69
	v_add_f32_e32 v78, v68, v69
	v_fmac_f32_e32 v79, v68, v68
	v_add_f32_e32 v78, v70, v78
	v_fmac_f32_e32 v79, v70, v70
	v_add_f32_e32 v78, v71, v78
	v_fmac_f32_e32 v79, v71, v71
	v_add_f32_e32 v76, v76, v78
	v_add_f32_e32 v77, v77, v79
	v_cvt_pk_bf16_f32 v68, v68, v69
	v_cvt_pk_bf16_f32 v69, v70, v71
	v_pk_fma_f32 v[74:75], v[208:209], v[74:75], v[212:213]
	v_pk_fma_f32 v[72:73], v[210:211], v[72:73], v[214:215]
	v_pk_fma_f32 v[64:65], v[74:75], s[24:25], v[64:65] op_sel_hi:[1,0,1]
	v_pk_fma_f32 v[66:67], v[72:73], s[24:25], v[66:67] op_sel_hi:[1,0,1]
	v_pk_add_f32 v[72:73], v[250:251], v[64:65]
	v_pk_add_f32 v[74:75], v[252:253], v[66:67]
	v_mul_f32_e32 v65, v73, v73
	v_add_f32_e32 v64, v72, v73
	v_fmac_f32_e32 v65, v72, v72
	v_add_f32_e32 v64, v74, v64
	v_fmac_f32_e32 v65, v74, v74
	v_add_f32_e32 v64, v75, v64
	v_fmac_f32_e32 v65, v75, v75
	v_add_f32_e32 v64, v76, v64
	v_add_f32_e32 v65, v77, v65
	ds_bpermute_b32 v66, v118, v64
	ds_bpermute_b32 v67, v118, v65
	global_store_dwordx4 v[82:83], v[72:75], off offset:528
	v_cvt_pk_bf16_f32 v70, v72, v73
	v_cvt_pk_bf16_f32 v71, v74, v75
	s_waitcnt lgkmcnt(0)
	v_add_f32_e32 v64, v64, v66
	v_add_f32_e32 v65, v65, v67
	ds_bpermute_b32 v66, v119, v64
	ds_bpermute_b32 v67, v119, v65
	flat_store_dwordx4 v[104:105], v[68:71] offset:256
	s_mov_b32 s100, -1
	s_mov_b32 s101, 0
	s_mov_b32 s98, 0xffff0000
	s_mov_b32 s99, 0
	s_and_saveexec_b64 s[36:37], s[100:101]
	s_cbranch_execz .LBB0_1991
	s_waitcnt lgkmcnt(0)
	v_add_f32_e32 v67, v65, v67
	v_add_f32_e32 v66, v64, v66
	v_lshl_add_u64 v[64:65], s[8:9], 0, v[80:81]
	v_cndmask_b32_e64 v66, v66, v67, s[98:99]
	v_cndmask_b32_e64 v67, 0, 4, s[98:99]
	v_or_b32_e32 v64, v64, v67
	flat_atomic_add_f32 v[64:65], v66
; DEVI unsigned pk2(float lo, float hi) { unsigned r; asm("v_cvt_pk_bf16_f32 %0, %1, %2" : "=v"(r) : "v"(lo), "v"(hi)); return r; }
;     DEVI void operator()(const f32x4 (&acc)[2][2][4][2], const pg8::Unit& u, int wr, int wc, int fr, int fq) const {
;     ...
;                 const int row = row0 + ai * 128 + m * 16; float mu, rs; row_stats(stin, row, mu, rs);
;                 float sum = 0.f, sq = 0.f;
; #pragma unroll
;                 for (int bj = 0; bj < 2; ++bj) {
;                     f32x4 z[2];
; #pragma unroll
;                     for (int n = 0; n < 2; ++n) {
;                         const int col = colb + bj * 128 + 4 * n;
;                         f32x4 xv = *(const f32x4*)(zsrc + (size_t)row * DM + col);
;                         if (stin) { const f32x4 gv = *(const f32x4*)(gin + col), bv = *(const f32x4*)(bin + col); xv = (xv - mu) * rs * gv + bv; }
;                         f32x4 zz = ALPHA * xv + acc[ai][bj][m][n];
;                         if (bias) zz += *(const f32x4*)(bias + col);
;                         *(f32x4*)(zdst + (size_t)row * DM + col) = zz;
;                         sum += zz[0] + zz[1] + zz[2] + zz[3]; sq += zz[0] * zz[0] + zz[1] * zz[1] + zz[2] * zz[2] + zz[3] * zz[3];
;                         z[n] = zz;
;                     }
;                     u32x4 o; o.x = pk2(z[0][0], z[0][1]); o.y = pk2(z[0][2], z[0][3]); o.z = pk2(z[1][0], z[1][1]); o.w = pk2(z[1][2], z[1][3]);
;                     if (zb) *(u32x4*)(zb + (size_t)row * DM + colb + bj * 128) = o;
;                 }
;                 sum += __shfl_xor(sum, 16); sq += __shfl_xor(sq, 16);
;                 sum += __shfl_xor(sum, 32); sq += __shfl_xor(sq, 32);
;                 if (fq == 0) { atomicAdd(stout + 2 * (size_t)row, sum); atomicAdd(stout + 2 * (size_t)row + 1, sq); }
.LBB0_1991:
	s_or_b64 exec, exec, s[36:37]
	v_add_u32_e32 v88, 0x80, v154
	v_ashrrev_i32_e32 v89, 31, v88
	v_lshlrev_b64 v[64:65], 3, v[88:89]
	s_waitcnt lgkmcnt(0)
	v_lshl_add_u64 v[66:67], s[6:7], 0, v[64:65]
	flat_load_dwordx2 v[90:91], v[66:67]
	v_lshlrev_b64 v[66:67], 12, v[88:89]
	v_lshl_add_u64 v[66:67], s[46:47], 0, v[66:67]
	v_lshl_add_u64 v[66:67], v[144:145], 2, v[66:67]
	global_load_dwordx4 v[68:71], v[66:67], off
	global_load_dwordx4 v[72:75], v[150:151], off
	global_load_dwordx4 v[76:79], v[152:153], off
	global_load_dwordx4 v[80:83], v[156:157], off
	global_load_dwordx4 v[84:87], v[66:67], off offset:16
	global_load_dwordx4 v[208:211], v[146:147], off
	global_load_dwordx4 v[212:215], v[148:149], off
	global_load_dwordx4 v[250:253], v[124:125], off
	s_waitcnt vmcnt(0) lgkmcnt(0)
	v_pk_mul_f32 v[90:91], v[90:91], s[22:23] op_sel:[1,0] op_sel_hi:[0,0]
	v_fma_f32 v90, -v91, v91, v90
	v_max_f32_e32 v90, 0, v90
	v_add_f32_e32 v90, 0x3727c5ac, v90
	v_mul_f32_e32 v92, 0x4b800000, v90
	v_cmp_gt_f32_e32 vcc, s72, v90
	v_sub_f32_e32 v71, v71, v91
	v_sub_f32_e32 v70, v70, v91
	v_cndmask_b32_e32 v90, v90, v92, vcc
	v_rsq_f32_e32 v90, v90
	v_sub_f32_e32 v69, v69, v91
	v_sub_f32_e32 v68, v68, v91
	v_mul_f32_e32 v92, 0x45800000, v90
	v_cndmask_b32_e32 v90, v90, v92, vcc
	v_pk_mul_f32 v[68:69], v[68:69], v[90:91] op_sel_hi:[1,0]
	v_pk_mul_f32 v[70:71], v[70:71], v[90:91] op_sel_hi:[1,0]
	v_pk_fma_f32 v[68:69], v[72:73], v[68:69], v[76:77]
	v_pk_fma_f32 v[70:71], v[74:75], v[70:71], v[78:79]
	v_pk_fma_f32 v[60:61], v[68:69], s[24:25], v[60:61] op_sel_hi:[1,0,1]
	v_pk_fma_f32 v[62:63], v[70:71], s[24:25], v[62:63] op_sel_hi:[1,0,1]
	v_pk_add_f32 v[60:61], v[80:81], v[60:61]
	v_pk_add_f32 v[62:63], v[82:83], v[62:63]
	global_store_dwordx4 v[66:67], v[60:63], off
	v_lshlrev_b64 v[80:81], 11, v[88:89]
	v_lshl_add_u64 v[80:81], s[10:11], 0, v[80:81]
	v_lshl_add_u64 v[88:89], v[144:145], 1, v[80:81]
	v_sub_f32_e32 v81, v87, v91
	v_sub_f32_e32 v80, v86, v91
	v_sub_f32_e32 v83, v85, v91
	v_sub_f32_e32 v82, v84, v91
	v_pk_mul_f32 v[82:83], v[82:83], v[90:91] op_sel_hi:[1,0]
	v_pk_mul_f32 v[84:85], v[80:81], v[90:91] op_sel_hi:[1,0]
	v_cvt_pk_bf16_f32 v80, v60, v61
	v_cvt_pk_bf16_f32 v81, v62, v63
	v_pk_fma_f32 v[68:69], v[208:209], v[82:83], v[212:213]
	v_pk_fma_f32 v[70:71], v[210:211], v[84:85], v[214:215]
	v_pk_fma_f32 v[56:57], v[68:69], s[24:25], v[56:57] op_sel_hi:[1,0,1]
	v_pk_fma_f32 v[58:59], v[70:71], s[24:25], v[58:59] op_sel_hi:[1,0,1]
	v_pk_add_f32 v[56:57], v[250:251], v[56:57]
	v_pk_add_f32 v[58:59], v[252:253], v[58:59]
	global_store_dwordx4 v[66:67], v[56:59], off offset:16
	v_cvt_pk_bf16_f32 v82, v56, v57
	v_cvt_pk_bf16_f32 v83, v58, v59
	flat_store_dwordx4 v[88:89], v[80:83]
	global_load_dwordx4 v[68:71], v[66:67], off offset:512
	global_load_dwordx4 v[72:75], v[126:127], off
	global_load_dwordx4 v[76:79], v[158:159], off
	s_nop 0
	global_load_dwordx4 v[80:83], v[160:161], off
	global_load_dwordx4 v[84:87], v[66:67], off offset:528
	global_load_dwordx4 v[208:211], v[120:121], off
	global_load_dwordx4 v[212:215], v[122:123], off
	global_load_dwordx4 v[250:253], v[116:117], off
	s_waitcnt vmcnt(0)
	v_sub_f32_e32 v71, v71, v91
	v_sub_f32_e32 v70, v70, v91
	v_sub_f32_e32 v69, v69, v91
	v_sub_f32_e32 v68, v68, v91
	v_pk_mul_f32 v[68:69], v[90:91], v[68:69] op_sel_hi:[0,1]
	v_pk_mul_f32 v[70:71], v[90:91], v[70:71] op_sel_hi:[0,1]
	v_pk_fma_f32 v[70:71], v[74:75], v[70:71], v[78:79]
	v_pk_fma_f32 v[68:69], v[72:73], v[68:69], v[76:77]
	v_pk_fma_f32 v[54:55], v[70:71], s[24:25], v[54:55] op_sel_hi:[1,0,1]
	v_pk_fma_f32 v[52:53], v[68:69], s[24:25], v[52:53] op_sel_hi:[1,0,1]
	v_pk_add_f32 v[54:55], v[82:83], v[54:55]
	v_pk_add_f32 v[52:53], v[80:81], v[52:53]
	global_store_dwordx4 v[66:67], v[52:55], off offset:512
	v_add_f32_e32 v80, v60, v61
	v_mul_f32_e32 v61, v61, v61
	v_fmac_f32_e32 v61, v60, v60
	v_add_f32_e32 v80, v62, v80
	v_fmac_f32_e32 v61, v62, v62
	v_add_f32_e32 v62, v56, v57
	v_mul_f32_e32 v57, v57, v57
	v_fmac_f32_e32 v57, v56, v56
	v_add_f32_e32 v60, v63, v80
	v_add_f32_e32 v62, v58, v62
	v_fmac_f32_e32 v57, v58, v58
	v_add_f32_e32 v60, 0, v60
	v_fmac_f32_e32 v61, v63, v63
	v_add_f32_e32 v56, v59, v62
	v_fmac_f32_e32 v57, v59, v59
	v_sub_f32_e32 v59, v85, v91
	v_sub_f32_e32 v58, v84, v91
	v_add_f32_e32 v60, v56, v60
	v_add_f32_e32 v61, v61, v57
	v_sub_f32_e32 v57, v87, v91
	v_sub_f32_e32 v56, v86, v91
	v_pk_mul_f32 v[58:59], v[90:91], v[58:59] op_sel_hi:[0,1]
	v_pk_mul_f32 v[56:57], v[90:91], v[56:57] op_sel_hi:[0,1]
	v_mul_f32_e32 v63, v53, v53
	v_add_f32_e32 v62, v52, v53
	v_fmac_f32_e32 v63, v52, v52
	v_add_f32_e32 v62, v54, v62
	v_fmac_f32_e32 v63, v54, v54
	v_add_f32_e32 v62, v55, v62
	v_fmac_f32_e32 v63, v55, v55
	v_add_f32_e32 v60, v60, v62
	v_add_f32_e32 v61, v61, v63
	v_cvt_pk_bf16_f32 v52, v52, v53
	v_cvt_pk_bf16_f32 v53, v54, v55
	v_pk_fma_f32 v[58:59], v[208:209], v[58:59], v[212:213]
	v_pk_fma_f32 v[56:57], v[210:211], v[56:57], v[214:215]
	v_pk_fma_f32 v[48:49], v[58:59], s[24:25], v[48:49] op_sel_hi:[1,0,1]
	v_pk_fma_f32 v[50:51], v[56:57], s[24:25], v[50:51] op_sel_hi:[1,0,1]
	v_pk_add_f32 v[56:57], v[250:251], v[48:49]
	v_pk_add_f32 v[58:59], v[252:253], v[50:51]
	v_mul_f32_e32 v49, v57, v57
	v_add_f32_e32 v48, v56, v57
	v_fmac_f32_e32 v49, v56, v56
	v_add_f32_e32 v48, v58, v48
	v_fmac_f32_e32 v49, v58, v58
	v_add_f32_e32 v48, v59, v48
	v_fmac_f32_e32 v49, v59, v59
	v_add_f32_e32 v48, v60, v48
	v_add_f32_e32 v49, v61, v49
	ds_bpermute_b32 v50, v118, v48
	ds_bpermute_b32 v51, v118, v49
	global_store_dwordx4 v[66:67], v[56:59], off offset:528
	v_cvt_pk_bf16_f32 v54, v56, v57
	v_cvt_pk_bf16_f32 v55, v58, v59
	s_waitcnt lgkmcnt(0)
	v_add_f32_e32 v48, v48, v50
	v_add_f32_e32 v49, v49, v51
	ds_bpermute_b32 v50, v119, v48
	ds_bpermute_b32 v51, v119, v49
	flat_store_dwordx4 v[88:89], v[52:55] offset:256
	s_mov_b32 s100, -1
	s_mov_b32 s101, 0
	s_mov_b32 s98, 0xffff0000
	s_mov_b32 s99, 0
	s_and_saveexec_b64 s[36:37], s[100:101]
	s_cbranch_execz .LBB0_1993
	s_waitcnt lgkmcnt(0)
	v_add_f32_e32 v51, v49, v51
	v_add_f32_e32 v50, v48, v50
	v_lshl_add_u64 v[48:49], s[8:9], 0, v[64:65]
	v_cndmask_b32_e64 v50, v50, v51, s[98:99]
	v_cndmask_b32_e64 v51, 0, 4, s[98:99]
	v_or_b32_e32 v48, v48, v51
	flat_atomic_add_f32 v[48:49], v50
; DEVI unsigned pk2(float lo, float hi) { unsigned r; asm("v_cvt_pk_bf16_f32 %0, %1, %2" : "=v"(r) : "v"(lo), "v"(hi)); return r; }
;     DEVI void operator()(const f32x4 (&acc)[2][2][4][2], const pg8::Unit& u, int wr, int wc, int fr, int fq) const {
;     ...
;                 const int row = row0 + ai * 128 + m * 16; float mu, rs; row_stats(stin, row, mu, rs);
;                 float sum = 0.f, sq = 0.f;
; #pragma unroll
;                 for (int bj = 0; bj < 2; ++bj) {
;                     f32x4 z[2];
; #pragma unroll
;                     for (int n = 0; n < 2; ++n) {
;                         const int col = colb + bj * 128 + 4 * n;
;                         f32x4 xv = *(const f32x4*)(zsrc + (size_t)row * DM + col);
;                         if (stin) { const f32x4 gv = *(const f32x4*)(gin + col), bv = *(const f32x4*)(bin + col); xv = (xv - mu) * rs * gv + bv; }
;                         f32x4 zz = ALPHA * xv + acc[ai][bj][m][n];
;                         if (bias) zz += *(const f32x4*)(bias + col);
;                         *(f32x4*)(zdst + (size_t)row * DM + col) = zz;
;                         sum += zz[0] + zz[1] + zz[2] + zz[3]; sq += zz[0] * zz[0] + zz[1] * zz[1] + zz[2] * zz[2] + zz[3] * zz[3];
;                         z[n] = zz;
;                     }
;                     u32x4 o; o.x = pk2(z[0][0], z[0][1]); o.y = pk2(z[0][2], z[0][3]); o.z = pk2(z[1][0], z[1][1]); o.w = pk2(z[1][2], z[1][3]);
;                     if (zb) *(u32x4*)(zb + (size_t)row * DM + colb + bj * 128) = o;
;                 }
;                 sum += __shfl_xor(sum, 16); sq += __shfl_xor(sq, 16);
;                 sum += __shfl_xor(sum, 32); sq += __shfl_xor(sq, 32);
;                 if (fq == 0) { atomicAdd(stout + 2 * (size_t)row, sum); atomicAdd(stout + 2 * (size_t)row + 1, sq); }
.LBB0_1993:
	s_or_b64 exec, exec, s[36:37]
	v_add_u32_e32 v72, 0x90, v154
	v_ashrrev_i32_e32 v73, 31, v72
	v_lshlrev_b64 v[48:49], 3, v[72:73]
	s_waitcnt lgkmcnt(0)
	v_lshl_add_u64 v[50:51], s[6:7], 0, v[48:49]
	flat_load_dwordx2 v[74:75], v[50:51]
	v_lshlrev_b64 v[50:51], 12, v[72:73]
	v_lshl_add_u64 v[50:51], s[46:47], 0, v[50:51]
	v_lshl_add_u64 v[50:51], v[144:145], 2, v[50:51]
	global_load_dwordx4 v[52:55], v[50:51], off
	global_load_dwordx4 v[56:59], v[150:151], off
	global_load_dwordx4 v[60:63], v[152:153], off
	global_load_dwordx4 v[64:67], v[156:157], off
	global_load_dwordx4 v[68:71], v[50:51], off offset:16
	global_load_dwordx4 v[208:211], v[146:147], off
	global_load_dwordx4 v[212:215], v[148:149], off
	global_load_dwordx4 v[250:253], v[124:125], off
	s_waitcnt vmcnt(0) lgkmcnt(0)
	v_pk_mul_f32 v[74:75], v[74:75], s[22:23] op_sel:[1,0] op_sel_hi:[0,0]
	v_fma_f32 v74, -v75, v75, v74
	v_max_f32_e32 v74, 0, v74
	v_add_f32_e32 v74, 0x3727c5ac, v74
	v_mul_f32_e32 v76, 0x4b800000, v74
	v_cmp_gt_f32_e32 vcc, s72, v74
	v_sub_f32_e32 v55, v55, v75
	v_sub_f32_e32 v54, v54, v75
	v_cndmask_b32_e32 v74, v74, v76, vcc
	v_rsq_f32_e32 v74, v74
	v_sub_f32_e32 v53, v53, v75
	v_sub_f32_e32 v52, v52, v75
	v_mul_f32_e32 v76, 0x45800000, v74
	v_cndmask_b32_e32 v74, v74, v76, vcc
	v_pk_mul_f32 v[52:53], v[52:53], v[74:75] op_sel_hi:[1,0]
	v_pk_mul_f32 v[54:55], v[54:55], v[74:75] op_sel_hi:[1,0]
	v_pk_fma_f32 v[52:53], v[56:57], v[52:53], v[60:61]
	v_pk_fma_f32 v[54:55], v[58:59], v[54:55], v[62:63]
	v_pk_fma_f32 v[44:45], v[52:53], s[24:25], v[44:45] op_sel_hi:[1,0,1]
	v_pk_fma_f32 v[46:47], v[54:55], s[24:25], v[46:47] op_sel_hi:[1,0,1]
	v_pk_add_f32 v[44:45], v[64:65], v[44:45]
	v_pk_add_f32 v[46:47], v[66:67], v[46:47]
	global_store_dwordx4 v[50:51], v[44:47], off
	v_lshlrev_b64 v[64:65], 11, v[72:73]
	v_lshl_add_u64 v[64:65], s[10:11], 0, v[64:65]
	v_lshl_add_u64 v[72:73], v[144:145], 1, v[64:65]
	v_sub_f32_e32 v65, v71, v75
	v_sub_f32_e32 v64, v70, v75
	v_sub_f32_e32 v67, v69, v75
	v_sub_f32_e32 v66, v68, v75
	v_pk_mul_f32 v[66:67], v[66:67], v[74:75] op_sel_hi:[1,0]
	v_pk_mul_f32 v[68:69], v[64:65], v[74:75] op_sel_hi:[1,0]
	v_cvt_pk_bf16_f32 v64, v44, v45
	v_cvt_pk_bf16_f32 v65, v46, v47
	v_pk_fma_f32 v[52:53], v[208:209], v[66:67], v[212:213]
	v_pk_fma_f32 v[54:55], v[210:211], v[68:69], v[214:215]
	v_pk_fma_f32 v[40:41], v[52:53], s[24:25], v[40:41] op_sel_hi:[1,0,1]
	v_pk_fma_f32 v[42:43], v[54:55], s[24:25], v[42:43] op_sel_hi:[1,0,1]
	v_pk_add_f32 v[40:41], v[250:251], v[40:41]
	v_pk_add_f32 v[42:43], v[252:253], v[42:43]
	global_store_dwordx4 v[50:51], v[40:43], off offset:16
	v_cvt_pk_bf16_f32 v66, v40, v41
	v_cvt_pk_bf16_f32 v67, v42, v43
	flat_store_dwordx4 v[72:73], v[64:67]
	global_load_dwordx4 v[52:55], v[50:51], off offset:512
	global_load_dwordx4 v[56:59], v[126:127], off
	global_load_dwordx4 v[60:63], v[158:159], off
	s_nop 0
	global_load_dwordx4 v[64:67], v[160:161], off
	global_load_dwordx4 v[68:71], v[50:51], off offset:528
	global_load_dwordx4 v[208:211], v[120:121], off
	global_load_dwordx4 v[212:215], v[122:123], off
	global_load_dwordx4 v[250:253], v[116:117], off
	s_waitcnt vmcnt(0)
	v_sub_f32_e32 v55, v55, v75
	v_sub_f32_e32 v54, v54, v75
	v_sub_f32_e32 v53, v53, v75
	v_sub_f32_e32 v52, v52, v75
	v_pk_mul_f32 v[52:53], v[74:75], v[52:53] op_sel_hi:[0,1]
	v_pk_mul_f32 v[54:55], v[74:75], v[54:55] op_sel_hi:[0,1]
	v_pk_fma_f32 v[54:55], v[58:59], v[54:55], v[62:63]
	v_pk_fma_f32 v[52:53], v[56:57], v[52:53], v[60:61]
	v_pk_fma_f32 v[38:39], v[54:55], s[24:25], v[38:39] op_sel_hi:[1,0,1]
	v_pk_fma_f32 v[36:37], v[52:53], s[24:25], v[36:37] op_sel_hi:[1,0,1]
	v_pk_add_f32 v[38:39], v[66:67], v[38:39]
	v_pk_add_f32 v[36:37], v[64:65], v[36:37]
	global_store_dwordx4 v[50:51], v[36:39], off offset:512
	v_add_f32_e32 v64, v44, v45
	v_mul_f32_e32 v45, v45, v45
	v_fmac_f32_e32 v45, v44, v44
	v_add_f32_e32 v64, v46, v64
	v_fmac_f32_e32 v45, v46, v46
	v_add_f32_e32 v46, v40, v41
	v_mul_f32_e32 v41, v41, v41
	v_fmac_f32_e32 v41, v40, v40
	v_add_f32_e32 v44, v47, v64
	v_add_f32_e32 v46, v42, v46
	v_fmac_f32_e32 v41, v42, v42
	v_add_f32_e32 v44, 0, v44
	v_fmac_f32_e32 v45, v47, v47
	v_add_f32_e32 v40, v43, v46
	v_fmac_f32_e32 v41, v43, v43
	v_sub_f32_e32 v43, v69, v75
	v_sub_f32_e32 v42, v68, v75
	v_add_f32_e32 v44, v40, v44
	v_add_f32_e32 v45, v45, v41
	v_sub_f32_e32 v41, v71, v75
	v_sub_f32_e32 v40, v70, v75
	v_pk_mul_f32 v[42:43], v[74:75], v[42:43] op_sel_hi:[0,1]
	v_pk_mul_f32 v[40:41], v[74:75], v[40:41] op_sel_hi:[0,1]
	v_mul_f32_e32 v47, v37, v37
	v_add_f32_e32 v46, v36, v37
	v_fmac_f32_e32 v47, v36, v36
	v_add_f32_e32 v46, v38, v46
	v_fmac_f32_e32 v47, v38, v38
	v_add_f32_e32 v46, v39, v46
	v_fmac_f32_e32 v47, v39, v39
	v_add_f32_e32 v44, v44, v46
	v_add_f32_e32 v45, v45, v47
	v_cvt_pk_bf16_f32 v36, v36, v37
	v_cvt_pk_bf16_f32 v37, v38, v39
	v_pk_fma_f32 v[42:43], v[208:209], v[42:43], v[212:213]
	v_pk_fma_f32 v[40:41], v[210:211], v[40:41], v[214:215]
	v_pk_fma_f32 v[32:33], v[42:43], s[24:25], v[32:33] op_sel_hi:[1,0,1]
	v_pk_fma_f32 v[34:35], v[40:41], s[24:25], v[34:35] op_sel_hi:[1,0,1]
	v_pk_add_f32 v[40:41], v[250:251], v[32:33]
	v_pk_add_f32 v[42:43], v[252:253], v[34:35]
	v_mul_f32_e32 v33, v41, v41
	v_add_f32_e32 v32, v40, v41
	v_fmac_f32_e32 v33, v40, v40
	v_add_f32_e32 v32, v42, v32
	v_fmac_f32_e32 v33, v42, v42
	v_add_f32_e32 v32, v43, v32
	v_fmac_f32_e32 v33, v43, v43
	v_add_f32_e32 v32, v44, v32
	v_add_f32_e32 v33, v45, v33
	ds_bpermute_b32 v34, v118, v32
	ds_bpermute_b32 v35, v118, v33
	global_store_dwordx4 v[50:51], v[40:43], off offset:528
	v_cvt_pk_bf16_f32 v38, v40, v41
	v_cvt_pk_bf16_f32 v39, v42, v43
	s_waitcnt lgkmcnt(0)
	v_add_f32_e32 v32, v32, v34
	v_add_f32_e32 v33, v33, v35
	ds_bpermute_b32 v34, v119, v32
	ds_bpermute_b32 v35, v119, v33
	flat_store_dwordx4 v[72:73], v[36:39] offset:256
	s_mov_b32 s100, -1
	s_mov_b32 s101, 0
	s_mov_b32 s98, 0xffff0000
	s_mov_b32 s99, 0
	s_and_saveexec_b64 s[36:37], s[100:101]
	s_cbranch_execz .LBB0_1995
	s_waitcnt lgkmcnt(0)
	v_add_f32_e32 v35, v33, v35
	v_add_f32_e32 v34, v32, v34
	v_lshl_add_u64 v[32:33], s[8:9], 0, v[48:49]
	v_cndmask_b32_e64 v34, v34, v35, s[98:99]
	v_cndmask_b32_e64 v35, 0, 4, s[98:99]
	v_or_b32_e32 v32, v32, v35
	flat_atomic_add_f32 v[32:33], v34
; DEVI unsigned pk2(float lo, float hi) { unsigned r; asm("v_cvt_pk_bf16_f32 %0, %1, %2" : "=v"(r) : "v"(lo), "v"(hi)); return r; }
;     DEVI void operator()(const f32x4 (&acc)[2][2][4][2], const pg8::Unit& u, int wr, int wc, int fr, int fq) const {
;     ...
;                 const int row = row0 + ai * 128 + m * 16; float mu, rs; row_stats(stin, row, mu, rs);
;                 float sum = 0.f, sq = 0.f;
; #pragma unroll
;                 for (int bj = 0; bj < 2; ++bj) {
;                     f32x4 z[2];
; #pragma unroll
;                     for (int n = 0; n < 2; ++n) {
;                         const int col = colb + bj * 128 + 4 * n;
;                         f32x4 xv = *(const f32x4*)(zsrc + (size_t)row * DM + col);
;                         if (stin) { const f32x4 gv = *(const f32x4*)(gin + col), bv = *(const f32x4*)(bin + col); xv = (xv - mu) * rs * gv + bv; }
;                         f32x4 zz = ALPHA * xv + acc[ai][bj][m][n];
;                         if (bias) zz += *(const f32x4*)(bias + col);
;                         *(f32x4*)(zdst + (size_t)row * DM + col) = zz;
;                         sum += zz[0] + zz[1] + zz[2] + zz[3]; sq += zz[0] * zz[0] + zz[1] * zz[1] + zz[2] * zz[2] + zz[3] * zz[3];
;                         z[n] = zz;
;                     }
;                     u32x4 o; o.x = pk2(z[0][0], z[0][1]); o.y = pk2(z[0][2], z[0][3]); o.z = pk2(z[1][0], z[1][1]); o.w = pk2(z[1][2], z[1][3]);
;                     if (zb) *(u32x4*)(zb + (size_t)row * DM + colb + bj * 128) = o;
;                 }
;                 sum += __shfl_xor(sum, 16); sq += __shfl_xor(sq, 16);
;                 sum += __shfl_xor(sum, 32); sq += __shfl_xor(sq, 32);
;                 if (fq == 0) { atomicAdd(stout + 2 * (size_t)row, sum); atomicAdd(stout + 2 * (size_t)row + 1, sq); }
.LBB0_1995:
	s_or_b64 exec, exec, s[36:37]
	v_add_u32_e32 v56, 0xa0, v154
	v_ashrrev_i32_e32 v57, 31, v56
	v_lshlrev_b64 v[32:33], 3, v[56:57]
	s_waitcnt lgkmcnt(0)
	v_lshl_add_u64 v[34:35], s[6:7], 0, v[32:33]
	flat_load_dwordx2 v[58:59], v[34:35]
	v_lshlrev_b64 v[34:35], 12, v[56:57]
	v_lshl_add_u64 v[34:35], s[46:47], 0, v[34:35]
	v_lshl_add_u64 v[34:35], v[144:145], 2, v[34:35]
	global_load_dwordx4 v[36:39], v[34:35], off
	global_load_dwordx4 v[40:43], v[150:151], off
	global_load_dwordx4 v[44:47], v[152:153], off
	global_load_dwordx4 v[48:51], v[156:157], off
	global_load_dwordx4 v[52:55], v[34:35], off offset:16
	global_load_dwordx4 v[208:211], v[146:147], off
	global_load_dwordx4 v[212:215], v[148:149], off
	global_load_dwordx4 v[250:253], v[124:125], off
	s_waitcnt vmcnt(0) lgkmcnt(0)
	v_pk_mul_f32 v[58:59], v[58:59], s[22:23] op_sel:[1,0] op_sel_hi:[0,0]
	v_fma_f32 v58, -v59, v59, v58
	v_max_f32_e32 v58, 0, v58
	v_add_f32_e32 v58, 0x3727c5ac, v58
	v_mul_f32_e32 v60, 0x4b800000, v58
	v_cmp_gt_f32_e32 vcc, s72, v58
	v_sub_f32_e32 v39, v39, v59
	v_sub_f32_e32 v38, v38, v59
	v_cndmask_b32_e32 v58, v58, v60, vcc
	v_rsq_f32_e32 v58, v58
	v_sub_f32_e32 v37, v37, v59
	v_sub_f32_e32 v36, v36, v59
	v_mul_f32_e32 v60, 0x45800000, v58
	v_cndmask_b32_e32 v58, v58, v60, vcc
	v_pk_mul_f32 v[36:37], v[36:37], v[58:59] op_sel_hi:[1,0]
	v_pk_mul_f32 v[38:39], v[38:39], v[58:59] op_sel_hi:[1,0]
	v_pk_fma_f32 v[36:37], v[40:41], v[36:37], v[44:45]
	v_pk_fma_f32 v[38:39], v[42:43], v[38:39], v[46:47]
	v_pk_fma_f32 v[28:29], v[36:37], s[24:25], v[28:29] op_sel_hi:[1,0,1]
	v_pk_fma_f32 v[30:31], v[38:39], s[24:25], v[30:31] op_sel_hi:[1,0,1]
	v_pk_add_f32 v[28:29], v[48:49], v[28:29]
	v_pk_add_f32 v[30:31], v[50:51], v[30:31]
	global_store_dwordx4 v[34:35], v[28:31], off
	v_lshlrev_b64 v[48:49], 11, v[56:57]
	v_lshl_add_u64 v[48:49], s[10:11], 0, v[48:49]
	v_lshl_add_u64 v[56:57], v[144:145], 1, v[48:49]
	v_sub_f32_e32 v49, v55, v59
	v_sub_f32_e32 v48, v54, v59
	v_sub_f32_e32 v51, v53, v59
	v_sub_f32_e32 v50, v52, v59
	v_pk_mul_f32 v[50:51], v[50:51], v[58:59] op_sel_hi:[1,0]
	v_pk_mul_f32 v[52:53], v[48:49], v[58:59] op_sel_hi:[1,0]
	v_cvt_pk_bf16_f32 v48, v28, v29
	v_cvt_pk_bf16_f32 v49, v30, v31
	v_pk_fma_f32 v[36:37], v[208:209], v[50:51], v[212:213]
	v_pk_fma_f32 v[38:39], v[210:211], v[52:53], v[214:215]
	v_pk_fma_f32 v[24:25], v[36:37], s[24:25], v[24:25] op_sel_hi:[1,0,1]
	v_pk_fma_f32 v[26:27], v[38:39], s[24:25], v[26:27] op_sel_hi:[1,0,1]
	v_pk_add_f32 v[24:25], v[250:251], v[24:25]
	v_pk_add_f32 v[26:27], v[252:253], v[26:27]
	global_store_dwordx4 v[34:35], v[24:27], off offset:16
	v_cvt_pk_bf16_f32 v50, v24, v25
	v_cvt_pk_bf16_f32 v51, v26, v27
	flat_store_dwordx4 v[56:57], v[48:51]
	global_load_dwordx4 v[36:39], v[34:35], off offset:512
	global_load_dwordx4 v[40:43], v[126:127], off
	global_load_dwordx4 v[44:47], v[158:159], off
	s_nop 0
	global_load_dwordx4 v[48:51], v[160:161], off
	global_load_dwordx4 v[52:55], v[34:35], off offset:528
	global_load_dwordx4 v[208:211], v[120:121], off
	global_load_dwordx4 v[212:215], v[122:123], off
	global_load_dwordx4 v[250:253], v[116:117], off
	s_waitcnt vmcnt(0)
	v_sub_f32_e32 v39, v39, v59
	v_sub_f32_e32 v38, v38, v59
	v_sub_f32_e32 v37, v37, v59
	v_sub_f32_e32 v36, v36, v59
	v_pk_mul_f32 v[36:37], v[58:59], v[36:37] op_sel_hi:[0,1]
	v_pk_mul_f32 v[38:39], v[58:59], v[38:39] op_sel_hi:[0,1]
	v_pk_fma_f32 v[38:39], v[42:43], v[38:39], v[46:47]
	v_pk_fma_f32 v[36:37], v[40:41], v[36:37], v[44:45]
	v_pk_fma_f32 v[22:23], v[38:39], s[24:25], v[22:23] op_sel_hi:[1,0,1]
	v_pk_fma_f32 v[20:21], v[36:37], s[24:25], v[20:21] op_sel_hi:[1,0,1]
	v_pk_add_f32 v[22:23], v[50:51], v[22:23]
	v_pk_add_f32 v[20:21], v[48:49], v[20:21]
	global_store_dwordx4 v[34:35], v[20:23], off offset:512
	v_add_f32_e32 v48, v28, v29
	v_mul_f32_e32 v29, v29, v29
	v_fmac_f32_e32 v29, v28, v28
	v_add_f32_e32 v48, v30, v48
	v_fmac_f32_e32 v29, v30, v30
	v_add_f32_e32 v30, v24, v25
	v_mul_f32_e32 v25, v25, v25
	v_fmac_f32_e32 v25, v24, v24
	v_add_f32_e32 v28, v31, v48
	v_add_f32_e32 v30, v26, v30
	v_fmac_f32_e32 v25, v26, v26
	v_add_f32_e32 v28, 0, v28
	v_fmac_f32_e32 v29, v31, v31
	v_add_f32_e32 v24, v27, v30
	v_fmac_f32_e32 v25, v27, v27
	v_sub_f32_e32 v27, v53, v59
	v_sub_f32_e32 v26, v52, v59
	v_add_f32_e32 v28, v24, v28
	v_add_f32_e32 v29, v29, v25
	v_sub_f32_e32 v25, v55, v59
	v_sub_f32_e32 v24, v54, v59
	v_pk_mul_f32 v[26:27], v[58:59], v[26:27] op_sel_hi:[0,1]
	v_pk_mul_f32 v[24:25], v[58:59], v[24:25] op_sel_hi:[0,1]
	v_mul_f32_e32 v31, v21, v21
	v_add_f32_e32 v30, v20, v21
	v_fmac_f32_e32 v31, v20, v20
	v_add_f32_e32 v30, v22, v30
	v_fmac_f32_e32 v31, v22, v22
	v_add_f32_e32 v30, v23, v30
	v_fmac_f32_e32 v31, v23, v23
	v_add_f32_e32 v28, v28, v30
	v_add_f32_e32 v29, v29, v31
	v_cvt_pk_bf16_f32 v20, v20, v21
	v_cvt_pk_bf16_f32 v21, v22, v23
	v_pk_fma_f32 v[26:27], v[208:209], v[26:27], v[212:213]
	v_pk_fma_f32 v[24:25], v[210:211], v[24:25], v[214:215]
	v_pk_fma_f32 v[16:17], v[26:27], s[24:25], v[16:17] op_sel_hi:[1,0,1]
	v_pk_fma_f32 v[18:19], v[24:25], s[24:25], v[18:19] op_sel_hi:[1,0,1]
	v_pk_add_f32 v[24:25], v[250:251], v[16:17]
	v_pk_add_f32 v[26:27], v[252:253], v[18:19]
	v_mul_f32_e32 v17, v25, v25
	v_add_f32_e32 v16, v24, v25
	v_fmac_f32_e32 v17, v24, v24
	v_add_f32_e32 v16, v26, v16
	v_fmac_f32_e32 v17, v26, v26
	v_add_f32_e32 v16, v27, v16
	v_fmac_f32_e32 v17, v27, v27
	v_add_f32_e32 v16, v28, v16
	v_add_f32_e32 v17, v29, v17
	ds_bpermute_b32 v18, v118, v16
	ds_bpermute_b32 v19, v118, v17
	global_store_dwordx4 v[34:35], v[24:27], off offset:528
	v_cvt_pk_bf16_f32 v22, v24, v25
	v_cvt_pk_bf16_f32 v23, v26, v27
	s_waitcnt lgkmcnt(0)
	v_add_f32_e32 v16, v16, v18
	v_add_f32_e32 v17, v17, v19
	ds_bpermute_b32 v18, v119, v16
	ds_bpermute_b32 v19, v119, v17
	flat_store_dwordx4 v[56:57], v[20:23] offset:256
	s_mov_b32 s100, -1
	s_mov_b32 s101, 0
	s_mov_b32 s98, 0xffff0000
	s_mov_b32 s99, 0
	s_and_saveexec_b64 s[36:37], s[100:101]
	s_cbranch_execz .LBB0_1997
	s_waitcnt lgkmcnt(0)
	v_add_f32_e32 v19, v17, v19
	v_add_f32_e32 v18, v16, v18
	v_lshl_add_u64 v[16:17], s[8:9], 0, v[32:33]
	v_cndmask_b32_e64 v18, v18, v19, s[98:99]
	v_cndmask_b32_e64 v19, 0, 4, s[98:99]
	v_or_b32_e32 v16, v16, v19
	flat_atomic_add_f32 v[16:17], v18
; DEVI unsigned pk2(float lo, float hi) { unsigned r; asm("v_cvt_pk_bf16_f32 %0, %1, %2" : "=v"(r) : "v"(lo), "v"(hi)); return r; }
;     DEVI void operator()(const f32x4 (&acc)[2][2][4][2], const pg8::Unit& u, int wr, int wc, int fr, int fq) const {
;     ...
;                 const int row = row0 + ai * 128 + m * 16; float mu, rs; row_stats(stin, row, mu, rs);
;                 float sum = 0.f, sq = 0.f;
; #pragma unroll
;                 for (int bj = 0; bj < 2; ++bj) {
;                     f32x4 z[2];
; #pragma unroll
;                     for (int n = 0; n < 2; ++n) {
;                         const int col = colb + bj * 128 + 4 * n;
;                         f32x4 xv = *(const f32x4*)(zsrc + (size_t)row * DM + col);
;                         if (stin) { const f32x4 gv = *(const f32x4*)(gin + col), bv = *(const f32x4*)(bin + col); xv = (xv - mu) * rs * gv + bv; }
;                         f32x4 zz = ALPHA * xv + acc[ai][bj][m][n];
;                         if (bias) zz += *(const f32x4*)(bias + col);
;                         *(f32x4*)(zdst + (size_t)row * DM + col) = zz;
;                         sum += zz[0] + zz[1] + zz[2] + zz[3]; sq += zz[0] * zz[0] + zz[1] * zz[1] + zz[2] * zz[2] + zz[3] * zz[3];
;                         z[n] = zz;
;                     }
;                     u32x4 o; o.x = pk2(z[0][0], z[0][1]); o.y = pk2(z[0][2], z[0][3]); o.z = pk2(z[1][0], z[1][1]); o.w = pk2(z[1][2], z[1][3]);
;                     if (zb) *(u32x4*)(zb + (size_t)row * DM + colb + bj * 128) = o;
;                 }
;                 sum += __shfl_xor(sum, 16); sq += __shfl_xor(sq, 16);
;                 sum += __shfl_xor(sum, 32); sq += __shfl_xor(sq, 32);
;                 if (fq == 0) { atomicAdd(stout + 2 * (size_t)row, sum); atomicAdd(stout + 2 * (size_t)row + 1, sq); }
.LBB0_1997:
	s_or_b64 exec, exec, s[36:37]
	v_add_u32_e32 v40, 0xb0, v154
	v_ashrrev_i32_e32 v41, 31, v40
	v_lshlrev_b64 v[16:17], 3, v[40:41]
	s_waitcnt lgkmcnt(0)
	v_lshl_add_u64 v[18:19], s[6:7], 0, v[16:17]
	flat_load_dwordx2 v[42:43], v[18:19]
	v_lshlrev_b64 v[18:19], 12, v[40:41]
	v_lshl_add_u64 v[18:19], s[46:47], 0, v[18:19]
	v_lshl_add_u64 v[18:19], v[144:145], 2, v[18:19]
	global_load_dwordx4 v[20:23], v[18:19], off
	global_load_dwordx4 v[24:27], v[150:151], off
	global_load_dwordx4 v[28:31], v[152:153], off
	global_load_dwordx4 v[32:35], v[156:157], off
	global_load_dwordx4 v[36:39], v[18:19], off offset:16
	global_load_dwordx4 v[208:211], v[146:147], off
	global_load_dwordx4 v[212:215], v[148:149], off
	global_load_dwordx4 v[250:253], v[124:125], off
	s_waitcnt vmcnt(0) lgkmcnt(0)
	v_pk_mul_f32 v[42:43], v[42:43], s[22:23] op_sel:[1,0] op_sel_hi:[0,0]
	v_fma_f32 v42, -v43, v43, v42
	v_max_f32_e32 v42, 0, v42
	v_add_f32_e32 v42, 0x3727c5ac, v42
	v_mul_f32_e32 v44, 0x4b800000, v42
	v_cmp_gt_f32_e32 vcc, s72, v42
	v_sub_f32_e32 v23, v23, v43
	v_sub_f32_e32 v22, v22, v43
	v_cndmask_b32_e32 v42, v42, v44, vcc
	v_rsq_f32_e32 v42, v42
	v_sub_f32_e32 v21, v21, v43
	v_sub_f32_e32 v20, v20, v43
	v_mul_f32_e32 v44, 0x45800000, v42
	v_cndmask_b32_e32 v42, v42, v44, vcc
	v_pk_mul_f32 v[20:21], v[20:21], v[42:43] op_sel_hi:[1,0]
	v_pk_mul_f32 v[22:23], v[22:23], v[42:43] op_sel_hi:[1,0]
	v_pk_fma_f32 v[20:21], v[24:25], v[20:21], v[28:29]
	v_pk_fma_f32 v[22:23], v[26:27], v[22:23], v[30:31]
	v_pk_fma_f32 v[12:13], v[20:21], s[24:25], v[12:13] op_sel_hi:[1,0,1]
	v_pk_fma_f32 v[14:15], v[22:23], s[24:25], v[14:15] op_sel_hi:[1,0,1]
	v_pk_add_f32 v[12:13], v[32:33], v[12:13]
	v_pk_add_f32 v[14:15], v[34:35], v[14:15]
	global_store_dwordx4 v[18:19], v[12:15], off
	v_lshlrev_b64 v[32:33], 11, v[40:41]
	v_lshl_add_u64 v[32:33], s[10:11], 0, v[32:33]
	v_lshl_add_u64 v[40:41], v[144:145], 1, v[32:33]
	v_sub_f32_e32 v33, v39, v43
	v_sub_f32_e32 v32, v38, v43
	v_sub_f32_e32 v35, v37, v43
	v_sub_f32_e32 v34, v36, v43
	v_pk_mul_f32 v[34:35], v[34:35], v[42:43] op_sel_hi:[1,0]
	v_pk_mul_f32 v[36:37], v[32:33], v[42:43] op_sel_hi:[1,0]
	v_cvt_pk_bf16_f32 v32, v12, v13
	v_cvt_pk_bf16_f32 v33, v14, v15
	v_pk_fma_f32 v[20:21], v[208:209], v[34:35], v[212:213]
	v_pk_fma_f32 v[22:23], v[210:211], v[36:37], v[214:215]
	v_pk_fma_f32 v[8:9], v[20:21], s[24:25], v[8:9] op_sel_hi:[1,0,1]
	v_pk_fma_f32 v[10:11], v[22:23], s[24:25], v[10:11] op_sel_hi:[1,0,1]
	v_pk_add_f32 v[8:9], v[250:251], v[8:9]
	v_pk_add_f32 v[10:11], v[252:253], v[10:11]
	global_store_dwordx4 v[18:19], v[8:11], off offset:16
	v_cvt_pk_bf16_f32 v34, v8, v9
	v_cvt_pk_bf16_f32 v35, v10, v11
	flat_store_dwordx4 v[40:41], v[32:35]
	global_load_dwordx4 v[20:23], v[18:19], off offset:512
	global_load_dwordx4 v[24:27], v[126:127], off
	global_load_dwordx4 v[28:31], v[158:159], off
	s_nop 0
	global_load_dwordx4 v[32:35], v[160:161], off
	global_load_dwordx4 v[36:39], v[18:19], off offset:528
	global_load_dwordx4 v[208:211], v[120:121], off
	global_load_dwordx4 v[212:215], v[122:123], off
	global_load_dwordx4 v[250:253], v[116:117], off
	s_waitcnt vmcnt(0)
	v_sub_f32_e32 v23, v23, v43
	v_sub_f32_e32 v22, v22, v43
	v_sub_f32_e32 v21, v21, v43
	v_sub_f32_e32 v20, v20, v43
	v_pk_mul_f32 v[20:21], v[42:43], v[20:21] op_sel_hi:[0,1]
	v_pk_mul_f32 v[22:23], v[42:43], v[22:23] op_sel_hi:[0,1]
	v_pk_fma_f32 v[22:23], v[26:27], v[22:23], v[30:31]
	v_pk_fma_f32 v[20:21], v[24:25], v[20:21], v[28:29]
	v_pk_fma_f32 v[6:7], v[22:23], s[24:25], v[6:7] op_sel_hi:[1,0,1]
	v_pk_fma_f32 v[4:5], v[20:21], s[24:25], v[4:5] op_sel_hi:[1,0,1]
	v_pk_add_f32 v[6:7], v[34:35], v[6:7]
	v_pk_add_f32 v[4:5], v[32:33], v[4:5]
	global_store_dwordx4 v[18:19], v[4:7], off offset:512
	v_add_f32_e32 v32, v12, v13
	v_mul_f32_e32 v13, v13, v13
	v_fmac_f32_e32 v13, v12, v12
	v_add_f32_e32 v32, v14, v32
	v_fmac_f32_e32 v13, v14, v14
	v_add_f32_e32 v14, v8, v9
	v_mul_f32_e32 v9, v9, v9
	v_fmac_f32_e32 v9, v8, v8
	v_add_f32_e32 v12, v15, v32
	v_add_f32_e32 v14, v10, v14
	v_fmac_f32_e32 v9, v10, v10
	v_add_f32_e32 v12, 0, v12
	v_fmac_f32_e32 v13, v15, v15
	v_add_f32_e32 v8, v11, v14
	v_fmac_f32_e32 v9, v11, v11
	v_sub_f32_e32 v11, v37, v43
	v_sub_f32_e32 v10, v36, v43
	v_add_f32_e32 v12, v8, v12
	v_add_f32_e32 v13, v13, v9
	v_sub_f32_e32 v9, v39, v43
	v_sub_f32_e32 v8, v38, v43
	v_pk_mul_f32 v[10:11], v[42:43], v[10:11] op_sel_hi:[0,1]
	v_pk_mul_f32 v[8:9], v[42:43], v[8:9] op_sel_hi:[0,1]
	v_mul_f32_e32 v15, v5, v5
	v_add_f32_e32 v14, v4, v5
	v_fmac_f32_e32 v15, v4, v4
	v_add_f32_e32 v14, v6, v14
	v_fmac_f32_e32 v15, v6, v6
	v_add_f32_e32 v14, v7, v14
	v_fmac_f32_e32 v15, v7, v7
	v_add_f32_e32 v12, v12, v14
	v_add_f32_e32 v13, v13, v15
	v_cvt_pk_bf16_f32 v4, v4, v5
	v_cvt_pk_bf16_f32 v5, v6, v7
	v_pk_fma_f32 v[10:11], v[208:209], v[10:11], v[212:213]
	v_pk_fma_f32 v[8:9], v[210:211], v[8:9], v[214:215]
	v_pk_fma_f32 v[0:1], v[10:11], s[24:25], v[0:1] op_sel_hi:[1,0,1]
	v_pk_fma_f32 v[2:3], v[8:9], s[24:25], v[2:3] op_sel_hi:[1,0,1]
	v_pk_add_f32 v[8:9], v[250:251], v[0:1]
	v_pk_add_f32 v[10:11], v[252:253], v[2:3]
	v_mul_f32_e32 v1, v9, v9
	v_add_f32_e32 v0, v8, v9
	v_fmac_f32_e32 v1, v8, v8
	v_add_f32_e32 v0, v10, v0
	v_fmac_f32_e32 v1, v10, v10
	v_add_f32_e32 v0, v11, v0
	v_fmac_f32_e32 v1, v11, v11
	v_add_f32_e32 v0, v12, v0
	v_add_f32_e32 v1, v13, v1
	ds_bpermute_b32 v2, v118, v0
	ds_bpermute_b32 v3, v118, v1
	global_store_dwordx4 v[18:19], v[8:11], off offset:528
	v_cvt_pk_bf16_f32 v6, v8, v9
	v_cvt_pk_bf16_f32 v7, v10, v11
	s_waitcnt lgkmcnt(0)
	v_add_f32_e32 v0, v0, v2
	v_add_f32_e32 v1, v1, v3
	ds_bpermute_b32 v2, v119, v0
	ds_bpermute_b32 v3, v119, v1
	flat_store_dwordx4 v[40:41], v[4:7] offset:256
	s_mov_b32 s100, -1
	s_mov_b32 s101, 0
	s_mov_b32 s98, 0xffff0000
	s_mov_b32 s99, 0
	s_and_saveexec_b64 s[36:37], s[100:101]
	s_cbranch_execz .LBB0_1999
	s_waitcnt lgkmcnt(0)
	v_add_f32_e32 v3, v1, v3
	v_add_f32_e32 v2, v0, v2
	v_lshl_add_u64 v[0:1], s[8:9], 0, v[16:17]
	v_cndmask_b32_e64 v2, v2, v3, s[98:99]
	v_cndmask_b32_e64 v3, 0, 4, s[98:99]
	v_or_b32_e32 v0, v0, v3
	flat_atomic_add_f32 v[0:1], v2

; DEVI unsigned pk2(float lo, float hi) { unsigned r; asm("v_cvt_pk_bf16_f32 %0, %1, %2" : "=v"(r) : "v"(lo), "v"(hi)); return r; }
;     DEVI void operator()(const f32x4 (&acc)[2][2][4][2], const pg8::Unit& u, int wr, int wc, int fr, int fq) const {
;     ...
;                 const int row = row0 + ai * 128 + m * 16; float mu, rs; row_stats(stin, row, mu, rs);
;                 float sum = 0.f, sq = 0.f;
; #pragma unroll
;                 for (int bj = 0; bj < 2; ++bj) {
;                     f32x4 z[2];
; #pragma unroll
;                     for (int n = 0; n < 2; ++n) {
;                         const int col = colb + bj * 128 + 4 * n;
;                         f32x4 xv = *(const f32x4*)(zsrc + (size_t)row * DM + col);
;                         if (stin) { const f32x4 gv = *(const f32x4*)(gin + col), bv = *(const f32x4*)(bin + col); xv = (xv - mu) * rs * gv + bv; }
;                         f32x4 zz = ALPHA * xv + acc[ai][bj][m][n];
;                         if (bias) zz += *(const f32x4*)(bias + col);
;                         *(f32x4*)(zdst + (size_t)row * DM + col) = zz;
;                         sum += zz[0] + zz[1] + zz[2] + zz[3]; sq += zz[0] * zz[0] + zz[1] * zz[1] + zz[2] * zz[2] + zz[3] * zz[3];
;                         z[n] = zz;
;                     }
;                     u32x4 o; o.x = pk2(z[0][0], z[0][1]); o.y = pk2(z[0][2], z[0][3]); o.z = pk2(z[1][0], z[1][1]); o.w = pk2(z[1][2], z[1][3]);
;                     if (zb) *(u32x4*)(zb + (size_t)row * DM + colb + bj * 128) = o;
;                 }
;                 sum += __shfl_xor(sum, 16); sq += __shfl_xor(sq, 16);
;                 sum += __shfl_xor(sum, 32); sq += __shfl_xor(sq, 32);
;                 if (fq == 0) { atomicAdd(stout + 2 * (size_t)row, sum); atomicAdd(stout + 2 * (size_t)row + 1, sq); }
.LBB0_2194:
	s_or_b64 exec, exec, s[30:31]
	v_or_b32_e32 v118, 16, v154
	v_ashrrev_i32_e32 v119, 31, v118
	v_lshlrev_b64 v[112:113], 3, v[118:119]
	s_waitcnt lgkmcnt(0)
	v_lshl_add_u64 v[114:115], s[12:13], 0, v[112:113]
	flat_load_dwordx2 v[160:161], v[114:115]
	v_lshlrev_b64 v[114:115], 12, v[118:119]
	v_lshl_add_u64 v[114:115], s[46:47], 0, v[114:115]
	v_lshl_add_u64 v[114:115], v[144:145], 2, v[114:115]
	global_load_dwordx4 v[156:159], v[114:115], off
	global_load_dwordx4 v[170:173], v[150:151], off
	global_load_dwordx4 v[174:177], v[152:153], off
	global_load_dwordx4 v[178:181], v[114:115], off offset:16
	v_lshlrev_b64 v[118:119], 11, v[118:119]
	v_lshl_add_u64 v[118:119], s[14:15], 0, v[118:119]
	v_lshl_add_u64 v[118:119], v[144:145], 1, v[118:119]
	global_load_dwordx4 v[196:199], v[146:147], off
	global_load_dwordx4 v[200:203], v[148:149], off
	global_load_dwordx4 v[204:207], v[114:115], off offset:512
	global_load_dwordx4 v[208:211], v[114:115], off offset:528
	s_waitcnt vmcnt(0) lgkmcnt(0)
	v_pk_mul_f32 v[160:161], v[160:161], s[24:25] op_sel:[1,0] op_sel_hi:[0,0]
	v_fma_f32 v155, -v161, v161, v160
	v_max_f32_e32 v155, 0, v155
	v_add_f32_e32 v155, 0x3727c5ac, v155
	v_mul_f32_e32 v160, 0x4b800000, v155
	v_cmp_gt_f32_e32 vcc, s61, v155
	v_sub_f32_e32 v157, v157, v161
	v_sub_f32_e32 v156, v156, v161
	v_cndmask_b32_e32 v155, v155, v160, vcc
	v_rsq_f32_e32 v155, v155
	v_sub_f32_e32 v159, v159, v161
	v_sub_f32_e32 v158, v158, v161
	v_mul_f32_e32 v160, 0x45800000, v155
	v_cndmask_b32_e32 v160, v155, v160, vcc
	v_pk_mul_f32 v[158:159], v[158:159], v[160:161] op_sel_hi:[1,0]
	v_pk_mul_f32 v[156:157], v[156:157], v[160:161] op_sel_hi:[1,0]
	v_pk_fma_f32 v[158:159], v[172:173], v[158:159], v[176:177]
	v_pk_fma_f32 v[156:157], v[170:171], v[156:157], v[174:175]
	v_pk_fma_f32 v[110:111], v[158:159], s[26:27], v[110:111] op_sel_hi:[1,0,1]
	v_pk_fma_f32 v[108:109], v[156:157], s[26:27], v[108:109] op_sel_hi:[1,0,1]
	global_store_dwordx4 v[114:115], v[108:111], off
	v_sub_f32_e32 v175, v179, v161
	v_sub_f32_e32 v174, v178, v161
	v_sub_f32_e32 v177, v181, v161
	v_sub_f32_e32 v176, v180, v161
	v_pk_mul_f32 v[176:177], v[176:177], v[160:161] op_sel_hi:[1,0]
	v_pk_mul_f32 v[178:179], v[174:175], v[160:161] op_sel_hi:[1,0]
	v_cvt_pk_bf16_f32 v174, v108, v109
	v_cvt_pk_bf16_f32 v175, v110, v111
	v_add_f32_e32 v155, v108, v109
	v_mul_f32_e32 v109, v109, v109
	v_fmac_f32_e32 v109, v108, v108
	v_add_f32_e32 v155, v110, v155
	v_fmac_f32_e32 v109, v110, v110
	v_add_f32_e32 v108, v111, v155
	v_add_f32_e32 v108, 0, v108
	v_fmac_f32_e32 v109, v111, v111
	v_pk_fma_f32 v[156:157], v[196:197], v[178:179], v[200:201]
	v_pk_fma_f32 v[158:159], v[198:199], v[176:177], v[202:203]
	v_pk_fma_f32 v[104:105], v[156:157], s[26:27], v[104:105] op_sel_hi:[1,0,1]
	v_pk_fma_f32 v[106:107], v[158:159], s[26:27], v[106:107] op_sel_hi:[1,0,1]
	global_store_dwordx4 v[114:115], v[104:107], off offset:16
	v_cvt_pk_bf16_f32 v176, v104, v105
	v_cvt_pk_bf16_f32 v177, v106, v107
	flat_store_dwordx4 v[118:119], v[174:177]
	global_load_dwordx4 v[170:173], v[120:121], off
	s_nop 0
	global_load_dwordx4 v[174:177], v[122:123], off
	v_add_f32_e32 v110, v104, v105
	v_mul_f32_e32 v105, v105, v105
	v_fmac_f32_e32 v105, v104, v104
	v_add_f32_e32 v110, v106, v110
	v_fmac_f32_e32 v105, v106, v106
	v_add_f32_e32 v104, v107, v110
	v_fmac_f32_e32 v105, v107, v107
	v_add_f32_e32 v108, v104, v108
	v_add_f32_e32 v109, v109, v105
	global_load_dwordx4 v[196:199], v[124:125], off
	global_load_dwordx4 v[200:203], v[126:127], off
	s_waitcnt vmcnt(0)
	v_sub_f32_e32 v157, v205, v161
	v_sub_f32_e32 v156, v204, v161
	v_sub_f32_e32 v159, v207, v161
	v_sub_f32_e32 v158, v206, v161
	v_pk_mul_f32 v[158:159], v[160:161], v[158:159] op_sel_hi:[0,1]
	v_pk_mul_f32 v[156:157], v[160:161], v[156:157] op_sel_hi:[0,1]
	v_pk_fma_f32 v[156:157], v[170:171], v[156:157], v[174:175]
	v_pk_fma_f32 v[158:159], v[172:173], v[158:159], v[176:177]
	v_pk_fma_f32 v[100:101], v[156:157], s[26:27], v[100:101] op_sel_hi:[1,0,1]
	v_pk_fma_f32 v[102:103], v[158:159], s[26:27], v[102:103] op_sel_hi:[1,0,1]
	global_store_dwordx4 v[114:115], v[100:103], off offset:512
	v_sub_f32_e32 v105, v209, v161
	v_sub_f32_e32 v104, v208, v161
	v_pk_mul_f32 v[104:105], v[160:161], v[104:105] op_sel_hi:[0,1]
	v_sub_f32_e32 v107, v211, v161
	v_sub_f32_e32 v106, v210, v161
	v_pk_mul_f32 v[106:107], v[160:161], v[106:107] op_sel_hi:[0,1]
	v_mul_f32_e32 v111, v101, v101
	v_add_f32_e32 v110, v100, v101
	v_fmac_f32_e32 v111, v100, v100
	v_add_f32_e32 v110, v102, v110
	v_fmac_f32_e32 v111, v102, v102
	v_add_f32_e32 v110, v103, v110
	v_fmac_f32_e32 v111, v103, v103
	v_add_f32_e32 v108, v108, v110
	v_add_f32_e32 v109, v109, v111
	v_cvt_pk_bf16_f32 v100, v100, v101
	v_cvt_pk_bf16_f32 v101, v102, v103
	v_pk_fma_f32 v[104:105], v[196:197], v[104:105], v[200:201]
	s_nop 0
	v_pk_fma_f32 v[104:105], v[104:105], s[26:27], v[96:97] op_sel_hi:[1,0,1]
	v_pk_fma_f32 v[106:107], v[198:199], v[106:107], v[202:203]
	v_mul_f32_e32 v97, v105, v105
	v_pk_fma_f32 v[106:107], v[106:107], s[26:27], v[98:99] op_sel_hi:[1,0,1]
	v_add_f32_e32 v96, v104, v105
	v_fmac_f32_e32 v97, v104, v104
	v_add_f32_e32 v96, v106, v96
	v_fmac_f32_e32 v97, v106, v106
	v_add_f32_e32 v96, v107, v96
	v_fmac_f32_e32 v97, v107, v107
	v_add_f32_e32 v96, v108, v96
	v_add_f32_e32 v97, v109, v97
	ds_bpermute_b32 v98, v116, v96
	ds_bpermute_b32 v99, v116, v97
	global_store_dwordx4 v[114:115], v[104:107], off offset:528
	v_cvt_pk_bf16_f32 v102, v104, v105
	v_cvt_pk_bf16_f32 v103, v106, v107
	s_waitcnt lgkmcnt(0)
	v_add_f32_e32 v96, v96, v98
	v_add_f32_e32 v97, v97, v99
	ds_bpermute_b32 v98, v117, v96
	ds_bpermute_b32 v99, v117, v97
	flat_store_dwordx4 v[118:119], v[100:103] offset:256
	s_mov_b32 s100, -1
	s_mov_b32 s101, 0
	s_mov_b32 s98, 0xffff0000
	s_mov_b32 s99, 0
	s_and_saveexec_b64 s[30:31], s[100:101]
	s_cbranch_execz .LBB0_2196
	s_waitcnt lgkmcnt(0)
	v_add_f32_e32 v99, v97, v99
	v_add_f32_e32 v98, v96, v98
	v_lshl_add_u64 v[96:97], s[10:11], 0, v[112:113]
	v_cndmask_b32_e64 v98, v98, v99, s[98:99]
	v_cndmask_b32_e64 v99, 0, 4, s[98:99]
	v_or_b32_e32 v96, v96, v99
	flat_atomic_add_f32 v[96:97], v98
; DEVI unsigned pk2(float lo, float hi) { unsigned r; asm("v_cvt_pk_bf16_f32 %0, %1, %2" : "=v"(r) : "v"(lo), "v"(hi)); return r; }
;     DEVI void operator()(const f32x4 (&acc)[2][2][4][2], const pg8::Unit& u, int wr, int wc, int fr, int fq) const {
;     ...
;                 const int row = row0 + ai * 128 + m * 16; float mu, rs; row_stats(stin, row, mu, rs);
;                 float sum = 0.f, sq = 0.f;
; #pragma unroll
;                 for (int bj = 0; bj < 2; ++bj) {
;                     f32x4 z[2];
; #pragma unroll
;                     for (int n = 0; n < 2; ++n) {
;                         const int col = colb + bj * 128 + 4 * n;
;                         f32x4 xv = *(const f32x4*)(zsrc + (size_t)row * DM + col);
;                         if (stin) { const f32x4 gv = *(const f32x4*)(gin + col), bv = *(const f32x4*)(bin + col); xv = (xv - mu) * rs * gv + bv; }
;                         f32x4 zz = ALPHA * xv + acc[ai][bj][m][n];
;                         if (bias) zz += *(const f32x4*)(bias + col);
;                         *(f32x4*)(zdst + (size_t)row * DM + col) = zz;
;                         sum += zz[0] + zz[1] + zz[2] + zz[3]; sq += zz[0] * zz[0] + zz[1] * zz[1] + zz[2] * zz[2] + zz[3] * zz[3];
;                         z[n] = zz;
;                     }
;                     u32x4 o; o.x = pk2(z[0][0], z[0][1]); o.y = pk2(z[0][2], z[0][3]); o.z = pk2(z[1][0], z[1][1]); o.w = pk2(z[1][2], z[1][3]);
;                     if (zb) *(u32x4*)(zb + (size_t)row * DM + colb + bj * 128) = o;
;                 }
;                 sum += __shfl_xor(sum, 16); sq += __shfl_xor(sq, 16);
;                 sum += __shfl_xor(sum, 32); sq += __shfl_xor(sq, 32);
;                 if (fq == 0) { atomicAdd(stout + 2 * (size_t)row, sum); atomicAdd(stout + 2 * (size_t)row + 1, sq); }
.LBB0_2196:
	s_or_b64 exec, exec, s[30:31]
	v_or_b32_e32 v118, 32, v154
	v_ashrrev_i32_e32 v119, 31, v118
	v_lshlrev_b64 v[96:97], 3, v[118:119]
	s_waitcnt lgkmcnt(0)
	v_lshl_add_u64 v[98:99], s[12:13], 0, v[96:97]
	flat_load_dwordx2 v[156:157], v[98:99]
	v_lshlrev_b64 v[98:99], 12, v[118:119]
	v_lshl_add_u64 v[98:99], s[46:47], 0, v[98:99]
	v_lshl_add_u64 v[98:99], v[144:145], 2, v[98:99]
	global_load_dwordx4 v[100:103], v[98:99], off
	global_load_dwordx4 v[104:107], v[150:151], off
	global_load_dwordx4 v[108:111], v[152:153], off
	global_load_dwordx4 v[112:115], v[98:99], off offset:16
	global_load_dwordx4 v[196:199], v[146:147], off
	global_load_dwordx4 v[200:203], v[148:149], off
	global_load_dwordx4 v[204:207], v[98:99], off offset:512
	global_load_dwordx4 v[208:211], v[98:99], off offset:528
	s_waitcnt vmcnt(0) lgkmcnt(0)
	v_pk_mul_f32 v[156:157], v[156:157], s[24:25] op_sel:[1,0] op_sel_hi:[0,0]
	v_fma_f32 v155, -v157, v157, v156
	v_max_f32_e32 v155, 0, v155
	v_add_f32_e32 v155, 0x3727c5ac, v155
	v_mul_f32_e32 v156, 0x4b800000, v155
	v_cmp_gt_f32_e32 vcc, s61, v155
	v_sub_f32_e32 v101, v101, v157
	v_sub_f32_e32 v100, v100, v157
	v_cndmask_b32_e32 v155, v155, v156, vcc
	v_rsq_f32_e32 v155, v155
	v_sub_f32_e32 v103, v103, v157
	v_sub_f32_e32 v102, v102, v157
	v_mul_f32_e32 v156, 0x45800000, v155
	v_cndmask_b32_e32 v156, v155, v156, vcc
	v_pk_mul_f32 v[102:103], v[102:103], v[156:157] op_sel_hi:[1,0]
	v_pk_mul_f32 v[100:101], v[100:101], v[156:157] op_sel_hi:[1,0]
	v_pk_fma_f32 v[102:103], v[106:107], v[102:103], v[110:111]
	v_pk_fma_f32 v[100:101], v[104:105], v[100:101], v[108:109]
	v_pk_fma_f32 v[94:95], v[102:103], s[26:27], v[94:95] op_sel_hi:[1,0,1]
	v_pk_fma_f32 v[92:93], v[100:101], s[26:27], v[92:93] op_sel_hi:[1,0,1]
	global_store_dwordx4 v[98:99], v[92:95], off
	v_lshlrev_b64 v[108:109], 11, v[118:119]
	v_lshl_add_u64 v[108:109], s[14:15], 0, v[108:109]
	v_lshl_add_u64 v[118:119], v[144:145], 1, v[108:109]
	v_sub_f32_e32 v109, v113, v157
	v_sub_f32_e32 v108, v112, v157
	v_sub_f32_e32 v111, v115, v157
	v_sub_f32_e32 v110, v114, v157
	v_pk_mul_f32 v[110:111], v[110:111], v[156:157] op_sel_hi:[1,0]
	v_pk_mul_f32 v[112:113], v[108:109], v[156:157] op_sel_hi:[1,0]
	v_cvt_pk_bf16_f32 v108, v92, v93
	v_cvt_pk_bf16_f32 v109, v94, v95
	v_pk_fma_f32 v[102:103], v[198:199], v[110:111], v[202:203]
	v_pk_fma_f32 v[100:101], v[196:197], v[112:113], v[200:201]
	v_pk_fma_f32 v[90:91], v[102:103], s[26:27], v[90:91] op_sel_hi:[1,0,1]
	v_pk_fma_f32 v[88:89], v[100:101], s[26:27], v[88:89] op_sel_hi:[1,0,1]
	global_store_dwordx4 v[98:99], v[88:91], off offset:16
	v_cvt_pk_bf16_f32 v110, v88, v89
	v_cvt_pk_bf16_f32 v111, v90, v91
	flat_store_dwordx4 v[118:119], v[108:111]
	global_load_dwordx4 v[104:107], v[120:121], off
	s_nop 0
	global_load_dwordx4 v[108:111], v[122:123], off
	global_load_dwordx4 v[196:199], v[124:125], off
	global_load_dwordx4 v[200:203], v[126:127], off
	s_waitcnt vmcnt(0)
	v_sub_f32_e32 v101, v205, v157
	v_sub_f32_e32 v100, v204, v157
	v_sub_f32_e32 v103, v207, v157
	v_sub_f32_e32 v102, v206, v157
	v_pk_mul_f32 v[102:103], v[156:157], v[102:103] op_sel_hi:[0,1]
	v_pk_mul_f32 v[100:101], v[156:157], v[100:101] op_sel_hi:[0,1]
	v_pk_fma_f32 v[100:101], v[104:105], v[100:101], v[108:109]
	v_pk_fma_f32 v[102:103], v[106:107], v[102:103], v[110:111]
	v_pk_fma_f32 v[84:85], v[100:101], s[26:27], v[84:85] op_sel_hi:[1,0,1]
	v_pk_fma_f32 v[86:87], v[102:103], s[26:27], v[86:87] op_sel_hi:[1,0,1]
	global_store_dwordx4 v[98:99], v[84:87], off offset:512
	v_add_f32_e32 v108, v92, v93
	v_mul_f32_e32 v93, v93, v93
	v_fmac_f32_e32 v93, v92, v92
	v_add_f32_e32 v108, v94, v108
	v_fmac_f32_e32 v93, v94, v94
	v_add_f32_e32 v94, v88, v89
	v_mul_f32_e32 v89, v89, v89
	v_fmac_f32_e32 v89, v88, v88
	v_add_f32_e32 v92, v95, v108
	v_add_f32_e32 v94, v90, v94
	v_fmac_f32_e32 v89, v90, v90
	v_add_f32_e32 v92, 0, v92
	v_fmac_f32_e32 v93, v95, v95
	v_add_f32_e32 v88, v91, v94
	v_fmac_f32_e32 v89, v91, v91
	v_add_f32_e32 v92, v88, v92
	v_add_f32_e32 v93, v93, v89
	v_sub_f32_e32 v89, v209, v157
	v_sub_f32_e32 v88, v208, v157
	v_pk_mul_f32 v[88:89], v[156:157], v[88:89] op_sel_hi:[0,1]
	v_sub_f32_e32 v91, v211, v157
	v_sub_f32_e32 v90, v210, v157
	v_pk_mul_f32 v[90:91], v[156:157], v[90:91] op_sel_hi:[0,1]
	v_mul_f32_e32 v95, v85, v85
	v_add_f32_e32 v94, v84, v85
	v_fmac_f32_e32 v95, v84, v84
	v_add_f32_e32 v94, v86, v94
	v_fmac_f32_e32 v95, v86, v86
	v_add_f32_e32 v94, v87, v94
	v_fmac_f32_e32 v95, v87, v87
	v_add_f32_e32 v92, v92, v94
	v_add_f32_e32 v93, v93, v95
	v_cvt_pk_bf16_f32 v84, v84, v85
	v_cvt_pk_bf16_f32 v85, v86, v87
	v_pk_fma_f32 v[88:89], v[196:197], v[88:89], v[200:201]
	s_nop 0
	v_pk_fma_f32 v[88:89], v[88:89], s[26:27], v[80:81] op_sel_hi:[1,0,1]
	v_pk_fma_f32 v[90:91], v[198:199], v[90:91], v[202:203]
	v_mul_f32_e32 v81, v89, v89
	v_pk_fma_f32 v[90:91], v[90:91], s[26:27], v[82:83] op_sel_hi:[1,0,1]
	v_add_f32_e32 v80, v88, v89
	v_fmac_f32_e32 v81, v88, v88
	v_add_f32_e32 v80, v90, v80
	v_fmac_f32_e32 v81, v90, v90
	v_add_f32_e32 v80, v91, v80
	v_fmac_f32_e32 v81, v91, v91
	v_add_f32_e32 v80, v92, v80
	v_add_f32_e32 v81, v93, v81
	ds_bpermute_b32 v82, v116, v80
	ds_bpermute_b32 v83, v116, v81
	global_store_dwordx4 v[98:99], v[88:91], off offset:528
	v_cvt_pk_bf16_f32 v86, v88, v89
	v_cvt_pk_bf16_f32 v87, v90, v91
	s_waitcnt lgkmcnt(0)
	v_add_f32_e32 v80, v80, v82
	v_add_f32_e32 v81, v81, v83
	ds_bpermute_b32 v82, v117, v80
	ds_bpermute_b32 v83, v117, v81
	flat_store_dwordx4 v[118:119], v[84:87] offset:256
	s_mov_b32 s100, -1
	s_mov_b32 s101, 0
	s_mov_b32 s98, 0xffff0000
	s_mov_b32 s99, 0
	s_and_saveexec_b64 s[30:31], s[100:101]
	s_cbranch_execz .LBB0_2198
	s_waitcnt lgkmcnt(0)
	v_add_f32_e32 v83, v81, v83
	v_add_f32_e32 v82, v80, v82
	v_lshl_add_u64 v[80:81], s[10:11], 0, v[96:97]
	v_cndmask_b32_e64 v82, v82, v83, s[98:99]
	v_cndmask_b32_e64 v83, 0, 4, s[98:99]
	v_or_b32_e32 v80, v80, v83
	flat_atomic_add_f32 v[80:81], v82
; DEVI unsigned pk2(float lo, float hi) { unsigned r; asm("v_cvt_pk_bf16_f32 %0, %1, %2" : "=v"(r) : "v"(lo), "v"(hi)); return r; }
;     DEVI void operator()(const f32x4 (&acc)[2][2][4][2], const pg8::Unit& u, int wr, int wc, int fr, int fq) const {
;     ...
;                 const int row = row0 + ai * 128 + m * 16; float mu, rs; row_stats(stin, row, mu, rs);
;                 float sum = 0.f, sq = 0.f;
; #pragma unroll
;                 for (int bj = 0; bj < 2; ++bj) {
;                     f32x4 z[2];
; #pragma unroll
;                     for (int n = 0; n < 2; ++n) {
;                         const int col = colb + bj * 128 + 4 * n;
;                         f32x4 xv = *(const f32x4*)(zsrc + (size_t)row * DM + col);
;                         if (stin) { const f32x4 gv = *(const f32x4*)(gin + col), bv = *(const f32x4*)(bin + col); xv = (xv - mu) * rs * gv + bv; }
;                         f32x4 zz = ALPHA * xv + acc[ai][bj][m][n];
;                         if (bias) zz += *(const f32x4*)(bias + col);
;                         *(f32x4*)(zdst + (size_t)row * DM + col) = zz;
;                         sum += zz[0] + zz[1] + zz[2] + zz[3]; sq += zz[0] * zz[0] + zz[1] * zz[1] + zz[2] * zz[2] + zz[3] * zz[3];
;                         z[n] = zz;
;                     }
;                     u32x4 o; o.x = pk2(z[0][0], z[0][1]); o.y = pk2(z[0][2], z[0][3]); o.z = pk2(z[1][0], z[1][1]); o.w = pk2(z[1][2], z[1][3]);
;                     if (zb) *(u32x4*)(zb + (size_t)row * DM + colb + bj * 128) = o;
;                 }
;                 sum += __shfl_xor(sum, 16); sq += __shfl_xor(sq, 16);
;                 sum += __shfl_xor(sum, 32); sq += __shfl_xor(sq, 32);
;                 if (fq == 0) { atomicAdd(stout + 2 * (size_t)row, sum); atomicAdd(stout + 2 * (size_t)row + 1, sq); }
.LBB0_2198:
	s_or_b64 exec, exec, s[30:31]
	v_or_b32_e32 v100, 48, v154
	v_ashrrev_i32_e32 v101, 31, v100
	v_lshlrev_b64 v[80:81], 3, v[100:101]
	s_waitcnt lgkmcnt(0)
	v_lshl_add_u64 v[82:83], s[12:13], 0, v[80:81]
	flat_load_dwordx2 v[102:103], v[82:83]
	v_lshlrev_b64 v[82:83], 12, v[100:101]
	v_lshl_add_u64 v[82:83], s[46:47], 0, v[82:83]
	v_lshl_add_u64 v[82:83], v[144:145], 2, v[82:83]
	global_load_dwordx4 v[84:87], v[82:83], off
	global_load_dwordx4 v[88:91], v[150:151], off
	global_load_dwordx4 v[92:95], v[152:153], off
	global_load_dwordx4 v[96:99], v[82:83], off offset:16
	global_load_dwordx4 v[196:199], v[146:147], off
	global_load_dwordx4 v[200:203], v[148:149], off
	global_load_dwordx4 v[204:207], v[82:83], off offset:512
	global_load_dwordx4 v[208:211], v[82:83], off offset:528
	s_waitcnt vmcnt(0) lgkmcnt(0)
	v_pk_mul_f32 v[102:103], v[102:103], s[24:25] op_sel:[1,0] op_sel_hi:[0,0]
	v_fma_f32 v102, -v103, v103, v102
	v_max_f32_e32 v102, 0, v102
	v_add_f32_e32 v102, 0x3727c5ac, v102
	v_mul_f32_e32 v104, 0x4b800000, v102
	v_cmp_gt_f32_e32 vcc, s61, v102
	v_sub_f32_e32 v85, v85, v103
	v_sub_f32_e32 v84, v84, v103
	v_cndmask_b32_e32 v102, v102, v104, vcc
	v_rsq_f32_e32 v102, v102
	v_sub_f32_e32 v87, v87, v103
	v_sub_f32_e32 v86, v86, v103
	v_mul_f32_e32 v104, 0x45800000, v102
	v_cndmask_b32_e32 v102, v102, v104, vcc
	v_pk_mul_f32 v[86:87], v[86:87], v[102:103] op_sel_hi:[1,0]
	v_pk_mul_f32 v[84:85], v[84:85], v[102:103] op_sel_hi:[1,0]
	v_pk_fma_f32 v[86:87], v[90:91], v[86:87], v[94:95]
	v_pk_fma_f32 v[84:85], v[88:89], v[84:85], v[92:93]
	v_pk_fma_f32 v[78:79], v[86:87], s[26:27], v[78:79] op_sel_hi:[1,0,1]
	v_pk_fma_f32 v[76:77], v[84:85], s[26:27], v[76:77] op_sel_hi:[1,0,1]
	global_store_dwordx4 v[82:83], v[76:79], off
	v_lshlrev_b64 v[92:93], 11, v[100:101]
	v_lshl_add_u64 v[92:93], s[14:15], 0, v[92:93]
	v_lshl_add_u64 v[100:101], v[144:145], 1, v[92:93]
	v_sub_f32_e32 v93, v97, v103
	v_sub_f32_e32 v92, v96, v103
	v_sub_f32_e32 v95, v99, v103
	v_sub_f32_e32 v94, v98, v103
	v_pk_mul_f32 v[94:95], v[94:95], v[102:103] op_sel_hi:[1,0]
	v_pk_mul_f32 v[96:97], v[92:93], v[102:103] op_sel_hi:[1,0]
	v_cvt_pk_bf16_f32 v92, v76, v77
	v_cvt_pk_bf16_f32 v93, v78, v79
	v_pk_fma_f32 v[86:87], v[198:199], v[94:95], v[202:203]
	v_pk_fma_f32 v[84:85], v[196:197], v[96:97], v[200:201]
	v_pk_fma_f32 v[74:75], v[86:87], s[26:27], v[74:75] op_sel_hi:[1,0,1]
	v_pk_fma_f32 v[72:73], v[84:85], s[26:27], v[72:73] op_sel_hi:[1,0,1]
	global_store_dwordx4 v[82:83], v[72:75], off offset:16
	v_cvt_pk_bf16_f32 v94, v72, v73
	v_cvt_pk_bf16_f32 v95, v74, v75
	flat_store_dwordx4 v[100:101], v[92:95]
	global_load_dwordx4 v[88:91], v[120:121], off
	s_nop 0
	global_load_dwordx4 v[92:95], v[122:123], off
	global_load_dwordx4 v[196:199], v[124:125], off
	global_load_dwordx4 v[200:203], v[126:127], off
	s_waitcnt vmcnt(0)
	v_sub_f32_e32 v85, v205, v103
	v_sub_f32_e32 v84, v204, v103
	v_sub_f32_e32 v87, v207, v103
	v_sub_f32_e32 v86, v206, v103
	v_pk_mul_f32 v[86:87], v[102:103], v[86:87] op_sel_hi:[0,1]
	v_pk_mul_f32 v[84:85], v[102:103], v[84:85] op_sel_hi:[0,1]
	v_pk_fma_f32 v[84:85], v[88:89], v[84:85], v[92:93]
	v_pk_fma_f32 v[86:87], v[90:91], v[86:87], v[94:95]
	v_pk_fma_f32 v[68:69], v[84:85], s[26:27], v[68:69] op_sel_hi:[1,0,1]
	v_pk_fma_f32 v[70:71], v[86:87], s[26:27], v[70:71] op_sel_hi:[1,0,1]
	global_store_dwordx4 v[82:83], v[68:71], off offset:512
	v_add_f32_e32 v92, v76, v77
	v_mul_f32_e32 v77, v77, v77
	v_fmac_f32_e32 v77, v76, v76
	v_add_f32_e32 v92, v78, v92
	v_fmac_f32_e32 v77, v78, v78
	v_add_f32_e32 v78, v72, v73
	v_mul_f32_e32 v73, v73, v73
	v_fmac_f32_e32 v73, v72, v72
	v_add_f32_e32 v76, v79, v92
	v_add_f32_e32 v78, v74, v78
	v_fmac_f32_e32 v73, v74, v74
	v_add_f32_e32 v76, 0, v76
	v_fmac_f32_e32 v77, v79, v79
	v_add_f32_e32 v72, v75, v78
	v_fmac_f32_e32 v73, v75, v75
	v_add_f32_e32 v76, v72, v76
	v_add_f32_e32 v77, v77, v73
	v_sub_f32_e32 v73, v209, v103
	v_sub_f32_e32 v72, v208, v103
	v_pk_mul_f32 v[72:73], v[102:103], v[72:73] op_sel_hi:[0,1]
	v_sub_f32_e32 v75, v211, v103
	v_sub_f32_e32 v74, v210, v103
	v_pk_mul_f32 v[74:75], v[102:103], v[74:75] op_sel_hi:[0,1]
	v_mul_f32_e32 v79, v69, v69
	v_add_f32_e32 v78, v68, v69
	v_fmac_f32_e32 v79, v68, v68
	v_add_f32_e32 v78, v70, v78
	v_fmac_f32_e32 v79, v70, v70
	v_add_f32_e32 v78, v71, v78
	v_fmac_f32_e32 v79, v71, v71
	v_add_f32_e32 v76, v76, v78
	v_add_f32_e32 v77, v77, v79
	v_cvt_pk_bf16_f32 v68, v68, v69
	v_cvt_pk_bf16_f32 v69, v70, v71
	v_pk_fma_f32 v[72:73], v[196:197], v[72:73], v[200:201]
	s_nop 0
	v_pk_fma_f32 v[72:73], v[72:73], s[26:27], v[64:65] op_sel_hi:[1,0,1]
	v_pk_fma_f32 v[74:75], v[198:199], v[74:75], v[202:203]
	v_mul_f32_e32 v65, v73, v73
	v_pk_fma_f32 v[74:75], v[74:75], s[26:27], v[66:67] op_sel_hi:[1,0,1]
	v_add_f32_e32 v64, v72, v73
	v_fmac_f32_e32 v65, v72, v72
	v_add_f32_e32 v64, v74, v64
	v_fmac_f32_e32 v65, v74, v74
	v_add_f32_e32 v64, v75, v64
	v_fmac_f32_e32 v65, v75, v75
	v_add_f32_e32 v64, v76, v64
	v_add_f32_e32 v65, v77, v65
	ds_bpermute_b32 v66, v116, v64
	ds_bpermute_b32 v67, v116, v65
	global_store_dwordx4 v[82:83], v[72:75], off offset:528
	v_cvt_pk_bf16_f32 v70, v72, v73
	v_cvt_pk_bf16_f32 v71, v74, v75
	s_waitcnt lgkmcnt(0)
	v_add_f32_e32 v64, v64, v66
	v_add_f32_e32 v65, v65, v67
	ds_bpermute_b32 v66, v117, v64
	ds_bpermute_b32 v67, v117, v65
	flat_store_dwordx4 v[100:101], v[68:71] offset:256
	s_mov_b32 s100, -1
	s_mov_b32 s101, 0
	s_mov_b32 s98, 0xffff0000
	s_mov_b32 s99, 0
	s_and_saveexec_b64 s[30:31], s[100:101]
	s_cbranch_execz .LBB0_2200
	s_waitcnt lgkmcnt(0)
	v_add_f32_e32 v67, v65, v67
	v_add_f32_e32 v66, v64, v66
	v_lshl_add_u64 v[64:65], s[10:11], 0, v[80:81]
	v_cndmask_b32_e64 v66, v66, v67, s[98:99]
	v_cndmask_b32_e64 v67, 0, 4, s[98:99]
	v_or_b32_e32 v64, v64, v67
	flat_atomic_add_f32 v[64:65], v66
; DEVI unsigned pk2(float lo, float hi) { unsigned r; asm("v_cvt_pk_bf16_f32 %0, %1, %2" : "=v"(r) : "v"(lo), "v"(hi)); return r; }
;     DEVI void operator()(const f32x4 (&acc)[2][2][4][2], const pg8::Unit& u, int wr, int wc, int fr, int fq) const {
;     ...
;                 const int row = row0 + ai * 128 + m * 16; float mu, rs; row_stats(stin, row, mu, rs);
;                 float sum = 0.f, sq = 0.f;
; #pragma unroll
;                 for (int bj = 0; bj < 2; ++bj) {
;                     f32x4 z[2];
; #pragma unroll
;                     for (int n = 0; n < 2; ++n) {
;                         const int col = colb + bj * 128 + 4 * n;
;                         f32x4 xv = *(const f32x4*)(zsrc + (size_t)row * DM + col);
;                         if (stin) { const f32x4 gv = *(const f32x4*)(gin + col), bv = *(const f32x4*)(bin + col); xv = (xv - mu) * rs * gv + bv; }
;                         f32x4 zz = ALPHA * xv + acc[ai][bj][m][n];
;                         if (bias) zz += *(const f32x4*)(bias + col);
;                         *(f32x4*)(zdst + (size_t)row * DM + col) = zz;
;                         sum += zz[0] + zz[1] + zz[2] + zz[3]; sq += zz[0] * zz[0] + zz[1] * zz[1] + zz[2] * zz[2] + zz[3] * zz[3];
;                         z[n] = zz;
;                     }
;                     u32x4 o; o.x = pk2(z[0][0], z[0][1]); o.y = pk2(z[0][2], z[0][3]); o.z = pk2(z[1][0], z[1][1]); o.w = pk2(z[1][2], z[1][3]);
;                     if (zb) *(u32x4*)(zb + (size_t)row * DM + colb + bj * 128) = o;
;                 }
;                 sum += __shfl_xor(sum, 16); sq += __shfl_xor(sq, 16);
;                 sum += __shfl_xor(sum, 32); sq += __shfl_xor(sq, 32);
;                 if (fq == 0) { atomicAdd(stout + 2 * (size_t)row, sum); atomicAdd(stout + 2 * (size_t)row + 1, sq); }
.LBB0_2200:
	s_or_b64 exec, exec, s[30:31]
	v_add_u32_e32 v84, 0x80, v154
	v_ashrrev_i32_e32 v85, 31, v84
	v_lshlrev_b64 v[64:65], 3, v[84:85]
	s_waitcnt lgkmcnt(0)
	v_lshl_add_u64 v[66:67], s[12:13], 0, v[64:65]
	flat_load_dwordx2 v[86:87], v[66:67]
	v_lshlrev_b64 v[66:67], 12, v[84:85]
	v_lshl_add_u64 v[66:67], s[46:47], 0, v[66:67]
	v_lshl_add_u64 v[66:67], v[144:145], 2, v[66:67]
	global_load_dwordx4 v[68:71], v[66:67], off
	global_load_dwordx4 v[72:75], v[150:151], off
	global_load_dwordx4 v[76:79], v[152:153], off
	global_load_dwordx4 v[80:83], v[66:67], off offset:16
	global_load_dwordx4 v[196:199], v[146:147], off
	global_load_dwordx4 v[200:203], v[148:149], off
	global_load_dwordx4 v[204:207], v[66:67], off offset:512
	global_load_dwordx4 v[208:211], v[66:67], off offset:528
	s_waitcnt vmcnt(0) lgkmcnt(0)
	v_pk_mul_f32 v[86:87], v[86:87], s[24:25] op_sel:[1,0] op_sel_hi:[0,0]
	v_fma_f32 v86, -v87, v87, v86
	v_max_f32_e32 v86, 0, v86
	v_add_f32_e32 v86, 0x3727c5ac, v86
	v_mul_f32_e32 v88, 0x4b800000, v86
	v_cmp_gt_f32_e32 vcc, s61, v86
	v_sub_f32_e32 v69, v69, v87
	v_sub_f32_e32 v68, v68, v87
	v_cndmask_b32_e32 v86, v86, v88, vcc
	v_rsq_f32_e32 v86, v86
	v_sub_f32_e32 v71, v71, v87
	v_sub_f32_e32 v70, v70, v87
	v_mul_f32_e32 v88, 0x45800000, v86
	v_cndmask_b32_e32 v86, v86, v88, vcc
	v_pk_mul_f32 v[70:71], v[70:71], v[86:87] op_sel_hi:[1,0]
	v_pk_mul_f32 v[68:69], v[68:69], v[86:87] op_sel_hi:[1,0]
	v_pk_fma_f32 v[70:71], v[74:75], v[70:71], v[78:79]
	v_pk_fma_f32 v[68:69], v[72:73], v[68:69], v[76:77]
	v_pk_fma_f32 v[62:63], v[70:71], s[26:27], v[62:63] op_sel_hi:[1,0,1]
	v_pk_fma_f32 v[60:61], v[68:69], s[26:27], v[60:61] op_sel_hi:[1,0,1]
	global_store_dwordx4 v[66:67], v[60:63], off
	v_lshlrev_b64 v[76:77], 11, v[84:85]
	v_lshl_add_u64 v[76:77], s[14:15], 0, v[76:77]
	v_lshl_add_u64 v[84:85], v[144:145], 1, v[76:77]
	v_sub_f32_e32 v77, v81, v87
	v_sub_f32_e32 v76, v80, v87
	v_sub_f32_e32 v79, v83, v87
	v_sub_f32_e32 v78, v82, v87
	v_pk_mul_f32 v[78:79], v[78:79], v[86:87] op_sel_hi:[1,0]
	v_pk_mul_f32 v[80:81], v[76:77], v[86:87] op_sel_hi:[1,0]
	v_cvt_pk_bf16_f32 v76, v60, v61
	v_cvt_pk_bf16_f32 v77, v62, v63
	v_pk_fma_f32 v[70:71], v[198:199], v[78:79], v[202:203]
	v_pk_fma_f32 v[68:69], v[196:197], v[80:81], v[200:201]
	v_pk_fma_f32 v[58:59], v[70:71], s[26:27], v[58:59] op_sel_hi:[1,0,1]
	v_pk_fma_f32 v[56:57], v[68:69], s[26:27], v[56:57] op_sel_hi:[1,0,1]
	global_store_dwordx4 v[66:67], v[56:59], off offset:16
	v_cvt_pk_bf16_f32 v78, v56, v57
	v_cvt_pk_bf16_f32 v79, v58, v59
	flat_store_dwordx4 v[84:85], v[76:79]
	global_load_dwordx4 v[72:75], v[120:121], off
	s_nop 0
	global_load_dwordx4 v[76:79], v[122:123], off
	global_load_dwordx4 v[196:199], v[124:125], off
	global_load_dwordx4 v[200:203], v[126:127], off
	s_waitcnt vmcnt(0)
	v_sub_f32_e32 v69, v205, v87
	v_sub_f32_e32 v68, v204, v87
	v_sub_f32_e32 v71, v207, v87
	v_sub_f32_e32 v70, v206, v87
	v_pk_mul_f32 v[70:71], v[86:87], v[70:71] op_sel_hi:[0,1]
	v_pk_mul_f32 v[68:69], v[86:87], v[68:69] op_sel_hi:[0,1]
	v_pk_fma_f32 v[68:69], v[72:73], v[68:69], v[76:77]
	v_pk_fma_f32 v[70:71], v[74:75], v[70:71], v[78:79]
	v_pk_fma_f32 v[52:53], v[68:69], s[26:27], v[52:53] op_sel_hi:[1,0,1]
	v_pk_fma_f32 v[54:55], v[70:71], s[26:27], v[54:55] op_sel_hi:[1,0,1]
	global_store_dwordx4 v[66:67], v[52:55], off offset:512
	v_add_f32_e32 v76, v60, v61
	v_mul_f32_e32 v61, v61, v61
	v_fmac_f32_e32 v61, v60, v60
	v_add_f32_e32 v76, v62, v76
	v_fmac_f32_e32 v61, v62, v62
	v_add_f32_e32 v62, v56, v57
	v_mul_f32_e32 v57, v57, v57
	v_fmac_f32_e32 v57, v56, v56
	v_add_f32_e32 v60, v63, v76
	v_add_f32_e32 v62, v58, v62
	v_fmac_f32_e32 v57, v58, v58
	v_add_f32_e32 v60, 0, v60
	v_fmac_f32_e32 v61, v63, v63
	v_add_f32_e32 v56, v59, v62
	v_fmac_f32_e32 v57, v59, v59
	v_add_f32_e32 v60, v56, v60
	v_add_f32_e32 v61, v61, v57
	v_sub_f32_e32 v57, v209, v87
	v_sub_f32_e32 v56, v208, v87
	v_pk_mul_f32 v[56:57], v[86:87], v[56:57] op_sel_hi:[0,1]
	v_sub_f32_e32 v59, v211, v87
	v_sub_f32_e32 v58, v210, v87
	v_pk_mul_f32 v[58:59], v[86:87], v[58:59] op_sel_hi:[0,1]
	v_mul_f32_e32 v63, v53, v53
	v_add_f32_e32 v62, v52, v53
	v_fmac_f32_e32 v63, v52, v52
	v_add_f32_e32 v62, v54, v62
	v_fmac_f32_e32 v63, v54, v54
	v_add_f32_e32 v62, v55, v62
	v_fmac_f32_e32 v63, v55, v55
	v_add_f32_e32 v60, v60, v62
	v_add_f32_e32 v61, v61, v63
	v_cvt_pk_bf16_f32 v52, v52, v53
	v_cvt_pk_bf16_f32 v53, v54, v55
	v_pk_fma_f32 v[56:57], v[196:197], v[56:57], v[200:201]
	s_nop 0
	v_pk_fma_f32 v[56:57], v[56:57], s[26:27], v[48:49] op_sel_hi:[1,0,1]
	v_pk_fma_f32 v[58:59], v[198:199], v[58:59], v[202:203]
	v_mul_f32_e32 v49, v57, v57
	v_pk_fma_f32 v[58:59], v[58:59], s[26:27], v[50:51] op_sel_hi:[1,0,1]
	v_add_f32_e32 v48, v56, v57
	v_fmac_f32_e32 v49, v56, v56
	v_add_f32_e32 v48, v58, v48
	v_fmac_f32_e32 v49, v58, v58
	v_add_f32_e32 v48, v59, v48
	v_fmac_f32_e32 v49, v59, v59
	v_add_f32_e32 v48, v60, v48
	v_add_f32_e32 v49, v61, v49
	ds_bpermute_b32 v50, v116, v48
	ds_bpermute_b32 v51, v116, v49
	global_store_dwordx4 v[66:67], v[56:59], off offset:528
	v_cvt_pk_bf16_f32 v54, v56, v57
	v_cvt_pk_bf16_f32 v55, v58, v59
	s_waitcnt lgkmcnt(0)
	v_add_f32_e32 v48, v48, v50
	v_add_f32_e32 v49, v49, v51
	ds_bpermute_b32 v50, v117, v48
	ds_bpermute_b32 v51, v117, v49
	flat_store_dwordx4 v[84:85], v[52:55] offset:256
	s_mov_b32 s100, -1
	s_mov_b32 s101, 0
	s_mov_b32 s98, 0xffff0000
	s_mov_b32 s99, 0
	s_and_saveexec_b64 s[30:31], s[100:101]
	s_cbranch_execz .LBB0_2202
	s_waitcnt lgkmcnt(0)
	v_add_f32_e32 v51, v49, v51
	v_add_f32_e32 v50, v48, v50
	v_lshl_add_u64 v[48:49], s[10:11], 0, v[64:65]
	v_cndmask_b32_e64 v50, v50, v51, s[98:99]
	v_cndmask_b32_e64 v51, 0, 4, s[98:99]
	v_or_b32_e32 v48, v48, v51
	flat_atomic_add_f32 v[48:49], v50
; DEVI unsigned pk2(float lo, float hi) { unsigned r; asm("v_cvt_pk_bf16_f32 %0, %1, %2" : "=v"(r) : "v"(lo), "v"(hi)); return r; }
;     DEVI void operator()(const f32x4 (&acc)[2][2][4][2], const pg8::Unit& u, int wr, int wc, int fr, int fq) const {
;     ...
;                 const int row = row0 + ai * 128 + m * 16; float mu, rs; row_stats(stin, row, mu, rs);
;                 float sum = 0.f, sq = 0.f;
; #pragma unroll
;                 for (int bj = 0; bj < 2; ++bj) {
;                     f32x4 z[2];
; #pragma unroll
;                     for (int n = 0; n < 2; ++n) {
;                         const int col = colb + bj * 128 + 4 * n;
;                         f32x4 xv = *(const f32x4*)(zsrc + (size_t)row * DM + col);
;                         if (stin) { const f32x4 gv = *(const f32x4*)(gin + col), bv = *(const f32x4*)(bin + col); xv = (xv - mu) * rs * gv + bv; }
;                         f32x4 zz = ALPHA * xv + acc[ai][bj][m][n];
;                         if (bias) zz += *(const f32x4*)(bias + col);
;                         *(f32x4*)(zdst + (size_t)row * DM + col) = zz;
;                         sum += zz[0] + zz[1] + zz[2] + zz[3]; sq += zz[0] * zz[0] + zz[1] * zz[1] + zz[2] * zz[2] + zz[3] * zz[3];
;                         z[n] = zz;
;                     }
;                     u32x4 o; o.x = pk2(z[0][0], z[0][1]); o.y = pk2(z[0][2], z[0][3]); o.z = pk2(z[1][0], z[1][1]); o.w = pk2(z[1][2], z[1][3]);
;                     if (zb) *(u32x4*)(zb + (size_t)row * DM + colb + bj * 128) = o;
;                 }
;                 sum += __shfl_xor(sum, 16); sq += __shfl_xor(sq, 16);
;                 sum += __shfl_xor(sum, 32); sq += __shfl_xor(sq, 32);
;                 if (fq == 0) { atomicAdd(stout + 2 * (size_t)row, sum); atomicAdd(stout + 2 * (size_t)row + 1, sq); }
.LBB0_2202:
	s_or_b64 exec, exec, s[30:31]
	v_add_u32_e32 v68, 0x90, v154
	v_ashrrev_i32_e32 v69, 31, v68
	v_lshlrev_b64 v[48:49], 3, v[68:69]
	s_waitcnt lgkmcnt(0)
	v_lshl_add_u64 v[50:51], s[12:13], 0, v[48:49]
	flat_load_dwordx2 v[70:71], v[50:51]
	v_lshlrev_b64 v[50:51], 12, v[68:69]
	v_lshl_add_u64 v[50:51], s[46:47], 0, v[50:51]
	v_lshl_add_u64 v[50:51], v[144:145], 2, v[50:51]
	global_load_dwordx4 v[52:55], v[50:51], off
	global_load_dwordx4 v[56:59], v[150:151], off
	global_load_dwordx4 v[60:63], v[152:153], off
	global_load_dwordx4 v[64:67], v[50:51], off offset:16
	global_load_dwordx4 v[196:199], v[146:147], off
	global_load_dwordx4 v[200:203], v[148:149], off
	global_load_dwordx4 v[204:207], v[50:51], off offset:512
	global_load_dwordx4 v[208:211], v[50:51], off offset:528
	s_waitcnt vmcnt(0) lgkmcnt(0)
	v_pk_mul_f32 v[70:71], v[70:71], s[24:25] op_sel:[1,0] op_sel_hi:[0,0]
	v_fma_f32 v70, -v71, v71, v70
	v_max_f32_e32 v70, 0, v70
	v_add_f32_e32 v70, 0x3727c5ac, v70
	v_mul_f32_e32 v72, 0x4b800000, v70
	v_cmp_gt_f32_e32 vcc, s61, v70
	v_sub_f32_e32 v53, v53, v71
	v_sub_f32_e32 v52, v52, v71
	v_cndmask_b32_e32 v70, v70, v72, vcc
	v_rsq_f32_e32 v70, v70
	v_sub_f32_e32 v55, v55, v71
	v_sub_f32_e32 v54, v54, v71
	v_mul_f32_e32 v72, 0x45800000, v70
	v_cndmask_b32_e32 v70, v70, v72, vcc
	v_pk_mul_f32 v[54:55], v[54:55], v[70:71] op_sel_hi:[1,0]
	v_pk_mul_f32 v[52:53], v[52:53], v[70:71] op_sel_hi:[1,0]
	v_pk_fma_f32 v[54:55], v[58:59], v[54:55], v[62:63]
	v_pk_fma_f32 v[52:53], v[56:57], v[52:53], v[60:61]
	v_pk_fma_f32 v[46:47], v[54:55], s[26:27], v[46:47] op_sel_hi:[1,0,1]
	v_pk_fma_f32 v[44:45], v[52:53], s[26:27], v[44:45] op_sel_hi:[1,0,1]
	global_store_dwordx4 v[50:51], v[44:47], off
	v_lshlrev_b64 v[60:61], 11, v[68:69]
	v_lshl_add_u64 v[60:61], s[14:15], 0, v[60:61]
	v_lshl_add_u64 v[68:69], v[144:145], 1, v[60:61]
	v_sub_f32_e32 v61, v65, v71
	v_sub_f32_e32 v60, v64, v71
	v_sub_f32_e32 v63, v67, v71
	v_sub_f32_e32 v62, v66, v71
	v_pk_mul_f32 v[62:63], v[62:63], v[70:71] op_sel_hi:[1,0]
	v_pk_mul_f32 v[64:65], v[60:61], v[70:71] op_sel_hi:[1,0]
	v_cvt_pk_bf16_f32 v60, v44, v45
	v_cvt_pk_bf16_f32 v61, v46, v47
	v_pk_fma_f32 v[54:55], v[198:199], v[62:63], v[202:203]
	v_pk_fma_f32 v[52:53], v[196:197], v[64:65], v[200:201]
	v_pk_fma_f32 v[42:43], v[54:55], s[26:27], v[42:43] op_sel_hi:[1,0,1]
	v_pk_fma_f32 v[40:41], v[52:53], s[26:27], v[40:41] op_sel_hi:[1,0,1]
	global_store_dwordx4 v[50:51], v[40:43], off offset:16
	v_cvt_pk_bf16_f32 v62, v40, v41
	v_cvt_pk_bf16_f32 v63, v42, v43
	flat_store_dwordx4 v[68:69], v[60:63]
	global_load_dwordx4 v[56:59], v[120:121], off
	s_nop 0
	global_load_dwordx4 v[60:63], v[122:123], off
	global_load_dwordx4 v[196:199], v[124:125], off
	global_load_dwordx4 v[200:203], v[126:127], off
	s_waitcnt vmcnt(0)
	v_sub_f32_e32 v53, v205, v71
	v_sub_f32_e32 v52, v204, v71
	v_sub_f32_e32 v55, v207, v71
	v_sub_f32_e32 v54, v206, v71
	v_pk_mul_f32 v[54:55], v[70:71], v[54:55] op_sel_hi:[0,1]
	v_pk_mul_f32 v[52:53], v[70:71], v[52:53] op_sel_hi:[0,1]
	v_pk_fma_f32 v[52:53], v[56:57], v[52:53], v[60:61]
	v_pk_fma_f32 v[54:55], v[58:59], v[54:55], v[62:63]
	v_pk_fma_f32 v[36:37], v[52:53], s[26:27], v[36:37] op_sel_hi:[1,0,1]
	v_pk_fma_f32 v[38:39], v[54:55], s[26:27], v[38:39] op_sel_hi:[1,0,1]
	global_store_dwordx4 v[50:51], v[36:39], off offset:512
	v_add_f32_e32 v60, v44, v45
	v_mul_f32_e32 v45, v45, v45
	v_fmac_f32_e32 v45, v44, v44
	v_add_f32_e32 v60, v46, v60
	v_fmac_f32_e32 v45, v46, v46
	v_add_f32_e32 v46, v40, v41
	v_mul_f32_e32 v41, v41, v41
	v_fmac_f32_e32 v41, v40, v40
	v_add_f32_e32 v44, v47, v60
	v_add_f32_e32 v46, v42, v46
	v_fmac_f32_e32 v41, v42, v42
	v_add_f32_e32 v44, 0, v44
	v_fmac_f32_e32 v45, v47, v47
	v_add_f32_e32 v40, v43, v46
	v_fmac_f32_e32 v41, v43, v43
	v_add_f32_e32 v44, v40, v44
	v_add_f32_e32 v45, v45, v41
	v_sub_f32_e32 v41, v209, v71
	v_sub_f32_e32 v40, v208, v71
	v_pk_mul_f32 v[40:41], v[70:71], v[40:41] op_sel_hi:[0,1]
	v_sub_f32_e32 v43, v211, v71
	v_sub_f32_e32 v42, v210, v71
	v_pk_mul_f32 v[42:43], v[70:71], v[42:43] op_sel_hi:[0,1]
	v_mul_f32_e32 v47, v37, v37
	v_add_f32_e32 v46, v36, v37
	v_fmac_f32_e32 v47, v36, v36
	v_add_f32_e32 v46, v38, v46
	v_fmac_f32_e32 v47, v38, v38
	v_add_f32_e32 v46, v39, v46
	v_fmac_f32_e32 v47, v39, v39
	v_add_f32_e32 v44, v44, v46
	v_add_f32_e32 v45, v45, v47
	v_cvt_pk_bf16_f32 v36, v36, v37
	v_cvt_pk_bf16_f32 v37, v38, v39
	v_pk_fma_f32 v[40:41], v[196:197], v[40:41], v[200:201]
	s_nop 0
	v_pk_fma_f32 v[40:41], v[40:41], s[26:27], v[32:33] op_sel_hi:[1,0,1]
	v_pk_fma_f32 v[42:43], v[198:199], v[42:43], v[202:203]
	v_mul_f32_e32 v33, v41, v41
	v_pk_fma_f32 v[42:43], v[42:43], s[26:27], v[34:35] op_sel_hi:[1,0,1]
	v_add_f32_e32 v32, v40, v41
	v_fmac_f32_e32 v33, v40, v40
	v_add_f32_e32 v32, v42, v32
	v_fmac_f32_e32 v33, v42, v42
	v_add_f32_e32 v32, v43, v32
	v_fmac_f32_e32 v33, v43, v43
	v_add_f32_e32 v32, v44, v32
	v_add_f32_e32 v33, v45, v33
	ds_bpermute_b32 v34, v116, v32
	ds_bpermute_b32 v35, v116, v33
	global_store_dwordx4 v[50:51], v[40:43], off offset:528
	v_cvt_pk_bf16_f32 v38, v40, v41
	v_cvt_pk_bf16_f32 v39, v42, v43
	s_waitcnt lgkmcnt(0)
	v_add_f32_e32 v32, v32, v34
	v_add_f32_e32 v33, v33, v35
	ds_bpermute_b32 v34, v117, v32
	ds_bpermute_b32 v35, v117, v33
	flat_store_dwordx4 v[68:69], v[36:39] offset:256
	s_mov_b32 s100, -1
	s_mov_b32 s101, 0
	s_mov_b32 s98, 0xffff0000
	s_mov_b32 s99, 0
	s_and_saveexec_b64 s[30:31], s[100:101]
	s_cbranch_execz .LBB0_2204
	s_waitcnt lgkmcnt(0)
	v_add_f32_e32 v35, v33, v35
	v_add_f32_e32 v34, v32, v34
	v_lshl_add_u64 v[32:33], s[10:11], 0, v[48:49]
	v_cndmask_b32_e64 v34, v34, v35, s[98:99]
	v_cndmask_b32_e64 v35, 0, 4, s[98:99]
	v_or_b32_e32 v32, v32, v35
	flat_atomic_add_f32 v[32:33], v34
; DEVI unsigned pk2(float lo, float hi) { unsigned r; asm("v_cvt_pk_bf16_f32 %0, %1, %2" : "=v"(r) : "v"(lo), "v"(hi)); return r; }
;     DEVI void operator()(const f32x4 (&acc)[2][2][4][2], const pg8::Unit& u, int wr, int wc, int fr, int fq) const {
;     ...
;                 const int row = row0 + ai * 128 + m * 16; float mu, rs; row_stats(stin, row, mu, rs);
;                 float sum = 0.f, sq = 0.f;
; #pragma unroll
;                 for (int bj = 0; bj < 2; ++bj) {
;                     f32x4 z[2];
; #pragma unroll
;                     for (int n = 0; n < 2; ++n) {
;                         const int col = colb + bj * 128 + 4 * n;
;                         f32x4 xv = *(const f32x4*)(zsrc + (size_t)row * DM + col);
;                         if (stin) { const f32x4 gv = *(const f32x4*)(gin + col), bv = *(const f32x4*)(bin + col); xv = (xv - mu) * rs * gv + bv; }
;                         f32x4 zz = ALPHA * xv + acc[ai][bj][m][n];
;                         if (bias) zz += *(const f32x4*)(bias + col);
;                         *(f32x4*)(zdst + (size_t)row * DM + col) = zz;
;                         sum += zz[0] + zz[1] + zz[2] + zz[3]; sq += zz[0] * zz[0] + zz[1] * zz[1] + zz[2] * zz[2] + zz[3] * zz[3];
;                         z[n] = zz;
;                     }
;                     u32x4 o; o.x = pk2(z[0][0], z[0][1]); o.y = pk2(z[0][2], z[0][3]); o.z = pk2(z[1][0], z[1][1]); o.w = pk2(z[1][2], z[1][3]);
;                     if (zb) *(u32x4*)(zb + (size_t)row * DM + colb + bj * 128) = o;
;                 }
;                 sum += __shfl_xor(sum, 16); sq += __shfl_xor(sq, 16);
;                 sum += __shfl_xor(sum, 32); sq += __shfl_xor(sq, 32);
;                 if (fq == 0) { atomicAdd(stout + 2 * (size_t)row, sum); atomicAdd(stout + 2 * (size_t)row + 1, sq); }
.LBB0_2204:
	s_or_b64 exec, exec, s[30:31]
	v_add_u32_e32 v52, 0xa0, v154
	v_ashrrev_i32_e32 v53, 31, v52
	v_lshlrev_b64 v[32:33], 3, v[52:53]
	s_waitcnt lgkmcnt(0)
	v_lshl_add_u64 v[34:35], s[12:13], 0, v[32:33]
	flat_load_dwordx2 v[54:55], v[34:35]
	v_lshlrev_b64 v[34:35], 12, v[52:53]
	v_lshl_add_u64 v[34:35], s[46:47], 0, v[34:35]
	v_lshl_add_u64 v[34:35], v[144:145], 2, v[34:35]
	global_load_dwordx4 v[36:39], v[34:35], off
	global_load_dwordx4 v[40:43], v[150:151], off
	global_load_dwordx4 v[44:47], v[152:153], off
	global_load_dwordx4 v[48:51], v[34:35], off offset:16
	global_load_dwordx4 v[196:199], v[146:147], off
	global_load_dwordx4 v[200:203], v[148:149], off
	global_load_dwordx4 v[204:207], v[34:35], off offset:512
	global_load_dwordx4 v[208:211], v[34:35], off offset:528
	s_waitcnt vmcnt(0) lgkmcnt(0)
	v_pk_mul_f32 v[54:55], v[54:55], s[24:25] op_sel:[1,0] op_sel_hi:[0,0]
	v_fma_f32 v54, -v55, v55, v54
	v_max_f32_e32 v54, 0, v54
	v_add_f32_e32 v54, 0x3727c5ac, v54
	v_mul_f32_e32 v56, 0x4b800000, v54
	v_cmp_gt_f32_e32 vcc, s61, v54
	v_sub_f32_e32 v37, v37, v55
	v_sub_f32_e32 v36, v36, v55
	v_cndmask_b32_e32 v54, v54, v56, vcc
	v_rsq_f32_e32 v54, v54
	v_sub_f32_e32 v39, v39, v55
	v_sub_f32_e32 v38, v38, v55
	v_mul_f32_e32 v56, 0x45800000, v54
	v_cndmask_b32_e32 v54, v54, v56, vcc
	v_pk_mul_f32 v[38:39], v[38:39], v[54:55] op_sel_hi:[1,0]
	v_pk_mul_f32 v[36:37], v[36:37], v[54:55] op_sel_hi:[1,0]
	v_pk_fma_f32 v[38:39], v[42:43], v[38:39], v[46:47]
	v_pk_fma_f32 v[36:37], v[40:41], v[36:37], v[44:45]
	v_pk_fma_f32 v[30:31], v[38:39], s[26:27], v[30:31] op_sel_hi:[1,0,1]
	v_pk_fma_f32 v[28:29], v[36:37], s[26:27], v[28:29] op_sel_hi:[1,0,1]
	global_store_dwordx4 v[34:35], v[28:31], off
	v_lshlrev_b64 v[44:45], 11, v[52:53]
	v_lshl_add_u64 v[44:45], s[14:15], 0, v[44:45]
	v_lshl_add_u64 v[52:53], v[144:145], 1, v[44:45]
	v_sub_f32_e32 v45, v49, v55
	v_sub_f32_e32 v44, v48, v55
	v_sub_f32_e32 v47, v51, v55
	v_sub_f32_e32 v46, v50, v55
	v_pk_mul_f32 v[46:47], v[46:47], v[54:55] op_sel_hi:[1,0]
	v_pk_mul_f32 v[48:49], v[44:45], v[54:55] op_sel_hi:[1,0]
	v_cvt_pk_bf16_f32 v44, v28, v29
	v_cvt_pk_bf16_f32 v45, v30, v31
	v_pk_fma_f32 v[38:39], v[198:199], v[46:47], v[202:203]
	v_pk_fma_f32 v[36:37], v[196:197], v[48:49], v[200:201]
	v_pk_fma_f32 v[26:27], v[38:39], s[26:27], v[26:27] op_sel_hi:[1,0,1]
	v_pk_fma_f32 v[24:25], v[36:37], s[26:27], v[24:25] op_sel_hi:[1,0,1]
	global_store_dwordx4 v[34:35], v[24:27], off offset:16
	v_cvt_pk_bf16_f32 v46, v24, v25
	v_cvt_pk_bf16_f32 v47, v26, v27
	flat_store_dwordx4 v[52:53], v[44:47]
	global_load_dwordx4 v[40:43], v[120:121], off
	s_nop 0
	global_load_dwordx4 v[44:47], v[122:123], off
	global_load_dwordx4 v[196:199], v[124:125], off
	global_load_dwordx4 v[200:203], v[126:127], off
	s_waitcnt vmcnt(0)
	v_sub_f32_e32 v37, v205, v55
	v_sub_f32_e32 v36, v204, v55
	v_sub_f32_e32 v39, v207, v55
	v_sub_f32_e32 v38, v206, v55
	v_pk_mul_f32 v[38:39], v[54:55], v[38:39] op_sel_hi:[0,1]
	v_pk_mul_f32 v[36:37], v[54:55], v[36:37] op_sel_hi:[0,1]
	v_pk_fma_f32 v[36:37], v[40:41], v[36:37], v[44:45]
	v_pk_fma_f32 v[38:39], v[42:43], v[38:39], v[46:47]
	v_pk_fma_f32 v[20:21], v[36:37], s[26:27], v[20:21] op_sel_hi:[1,0,1]
	v_pk_fma_f32 v[22:23], v[38:39], s[26:27], v[22:23] op_sel_hi:[1,0,1]
	global_store_dwordx4 v[34:35], v[20:23], off offset:512
	v_add_f32_e32 v44, v28, v29
	v_mul_f32_e32 v29, v29, v29
	v_fmac_f32_e32 v29, v28, v28
	v_add_f32_e32 v44, v30, v44
	v_fmac_f32_e32 v29, v30, v30
	v_add_f32_e32 v30, v24, v25
	v_mul_f32_e32 v25, v25, v25
	v_fmac_f32_e32 v25, v24, v24
	v_add_f32_e32 v28, v31, v44
	v_add_f32_e32 v30, v26, v30
	v_fmac_f32_e32 v25, v26, v26
	v_add_f32_e32 v28, 0, v28
	v_fmac_f32_e32 v29, v31, v31
	v_add_f32_e32 v24, v27, v30
	v_fmac_f32_e32 v25, v27, v27
	v_add_f32_e32 v28, v24, v28
	v_add_f32_e32 v29, v29, v25
	v_sub_f32_e32 v25, v209, v55
	v_sub_f32_e32 v24, v208, v55
	v_pk_mul_f32 v[24:25], v[54:55], v[24:25] op_sel_hi:[0,1]
	v_sub_f32_e32 v27, v211, v55
	v_sub_f32_e32 v26, v210, v55
	v_pk_mul_f32 v[26:27], v[54:55], v[26:27] op_sel_hi:[0,1]
	v_mul_f32_e32 v31, v21, v21
	v_add_f32_e32 v30, v20, v21
	v_fmac_f32_e32 v31, v20, v20
	v_add_f32_e32 v30, v22, v30
	v_fmac_f32_e32 v31, v22, v22
	v_add_f32_e32 v30, v23, v30
	v_fmac_f32_e32 v31, v23, v23
	v_add_f32_e32 v28, v28, v30
	v_add_f32_e32 v29, v29, v31
	v_cvt_pk_bf16_f32 v20, v20, v21
	v_cvt_pk_bf16_f32 v21, v22, v23
	v_pk_fma_f32 v[24:25], v[196:197], v[24:25], v[200:201]
	s_nop 0
	v_pk_fma_f32 v[24:25], v[24:25], s[26:27], v[16:17] op_sel_hi:[1,0,1]
	v_pk_fma_f32 v[26:27], v[198:199], v[26:27], v[202:203]
	v_mul_f32_e32 v17, v25, v25
	v_pk_fma_f32 v[26:27], v[26:27], s[26:27], v[18:19] op_sel_hi:[1,0,1]
	v_add_f32_e32 v16, v24, v25
	v_fmac_f32_e32 v17, v24, v24
	v_add_f32_e32 v16, v26, v16
	v_fmac_f32_e32 v17, v26, v26
	v_add_f32_e32 v16, v27, v16
	v_fmac_f32_e32 v17, v27, v27
	v_add_f32_e32 v16, v28, v16
	v_add_f32_e32 v17, v29, v17
	ds_bpermute_b32 v18, v116, v16
	ds_bpermute_b32 v19, v116, v17
	global_store_dwordx4 v[34:35], v[24:27], off offset:528
	v_cvt_pk_bf16_f32 v22, v24, v25
	v_cvt_pk_bf16_f32 v23, v26, v27
	s_waitcnt lgkmcnt(0)
	v_add_f32_e32 v16, v16, v18
	v_add_f32_e32 v17, v17, v19
	ds_bpermute_b32 v18, v117, v16
	ds_bpermute_b32 v19, v117, v17
	flat_store_dwordx4 v[52:53], v[20:23] offset:256
	s_mov_b32 s100, -1
	s_mov_b32 s101, 0
	s_mov_b32 s98, 0xffff0000
	s_mov_b32 s99, 0
	s_and_saveexec_b64 s[30:31], s[100:101]
	s_cbranch_execz .LBB0_2206
	s_waitcnt lgkmcnt(0)
	v_add_f32_e32 v19, v17, v19
	v_add_f32_e32 v18, v16, v18
	v_lshl_add_u64 v[16:17], s[10:11], 0, v[32:33]
	v_cndmask_b32_e64 v18, v18, v19, s[98:99]
	v_cndmask_b32_e64 v19, 0, 4, s[98:99]
	v_or_b32_e32 v16, v16, v19
	flat_atomic_add_f32 v[16:17], v18
; DEVI unsigned pk2(float lo, float hi) { unsigned r; asm("v_cvt_pk_bf16_f32 %0, %1, %2" : "=v"(r) : "v"(lo), "v"(hi)); return r; }
;     DEVI void operator()(const f32x4 (&acc)[2][2][4][2], const pg8::Unit& u, int wr, int wc, int fr, int fq) const {
;     ...
;                 const int row = row0 + ai * 128 + m * 16; float mu, rs; row_stats(stin, row, mu, rs);
;                 float sum = 0.f, sq = 0.f;
; #pragma unroll
;                 for (int bj = 0; bj < 2; ++bj) {
;                     f32x4 z[2];
; #pragma unroll
;                     for (int n = 0; n < 2; ++n) {
;                         const int col = colb + bj * 128 + 4 * n;
;                         f32x4 xv = *(const f32x4*)(zsrc + (size_t)row * DM + col);
;                         if (stin) { const f32x4 gv = *(const f32x4*)(gin + col), bv = *(const f32x4*)(bin + col); xv = (xv - mu) * rs * gv + bv; }
;                         f32x4 zz = ALPHA * xv + acc[ai][bj][m][n];
;                         if (bias) zz += *(const f32x4*)(bias + col);
;                         *(f32x4*)(zdst + (size_t)row * DM + col) = zz;
;                         sum += zz[0] + zz[1] + zz[2] + zz[3]; sq += zz[0] * zz[0] + zz[1] * zz[1] + zz[2] * zz[2] + zz[3] * zz[3];
;                         z[n] = zz;
;                     }
;                     u32x4 o; o.x = pk2(z[0][0], z[0][1]); o.y = pk2(z[0][2], z[0][3]); o.z = pk2(z[1][0], z[1][1]); o.w = pk2(z[1][2], z[1][3]);
;                     if (zb) *(u32x4*)(zb + (size_t)row * DM + colb + bj * 128) = o;
;                 }
;                 sum += __shfl_xor(sum, 16); sq += __shfl_xor(sq, 16);
;                 sum += __shfl_xor(sum, 32); sq += __shfl_xor(sq, 32);
;                 if (fq == 0) { atomicAdd(stout + 2 * (size_t)row, sum); atomicAdd(stout + 2 * (size_t)row + 1, sq); }
.LBB0_2206:
	s_or_b64 exec, exec, s[30:31]
	v_add_u32_e32 v36, 0xb0, v154
	v_ashrrev_i32_e32 v37, 31, v36
	v_lshlrev_b64 v[16:17], 3, v[36:37]
	s_waitcnt lgkmcnt(0)
	v_lshl_add_u64 v[18:19], s[12:13], 0, v[16:17]
	flat_load_dwordx2 v[38:39], v[18:19]
	v_lshlrev_b64 v[18:19], 12, v[36:37]
	v_lshl_add_u64 v[18:19], s[46:47], 0, v[18:19]
	v_lshl_add_u64 v[18:19], v[144:145], 2, v[18:19]
	global_load_dwordx4 v[20:23], v[18:19], off
	global_load_dwordx4 v[24:27], v[150:151], off
	global_load_dwordx4 v[28:31], v[152:153], off
	global_load_dwordx4 v[32:35], v[18:19], off offset:16
	global_load_dwordx4 v[196:199], v[146:147], off
	global_load_dwordx4 v[200:203], v[148:149], off
	global_load_dwordx4 v[204:207], v[18:19], off offset:512
	global_load_dwordx4 v[208:211], v[18:19], off offset:528
	s_waitcnt vmcnt(0) lgkmcnt(0)
	v_pk_mul_f32 v[38:39], v[38:39], s[24:25] op_sel:[1,0] op_sel_hi:[0,0]
	v_fma_f32 v38, -v39, v39, v38
	v_max_f32_e32 v38, 0, v38
	v_add_f32_e32 v38, 0x3727c5ac, v38
	v_mul_f32_e32 v40, 0x4b800000, v38
	v_cmp_gt_f32_e32 vcc, s61, v38
	v_sub_f32_e32 v21, v21, v39
	v_sub_f32_e32 v20, v20, v39
	v_cndmask_b32_e32 v38, v38, v40, vcc
	v_rsq_f32_e32 v38, v38
	v_sub_f32_e32 v23, v23, v39
	v_sub_f32_e32 v22, v22, v39
	v_mul_f32_e32 v40, 0x45800000, v38
	v_cndmask_b32_e32 v38, v38, v40, vcc
	v_pk_mul_f32 v[22:23], v[22:23], v[38:39] op_sel_hi:[1,0]
	v_pk_mul_f32 v[20:21], v[20:21], v[38:39] op_sel_hi:[1,0]
	v_pk_fma_f32 v[22:23], v[26:27], v[22:23], v[30:31]
	v_pk_fma_f32 v[20:21], v[24:25], v[20:21], v[28:29]
	v_pk_fma_f32 v[14:15], v[22:23], s[26:27], v[14:15] op_sel_hi:[1,0,1]
	v_pk_fma_f32 v[12:13], v[20:21], s[26:27], v[12:13] op_sel_hi:[1,0,1]
	global_store_dwordx4 v[18:19], v[12:15], off
	v_lshlrev_b64 v[28:29], 11, v[36:37]
	v_lshl_add_u64 v[28:29], s[14:15], 0, v[28:29]
	v_lshl_add_u64 v[36:37], v[144:145], 1, v[28:29]
	v_sub_f32_e32 v29, v33, v39
	v_sub_f32_e32 v28, v32, v39
	v_sub_f32_e32 v31, v35, v39
	v_sub_f32_e32 v30, v34, v39
	v_pk_mul_f32 v[30:31], v[30:31], v[38:39] op_sel_hi:[1,0]
	v_pk_mul_f32 v[32:33], v[28:29], v[38:39] op_sel_hi:[1,0]
	v_cvt_pk_bf16_f32 v28, v12, v13
	v_cvt_pk_bf16_f32 v29, v14, v15
	v_pk_fma_f32 v[22:23], v[198:199], v[30:31], v[202:203]
	v_pk_fma_f32 v[20:21], v[196:197], v[32:33], v[200:201]
	v_pk_fma_f32 v[10:11], v[22:23], s[26:27], v[10:11] op_sel_hi:[1,0,1]
	v_pk_fma_f32 v[8:9], v[20:21], s[26:27], v[8:9] op_sel_hi:[1,0,1]
	global_store_dwordx4 v[18:19], v[8:11], off offset:16
	v_cvt_pk_bf16_f32 v30, v8, v9
	v_cvt_pk_bf16_f32 v31, v10, v11
	flat_store_dwordx4 v[36:37], v[28:31]
	global_load_dwordx4 v[24:27], v[120:121], off
	s_nop 0
	global_load_dwordx4 v[28:31], v[122:123], off
	global_load_dwordx4 v[196:199], v[124:125], off
	global_load_dwordx4 v[200:203], v[126:127], off
	s_waitcnt vmcnt(0)
	v_sub_f32_e32 v21, v205, v39
	v_sub_f32_e32 v20, v204, v39
	v_sub_f32_e32 v23, v207, v39
	v_sub_f32_e32 v22, v206, v39
	v_pk_mul_f32 v[22:23], v[38:39], v[22:23] op_sel_hi:[0,1]
	v_pk_mul_f32 v[20:21], v[38:39], v[20:21] op_sel_hi:[0,1]
	v_pk_fma_f32 v[20:21], v[24:25], v[20:21], v[28:29]
	v_pk_fma_f32 v[22:23], v[26:27], v[22:23], v[30:31]
	v_pk_fma_f32 v[4:5], v[20:21], s[26:27], v[4:5] op_sel_hi:[1,0,1]
	v_pk_fma_f32 v[6:7], v[22:23], s[26:27], v[6:7] op_sel_hi:[1,0,1]
	global_store_dwordx4 v[18:19], v[4:7], off offset:512
	v_add_f32_e32 v28, v12, v13
	v_mul_f32_e32 v13, v13, v13
	v_fmac_f32_e32 v13, v12, v12
	v_add_f32_e32 v28, v14, v28
	v_fmac_f32_e32 v13, v14, v14
	v_add_f32_e32 v14, v8, v9
	v_mul_f32_e32 v9, v9, v9
	v_fmac_f32_e32 v9, v8, v8
	v_add_f32_e32 v12, v15, v28
	v_add_f32_e32 v14, v10, v14
	v_fmac_f32_e32 v9, v10, v10
	v_add_f32_e32 v12, 0, v12
	v_fmac_f32_e32 v13, v15, v15
	v_add_f32_e32 v8, v11, v14
	v_fmac_f32_e32 v9, v11, v11
	v_add_f32_e32 v12, v8, v12
	v_add_f32_e32 v13, v13, v9
	v_sub_f32_e32 v9, v209, v39
	v_sub_f32_e32 v8, v208, v39
	v_pk_mul_f32 v[8:9], v[38:39], v[8:9] op_sel_hi:[0,1]
	v_sub_f32_e32 v11, v211, v39
	v_sub_f32_e32 v10, v210, v39
	v_pk_mul_f32 v[10:11], v[38:39], v[10:11] op_sel_hi:[0,1]
	v_mul_f32_e32 v15, v5, v5
	v_add_f32_e32 v14, v4, v5
	v_fmac_f32_e32 v15, v4, v4
	v_add_f32_e32 v14, v6, v14
	v_fmac_f32_e32 v15, v6, v6
	v_add_f32_e32 v14, v7, v14
	v_fmac_f32_e32 v15, v7, v7
	v_add_f32_e32 v12, v12, v14
	v_add_f32_e32 v13, v13, v15
	v_cvt_pk_bf16_f32 v4, v4, v5
	v_cvt_pk_bf16_f32 v5, v6, v7
	v_pk_fma_f32 v[8:9], v[196:197], v[8:9], v[200:201]
	s_nop 0
	v_pk_fma_f32 v[8:9], v[8:9], s[26:27], v[0:1] op_sel_hi:[1,0,1]
	v_pk_fma_f32 v[10:11], v[198:199], v[10:11], v[202:203]
	v_mul_f32_e32 v1, v9, v9
	v_pk_fma_f32 v[10:11], v[10:11], s[26:27], v[2:3] op_sel_hi:[1,0,1]
	v_add_f32_e32 v0, v8, v9
	v_fmac_f32_e32 v1, v8, v8
	v_add_f32_e32 v0, v10, v0
	v_fmac_f32_e32 v1, v10, v10
	v_add_f32_e32 v0, v11, v0
	v_fmac_f32_e32 v1, v11, v11
	v_add_f32_e32 v0, v12, v0
	v_add_f32_e32 v1, v13, v1
	ds_bpermute_b32 v2, v116, v0
	ds_bpermute_b32 v3, v116, v1
	global_store_dwordx4 v[18:19], v[8:11], off offset:528
	v_cvt_pk_bf16_f32 v6, v8, v9
	v_cvt_pk_bf16_f32 v7, v10, v11
	s_waitcnt lgkmcnt(0)
	v_add_f32_e32 v0, v0, v2
	v_add_f32_e32 v1, v1, v3
	ds_bpermute_b32 v2, v117, v0
	ds_bpermute_b32 v3, v117, v1
	flat_store_dwordx4 v[36:37], v[4:7] offset:256
	s_mov_b32 s100, -1
	s_mov_b32 s101, 0
	s_mov_b32 s98, 0xffff0000
	s_mov_b32 s99, 0
	s_and_saveexec_b64 s[30:31], s[100:101]
	s_cbranch_execz .LBB0_2208
	s_waitcnt lgkmcnt(0)
	v_add_f32_e32 v3, v1, v3
	v_add_f32_e32 v2, v0, v2
	v_lshl_add_u64 v[0:1], s[10:11], 0, v[16:17]
	v_cndmask_b32_e64 v2, v2, v3, s[98:99]
	v_cndmask_b32_e64 v3, 0, 4, s[98:99]
	v_or_b32_e32 v0, v0, v3
	flat_atomic_add_f32 v[0:1], v2

; DEVI unsigned pk2(float lo, float hi) { unsigned r; asm("v_cvt_pk_bf16_f32 %0, %1, %2" : "=v"(r) : "v"(lo), "v"(hi)); return r; }
;     DEVI void operator()(const f32x4 (&acc)[2][2][4][2], const pg8::Unit& u, int wr, int wc, int fr, int fq) const {
;     ...
;                 const int row = row0 + ai * 128 + m * 16; float mu, rs; row_stats(stin, row, mu, rs);
;                 float sum = 0.f, sq = 0.f;
; #pragma unroll
;                 for (int bj = 0; bj < 2; ++bj) {
;                     f32x4 z[2];
; #pragma unroll
;                     for (int n = 0; n < 2; ++n) {
;                         const int col = colb + bj * 128 + 4 * n;
;                         f32x4 xv = *(const f32x4*)(zsrc + (size_t)row * DM + col);
;                         if (stin) { const f32x4 gv = *(const f32x4*)(gin + col), bv = *(const f32x4*)(bin + col); xv = (xv - mu) * rs * gv + bv; }
;                         f32x4 zz = ALPHA * xv + acc[ai][bj][m][n];
;                         if (bias) zz += *(const f32x4*)(bias + col);
;                         *(f32x4*)(zdst + (size_t)row * DM + col) = zz;
;                         sum += zz[0] + zz[1] + zz[2] + zz[3]; sq += zz[0] * zz[0] + zz[1] * zz[1] + zz[2] * zz[2] + zz[3] * zz[3];
;                         z[n] = zz;
;                     }
;                     u32x4 o; o.x = pk2(z[0][0], z[0][1]); o.y = pk2(z[0][2], z[0][3]); o.z = pk2(z[1][0], z[1][1]); o.w = pk2(z[1][2], z[1][3]);
;                     if (zb) *(u32x4*)(zb + (size_t)row * DM + colb + bj * 128) = o;
;                 }
;                 sum += __shfl_xor(sum, 16); sq += __shfl_xor(sq, 16);
;                 sum += __shfl_xor(sum, 32); sq += __shfl_xor(sq, 32);
;                 if (fq == 0) { atomicAdd(stout + 2 * (size_t)row, sum); atomicAdd(stout + 2 * (size_t)row + 1, sq); }
.LBB0_2638:
	s_or_b64 exec, exec, s[36:37]
	v_or_b32_e32 v166, 16, v154
	v_ashrrev_i32_e32 v167, 31, v166
	v_lshlrev_b64 v[112:113], 3, v[166:167]
	s_waitcnt lgkmcnt(0)
	v_lshl_add_u64 v[114:115], s[6:7], 0, v[112:113]
	flat_load_dwordx2 v[192:193], v[114:115]
	v_lshlrev_b64 v[114:115], 12, v[166:167]
	v_lshl_add_u64 v[114:115], s[46:47], 0, v[114:115]
	v_lshl_add_u64 v[114:115], v[144:145], 2, v[114:115]
	global_load_dwordx4 v[162:165], v[114:115], off
	global_load_dwordx4 v[176:179], v[150:151], off
	global_load_dwordx4 v[180:183], v[152:153], off
	global_load_dwordx4 v[184:187], v[156:157], off
	global_load_dwordx4 v[188:191], v[114:115], off offset:16
	v_lshlrev_b64 v[166:167], 11, v[166:167]
	v_lshl_add_u64 v[166:167], s[10:11], 0, v[166:167]
	v_lshl_add_u64 v[166:167], v[144:145], 1, v[166:167]
	global_load_dwordx4 v[208:211], v[146:147], off
	global_load_dwordx4 v[212:215], v[148:149], off
	global_load_dwordx4 v[250:253], v[124:125], off
	s_waitcnt vmcnt(0) lgkmcnt(0)
	v_pk_mul_f32 v[192:193], v[192:193], s[22:23] op_sel:[1,0] op_sel_hi:[0,0]
	v_fma_f32 v155, -v193, v193, v192
	v_max_f32_e32 v155, 0, v155
	v_add_f32_e32 v155, 0x3727c5ac, v155
	v_mul_f32_e32 v175, 0x4b800000, v155
	v_cmp_gt_f32_e32 vcc, s64, v155
	v_sub_f32_e32 v165, v165, v193
	v_sub_f32_e32 v164, v164, v193
	v_cndmask_b32_e32 v155, v155, v175, vcc
	v_rsq_f32_e32 v155, v155
	v_sub_f32_e32 v163, v163, v193
	v_sub_f32_e32 v162, v162, v193
	v_mul_f32_e32 v175, 0x45800000, v155
	v_cndmask_b32_e32 v192, v155, v175, vcc
	v_pk_mul_f32 v[162:163], v[162:163], v[192:193] op_sel_hi:[1,0]
	v_pk_mul_f32 v[164:165], v[164:165], v[192:193] op_sel_hi:[1,0]
	v_pk_fma_f32 v[162:163], v[176:177], v[162:163], v[180:181]
	v_pk_fma_f32 v[164:165], v[178:179], v[164:165], v[182:183]
	v_pk_fma_f32 v[108:109], v[162:163], s[24:25], v[108:109] op_sel_hi:[1,0,1]
	v_pk_fma_f32 v[110:111], v[164:165], s[24:25], v[110:111] op_sel_hi:[1,0,1]
	v_pk_add_f32 v[108:109], v[184:185], v[108:109]
	v_pk_add_f32 v[110:111], v[186:187], v[110:111]
	global_store_dwordx4 v[114:115], v[108:111], off
	v_sub_f32_e32 v185, v191, v193
	v_sub_f32_e32 v184, v190, v193
	v_sub_f32_e32 v187, v189, v193
	v_sub_f32_e32 v186, v188, v193
	v_pk_mul_f32 v[186:187], v[186:187], v[192:193] op_sel_hi:[1,0]
	v_pk_mul_f32 v[188:189], v[184:185], v[192:193] op_sel_hi:[1,0]
	v_cvt_pk_bf16_f32 v184, v108, v109
	v_cvt_pk_bf16_f32 v185, v110, v111
	v_add_f32_e32 v155, v108, v109
	v_mul_f32_e32 v109, v109, v109
	v_fmac_f32_e32 v109, v108, v108
	v_add_f32_e32 v155, v110, v155
	v_fmac_f32_e32 v109, v110, v110
	v_add_f32_e32 v108, v111, v155
	v_add_f32_e32 v108, 0, v108
	v_fmac_f32_e32 v109, v111, v111
	v_pk_fma_f32 v[164:165], v[210:211], v[188:189], v[214:215]
	v_pk_fma_f32 v[162:163], v[208:209], v[186:187], v[212:213]
	v_pk_fma_f32 v[106:107], v[164:165], s[24:25], v[106:107] op_sel_hi:[1,0,1]
	v_pk_fma_f32 v[104:105], v[162:163], s[24:25], v[104:105] op_sel_hi:[1,0,1]
	v_pk_add_f32 v[106:107], v[252:253], v[106:107]
	v_pk_add_f32 v[104:105], v[250:251], v[104:105]
	global_store_dwordx4 v[114:115], v[104:107], off offset:16
	v_cvt_pk_bf16_f32 v186, v104, v105
	v_cvt_pk_bf16_f32 v187, v106, v107
	flat_store_dwordx4 v[166:167], v[184:187]
	global_load_dwordx4 v[162:165], v[114:115], off offset:512
	global_load_dwordx4 v[176:179], v[126:127], off
	global_load_dwordx4 v[180:183], v[158:159], off
	s_nop 0
	global_load_dwordx4 v[184:187], v[160:161], off
	global_load_dwordx4 v[188:191], v[114:115], off offset:528
	v_add_f32_e32 v110, v104, v105
	v_mul_f32_e32 v105, v105, v105
	v_fmac_f32_e32 v105, v104, v104
	v_add_f32_e32 v110, v106, v110
	v_fmac_f32_e32 v105, v106, v106
	v_add_f32_e32 v104, v107, v110
	v_fmac_f32_e32 v105, v107, v107
	v_add_f32_e32 v108, v104, v108
	v_add_f32_e32 v109, v109, v105
	global_load_dwordx4 v[208:211], v[120:121], off
	global_load_dwordx4 v[212:215], v[122:123], off
	global_load_dwordx4 v[250:253], v[116:117], off
	s_waitcnt vmcnt(0)
	v_sub_f32_e32 v165, v165, v193
	v_sub_f32_e32 v164, v164, v193
	v_sub_f32_e32 v163, v163, v193
	v_sub_f32_e32 v162, v162, v193
	v_pk_mul_f32 v[162:163], v[192:193], v[162:163] op_sel_hi:[0,1]
	v_pk_mul_f32 v[164:165], v[192:193], v[164:165] op_sel_hi:[0,1]
	v_pk_fma_f32 v[164:165], v[178:179], v[164:165], v[182:183]
	v_pk_fma_f32 v[162:163], v[176:177], v[162:163], v[180:181]
	v_pk_fma_f32 v[102:103], v[164:165], s[24:25], v[102:103] op_sel_hi:[1,0,1]
	v_pk_fma_f32 v[100:101], v[162:163], s[24:25], v[100:101] op_sel_hi:[1,0,1]
	v_pk_add_f32 v[102:103], v[186:187], v[102:103]
	v_pk_add_f32 v[100:101], v[184:185], v[100:101]
	global_store_dwordx4 v[114:115], v[100:103], off offset:512
	v_sub_f32_e32 v107, v189, v193
	v_sub_f32_e32 v106, v188, v193
	v_sub_f32_e32 v105, v191, v193
	v_sub_f32_e32 v104, v190, v193
	v_pk_mul_f32 v[106:107], v[192:193], v[106:107] op_sel_hi:[0,1]
	v_pk_mul_f32 v[104:105], v[192:193], v[104:105] op_sel_hi:[0,1]
	v_mul_f32_e32 v111, v101, v101
	v_add_f32_e32 v110, v100, v101
	v_fmac_f32_e32 v111, v100, v100
	v_add_f32_e32 v110, v102, v110
	v_fmac_f32_e32 v111, v102, v102
	v_add_f32_e32 v110, v103, v110
	v_fmac_f32_e32 v111, v103, v103
	v_add_f32_e32 v108, v108, v110
	v_add_f32_e32 v109, v109, v111
	v_cvt_pk_bf16_f32 v100, v100, v101
	v_cvt_pk_bf16_f32 v101, v102, v103
	v_pk_fma_f32 v[106:107], v[208:209], v[106:107], v[212:213]
	v_pk_fma_f32 v[104:105], v[210:211], v[104:105], v[214:215]
	v_pk_fma_f32 v[96:97], v[106:107], s[24:25], v[96:97] op_sel_hi:[1,0,1]
	v_pk_fma_f32 v[98:99], v[104:105], s[24:25], v[98:99] op_sel_hi:[1,0,1]
	v_pk_add_f32 v[104:105], v[250:251], v[96:97]
	v_pk_add_f32 v[106:107], v[252:253], v[98:99]
	v_mul_f32_e32 v97, v105, v105
	v_add_f32_e32 v96, v104, v105
	v_fmac_f32_e32 v97, v104, v104
	v_add_f32_e32 v96, v106, v96
	v_fmac_f32_e32 v97, v106, v106
	v_add_f32_e32 v96, v107, v96
	v_fmac_f32_e32 v97, v107, v107
	v_add_f32_e32 v96, v108, v96
	v_add_f32_e32 v97, v109, v97
	ds_bpermute_b32 v98, v118, v96
	ds_bpermute_b32 v99, v118, v97
	global_store_dwordx4 v[114:115], v[104:107], off offset:528
	v_cvt_pk_bf16_f32 v102, v104, v105
	v_cvt_pk_bf16_f32 v103, v106, v107
	s_waitcnt lgkmcnt(0)
	v_add_f32_e32 v96, v96, v98
	v_add_f32_e32 v97, v97, v99
	ds_bpermute_b32 v98, v119, v96
	ds_bpermute_b32 v99, v119, v97
	flat_store_dwordx4 v[166:167], v[100:103] offset:256
	s_mov_b32 s100, -1
	s_mov_b32 s101, 0
	s_mov_b32 s98, 0xffff0000
	s_mov_b32 s99, 0
	s_and_saveexec_b64 s[36:37], s[100:101]
	s_cbranch_execz .LBB0_2640
	v_lshl_add_u64 v[100:101], s[8:9], 0, v[112:113]
	s_waitcnt lgkmcnt(0)
	v_add_f32_e32 v96, v96, v98
	v_add_f32_e32 v97, v97, v99
	v_cndmask_b32_e64 v96, v96, v97, s[98:99]
	v_cndmask_b32_e64 v97, 0, 4, s[98:99]
	v_or_b32_e32 v100, v100, v97
	flat_atomic_add_f32 v[100:101], v96
; DEVI unsigned pk2(float lo, float hi) { unsigned r; asm("v_cvt_pk_bf16_f32 %0, %1, %2" : "=v"(r) : "v"(lo), "v"(hi)); return r; }
;     DEVI void operator()(const f32x4 (&acc)[2][2][4][2], const pg8::Unit& u, int wr, int wc, int fr, int fq) const {
;     ...
;                 const int row = row0 + ai * 128 + m * 16; float mu, rs; row_stats(stin, row, mu, rs);
;                 float sum = 0.f, sq = 0.f;
; #pragma unroll
;                 for (int bj = 0; bj < 2; ++bj) {
;                     f32x4 z[2];
; #pragma unroll
;                     for (int n = 0; n < 2; ++n) {
;                         const int col = colb + bj * 128 + 4 * n;
;                         f32x4 xv = *(const f32x4*)(zsrc + (size_t)row * DM + col);
;                         if (stin) { const f32x4 gv = *(const f32x4*)(gin + col), bv = *(const f32x4*)(bin + col); xv = (xv - mu) * rs * gv + bv; }
;                         f32x4 zz = ALPHA * xv + acc[ai][bj][m][n];
;                         if (bias) zz += *(const f32x4*)(bias + col);
;                         *(f32x4*)(zdst + (size_t)row * DM + col) = zz;
;                         sum += zz[0] + zz[1] + zz[2] + zz[3]; sq += zz[0] * zz[0] + zz[1] * zz[1] + zz[2] * zz[2] + zz[3] * zz[3];
;                         z[n] = zz;
;                     }
;                     u32x4 o; o.x = pk2(z[0][0], z[0][1]); o.y = pk2(z[0][2], z[0][3]); o.z = pk2(z[1][0], z[1][1]); o.w = pk2(z[1][2], z[1][3]);
;                     if (zb) *(u32x4*)(zb + (size_t)row * DM + colb + bj * 128) = o;
;                 }
;                 sum += __shfl_xor(sum, 16); sq += __shfl_xor(sq, 16);
;                 sum += __shfl_xor(sum, 32); sq += __shfl_xor(sq, 32);
;                 if (fq == 0) { atomicAdd(stout + 2 * (size_t)row, sum); atomicAdd(stout + 2 * (size_t)row + 1, sq); }
.LBB0_2640:
	s_or_b64 exec, exec, s[36:37]
	v_or_b32_e32 v166, 32, v154
	v_ashrrev_i32_e32 v167, 31, v166
	v_lshlrev_b64 v[96:97], 3, v[166:167]
	s_waitcnt lgkmcnt(0)
	v_lshl_add_u64 v[98:99], s[6:7], 0, v[96:97]
	flat_load_dwordx2 v[176:177], v[98:99]
	v_lshlrev_b64 v[98:99], 12, v[166:167]
	v_lshl_add_u64 v[98:99], s[46:47], 0, v[98:99]
	v_lshl_add_u64 v[98:99], v[144:145], 2, v[98:99]
	global_load_dwordx4 v[100:103], v[98:99], off
	global_load_dwordx4 v[104:107], v[150:151], off
	global_load_dwordx4 v[108:111], v[152:153], off
	global_load_dwordx4 v[112:115], v[156:157], off
	global_load_dwordx4 v[162:165], v[98:99], off offset:16
	global_load_dwordx4 v[208:211], v[146:147], off
	global_load_dwordx4 v[212:215], v[148:149], off
	global_load_dwordx4 v[250:253], v[124:125], off
	s_waitcnt vmcnt(0) lgkmcnt(0)
	v_pk_mul_f32 v[176:177], v[176:177], s[22:23] op_sel:[1,0] op_sel_hi:[0,0]
	v_fma_f32 v155, -v177, v177, v176
	v_max_f32_e32 v155, 0, v155
	v_add_f32_e32 v155, 0x3727c5ac, v155
	v_mul_f32_e32 v175, 0x4b800000, v155
	v_cmp_gt_f32_e32 vcc, s64, v155
	v_sub_f32_e32 v103, v103, v177
	v_sub_f32_e32 v102, v102, v177
	v_cndmask_b32_e32 v155, v155, v175, vcc
	v_rsq_f32_e32 v155, v155
	v_sub_f32_e32 v101, v101, v177
	v_sub_f32_e32 v100, v100, v177
	v_mul_f32_e32 v175, 0x45800000, v155
	v_cndmask_b32_e32 v176, v155, v175, vcc
	v_pk_mul_f32 v[100:101], v[100:101], v[176:177] op_sel_hi:[1,0]
	v_pk_mul_f32 v[102:103], v[102:103], v[176:177] op_sel_hi:[1,0]
	v_pk_fma_f32 v[100:101], v[104:105], v[100:101], v[108:109]
	v_pk_fma_f32 v[102:103], v[106:107], v[102:103], v[110:111]
	v_pk_fma_f32 v[92:93], v[100:101], s[24:25], v[92:93] op_sel_hi:[1,0,1]
	v_pk_fma_f32 v[94:95], v[102:103], s[24:25], v[94:95] op_sel_hi:[1,0,1]
	v_pk_add_f32 v[92:93], v[112:113], v[92:93]
	v_pk_add_f32 v[94:95], v[114:115], v[94:95]
	global_store_dwordx4 v[98:99], v[92:95], off
	v_lshlrev_b64 v[112:113], 11, v[166:167]
	v_lshl_add_u64 v[112:113], s[10:11], 0, v[112:113]
	v_lshl_add_u64 v[166:167], v[144:145], 1, v[112:113]
	v_sub_f32_e32 v113, v165, v177
	v_sub_f32_e32 v112, v164, v177
	v_sub_f32_e32 v115, v163, v177
	v_sub_f32_e32 v114, v162, v177
	v_pk_mul_f32 v[114:115], v[114:115], v[176:177] op_sel_hi:[1,0]
	v_pk_mul_f32 v[162:163], v[112:113], v[176:177] op_sel_hi:[1,0]
	v_cvt_pk_bf16_f32 v112, v92, v93
	v_cvt_pk_bf16_f32 v113, v94, v95
	v_pk_fma_f32 v[100:101], v[208:209], v[114:115], v[212:213]
	v_pk_fma_f32 v[102:103], v[210:211], v[162:163], v[214:215]
	v_pk_fma_f32 v[88:89], v[100:101], s[24:25], v[88:89] op_sel_hi:[1,0,1]
	v_pk_fma_f32 v[90:91], v[102:103], s[24:25], v[90:91] op_sel_hi:[1,0,1]
	v_pk_add_f32 v[88:89], v[250:251], v[88:89]
	v_pk_add_f32 v[90:91], v[252:253], v[90:91]
	global_store_dwordx4 v[98:99], v[88:91], off offset:16
	v_cvt_pk_bf16_f32 v114, v88, v89
	v_cvt_pk_bf16_f32 v115, v90, v91
	flat_store_dwordx4 v[166:167], v[112:115]
	global_load_dwordx4 v[100:103], v[98:99], off offset:512
	global_load_dwordx4 v[104:107], v[126:127], off
	global_load_dwordx4 v[108:111], v[158:159], off
	s_nop 0
	global_load_dwordx4 v[112:115], v[160:161], off
	global_load_dwordx4 v[162:165], v[98:99], off offset:528
	global_load_dwordx4 v[208:211], v[120:121], off
	global_load_dwordx4 v[212:215], v[122:123], off
	global_load_dwordx4 v[250:253], v[116:117], off
	s_waitcnt vmcnt(0)
	v_sub_f32_e32 v103, v103, v177
	v_sub_f32_e32 v102, v102, v177
	v_sub_f32_e32 v101, v101, v177
	v_sub_f32_e32 v100, v100, v177
	v_pk_mul_f32 v[100:101], v[176:177], v[100:101] op_sel_hi:[0,1]
	v_pk_mul_f32 v[102:103], v[176:177], v[102:103] op_sel_hi:[0,1]
	v_pk_fma_f32 v[102:103], v[106:107], v[102:103], v[110:111]
	v_pk_fma_f32 v[100:101], v[104:105], v[100:101], v[108:109]
	v_pk_fma_f32 v[86:87], v[102:103], s[24:25], v[86:87] op_sel_hi:[1,0,1]
	v_pk_fma_f32 v[84:85], v[100:101], s[24:25], v[84:85] op_sel_hi:[1,0,1]
	v_pk_add_f32 v[86:87], v[114:115], v[86:87]
	v_pk_add_f32 v[84:85], v[112:113], v[84:85]
	global_store_dwordx4 v[98:99], v[84:87], off offset:512
	v_add_f32_e32 v112, v92, v93
	v_mul_f32_e32 v93, v93, v93
	v_fmac_f32_e32 v93, v92, v92
	v_add_f32_e32 v112, v94, v112
	v_fmac_f32_e32 v93, v94, v94
	v_add_f32_e32 v94, v88, v89
	v_mul_f32_e32 v89, v89, v89
	v_fmac_f32_e32 v89, v88, v88
	v_add_f32_e32 v92, v95, v112
	v_add_f32_e32 v94, v90, v94
	v_fmac_f32_e32 v89, v90, v90
	v_add_f32_e32 v92, 0, v92
	v_fmac_f32_e32 v93, v95, v95
	v_add_f32_e32 v88, v91, v94
	v_fmac_f32_e32 v89, v91, v91
	v_sub_f32_e32 v91, v163, v177
	v_sub_f32_e32 v90, v162, v177
	v_add_f32_e32 v92, v88, v92
	v_add_f32_e32 v93, v93, v89
	v_sub_f32_e32 v89, v165, v177
	v_sub_f32_e32 v88, v164, v177
	v_pk_mul_f32 v[90:91], v[176:177], v[90:91] op_sel_hi:[0,1]
	v_pk_mul_f32 v[88:89], v[176:177], v[88:89] op_sel_hi:[0,1]
	v_mul_f32_e32 v95, v85, v85
	v_add_f32_e32 v94, v84, v85
	v_fmac_f32_e32 v95, v84, v84
	v_add_f32_e32 v94, v86, v94
	v_fmac_f32_e32 v95, v86, v86
	v_add_f32_e32 v94, v87, v94
	v_fmac_f32_e32 v95, v87, v87
	v_add_f32_e32 v92, v92, v94
	v_add_f32_e32 v93, v93, v95
	v_cvt_pk_bf16_f32 v84, v84, v85
	v_cvt_pk_bf16_f32 v85, v86, v87
	v_pk_fma_f32 v[90:91], v[208:209], v[90:91], v[212:213]
	v_pk_fma_f32 v[88:89], v[210:211], v[88:89], v[214:215]
	v_pk_fma_f32 v[80:81], v[90:91], s[24:25], v[80:81] op_sel_hi:[1,0,1]
	v_pk_fma_f32 v[82:83], v[88:89], s[24:25], v[82:83] op_sel_hi:[1,0,1]
	v_pk_add_f32 v[88:89], v[250:251], v[80:81]
	v_pk_add_f32 v[90:91], v[252:253], v[82:83]
	v_mul_f32_e32 v81, v89, v89
	v_add_f32_e32 v80, v88, v89
	v_fmac_f32_e32 v81, v88, v88
	v_add_f32_e32 v80, v90, v80
	v_fmac_f32_e32 v81, v90, v90
	v_add_f32_e32 v80, v91, v80
	v_fmac_f32_e32 v81, v91, v91
	v_add_f32_e32 v80, v92, v80
	v_add_f32_e32 v81, v93, v81
	ds_bpermute_b32 v82, v118, v80
	ds_bpermute_b32 v83, v118, v81
	global_store_dwordx4 v[98:99], v[88:91], off offset:528
	v_cvt_pk_bf16_f32 v86, v88, v89
	v_cvt_pk_bf16_f32 v87, v90, v91
	s_waitcnt lgkmcnt(0)
	v_add_f32_e32 v80, v80, v82
	v_add_f32_e32 v81, v81, v83
	ds_bpermute_b32 v82, v119, v80
	ds_bpermute_b32 v83, v119, v81
	flat_store_dwordx4 v[166:167], v[84:87] offset:256
	s_mov_b32 s100, -1
	s_mov_b32 s101, 0
	s_mov_b32 s98, 0xffff0000
	s_mov_b32 s99, 0
	s_and_saveexec_b64 s[36:37], s[100:101]
	s_cbranch_execz .LBB0_2642
	v_lshl_add_u64 v[84:85], s[8:9], 0, v[96:97]
	s_waitcnt lgkmcnt(0)
	v_add_f32_e32 v80, v80, v82
	v_add_f32_e32 v81, v81, v83
	v_cndmask_b32_e64 v80, v80, v81, s[98:99]
	v_cndmask_b32_e64 v81, 0, 4, s[98:99]
	v_or_b32_e32 v84, v84, v81
	flat_atomic_add_f32 v[84:85], v80
; DEVI unsigned pk2(float lo, float hi) { unsigned r; asm("v_cvt_pk_bf16_f32 %0, %1, %2" : "=v"(r) : "v"(lo), "v"(hi)); return r; }
;     DEVI void operator()(const f32x4 (&acc)[2][2][4][2], const pg8::Unit& u, int wr, int wc, int fr, int fq) const {
;     ...
;                 const int row = row0 + ai * 128 + m * 16; float mu, rs; row_stats(stin, row, mu, rs);
;                 float sum = 0.f, sq = 0.f;
; #pragma unroll
;                 for (int bj = 0; bj < 2; ++bj) {
;                     f32x4 z[2];
; #pragma unroll
;                     for (int n = 0; n < 2; ++n) {
;                         const int col = colb + bj * 128 + 4 * n;
;                         f32x4 xv = *(const f32x4*)(zsrc + (size_t)row * DM + col);
;                         if (stin) { const f32x4 gv = *(const f32x4*)(gin + col), bv = *(const f32x4*)(bin + col); xv = (xv - mu) * rs * gv + bv; }
;                         f32x4 zz = ALPHA * xv + acc[ai][bj][m][n];
;                         if (bias) zz += *(const f32x4*)(bias + col);
;                         *(f32x4*)(zdst + (size_t)row * DM + col) = zz;
;                         sum += zz[0] + zz[1] + zz[2] + zz[3]; sq += zz[0] * zz[0] + zz[1] * zz[1] + zz[2] * zz[2] + zz[3] * zz[3];
;                         z[n] = zz;
;                     }
;                     u32x4 o; o.x = pk2(z[0][0], z[0][1]); o.y = pk2(z[0][2], z[0][3]); o.z = pk2(z[1][0], z[1][1]); o.w = pk2(z[1][2], z[1][3]);
;                     if (zb) *(u32x4*)(zb + (size_t)row * DM + colb + bj * 128) = o;
;                 }
;                 sum += __shfl_xor(sum, 16); sq += __shfl_xor(sq, 16);
;                 sum += __shfl_xor(sum, 32); sq += __shfl_xor(sq, 32);
;                 if (fq == 0) { atomicAdd(stout + 2 * (size_t)row, sum); atomicAdd(stout + 2 * (size_t)row + 1, sq); }
.LBB0_2642:
	s_or_b64 exec, exec, s[36:37]
	v_or_b32_e32 v104, 48, v154
	v_ashrrev_i32_e32 v105, 31, v104
	v_lshlrev_b64 v[80:81], 3, v[104:105]
	s_waitcnt lgkmcnt(0)
	v_lshl_add_u64 v[82:83], s[6:7], 0, v[80:81]
	flat_load_dwordx2 v[106:107], v[82:83]
	v_lshlrev_b64 v[82:83], 12, v[104:105]
	v_lshl_add_u64 v[82:83], s[46:47], 0, v[82:83]
	v_lshl_add_u64 v[82:83], v[144:145], 2, v[82:83]
	global_load_dwordx4 v[84:87], v[82:83], off
	global_load_dwordx4 v[88:91], v[150:151], off
	global_load_dwordx4 v[92:95], v[152:153], off
	global_load_dwordx4 v[96:99], v[156:157], off
	global_load_dwordx4 v[100:103], v[82:83], off offset:16
	global_load_dwordx4 v[208:211], v[146:147], off
	global_load_dwordx4 v[212:215], v[148:149], off
	global_load_dwordx4 v[250:253], v[124:125], off
	s_waitcnt vmcnt(0) lgkmcnt(0)
	v_pk_mul_f32 v[106:107], v[106:107], s[22:23] op_sel:[1,0] op_sel_hi:[0,0]
	v_fma_f32 v106, -v107, v107, v106
	v_max_f32_e32 v106, 0, v106
	v_add_f32_e32 v106, 0x3727c5ac, v106
	v_mul_f32_e32 v108, 0x4b800000, v106
	v_cmp_gt_f32_e32 vcc, s64, v106
	v_sub_f32_e32 v87, v87, v107
	v_sub_f32_e32 v86, v86, v107
	v_cndmask_b32_e32 v106, v106, v108, vcc
	v_rsq_f32_e32 v106, v106
	v_sub_f32_e32 v85, v85, v107
	v_sub_f32_e32 v84, v84, v107
	v_mul_f32_e32 v108, 0x45800000, v106
	v_cndmask_b32_e32 v106, v106, v108, vcc
	v_pk_mul_f32 v[84:85], v[84:85], v[106:107] op_sel_hi:[1,0]
	v_pk_mul_f32 v[86:87], v[86:87], v[106:107] op_sel_hi:[1,0]
	v_pk_fma_f32 v[84:85], v[88:89], v[84:85], v[92:93]
	v_pk_fma_f32 v[86:87], v[90:91], v[86:87], v[94:95]
	v_pk_fma_f32 v[76:77], v[84:85], s[24:25], v[76:77] op_sel_hi:[1,0,1]
	v_pk_fma_f32 v[78:79], v[86:87], s[24:25], v[78:79] op_sel_hi:[1,0,1]
	v_pk_add_f32 v[76:77], v[96:97], v[76:77]
	v_pk_add_f32 v[78:79], v[98:99], v[78:79]
	global_store_dwordx4 v[82:83], v[76:79], off
	v_lshlrev_b64 v[96:97], 11, v[104:105]
	v_lshl_add_u64 v[96:97], s[10:11], 0, v[96:97]
	v_lshl_add_u64 v[104:105], v[144:145], 1, v[96:97]
	v_sub_f32_e32 v97, v103, v107
	v_sub_f32_e32 v96, v102, v107
	v_sub_f32_e32 v99, v101, v107
	v_sub_f32_e32 v98, v100, v107
	v_pk_mul_f32 v[98:99], v[98:99], v[106:107] op_sel_hi:[1,0]
	v_pk_mul_f32 v[100:101], v[96:97], v[106:107] op_sel_hi:[1,0]
	v_cvt_pk_bf16_f32 v96, v76, v77
	v_cvt_pk_bf16_f32 v97, v78, v79
	v_pk_fma_f32 v[84:85], v[208:209], v[98:99], v[212:213]
	v_pk_fma_f32 v[86:87], v[210:211], v[100:101], v[214:215]
	v_pk_fma_f32 v[72:73], v[84:85], s[24:25], v[72:73] op_sel_hi:[1,0,1]
	v_pk_fma_f32 v[74:75], v[86:87], s[24:25], v[74:75] op_sel_hi:[1,0,1]
	v_pk_add_f32 v[72:73], v[250:251], v[72:73]
	v_pk_add_f32 v[74:75], v[252:253], v[74:75]
	global_store_dwordx4 v[82:83], v[72:75], off offset:16
	v_cvt_pk_bf16_f32 v98, v72, v73
	v_cvt_pk_bf16_f32 v99, v74, v75
	flat_store_dwordx4 v[104:105], v[96:99]
	global_load_dwordx4 v[84:87], v[82:83], off offset:512
	global_load_dwordx4 v[88:91], v[126:127], off
	global_load_dwordx4 v[92:95], v[158:159], off
	s_nop 0
	global_load_dwordx4 v[96:99], v[160:161], off
	global_load_dwordx4 v[100:103], v[82:83], off offset:528
	global_load_dwordx4 v[208:211], v[120:121], off
	global_load_dwordx4 v[212:215], v[122:123], off
	global_load_dwordx4 v[250:253], v[116:117], off
	s_waitcnt vmcnt(0)
	v_sub_f32_e32 v87, v87, v107
	v_sub_f32_e32 v86, v86, v107
	v_sub_f32_e32 v85, v85, v107
	v_sub_f32_e32 v84, v84, v107
	v_pk_mul_f32 v[84:85], v[106:107], v[84:85] op_sel_hi:[0,1]
	v_pk_mul_f32 v[86:87], v[106:107], v[86:87] op_sel_hi:[0,1]
	v_pk_fma_f32 v[86:87], v[90:91], v[86:87], v[94:95]
	v_pk_fma_f32 v[84:85], v[88:89], v[84:85], v[92:93]
	v_pk_fma_f32 v[70:71], v[86:87], s[24:25], v[70:71] op_sel_hi:[1,0,1]
	v_pk_fma_f32 v[68:69], v[84:85], s[24:25], v[68:69] op_sel_hi:[1,0,1]
	v_pk_add_f32 v[70:71], v[98:99], v[70:71]
	v_pk_add_f32 v[68:69], v[96:97], v[68:69]
	global_store_dwordx4 v[82:83], v[68:71], off offset:512
	v_add_f32_e32 v96, v76, v77
	v_mul_f32_e32 v77, v77, v77
	v_fmac_f32_e32 v77, v76, v76
	v_add_f32_e32 v96, v78, v96
	v_fmac_f32_e32 v77, v78, v78
	v_add_f32_e32 v78, v72, v73
	v_mul_f32_e32 v73, v73, v73
	v_fmac_f32_e32 v73, v72, v72
	v_add_f32_e32 v76, v79, v96
	v_add_f32_e32 v78, v74, v78
	v_fmac_f32_e32 v73, v74, v74
	v_add_f32_e32 v76, 0, v76
	v_fmac_f32_e32 v77, v79, v79
	v_add_f32_e32 v72, v75, v78
	v_fmac_f32_e32 v73, v75, v75
	v_sub_f32_e32 v75, v101, v107
	v_sub_f32_e32 v74, v100, v107
	v_add_f32_e32 v76, v72, v76
	v_add_f32_e32 v77, v77, v73
	v_sub_f32_e32 v73, v103, v107
	v_sub_f32_e32 v72, v102, v107
	v_pk_mul_f32 v[74:75], v[106:107], v[74:75] op_sel_hi:[0,1]
	v_pk_mul_f32 v[72:73], v[106:107], v[72:73] op_sel_hi:[0,1]
	v_mul_f32_e32 v79, v69, v69
	v_add_f32_e32 v78, v68, v69
	v_fmac_f32_e32 v79, v68, v68
	v_add_f32_e32 v78, v70, v78
	v_fmac_f32_e32 v79, v70, v70
	v_add_f32_e32 v78, v71, v78
	v_fmac_f32_e32 v79, v71, v71
	v_add_f32_e32 v76, v76, v78
	v_add_f32_e32 v77, v77, v79
	v_cvt_pk_bf16_f32 v68, v68, v69
	v_cvt_pk_bf16_f32 v69, v70, v71
	v_pk_fma_f32 v[74:75], v[208:209], v[74:75], v[212:213]
	v_pk_fma_f32 v[72:73], v[210:211], v[72:73], v[214:215]
	v_pk_fma_f32 v[64:65], v[74:75], s[24:25], v[64:65] op_sel_hi:[1,0,1]
	v_pk_fma_f32 v[66:67], v[72:73], s[24:25], v[66:67] op_sel_hi:[1,0,1]
	v_pk_add_f32 v[72:73], v[250:251], v[64:65]
	v_pk_add_f32 v[74:75], v[252:253], v[66:67]
	v_mul_f32_e32 v65, v73, v73
	v_add_f32_e32 v64, v72, v73
	v_fmac_f32_e32 v65, v72, v72
	v_add_f32_e32 v64, v74, v64
	v_fmac_f32_e32 v65, v74, v74
	v_add_f32_e32 v64, v75, v64
	v_fmac_f32_e32 v65, v75, v75
	v_add_f32_e32 v64, v76, v64
	v_add_f32_e32 v65, v77, v65
	ds_bpermute_b32 v66, v118, v64
	ds_bpermute_b32 v67, v118, v65
	global_store_dwordx4 v[82:83], v[72:75], off offset:528
	v_cvt_pk_bf16_f32 v70, v72, v73
	v_cvt_pk_bf16_f32 v71, v74, v75
	s_waitcnt lgkmcnt(0)
	v_add_f32_e32 v64, v64, v66
	v_add_f32_e32 v65, v65, v67
	ds_bpermute_b32 v66, v119, v64
	ds_bpermute_b32 v67, v119, v65
	flat_store_dwordx4 v[104:105], v[68:71] offset:256
	s_mov_b32 s100, -1
	s_mov_b32 s101, 0
	s_mov_b32 s98, 0xffff0000
	s_mov_b32 s99, 0
	s_and_saveexec_b64 s[36:37], s[100:101]
	s_cbranch_execz .LBB0_2644
	v_lshl_add_u64 v[68:69], s[8:9], 0, v[80:81]
	s_waitcnt lgkmcnt(0)
	v_add_f32_e32 v64, v64, v66
	v_add_f32_e32 v65, v65, v67
	v_cndmask_b32_e64 v64, v64, v65, s[98:99]
	v_cndmask_b32_e64 v65, 0, 4, s[98:99]
	v_or_b32_e32 v68, v68, v65
	flat_atomic_add_f32 v[68:69], v64
; DEVI unsigned pk2(float lo, float hi) { unsigned r; asm("v_cvt_pk_bf16_f32 %0, %1, %2" : "=v"(r) : "v"(lo), "v"(hi)); return r; }
;     DEVI void operator()(const f32x4 (&acc)[2][2][4][2], const pg8::Unit& u, int wr, int wc, int fr, int fq) const {
;     ...
;                 const int row = row0 + ai * 128 + m * 16; float mu, rs; row_stats(stin, row, mu, rs);
;                 float sum = 0.f, sq = 0.f;
; #pragma unroll
;                 for (int bj = 0; bj < 2; ++bj) {
;                     f32x4 z[2];
; #pragma unroll
;                     for (int n = 0; n < 2; ++n) {
;                         const int col = colb + bj * 128 + 4 * n;
;                         f32x4 xv = *(const f32x4*)(zsrc + (size_t)row * DM + col);
;                         if (stin) { const f32x4 gv = *(const f32x4*)(gin + col), bv = *(const f32x4*)(bin + col); xv = (xv - mu) * rs * gv + bv; }
;                         f32x4 zz = ALPHA * xv + acc[ai][bj][m][n];
;                         if (bias) zz += *(const f32x4*)(bias + col);
;                         *(f32x4*)(zdst + (size_t)row * DM + col) = zz;
;                         sum += zz[0] + zz[1] + zz[2] + zz[3]; sq += zz[0] * zz[0] + zz[1] * zz[1] + zz[2] * zz[2] + zz[3] * zz[3];
;                         z[n] = zz;
;                     }
;                     u32x4 o; o.x = pk2(z[0][0], z[0][1]); o.y = pk2(z[0][2], z[0][3]); o.z = pk2(z[1][0], z[1][1]); o.w = pk2(z[1][2], z[1][3]);
;                     if (zb) *(u32x4*)(zb + (size_t)row * DM + colb + bj * 128) = o;
;                 }
;                 sum += __shfl_xor(sum, 16); sq += __shfl_xor(sq, 16);
;                 sum += __shfl_xor(sum, 32); sq += __shfl_xor(sq, 32);
;                 if (fq == 0) { atomicAdd(stout + 2 * (size_t)row, sum); atomicAdd(stout + 2 * (size_t)row + 1, sq); }
.LBB0_2644:
	s_or_b64 exec, exec, s[36:37]
	v_add_u32_e32 v88, 0x80, v154
	v_ashrrev_i32_e32 v89, 31, v88
	v_lshlrev_b64 v[64:65], 3, v[88:89]
	s_waitcnt lgkmcnt(0)
	v_lshl_add_u64 v[66:67], s[6:7], 0, v[64:65]
	flat_load_dwordx2 v[90:91], v[66:67]
	v_lshlrev_b64 v[66:67], 12, v[88:89]
	v_lshl_add_u64 v[66:67], s[46:47], 0, v[66:67]
	v_lshl_add_u64 v[66:67], v[144:145], 2, v[66:67]
	global_load_dwordx4 v[68:71], v[66:67], off
	global_load_dwordx4 v[72:75], v[150:151], off
	global_load_dwordx4 v[76:79], v[152:153], off
	global_load_dwordx4 v[80:83], v[156:157], off
	global_load_dwordx4 v[84:87], v[66:67], off offset:16
	global_load_dwordx4 v[208:211], v[146:147], off
	global_load_dwordx4 v[212:215], v[148:149], off
	global_load_dwordx4 v[250:253], v[124:125], off
	s_waitcnt vmcnt(0) lgkmcnt(0)
	v_pk_mul_f32 v[90:91], v[90:91], s[22:23] op_sel:[1,0] op_sel_hi:[0,0]
	v_fma_f32 v90, -v91, v91, v90
	v_max_f32_e32 v90, 0, v90
	v_add_f32_e32 v90, 0x3727c5ac, v90
	v_mul_f32_e32 v92, 0x4b800000, v90
	v_cmp_gt_f32_e32 vcc, s64, v90
	v_sub_f32_e32 v71, v71, v91
	v_sub_f32_e32 v70, v70, v91
	v_cndmask_b32_e32 v90, v90, v92, vcc
	v_rsq_f32_e32 v90, v90
	v_sub_f32_e32 v69, v69, v91
	v_sub_f32_e32 v68, v68, v91
	v_mul_f32_e32 v92, 0x45800000, v90
	v_cndmask_b32_e32 v90, v90, v92, vcc
	v_pk_mul_f32 v[68:69], v[68:69], v[90:91] op_sel_hi:[1,0]
	v_pk_mul_f32 v[70:71], v[70:71], v[90:91] op_sel_hi:[1,0]
	v_pk_fma_f32 v[68:69], v[72:73], v[68:69], v[76:77]
	v_pk_fma_f32 v[70:71], v[74:75], v[70:71], v[78:79]
	v_pk_fma_f32 v[60:61], v[68:69], s[24:25], v[60:61] op_sel_hi:[1,0,1]
	v_pk_fma_f32 v[62:63], v[70:71], s[24:25], v[62:63] op_sel_hi:[1,0,1]
	v_pk_add_f32 v[60:61], v[80:81], v[60:61]
	v_pk_add_f32 v[62:63], v[82:83], v[62:63]
	global_store_dwordx4 v[66:67], v[60:63], off
	v_lshlrev_b64 v[80:81], 11, v[88:89]
	v_lshl_add_u64 v[80:81], s[10:11], 0, v[80:81]
	v_lshl_add_u64 v[88:89], v[144:145], 1, v[80:81]
	v_sub_f32_e32 v81, v87, v91
	v_sub_f32_e32 v80, v86, v91
	v_sub_f32_e32 v83, v85, v91
	v_sub_f32_e32 v82, v84, v91
	v_pk_mul_f32 v[82:83], v[82:83], v[90:91] op_sel_hi:[1,0]
	v_pk_mul_f32 v[84:85], v[80:81], v[90:91] op_sel_hi:[1,0]
	v_cvt_pk_bf16_f32 v80, v60, v61
	v_cvt_pk_bf16_f32 v81, v62, v63
	v_pk_fma_f32 v[68:69], v[208:209], v[82:83], v[212:213]
	v_pk_fma_f32 v[70:71], v[210:211], v[84:85], v[214:215]
	v_pk_fma_f32 v[56:57], v[68:69], s[24:25], v[56:57] op_sel_hi:[1,0,1]
	v_pk_fma_f32 v[58:59], v[70:71], s[24:25], v[58:59] op_sel_hi:[1,0,1]
	v_pk_add_f32 v[56:57], v[250:251], v[56:57]
	v_pk_add_f32 v[58:59], v[252:253], v[58:59]
	global_store_dwordx4 v[66:67], v[56:59], off offset:16
	v_cvt_pk_bf16_f32 v82, v56, v57
	v_cvt_pk_bf16_f32 v83, v58, v59
	flat_store_dwordx4 v[88:89], v[80:83]
	global_load_dwordx4 v[68:71], v[66:67], off offset:512
	global_load_dwordx4 v[72:75], v[126:127], off
	global_load_dwordx4 v[76:79], v[158:159], off
	s_nop 0
	global_load_dwordx4 v[80:83], v[160:161], off
	global_load_dwordx4 v[84:87], v[66:67], off offset:528
	global_load_dwordx4 v[208:211], v[120:121], off
	global_load_dwordx4 v[212:215], v[122:123], off
	global_load_dwordx4 v[250:253], v[116:117], off
	s_waitcnt vmcnt(0)
	v_sub_f32_e32 v71, v71, v91
	v_sub_f32_e32 v70, v70, v91
	v_sub_f32_e32 v69, v69, v91
	v_sub_f32_e32 v68, v68, v91
	v_pk_mul_f32 v[68:69], v[90:91], v[68:69] op_sel_hi:[0,1]
	v_pk_mul_f32 v[70:71], v[90:91], v[70:71] op_sel_hi:[0,1]
	v_pk_fma_f32 v[70:71], v[74:75], v[70:71], v[78:79]
	v_pk_fma_f32 v[68:69], v[72:73], v[68:69], v[76:77]
	v_pk_fma_f32 v[54:55], v[70:71], s[24:25], v[54:55] op_sel_hi:[1,0,1]
	v_pk_fma_f32 v[52:53], v[68:69], s[24:25], v[52:53] op_sel_hi:[1,0,1]
	v_pk_add_f32 v[54:55], v[82:83], v[54:55]
	v_pk_add_f32 v[52:53], v[80:81], v[52:53]
	global_store_dwordx4 v[66:67], v[52:55], off offset:512
	v_add_f32_e32 v80, v60, v61
	v_mul_f32_e32 v61, v61, v61
	v_fmac_f32_e32 v61, v60, v60
	v_add_f32_e32 v80, v62, v80
	v_fmac_f32_e32 v61, v62, v62
	v_add_f32_e32 v62, v56, v57
	v_mul_f32_e32 v57, v57, v57
	v_fmac_f32_e32 v57, v56, v56
	v_add_f32_e32 v60, v63, v80
	v_add_f32_e32 v62, v58, v62
	v_fmac_f32_e32 v57, v58, v58
	v_add_f32_e32 v60, 0, v60
	v_fmac_f32_e32 v61, v63, v63
	v_add_f32_e32 v56, v59, v62
	v_fmac_f32_e32 v57, v59, v59
	v_sub_f32_e32 v59, v85, v91
	v_sub_f32_e32 v58, v84, v91
	v_add_f32_e32 v60, v56, v60
	v_add_f32_e32 v61, v61, v57
	v_sub_f32_e32 v57, v87, v91
	v_sub_f32_e32 v56, v86, v91
	v_pk_mul_f32 v[58:59], v[90:91], v[58:59] op_sel_hi:[0,1]
	v_pk_mul_f32 v[56:57], v[90:91], v[56:57] op_sel_hi:[0,1]
	v_mul_f32_e32 v63, v53, v53
	v_add_f32_e32 v62, v52, v53
	v_fmac_f32_e32 v63, v52, v52
	v_add_f32_e32 v62, v54, v62
	v_fmac_f32_e32 v63, v54, v54
	v_add_f32_e32 v62, v55, v62
	v_fmac_f32_e32 v63, v55, v55
	v_add_f32_e32 v60, v60, v62
	v_add_f32_e32 v61, v61, v63
	v_cvt_pk_bf16_f32 v52, v52, v53
	v_cvt_pk_bf16_f32 v53, v54, v55
	v_pk_fma_f32 v[58:59], v[208:209], v[58:59], v[212:213]
	v_pk_fma_f32 v[56:57], v[210:211], v[56:57], v[214:215]
	v_pk_fma_f32 v[48:49], v[58:59], s[24:25], v[48:49] op_sel_hi:[1,0,1]
	v_pk_fma_f32 v[50:51], v[56:57], s[24:25], v[50:51] op_sel_hi:[1,0,1]
	v_pk_add_f32 v[56:57], v[250:251], v[48:49]
	v_pk_add_f32 v[58:59], v[252:253], v[50:51]
	v_mul_f32_e32 v49, v57, v57
	v_add_f32_e32 v48, v56, v57
	v_fmac_f32_e32 v49, v56, v56
	v_add_f32_e32 v48, v58, v48
	v_fmac_f32_e32 v49, v58, v58
	v_add_f32_e32 v48, v59, v48
	v_fmac_f32_e32 v49, v59, v59
	v_add_f32_e32 v48, v60, v48
	v_add_f32_e32 v49, v61, v49
	ds_bpermute_b32 v50, v118, v48
	ds_bpermute_b32 v51, v118, v49
	global_store_dwordx4 v[66:67], v[56:59], off offset:528
	v_cvt_pk_bf16_f32 v54, v56, v57
	v_cvt_pk_bf16_f32 v55, v58, v59
	s_waitcnt lgkmcnt(0)
	v_add_f32_e32 v48, v48, v50
	v_add_f32_e32 v49, v49, v51
	ds_bpermute_b32 v50, v119, v48
	ds_bpermute_b32 v51, v119, v49
	flat_store_dwordx4 v[88:89], v[52:55] offset:256
	s_mov_b32 s100, -1
	s_mov_b32 s101, 0
	s_mov_b32 s98, 0xffff0000
	s_mov_b32 s99, 0
	s_and_saveexec_b64 s[36:37], s[100:101]
	s_cbranch_execz .LBB0_2646
	v_lshl_add_u64 v[52:53], s[8:9], 0, v[64:65]
	s_waitcnt lgkmcnt(0)
	v_add_f32_e32 v48, v48, v50
	v_add_f32_e32 v49, v49, v51
	v_cndmask_b32_e64 v48, v48, v49, s[98:99]
	v_cndmask_b32_e64 v49, 0, 4, s[98:99]
	v_or_b32_e32 v52, v52, v49
	flat_atomic_add_f32 v[52:53], v48
; DEVI unsigned pk2(float lo, float hi) { unsigned r; asm("v_cvt_pk_bf16_f32 %0, %1, %2" : "=v"(r) : "v"(lo), "v"(hi)); return r; }
;     DEVI void operator()(const f32x4 (&acc)[2][2][4][2], const pg8::Unit& u, int wr, int wc, int fr, int fq) const {
;     ...
;                 const int row = row0 + ai * 128 + m * 16; float mu, rs; row_stats(stin, row, mu, rs);
;                 float sum = 0.f, sq = 0.f;
; #pragma unroll
;                 for (int bj = 0; bj < 2; ++bj) {
;                     f32x4 z[2];
; #pragma unroll
;                     for (int n = 0; n < 2; ++n) {
;                         const int col = colb + bj * 128 + 4 * n;
;                         f32x4 xv = *(const f32x4*)(zsrc + (size_t)row * DM + col);
;                         if (stin) { const f32x4 gv = *(const f32x4*)(gin + col), bv = *(const f32x4*)(bin + col); xv = (xv - mu) * rs * gv + bv; }
;                         f32x4 zz = ALPHA * xv + acc[ai][bj][m][n];
;                         if (bias) zz += *(const f32x4*)(bias + col);
;                         *(f32x4*)(zdst + (size_t)row * DM + col) = zz;
;                         sum += zz[0] + zz[1] + zz[2] + zz[3]; sq += zz[0] * zz[0] + zz[1] * zz[1] + zz[2] * zz[2] + zz[3] * zz[3];
;                         z[n] = zz;
;                     }
;                     u32x4 o; o.x = pk2(z[0][0], z[0][1]); o.y = pk2(z[0][2], z[0][3]); o.z = pk2(z[1][0], z[1][1]); o.w = pk2(z[1][2], z[1][3]);
;                     if (zb) *(u32x4*)(zb + (size_t)row * DM + colb + bj * 128) = o;
;                 }
;                 sum += __shfl_xor(sum, 16); sq += __shfl_xor(sq, 16);
;                 sum += __shfl_xor(sum, 32); sq += __shfl_xor(sq, 32);
;                 if (fq == 0) { atomicAdd(stout + 2 * (size_t)row, sum); atomicAdd(stout + 2 * (size_t)row + 1, sq); }
.LBB0_2646:
	s_or_b64 exec, exec, s[36:37]
	v_add_u32_e32 v72, 0x90, v154
	v_ashrrev_i32_e32 v73, 31, v72
	v_lshlrev_b64 v[48:49], 3, v[72:73]
	s_waitcnt lgkmcnt(0)
	v_lshl_add_u64 v[50:51], s[6:7], 0, v[48:49]
	flat_load_dwordx2 v[74:75], v[50:51]
	v_lshlrev_b64 v[50:51], 12, v[72:73]
	v_lshl_add_u64 v[50:51], s[46:47], 0, v[50:51]
	v_lshl_add_u64 v[50:51], v[144:145], 2, v[50:51]
	global_load_dwordx4 v[52:55], v[50:51], off
	global_load_dwordx4 v[56:59], v[150:151], off
	global_load_dwordx4 v[60:63], v[152:153], off
	global_load_dwordx4 v[64:67], v[156:157], off
	global_load_dwordx4 v[68:71], v[50:51], off offset:16
	global_load_dwordx4 v[208:211], v[146:147], off
	global_load_dwordx4 v[212:215], v[148:149], off
	global_load_dwordx4 v[250:253], v[124:125], off
	s_waitcnt vmcnt(0) lgkmcnt(0)
	v_pk_mul_f32 v[74:75], v[74:75], s[22:23] op_sel:[1,0] op_sel_hi:[0,0]
	v_fma_f32 v74, -v75, v75, v74
	v_max_f32_e32 v74, 0, v74
	v_add_f32_e32 v74, 0x3727c5ac, v74
	v_mul_f32_e32 v76, 0x4b800000, v74
	v_cmp_gt_f32_e32 vcc, s64, v74
	v_sub_f32_e32 v55, v55, v75
	v_sub_f32_e32 v54, v54, v75
	v_cndmask_b32_e32 v74, v74, v76, vcc
	v_rsq_f32_e32 v74, v74
	v_sub_f32_e32 v53, v53, v75
	v_sub_f32_e32 v52, v52, v75
	v_mul_f32_e32 v76, 0x45800000, v74
	v_cndmask_b32_e32 v74, v74, v76, vcc
	v_pk_mul_f32 v[52:53], v[52:53], v[74:75] op_sel_hi:[1,0]
	v_pk_mul_f32 v[54:55], v[54:55], v[74:75] op_sel_hi:[1,0]
	v_pk_fma_f32 v[52:53], v[56:57], v[52:53], v[60:61]
	v_pk_fma_f32 v[54:55], v[58:59], v[54:55], v[62:63]
	v_pk_fma_f32 v[44:45], v[52:53], s[24:25], v[44:45] op_sel_hi:[1,0,1]
	v_pk_fma_f32 v[46:47], v[54:55], s[24:25], v[46:47] op_sel_hi:[1,0,1]
	v_pk_add_f32 v[44:45], v[64:65], v[44:45]
	v_pk_add_f32 v[46:47], v[66:67], v[46:47]
	global_store_dwordx4 v[50:51], v[44:47], off
	v_lshlrev_b64 v[64:65], 11, v[72:73]
	v_lshl_add_u64 v[64:65], s[10:11], 0, v[64:65]
	v_lshl_add_u64 v[72:73], v[144:145], 1, v[64:65]
	v_sub_f32_e32 v65, v71, v75
	v_sub_f32_e32 v64, v70, v75
	v_sub_f32_e32 v67, v69, v75
	v_sub_f32_e32 v66, v68, v75
	v_pk_mul_f32 v[66:67], v[66:67], v[74:75] op_sel_hi:[1,0]
	v_pk_mul_f32 v[68:69], v[64:65], v[74:75] op_sel_hi:[1,0]
	v_cvt_pk_bf16_f32 v64, v44, v45
	v_cvt_pk_bf16_f32 v65, v46, v47
	v_pk_fma_f32 v[52:53], v[208:209], v[66:67], v[212:213]
	v_pk_fma_f32 v[54:55], v[210:211], v[68:69], v[214:215]
	v_pk_fma_f32 v[40:41], v[52:53], s[24:25], v[40:41] op_sel_hi:[1,0,1]
	v_pk_fma_f32 v[42:43], v[54:55], s[24:25], v[42:43] op_sel_hi:[1,0,1]
	v_pk_add_f32 v[40:41], v[250:251], v[40:41]
	v_pk_add_f32 v[42:43], v[252:253], v[42:43]
	global_store_dwordx4 v[50:51], v[40:43], off offset:16
	v_cvt_pk_bf16_f32 v66, v40, v41
	v_cvt_pk_bf16_f32 v67, v42, v43
	flat_store_dwordx4 v[72:73], v[64:67]
	global_load_dwordx4 v[52:55], v[50:51], off offset:512
	global_load_dwordx4 v[56:59], v[126:127], off
	global_load_dwordx4 v[60:63], v[158:159], off
	s_nop 0
	global_load_dwordx4 v[64:67], v[160:161], off
	global_load_dwordx4 v[68:71], v[50:51], off offset:528
	global_load_dwordx4 v[208:211], v[120:121], off
	global_load_dwordx4 v[212:215], v[122:123], off
	global_load_dwordx4 v[250:253], v[116:117], off
	s_waitcnt vmcnt(0)
	v_sub_f32_e32 v55, v55, v75
	v_sub_f32_e32 v54, v54, v75
	v_sub_f32_e32 v53, v53, v75
	v_sub_f32_e32 v52, v52, v75
	v_pk_mul_f32 v[52:53], v[74:75], v[52:53] op_sel_hi:[0,1]
	v_pk_mul_f32 v[54:55], v[74:75], v[54:55] op_sel_hi:[0,1]
	v_pk_fma_f32 v[54:55], v[58:59], v[54:55], v[62:63]
	v_pk_fma_f32 v[52:53], v[56:57], v[52:53], v[60:61]
	v_pk_fma_f32 v[38:39], v[54:55], s[24:25], v[38:39] op_sel_hi:[1,0,1]
	v_pk_fma_f32 v[36:37], v[52:53], s[24:25], v[36:37] op_sel_hi:[1,0,1]
	v_pk_add_f32 v[38:39], v[66:67], v[38:39]
	v_pk_add_f32 v[36:37], v[64:65], v[36:37]
	global_store_dwordx4 v[50:51], v[36:39], off offset:512
	v_add_f32_e32 v64, v44, v45
	v_mul_f32_e32 v45, v45, v45
	v_fmac_f32_e32 v45, v44, v44
	v_add_f32_e32 v64, v46, v64
	v_fmac_f32_e32 v45, v46, v46
	v_add_f32_e32 v46, v40, v41
	v_mul_f32_e32 v41, v41, v41
	v_fmac_f32_e32 v41, v40, v40
	v_add_f32_e32 v44, v47, v64
	v_add_f32_e32 v46, v42, v46
	v_fmac_f32_e32 v41, v42, v42
	v_add_f32_e32 v44, 0, v44
	v_fmac_f32_e32 v45, v47, v47
	v_add_f32_e32 v40, v43, v46
	v_fmac_f32_e32 v41, v43, v43
	v_sub_f32_e32 v43, v69, v75
	v_sub_f32_e32 v42, v68, v75
	v_add_f32_e32 v44, v40, v44
	v_add_f32_e32 v45, v45, v41
	v_sub_f32_e32 v41, v71, v75
	v_sub_f32_e32 v40, v70, v75
	v_pk_mul_f32 v[42:43], v[74:75], v[42:43] op_sel_hi:[0,1]
	v_pk_mul_f32 v[40:41], v[74:75], v[40:41] op_sel_hi:[0,1]
	v_mul_f32_e32 v47, v37, v37
	v_add_f32_e32 v46, v36, v37
	v_fmac_f32_e32 v47, v36, v36
	v_add_f32_e32 v46, v38, v46
	v_fmac_f32_e32 v47, v38, v38
	v_add_f32_e32 v46, v39, v46
	v_fmac_f32_e32 v47, v39, v39
	v_add_f32_e32 v44, v44, v46
	v_add_f32_e32 v45, v45, v47
	v_cvt_pk_bf16_f32 v36, v36, v37
	v_cvt_pk_bf16_f32 v37, v38, v39
	v_pk_fma_f32 v[42:43], v[208:209], v[42:43], v[212:213]
	v_pk_fma_f32 v[40:41], v[210:211], v[40:41], v[214:215]
	v_pk_fma_f32 v[32:33], v[42:43], s[24:25], v[32:33] op_sel_hi:[1,0,1]
	v_pk_fma_f32 v[34:35], v[40:41], s[24:25], v[34:35] op_sel_hi:[1,0,1]
	v_pk_add_f32 v[40:41], v[250:251], v[32:33]
	v_pk_add_f32 v[42:43], v[252:253], v[34:35]
	v_mul_f32_e32 v33, v41, v41
	v_add_f32_e32 v32, v40, v41
	v_fmac_f32_e32 v33, v40, v40
	v_add_f32_e32 v32, v42, v32
	v_fmac_f32_e32 v33, v42, v42
	v_add_f32_e32 v32, v43, v32
	v_fmac_f32_e32 v33, v43, v43
	v_add_f32_e32 v32, v44, v32
	v_add_f32_e32 v33, v45, v33
	ds_bpermute_b32 v34, v118, v32
	ds_bpermute_b32 v35, v118, v33
	global_store_dwordx4 v[50:51], v[40:43], off offset:528
	v_cvt_pk_bf16_f32 v38, v40, v41
	v_cvt_pk_bf16_f32 v39, v42, v43
	s_waitcnt lgkmcnt(0)
	v_add_f32_e32 v32, v32, v34
	v_add_f32_e32 v33, v33, v35
	ds_bpermute_b32 v34, v119, v32
	ds_bpermute_b32 v35, v119, v33
	flat_store_dwordx4 v[72:73], v[36:39] offset:256
	s_mov_b32 s100, -1
	s_mov_b32 s101, 0
	s_mov_b32 s98, 0xffff0000
	s_mov_b32 s99, 0
	s_and_saveexec_b64 s[36:37], s[100:101]
	s_cbranch_execz .LBB0_2648
	v_lshl_add_u64 v[36:37], s[8:9], 0, v[48:49]
	s_waitcnt lgkmcnt(0)
	v_add_f32_e32 v32, v32, v34
	v_add_f32_e32 v33, v33, v35
	v_cndmask_b32_e64 v32, v32, v33, s[98:99]
	v_cndmask_b32_e64 v33, 0, 4, s[98:99]
	v_or_b32_e32 v36, v36, v33
	flat_atomic_add_f32 v[36:37], v32
; DEVI unsigned pk2(float lo, float hi) { unsigned r; asm("v_cvt_pk_bf16_f32 %0, %1, %2" : "=v"(r) : "v"(lo), "v"(hi)); return r; }
;     DEVI void operator()(const f32x4 (&acc)[2][2][4][2], const pg8::Unit& u, int wr, int wc, int fr, int fq) const {
;     ...
;                 const int row = row0 + ai * 128 + m * 16; float mu, rs; row_stats(stin, row, mu, rs);
;                 float sum = 0.f, sq = 0.f;
; #pragma unroll
;                 for (int bj = 0; bj < 2; ++bj) {
;                     f32x4 z[2];
; #pragma unroll
;                     for (int n = 0; n < 2; ++n) {
;                         const int col = colb + bj * 128 + 4 * n;
;                         f32x4 xv = *(const f32x4*)(zsrc + (size_t)row * DM + col);
;                         if (stin) { const f32x4 gv = *(const f32x4*)(gin + col), bv = *(const f32x4*)(bin + col); xv = (xv - mu) * rs * gv + bv; }
;                         f32x4 zz = ALPHA * xv + acc[ai][bj][m][n];
;                         if (bias) zz += *(const f32x4*)(bias + col);
;                         *(f32x4*)(zdst + (size_t)row * DM + col) = zz;
;                         sum += zz[0] + zz[1] + zz[2] + zz[3]; sq += zz[0] * zz[0] + zz[1] * zz[1] + zz[2] * zz[2] + zz[3] * zz[3];
;                         z[n] = zz;
;                     }
;                     u32x4 o; o.x = pk2(z[0][0], z[0][1]); o.y = pk2(z[0][2], z[0][3]); o.z = pk2(z[1][0], z[1][1]); o.w = pk2(z[1][2], z[1][3]);
;                     if (zb) *(u32x4*)(zb + (size_t)row * DM + colb + bj * 128) = o;
;                 }
;                 sum += __shfl_xor(sum, 16); sq += __shfl_xor(sq, 16);
;                 sum += __shfl_xor(sum, 32); sq += __shfl_xor(sq, 32);
;                 if (fq == 0) { atomicAdd(stout + 2 * (size_t)row, sum); atomicAdd(stout + 2 * (size_t)row + 1, sq); }
.LBB0_2648:
	s_or_b64 exec, exec, s[36:37]
	v_add_u32_e32 v56, 0xa0, v154
	v_ashrrev_i32_e32 v57, 31, v56
	v_lshlrev_b64 v[32:33], 3, v[56:57]
	s_waitcnt lgkmcnt(0)
	v_lshl_add_u64 v[34:35], s[6:7], 0, v[32:33]
	flat_load_dwordx2 v[58:59], v[34:35]
	v_lshlrev_b64 v[34:35], 12, v[56:57]
	v_lshl_add_u64 v[34:35], s[46:47], 0, v[34:35]
	v_lshl_add_u64 v[34:35], v[144:145], 2, v[34:35]
	global_load_dwordx4 v[36:39], v[34:35], off
	global_load_dwordx4 v[40:43], v[150:151], off
	global_load_dwordx4 v[44:47], v[152:153], off
	global_load_dwordx4 v[48:51], v[156:157], off
	global_load_dwordx4 v[52:55], v[34:35], off offset:16
	global_load_dwordx4 v[208:211], v[146:147], off
	global_load_dwordx4 v[212:215], v[148:149], off
	global_load_dwordx4 v[250:253], v[124:125], off
	s_waitcnt vmcnt(0) lgkmcnt(0)
	v_pk_mul_f32 v[58:59], v[58:59], s[22:23] op_sel:[1,0] op_sel_hi:[0,0]
	v_fma_f32 v58, -v59, v59, v58
	v_max_f32_e32 v58, 0, v58
	v_add_f32_e32 v58, 0x3727c5ac, v58
	v_mul_f32_e32 v60, 0x4b800000, v58
	v_cmp_gt_f32_e32 vcc, s64, v58
	v_sub_f32_e32 v39, v39, v59
	v_sub_f32_e32 v38, v38, v59
	v_cndmask_b32_e32 v58, v58, v60, vcc
	v_rsq_f32_e32 v58, v58
	v_sub_f32_e32 v37, v37, v59
	v_sub_f32_e32 v36, v36, v59
	v_mul_f32_e32 v60, 0x45800000, v58
	v_cndmask_b32_e32 v58, v58, v60, vcc
	v_pk_mul_f32 v[36:37], v[36:37], v[58:59] op_sel_hi:[1,0]
	v_pk_mul_f32 v[38:39], v[38:39], v[58:59] op_sel_hi:[1,0]
	v_pk_fma_f32 v[36:37], v[40:41], v[36:37], v[44:45]
	v_pk_fma_f32 v[38:39], v[42:43], v[38:39], v[46:47]
	v_pk_fma_f32 v[28:29], v[36:37], s[24:25], v[28:29] op_sel_hi:[1,0,1]
	v_pk_fma_f32 v[30:31], v[38:39], s[24:25], v[30:31] op_sel_hi:[1,0,1]
	v_pk_add_f32 v[28:29], v[48:49], v[28:29]
	v_pk_add_f32 v[30:31], v[50:51], v[30:31]
	global_store_dwordx4 v[34:35], v[28:31], off
	v_lshlrev_b64 v[48:49], 11, v[56:57]
	v_lshl_add_u64 v[48:49], s[10:11], 0, v[48:49]
	v_lshl_add_u64 v[56:57], v[144:145], 1, v[48:49]
	v_sub_f32_e32 v49, v55, v59
	v_sub_f32_e32 v48, v54, v59
	v_sub_f32_e32 v51, v53, v59
	v_sub_f32_e32 v50, v52, v59
	v_pk_mul_f32 v[50:51], v[50:51], v[58:59] op_sel_hi:[1,0]
	v_pk_mul_f32 v[52:53], v[48:49], v[58:59] op_sel_hi:[1,0]
	v_cvt_pk_bf16_f32 v48, v28, v29
	v_cvt_pk_bf16_f32 v49, v30, v31
	v_pk_fma_f32 v[36:37], v[208:209], v[50:51], v[212:213]
	v_pk_fma_f32 v[38:39], v[210:211], v[52:53], v[214:215]
	v_pk_fma_f32 v[24:25], v[36:37], s[24:25], v[24:25] op_sel_hi:[1,0,1]
	v_pk_fma_f32 v[26:27], v[38:39], s[24:25], v[26:27] op_sel_hi:[1,0,1]
	v_pk_add_f32 v[24:25], v[250:251], v[24:25]
	v_pk_add_f32 v[26:27], v[252:253], v[26:27]
	global_store_dwordx4 v[34:35], v[24:27], off offset:16
	v_cvt_pk_bf16_f32 v50, v24, v25
	v_cvt_pk_bf16_f32 v51, v26, v27
	flat_store_dwordx4 v[56:57], v[48:51]
	global_load_dwordx4 v[36:39], v[34:35], off offset:512
	global_load_dwordx4 v[40:43], v[126:127], off
	global_load_dwordx4 v[44:47], v[158:159], off
	s_nop 0
	global_load_dwordx4 v[48:51], v[160:161], off
	global_load_dwordx4 v[52:55], v[34:35], off offset:528
	global_load_dwordx4 v[208:211], v[120:121], off
	global_load_dwordx4 v[212:215], v[122:123], off
	global_load_dwordx4 v[250:253], v[116:117], off
	s_waitcnt vmcnt(0)
	v_sub_f32_e32 v39, v39, v59
	v_sub_f32_e32 v38, v38, v59
	v_sub_f32_e32 v37, v37, v59
	v_sub_f32_e32 v36, v36, v59
	v_pk_mul_f32 v[36:37], v[58:59], v[36:37] op_sel_hi:[0,1]
	v_pk_mul_f32 v[38:39], v[58:59], v[38:39] op_sel_hi:[0,1]
	v_pk_fma_f32 v[38:39], v[42:43], v[38:39], v[46:47]
	v_pk_fma_f32 v[36:37], v[40:41], v[36:37], v[44:45]
	v_pk_fma_f32 v[22:23], v[38:39], s[24:25], v[22:23] op_sel_hi:[1,0,1]
	v_pk_fma_f32 v[20:21], v[36:37], s[24:25], v[20:21] op_sel_hi:[1,0,1]
	v_pk_add_f32 v[22:23], v[50:51], v[22:23]
	v_pk_add_f32 v[20:21], v[48:49], v[20:21]
	global_store_dwordx4 v[34:35], v[20:23], off offset:512
	v_add_f32_e32 v48, v28, v29
	v_mul_f32_e32 v29, v29, v29
	v_fmac_f32_e32 v29, v28, v28
	v_add_f32_e32 v48, v30, v48
	v_fmac_f32_e32 v29, v30, v30
	v_add_f32_e32 v30, v24, v25
	v_mul_f32_e32 v25, v25, v25
	v_fmac_f32_e32 v25, v24, v24
	v_add_f32_e32 v28, v31, v48
	v_add_f32_e32 v30, v26, v30
	v_fmac_f32_e32 v25, v26, v26
	v_add_f32_e32 v28, 0, v28
	v_fmac_f32_e32 v29, v31, v31
	v_add_f32_e32 v24, v27, v30
	v_fmac_f32_e32 v25, v27, v27
	v_sub_f32_e32 v27, v53, v59
	v_sub_f32_e32 v26, v52, v59
	v_add_f32_e32 v28, v24, v28
	v_add_f32_e32 v29, v29, v25
	v_sub_f32_e32 v25, v55, v59
	v_sub_f32_e32 v24, v54, v59
	v_pk_mul_f32 v[26:27], v[58:59], v[26:27] op_sel_hi:[0,1]
	v_pk_mul_f32 v[24:25], v[58:59], v[24:25] op_sel_hi:[0,1]
	v_mul_f32_e32 v31, v21, v21
	v_add_f32_e32 v30, v20, v21
	v_fmac_f32_e32 v31, v20, v20
	v_add_f32_e32 v30, v22, v30
	v_fmac_f32_e32 v31, v22, v22
	v_add_f32_e32 v30, v23, v30
	v_fmac_f32_e32 v31, v23, v23
	v_add_f32_e32 v28, v28, v30
	v_add_f32_e32 v29, v29, v31
	v_cvt_pk_bf16_f32 v20, v20, v21
	v_cvt_pk_bf16_f32 v21, v22, v23
	v_pk_fma_f32 v[26:27], v[208:209], v[26:27], v[212:213]
	v_pk_fma_f32 v[24:25], v[210:211], v[24:25], v[214:215]
	v_pk_fma_f32 v[16:17], v[26:27], s[24:25], v[16:17] op_sel_hi:[1,0,1]
	v_pk_fma_f32 v[18:19], v[24:25], s[24:25], v[18:19] op_sel_hi:[1,0,1]
	v_pk_add_f32 v[24:25], v[250:251], v[16:17]
	v_pk_add_f32 v[26:27], v[252:253], v[18:19]
	v_mul_f32_e32 v17, v25, v25
	v_add_f32_e32 v16, v24, v25
	v_fmac_f32_e32 v17, v24, v24
	v_add_f32_e32 v16, v26, v16
	v_fmac_f32_e32 v17, v26, v26
	v_add_f32_e32 v16, v27, v16
	v_fmac_f32_e32 v17, v27, v27
	v_add_f32_e32 v16, v28, v16
	v_add_f32_e32 v17, v29, v17
	ds_bpermute_b32 v18, v118, v16
	ds_bpermute_b32 v19, v118, v17
	global_store_dwordx4 v[34:35], v[24:27], off offset:528
	v_cvt_pk_bf16_f32 v22, v24, v25
	v_cvt_pk_bf16_f32 v23, v26, v27
	s_waitcnt lgkmcnt(0)
	v_add_f32_e32 v16, v16, v18
	v_add_f32_e32 v17, v17, v19
	ds_bpermute_b32 v18, v119, v16
	ds_bpermute_b32 v19, v119, v17
	flat_store_dwordx4 v[56:57], v[20:23] offset:256
	s_mov_b32 s100, -1
	s_mov_b32 s101, 0
	s_mov_b32 s98, 0xffff0000
	s_mov_b32 s99, 0
	s_and_saveexec_b64 s[36:37], s[100:101]
	s_cbranch_execz .LBB0_2650
	v_lshl_add_u64 v[20:21], s[8:9], 0, v[32:33]
	s_waitcnt lgkmcnt(0)
	v_add_f32_e32 v16, v16, v18
	v_add_f32_e32 v17, v17, v19
	v_cndmask_b32_e64 v16, v16, v17, s[98:99]
	v_cndmask_b32_e64 v17, 0, 4, s[98:99]
	v_or_b32_e32 v20, v20, v17
	flat_atomic_add_f32 v[20:21], v16
; DEVI unsigned pk2(float lo, float hi) { unsigned r; asm("v_cvt_pk_bf16_f32 %0, %1, %2" : "=v"(r) : "v"(lo), "v"(hi)); return r; }
;     DEVI void operator()(const f32x4 (&acc)[2][2][4][2], const pg8::Unit& u, int wr, int wc, int fr, int fq) const {
;     ...
;                 const int row = row0 + ai * 128 + m * 16; float mu, rs; row_stats(stin, row, mu, rs);
;                 float sum = 0.f, sq = 0.f;
; #pragma unroll
;                 for (int bj = 0; bj < 2; ++bj) {
;                     f32x4 z[2];
; #pragma unroll
;                     for (int n = 0; n < 2; ++n) {
;                         const int col = colb + bj * 128 + 4 * n;
;                         f32x4 xv = *(const f32x4*)(zsrc + (size_t)row * DM + col);
;                         if (stin) { const f32x4 gv = *(const f32x4*)(gin + col), bv = *(const f32x4*)(bin + col); xv = (xv - mu) * rs * gv + bv; }
;                         f32x4 zz = ALPHA * xv + acc[ai][bj][m][n];
;                         if (bias) zz += *(const f32x4*)(bias + col);
;                         *(f32x4*)(zdst + (size_t)row * DM + col) = zz;
;                         sum += zz[0] + zz[1] + zz[2] + zz[3]; sq += zz[0] * zz[0] + zz[1] * zz[1] + zz[2] * zz[2] + zz[3] * zz[3];
;                         z[n] = zz;
;                     }
;                     u32x4 o; o.x = pk2(z[0][0], z[0][1]); o.y = pk2(z[0][2], z[0][3]); o.z = pk2(z[1][0], z[1][1]); o.w = pk2(z[1][2], z[1][3]);
;                     if (zb) *(u32x4*)(zb + (size_t)row * DM + colb + bj * 128) = o;
;                 }
;                 sum += __shfl_xor(sum, 16); sq += __shfl_xor(sq, 16);
;                 sum += __shfl_xor(sum, 32); sq += __shfl_xor(sq, 32);
;                 if (fq == 0) { atomicAdd(stout + 2 * (size_t)row, sum); atomicAdd(stout + 2 * (size_t)row + 1, sq); }
.LBB0_2650:
	s_or_b64 exec, exec, s[36:37]
	v_add_u32_e32 v40, 0xb0, v154
	v_ashrrev_i32_e32 v41, 31, v40
	v_lshlrev_b64 v[16:17], 3, v[40:41]
	s_waitcnt lgkmcnt(0)
	v_lshl_add_u64 v[18:19], s[6:7], 0, v[16:17]
	flat_load_dwordx2 v[42:43], v[18:19]
	v_lshlrev_b64 v[18:19], 12, v[40:41]
	v_lshl_add_u64 v[18:19], s[46:47], 0, v[18:19]
	v_lshl_add_u64 v[18:19], v[144:145], 2, v[18:19]
	global_load_dwordx4 v[20:23], v[18:19], off
	global_load_dwordx4 v[24:27], v[150:151], off
	global_load_dwordx4 v[28:31], v[152:153], off
	global_load_dwordx4 v[32:35], v[156:157], off
	global_load_dwordx4 v[36:39], v[18:19], off offset:16
	global_load_dwordx4 v[208:211], v[146:147], off
	global_load_dwordx4 v[212:215], v[148:149], off
	global_load_dwordx4 v[250:253], v[124:125], off
	s_waitcnt vmcnt(0) lgkmcnt(0)
	v_pk_mul_f32 v[42:43], v[42:43], s[22:23] op_sel:[1,0] op_sel_hi:[0,0]
	v_fma_f32 v42, -v43, v43, v42
	v_max_f32_e32 v42, 0, v42
	v_add_f32_e32 v42, 0x3727c5ac, v42
	v_mul_f32_e32 v44, 0x4b800000, v42
	v_cmp_gt_f32_e32 vcc, s64, v42
	v_sub_f32_e32 v23, v23, v43
	v_sub_f32_e32 v22, v22, v43
	v_cndmask_b32_e32 v42, v42, v44, vcc
	v_rsq_f32_e32 v42, v42
	v_sub_f32_e32 v21, v21, v43
	v_sub_f32_e32 v20, v20, v43
	v_mul_f32_e32 v44, 0x45800000, v42
	v_cndmask_b32_e32 v42, v42, v44, vcc
	v_pk_mul_f32 v[20:21], v[20:21], v[42:43] op_sel_hi:[1,0]
	v_pk_mul_f32 v[22:23], v[22:23], v[42:43] op_sel_hi:[1,0]
	v_pk_fma_f32 v[20:21], v[24:25], v[20:21], v[28:29]
	v_pk_fma_f32 v[22:23], v[26:27], v[22:23], v[30:31]
	v_pk_fma_f32 v[12:13], v[20:21], s[24:25], v[12:13] op_sel_hi:[1,0,1]
	v_pk_fma_f32 v[14:15], v[22:23], s[24:25], v[14:15] op_sel_hi:[1,0,1]
	v_pk_add_f32 v[12:13], v[32:33], v[12:13]
	v_pk_add_f32 v[14:15], v[34:35], v[14:15]
	global_store_dwordx4 v[18:19], v[12:15], off
	v_lshlrev_b64 v[32:33], 11, v[40:41]
	v_lshl_add_u64 v[32:33], s[10:11], 0, v[32:33]
	v_lshl_add_u64 v[40:41], v[144:145], 1, v[32:33]
	v_sub_f32_e32 v33, v39, v43
	v_sub_f32_e32 v32, v38, v43
	v_sub_f32_e32 v35, v37, v43
	v_sub_f32_e32 v34, v36, v43
	v_pk_mul_f32 v[34:35], v[34:35], v[42:43] op_sel_hi:[1,0]
	v_pk_mul_f32 v[36:37], v[32:33], v[42:43] op_sel_hi:[1,0]
	v_cvt_pk_bf16_f32 v32, v12, v13
	v_cvt_pk_bf16_f32 v33, v14, v15
	v_pk_fma_f32 v[20:21], v[208:209], v[34:35], v[212:213]
	v_pk_fma_f32 v[22:23], v[210:211], v[36:37], v[214:215]
	v_pk_fma_f32 v[8:9], v[20:21], s[24:25], v[8:9] op_sel_hi:[1,0,1]
	v_pk_fma_f32 v[10:11], v[22:23], s[24:25], v[10:11] op_sel_hi:[1,0,1]
	v_pk_add_f32 v[8:9], v[250:251], v[8:9]
	v_pk_add_f32 v[10:11], v[252:253], v[10:11]
	global_store_dwordx4 v[18:19], v[8:11], off offset:16
	v_cvt_pk_bf16_f32 v34, v8, v9
	v_cvt_pk_bf16_f32 v35, v10, v11
	flat_store_dwordx4 v[40:41], v[32:35]
	global_load_dwordx4 v[20:23], v[18:19], off offset:512
	global_load_dwordx4 v[24:27], v[126:127], off
	global_load_dwordx4 v[28:31], v[158:159], off
	s_nop 0
	global_load_dwordx4 v[32:35], v[160:161], off
	global_load_dwordx4 v[36:39], v[18:19], off offset:528
	global_load_dwordx4 v[208:211], v[120:121], off
	global_load_dwordx4 v[212:215], v[122:123], off
	global_load_dwordx4 v[250:253], v[116:117], off
	s_waitcnt vmcnt(0)
	v_sub_f32_e32 v23, v23, v43
	v_sub_f32_e32 v22, v22, v43
	v_sub_f32_e32 v21, v21, v43
	v_sub_f32_e32 v20, v20, v43
	v_pk_mul_f32 v[20:21], v[42:43], v[20:21] op_sel_hi:[0,1]
	v_pk_mul_f32 v[22:23], v[42:43], v[22:23] op_sel_hi:[0,1]
	v_pk_fma_f32 v[22:23], v[26:27], v[22:23], v[30:31]
	v_pk_fma_f32 v[20:21], v[24:25], v[20:21], v[28:29]
	v_pk_fma_f32 v[6:7], v[22:23], s[24:25], v[6:7] op_sel_hi:[1,0,1]
	v_pk_fma_f32 v[4:5], v[20:21], s[24:25], v[4:5] op_sel_hi:[1,0,1]
	v_pk_add_f32 v[6:7], v[34:35], v[6:7]
	v_pk_add_f32 v[4:5], v[32:33], v[4:5]
	global_store_dwordx4 v[18:19], v[4:7], off offset:512
	v_add_f32_e32 v32, v12, v13
	v_mul_f32_e32 v13, v13, v13
	v_fmac_f32_e32 v13, v12, v12
	v_add_f32_e32 v32, v14, v32
	v_fmac_f32_e32 v13, v14, v14
	v_add_f32_e32 v14, v8, v9
	v_mul_f32_e32 v9, v9, v9
	v_fmac_f32_e32 v9, v8, v8
	v_add_f32_e32 v12, v15, v32
	v_add_f32_e32 v14, v10, v14
	v_fmac_f32_e32 v9, v10, v10
	v_add_f32_e32 v12, 0, v12
	v_fmac_f32_e32 v13, v15, v15
	v_add_f32_e32 v8, v11, v14
	v_fmac_f32_e32 v9, v11, v11
	v_sub_f32_e32 v11, v37, v43
	v_sub_f32_e32 v10, v36, v43
	v_add_f32_e32 v12, v8, v12
	v_add_f32_e32 v13, v13, v9
	v_sub_f32_e32 v9, v39, v43
	v_sub_f32_e32 v8, v38, v43
	v_pk_mul_f32 v[10:11], v[42:43], v[10:11] op_sel_hi:[0,1]
	v_pk_mul_f32 v[8:9], v[42:43], v[8:9] op_sel_hi:[0,1]
	v_mul_f32_e32 v15, v5, v5
	v_add_f32_e32 v14, v4, v5
	v_fmac_f32_e32 v15, v4, v4
	v_add_f32_e32 v14, v6, v14
	v_fmac_f32_e32 v15, v6, v6
	v_add_f32_e32 v14, v7, v14
	v_fmac_f32_e32 v15, v7, v7
	v_add_f32_e32 v12, v12, v14
	v_add_f32_e32 v13, v13, v15
	v_cvt_pk_bf16_f32 v4, v4, v5
	v_cvt_pk_bf16_f32 v5, v6, v7
	v_pk_fma_f32 v[10:11], v[208:209], v[10:11], v[212:213]
	v_pk_fma_f32 v[8:9], v[210:211], v[8:9], v[214:215]
	v_pk_fma_f32 v[0:1], v[10:11], s[24:25], v[0:1] op_sel_hi:[1,0,1]
	v_pk_fma_f32 v[2:3], v[8:9], s[24:25], v[2:3] op_sel_hi:[1,0,1]
	v_pk_add_f32 v[8:9], v[250:251], v[0:1]
	v_pk_add_f32 v[10:11], v[252:253], v[2:3]
	v_mul_f32_e32 v1, v9, v9
	v_add_f32_e32 v0, v8, v9
	v_fmac_f32_e32 v1, v8, v8
	v_add_f32_e32 v0, v10, v0
	v_fmac_f32_e32 v1, v10, v10
	v_add_f32_e32 v0, v11, v0
	v_fmac_f32_e32 v1, v11, v11
	v_add_f32_e32 v0, v12, v0
	v_add_f32_e32 v1, v13, v1
	ds_bpermute_b32 v2, v118, v0
	ds_bpermute_b32 v3, v118, v1
	global_store_dwordx4 v[18:19], v[8:11], off offset:528
	v_cvt_pk_bf16_f32 v6, v8, v9
	v_cvt_pk_bf16_f32 v7, v10, v11
	s_waitcnt lgkmcnt(0)
	v_add_f32_e32 v0, v0, v2
	v_add_f32_e32 v1, v1, v3
	ds_bpermute_b32 v2, v119, v0
	ds_bpermute_b32 v3, v119, v1
	flat_store_dwordx4 v[40:41], v[4:7] offset:256
	s_mov_b32 s100, -1
	s_mov_b32 s101, 0
	s_mov_b32 s98, 0xffff0000
	s_mov_b32 s99, 0
	s_and_saveexec_b64 s[36:37], s[100:101]
	s_cbranch_execz .LBB0_2652
	v_lshl_add_u64 v[4:5], s[8:9], 0, v[16:17]
	s_waitcnt lgkmcnt(0)
	v_add_f32_e32 v0, v0, v2
	v_add_f32_e32 v1, v1, v3
	v_cndmask_b32_e64 v0, v0, v1, s[98:99]
	v_cndmask_b32_e64 v1, 0, 4, s[98:99]
	v_or_b32_e32 v4, v4, v1
	flat_atomic_add_f32 v[4:5], v0

; DEVI unsigned pk2(float lo, float hi) { unsigned r; asm("v_cvt_pk_bf16_f32 %0, %1, %2" : "=v"(r) : "v"(lo), "v"(hi)); return r; }
;     DEVI void operator()(const f32x4 (&acc)[2][2][4][2], const pg8::Unit& u, int wr, int wc, int fr, int fq) const {
;     ...
;                 const int row = row0 + ai * 128 + m * 16; float mu, rs; row_stats(stin, row, mu, rs);
;                 float sum = 0.f, sq = 0.f;
; #pragma unroll
;                 for (int bj = 0; bj < 2; ++bj) {
;                     f32x4 z[2];
; #pragma unroll
;                     for (int n = 0; n < 2; ++n) {
;                         const int col = colb + bj * 128 + 4 * n;
;                         f32x4 xv = *(const f32x4*)(zsrc + (size_t)row * DM + col);
;                         if (stin) { const f32x4 gv = *(const f32x4*)(gin + col), bv = *(const f32x4*)(bin + col); xv = (xv - mu) * rs * gv + bv; }
;                         f32x4 zz = ALPHA * xv + acc[ai][bj][m][n];
;                         if (bias) zz += *(const f32x4*)(bias + col);
;                         *(f32x4*)(zdst + (size_t)row * DM + col) = zz;
;                         sum += zz[0] + zz[1] + zz[2] + zz[3]; sq += zz[0] * zz[0] + zz[1] * zz[1] + zz[2] * zz[2] + zz[3] * zz[3];
;                         z[n] = zz;
;                     }
;                     u32x4 o; o.x = pk2(z[0][0], z[0][1]); o.y = pk2(z[0][2], z[0][3]); o.z = pk2(z[1][0], z[1][1]); o.w = pk2(z[1][2], z[1][3]);
;                     if (zb) *(u32x4*)(zb + (size_t)row * DM + colb + bj * 128) = o;
;                 }
;                 sum += __shfl_xor(sum, 16); sq += __shfl_xor(sq, 16);
;                 sum += __shfl_xor(sum, 32); sq += __shfl_xor(sq, 32);
;                 if (fq == 0) { atomicAdd(stout + 2 * (size_t)row, sum); atomicAdd(stout + 2 * (size_t)row + 1, sq); }
.LBB0_2847:
	s_or_b64 exec, exec, s[28:29]
	v_or_b32_e32 v118, 16, v154
	v_ashrrev_i32_e32 v119, 31, v118
	v_lshlrev_b64 v[112:113], 3, v[118:119]
	v_lshl_add_u64 v[156:157], s[12:13], 0, v[112:113]
	flat_load_dwordx2 v[180:181], v[156:157]
	v_lshlrev_b64 v[118:119], 12, v[118:119]
	v_lshl_add_u64 v[118:119], s[46:47], 0, v[118:119]
	v_lshl_add_u64 v[118:119], v[144:145], 2, v[118:119]
	global_load_dwordx4 v[156:159], v[118:119], off
	global_load_dwordx4 v[168:171], v[150:151], off
	global_load_dwordx4 v[172:175], v[152:153], off
	global_load_dwordx4 v[176:179], v[118:119], off offset:16
	global_load_dwordx4 v[194:197], v[118:119], off offset:512
	global_load_dwordx4 v[198:201], v[118:119], off offset:528
	s_waitcnt vmcnt(0) lgkmcnt(0)
	v_pk_mul_f32 v[180:181], v[180:181], s[22:23] op_sel:[1,0] op_sel_hi:[0,0]
	v_fma_f32 v115, -v181, v181, v180
	v_max_f32_e32 v115, 0, v115
	v_add_f32_e32 v115, 0x3727c5ac, v115
	v_mul_f32_e32 v117, 0x4b800000, v115
	v_cmp_gt_f32_e32 vcc, s55, v115
	v_sub_f32_e32 v157, v157, v181
	v_sub_f32_e32 v156, v156, v181
	v_cndmask_b32_e32 v115, v115, v117, vcc
	v_rsq_f32_e32 v115, v115
	v_sub_f32_e32 v159, v159, v181
	v_sub_f32_e32 v158, v158, v181
	v_sub_f32_e32 v177, v177, v181
	v_mul_f32_e32 v117, 0x45800000, v115
	v_cndmask_b32_e32 v180, v115, v117, vcc
	v_pk_mul_f32 v[158:159], v[158:159], v[180:181] op_sel_hi:[1,0]
	v_pk_mul_f32 v[156:157], v[156:157], v[180:181] op_sel_hi:[1,0]
	v_pk_fma_f32 v[158:159], v[170:171], v[158:159], v[174:175]
	v_pk_fma_f32 v[156:157], v[168:169], v[156:157], v[172:173]
	v_pk_fma_f32 v[110:111], v[158:159], s[24:25], v[110:111] op_sel_hi:[1,0,1]
	v_pk_fma_f32 v[108:109], v[156:157], s[24:25], v[108:109] op_sel_hi:[1,0,1]
	global_store_dwordx4 v[118:119], v[108:111], off
	global_load_dwordx4 v[156:159], v[146:147], off
	global_load_dwordx4 v[168:171], v[148:149], off
	v_sub_f32_e32 v176, v176, v181
	v_sub_f32_e32 v179, v179, v181
	v_sub_f32_e32 v178, v178, v181
	v_pk_mul_f32 v[178:179], v[178:179], v[180:181] op_sel_hi:[1,0]
	v_pk_mul_f32 v[176:177], v[176:177], v[180:181] op_sel_hi:[1,0]
	v_add_f32_e32 v115, v108, v109
	v_mul_f32_e32 v109, v109, v109
	v_fmac_f32_e32 v109, v108, v108
	v_add_f32_e32 v115, v110, v115
	v_fmac_f32_e32 v109, v110, v110
	v_add_f32_e32 v108, v111, v115
	v_add_f32_e32 v108, 0, v108
	v_fmac_f32_e32 v109, v111, v111
	s_waitcnt vmcnt(0)
	v_pk_fma_f32 v[156:157], v[156:157], v[176:177], v[168:169]
	v_pk_fma_f32 v[158:159], v[158:159], v[178:179], v[170:171]
	v_pk_fma_f32 v[104:105], v[156:157], s[24:25], v[104:105] op_sel_hi:[1,0,1]
	v_pk_fma_f32 v[106:107], v[158:159], s[24:25], v[106:107] op_sel_hi:[1,0,1]
	global_store_dwordx4 v[118:119], v[104:107], off offset:16
	global_load_dwordx4 v[156:159], v[124:125], off
	global_load_dwordx4 v[168:171], v[126:127], off
	s_waitcnt vmcnt(2)
	v_sub_f32_e32 v173, v195, v181
	v_sub_f32_e32 v172, v194, v181
	v_sub_f32_e32 v175, v197, v181
	v_sub_f32_e32 v174, v196, v181
	v_pk_mul_f32 v[174:175], v[180:181], v[174:175] op_sel_hi:[0,1]
	v_pk_mul_f32 v[172:173], v[180:181], v[172:173] op_sel_hi:[0,1]
	v_add_f32_e32 v110, v104, v105
	v_mul_f32_e32 v105, v105, v105
	v_fmac_f32_e32 v105, v104, v104
	v_add_f32_e32 v110, v106, v110
	v_fmac_f32_e32 v105, v106, v106
	v_add_f32_e32 v104, v107, v110
	v_fmac_f32_e32 v105, v107, v107
	v_add_f32_e32 v104, v104, v108
	v_add_f32_e32 v105, v109, v105
	s_waitcnt vmcnt(0)
	v_pk_fma_f32 v[156:157], v[156:157], v[172:173], v[168:169]
	v_pk_fma_f32 v[158:159], v[158:159], v[174:175], v[170:171]
	v_pk_fma_f32 v[100:101], v[156:157], s[24:25], v[100:101] op_sel_hi:[1,0,1]
	v_pk_fma_f32 v[102:103], v[158:159], s[24:25], v[102:103] op_sel_hi:[1,0,1]
	global_store_dwordx4 v[118:119], v[100:103], off offset:512
	global_load_dwordx4 v[156:159], v[120:121], off
	global_load_dwordx4 v[168:171], v[122:123], off
	v_add_f32_e32 v106, v100, v101
	v_mul_f32_e32 v101, v101, v101
	v_fmac_f32_e32 v101, v100, v100
	s_waitcnt vmcnt(1)
	v_sub_f32_e32 v173, v199, v181
	v_sub_f32_e32 v172, v198, v181
	v_add_f32_e32 v106, v102, v106
	v_fmac_f32_e32 v101, v102, v102
	v_pk_mul_f32 v[172:173], v[180:181], v[172:173] op_sel_hi:[0,1]
	v_add_f32_e32 v100, v103, v106
	v_fmac_f32_e32 v101, v103, v103
	v_sub_f32_e32 v175, v201, v181
	v_sub_f32_e32 v174, v200, v181
	v_add_f32_e32 v104, v104, v100
	v_add_f32_e32 v105, v105, v101
	v_pk_mul_f32 v[174:175], v[180:181], v[174:175] op_sel_hi:[0,1]
	s_waitcnt vmcnt(0)
	v_pk_fma_f32 v[100:101], v[156:157], v[172:173], v[168:169]
	s_nop 0
	v_pk_fma_f32 v[100:101], v[100:101], s[24:25], v[96:97] op_sel_hi:[1,0,1]
	v_pk_fma_f32 v[102:103], v[158:159], v[174:175], v[170:171]
	v_mul_f32_e32 v97, v101, v101
	v_pk_fma_f32 v[102:103], v[102:103], s[24:25], v[98:99] op_sel_hi:[1,0,1]
	v_add_f32_e32 v96, v100, v101
	v_fmac_f32_e32 v97, v100, v100
	v_add_f32_e32 v96, v102, v96
	v_fmac_f32_e32 v97, v102, v102
	v_add_f32_e32 v96, v103, v96
	v_fmac_f32_e32 v97, v103, v103
	v_add_f32_e32 v96, v104, v96
	v_add_f32_e32 v97, v105, v97
	ds_bpermute_b32 v98, v116, v96
	ds_bpermute_b32 v99, v116, v97
	global_store_dwordx4 v[118:119], v[100:103], off offset:528
	s_waitcnt lgkmcnt(1)
	v_add_f32_e32 v96, v96, v98
	s_waitcnt lgkmcnt(0)
	v_add_f32_e32 v97, v97, v99
	ds_bpermute_b32 v98, v114, v96
	ds_bpermute_b32 v99, v114, v97
	s_mov_b32 s100, -1
	s_mov_b32 s101, 0
	s_mov_b32 s98, 0xffff0000
	s_mov_b32 s99, 0
	s_and_saveexec_b64 s[28:29], s[100:101]
	s_cbranch_execz .LBB0_2849
	v_lshl_add_u64 v[100:101], s[10:11], 0, v[112:113]
	s_waitcnt lgkmcnt(1)
	v_add_f32_e32 v96, v96, v98
	s_waitcnt lgkmcnt(0)
	v_add_f32_e32 v97, v97, v99
	v_cndmask_b32_e64 v96, v96, v97, s[98:99]
	v_cndmask_b32_e64 v97, 0, 4, s[98:99]
	v_or_b32_e32 v100, v100, v97
	flat_atomic_add_f32 v[100:101], v96
; DEVI unsigned pk2(float lo, float hi) { unsigned r; asm("v_cvt_pk_bf16_f32 %0, %1, %2" : "=v"(r) : "v"(lo), "v"(hi)); return r; }
;     DEVI void operator()(const f32x4 (&acc)[2][2][4][2], const pg8::Unit& u, int wr, int wc, int fr, int fq) const {
;     ...
;                 const int row = row0 + ai * 128 + m * 16; float mu, rs; row_stats(stin, row, mu, rs);
;                 float sum = 0.f, sq = 0.f;
; #pragma unroll
;                 for (int bj = 0; bj < 2; ++bj) {
;                     f32x4 z[2];
; #pragma unroll
;                     for (int n = 0; n < 2; ++n) {
;                         const int col = colb + bj * 128 + 4 * n;
;                         f32x4 xv = *(const f32x4*)(zsrc + (size_t)row * DM + col);
;                         if (stin) { const f32x4 gv = *(const f32x4*)(gin + col), bv = *(const f32x4*)(bin + col); xv = (xv - mu) * rs * gv + bv; }
;                         f32x4 zz = ALPHA * xv + acc[ai][bj][m][n];
;                         if (bias) zz += *(const f32x4*)(bias + col);
;                         *(f32x4*)(zdst + (size_t)row * DM + col) = zz;
;                         sum += zz[0] + zz[1] + zz[2] + zz[3]; sq += zz[0] * zz[0] + zz[1] * zz[1] + zz[2] * zz[2] + zz[3] * zz[3];
;                         z[n] = zz;
;                     }
;                     u32x4 o; o.x = pk2(z[0][0], z[0][1]); o.y = pk2(z[0][2], z[0][3]); o.z = pk2(z[1][0], z[1][1]); o.w = pk2(z[1][2], z[1][3]);
;                     if (zb) *(u32x4*)(zb + (size_t)row * DM + colb + bj * 128) = o;
;                 }
;                 sum += __shfl_xor(sum, 16); sq += __shfl_xor(sq, 16);
;                 sum += __shfl_xor(sum, 32); sq += __shfl_xor(sq, 32);
;                 if (fq == 0) { atomicAdd(stout + 2 * (size_t)row, sum); atomicAdd(stout + 2 * (size_t)row + 1, sq); }
.LBB0_2849:
	s_or_b64 exec, exec, s[28:29]
	s_waitcnt lgkmcnt(0)
	v_or_b32_e32 v98, 32, v154
	v_ashrrev_i32_e32 v99, 31, v98
	v_lshlrev_b64 v[96:97], 3, v[98:99]
	v_lshl_add_u64 v[100:101], s[12:13], 0, v[96:97]
	flat_load_dwordx2 v[118:119], v[100:101]
	v_lshlrev_b64 v[98:99], 12, v[98:99]
	v_lshl_add_u64 v[98:99], s[46:47], 0, v[98:99]
	v_lshl_add_u64 v[156:157], v[144:145], 2, v[98:99]
	global_load_dwordx4 v[98:101], v[156:157], off
	global_load_dwordx4 v[102:105], v[150:151], off
	global_load_dwordx4 v[106:109], v[152:153], off
	global_load_dwordx4 v[110:113], v[156:157], off offset:16
	global_load_dwordx4 v[194:197], v[156:157], off offset:512
	global_load_dwordx4 v[198:201], v[156:157], off offset:528
	s_waitcnt vmcnt(0) lgkmcnt(0)
	v_pk_mul_f32 v[118:119], v[118:119], s[22:23] op_sel:[1,0] op_sel_hi:[0,0]
	v_fma_f32 v115, -v119, v119, v118
	v_max_f32_e32 v115, 0, v115
	v_add_f32_e32 v115, 0x3727c5ac, v115
	v_mul_f32_e32 v117, 0x4b800000, v115
	v_cmp_gt_f32_e32 vcc, s55, v115
	v_sub_f32_e32 v99, v99, v119
	v_sub_f32_e32 v98, v98, v119
	v_cndmask_b32_e32 v115, v115, v117, vcc
	v_rsq_f32_e32 v115, v115
	v_sub_f32_e32 v101, v101, v119
	v_sub_f32_e32 v100, v100, v119
	v_sub_f32_e32 v111, v111, v119
	v_mul_f32_e32 v117, 0x45800000, v115
	v_cndmask_b32_e32 v118, v115, v117, vcc
	v_pk_mul_f32 v[100:101], v[100:101], v[118:119] op_sel_hi:[1,0]
	v_pk_mul_f32 v[98:99], v[98:99], v[118:119] op_sel_hi:[1,0]
	v_pk_fma_f32 v[100:101], v[104:105], v[100:101], v[108:109]
	v_pk_fma_f32 v[98:99], v[102:103], v[98:99], v[106:107]
	v_pk_fma_f32 v[94:95], v[100:101], s[24:25], v[94:95] op_sel_hi:[1,0,1]
	v_pk_fma_f32 v[92:93], v[98:99], s[24:25], v[92:93] op_sel_hi:[1,0,1]
	global_store_dwordx4 v[156:157], v[92:95], off
	global_load_dwordx4 v[98:101], v[146:147], off
	global_load_dwordx4 v[102:105], v[148:149], off
	v_sub_f32_e32 v110, v110, v119
	v_sub_f32_e32 v113, v113, v119
	v_sub_f32_e32 v112, v112, v119
	v_pk_mul_f32 v[112:113], v[112:113], v[118:119] op_sel_hi:[1,0]
	v_pk_mul_f32 v[110:111], v[110:111], v[118:119] op_sel_hi:[1,0]
	s_waitcnt vmcnt(0)
	v_pk_fma_f32 v[100:101], v[100:101], v[112:113], v[104:105]
	v_pk_fma_f32 v[98:99], v[98:99], v[110:111], v[102:103]
	v_pk_fma_f32 v[90:91], v[100:101], s[24:25], v[90:91] op_sel_hi:[1,0,1]
	v_pk_fma_f32 v[88:89], v[98:99], s[24:25], v[88:89] op_sel_hi:[1,0,1]
	global_store_dwordx4 v[156:157], v[88:91], off offset:16
	global_load_dwordx4 v[98:101], v[124:125], off
	global_load_dwordx4 v[102:105], v[126:127], off
	s_waitcnt vmcnt(2)
	v_sub_f32_e32 v107, v195, v119
	v_sub_f32_e32 v106, v194, v119
	v_sub_f32_e32 v109, v197, v119
	v_sub_f32_e32 v108, v196, v119
	v_pk_mul_f32 v[108:109], v[118:119], v[108:109] op_sel_hi:[0,1]
	v_pk_mul_f32 v[106:107], v[118:119], v[106:107] op_sel_hi:[0,1]
	s_waitcnt vmcnt(0)
	v_pk_fma_f32 v[98:99], v[98:99], v[106:107], v[102:103]
	v_pk_fma_f32 v[100:101], v[100:101], v[108:109], v[104:105]
	v_pk_fma_f32 v[84:85], v[98:99], s[24:25], v[84:85] op_sel_hi:[1,0,1]
	v_pk_fma_f32 v[86:87], v[100:101], s[24:25], v[86:87] op_sel_hi:[1,0,1]
	global_store_dwordx4 v[156:157], v[84:87], off offset:512
	global_load_dwordx4 v[98:101], v[120:121], off
	global_load_dwordx4 v[102:105], v[122:123], off
	s_waitcnt vmcnt(1)
	v_sub_f32_e32 v106, v198, v119
	v_add_f32_e32 v110, v92, v93
	v_mul_f32_e32 v93, v93, v93
	v_fmac_f32_e32 v93, v92, v92
	v_add_f32_e32 v110, v94, v110
	v_fmac_f32_e32 v93, v94, v94
	v_add_f32_e32 v94, v88, v89
	v_mul_f32_e32 v89, v89, v89
	v_fmac_f32_e32 v89, v88, v88
	v_add_f32_e32 v94, v90, v94
	v_fmac_f32_e32 v89, v90, v90
	v_add_f32_e32 v90, v84, v85
	v_mul_f32_e32 v85, v85, v85
	v_add_f32_e32 v92, v95, v110
	v_fmac_f32_e32 v85, v84, v84
	v_sub_f32_e32 v107, v199, v119
	v_add_f32_e32 v92, 0, v92
	v_fmac_f32_e32 v93, v95, v95
	v_add_f32_e32 v88, v91, v94
	v_fmac_f32_e32 v89, v91, v91
	v_add_f32_e32 v90, v86, v90
	v_fmac_f32_e32 v85, v86, v86
	v_pk_mul_f32 v[106:107], v[118:119], v[106:107] op_sel_hi:[0,1]
	v_add_f32_e32 v88, v88, v92
	v_add_f32_e32 v89, v93, v89
	v_add_f32_e32 v84, v87, v90
	v_fmac_f32_e32 v85, v87, v87
	v_sub_f32_e32 v109, v201, v119
	v_sub_f32_e32 v108, v200, v119
	v_add_f32_e32 v88, v88, v84
	v_add_f32_e32 v89, v89, v85
	v_pk_mul_f32 v[108:109], v[118:119], v[108:109] op_sel_hi:[0,1]
	s_waitcnt vmcnt(0)
	v_pk_fma_f32 v[84:85], v[98:99], v[106:107], v[102:103]
	s_nop 0
	v_pk_fma_f32 v[84:85], v[84:85], s[24:25], v[80:81] op_sel_hi:[1,0,1]
	v_pk_fma_f32 v[86:87], v[100:101], v[108:109], v[104:105]
	v_mul_f32_e32 v81, v85, v85
	v_pk_fma_f32 v[86:87], v[86:87], s[24:25], v[82:83] op_sel_hi:[1,0,1]
	v_add_f32_e32 v80, v84, v85
	v_fmac_f32_e32 v81, v84, v84
	v_add_f32_e32 v80, v86, v80
	v_fmac_f32_e32 v81, v86, v86
	v_add_f32_e32 v80, v87, v80
	v_fmac_f32_e32 v81, v87, v87
	v_add_f32_e32 v80, v88, v80
	v_add_f32_e32 v81, v89, v81
	ds_bpermute_b32 v82, v116, v80
	ds_bpermute_b32 v83, v116, v81
	global_store_dwordx4 v[156:157], v[84:87], off offset:528
	s_waitcnt lgkmcnt(1)
	v_add_f32_e32 v80, v80, v82
	s_waitcnt lgkmcnt(0)
	v_add_f32_e32 v81, v81, v83
	ds_bpermute_b32 v82, v114, v80
	ds_bpermute_b32 v83, v114, v81
	s_mov_b32 s100, -1
	s_mov_b32 s101, 0
	s_mov_b32 s98, 0xffff0000
	s_mov_b32 s99, 0
	s_and_saveexec_b64 s[28:29], s[100:101]
	s_cbranch_execz .LBB0_2851
	v_lshl_add_u64 v[84:85], s[10:11], 0, v[96:97]
	s_waitcnt lgkmcnt(1)
	v_add_f32_e32 v80, v80, v82
	s_waitcnt lgkmcnt(0)
	v_add_f32_e32 v81, v81, v83
	v_cndmask_b32_e64 v80, v80, v81, s[98:99]
	v_cndmask_b32_e64 v81, 0, 4, s[98:99]
	v_or_b32_e32 v84, v84, v81
	flat_atomic_add_f32 v[84:85], v80
; DEVI unsigned pk2(float lo, float hi) { unsigned r; asm("v_cvt_pk_bf16_f32 %0, %1, %2" : "=v"(r) : "v"(lo), "v"(hi)); return r; }
;     DEVI void operator()(const f32x4 (&acc)[2][2][4][2], const pg8::Unit& u, int wr, int wc, int fr, int fq) const {
;     ...
;                 const int row = row0 + ai * 128 + m * 16; float mu, rs; row_stats(stin, row, mu, rs);
;                 float sum = 0.f, sq = 0.f;
; #pragma unroll
;                 for (int bj = 0; bj < 2; ++bj) {
;                     f32x4 z[2];
; #pragma unroll
;                     for (int n = 0; n < 2; ++n) {
;                         const int col = colb + bj * 128 + 4 * n;
;                         f32x4 xv = *(const f32x4*)(zsrc + (size_t)row * DM + col);
;                         if (stin) { const f32x4 gv = *(const f32x4*)(gin + col), bv = *(const f32x4*)(bin + col); xv = (xv - mu) * rs * gv + bv; }
;                         f32x4 zz = ALPHA * xv + acc[ai][bj][m][n];
;                         if (bias) zz += *(const f32x4*)(bias + col);
;                         *(f32x4*)(zdst + (size_t)row * DM + col) = zz;
;                         sum += zz[0] + zz[1] + zz[2] + zz[3]; sq += zz[0] * zz[0] + zz[1] * zz[1] + zz[2] * zz[2] + zz[3] * zz[3];
;                         z[n] = zz;
;                     }
;                     u32x4 o; o.x = pk2(z[0][0], z[0][1]); o.y = pk2(z[0][2], z[0][3]); o.z = pk2(z[1][0], z[1][1]); o.w = pk2(z[1][2], z[1][3]);
;                     if (zb) *(u32x4*)(zb + (size_t)row * DM + colb + bj * 128) = o;
;                 }
;                 sum += __shfl_xor(sum, 16); sq += __shfl_xor(sq, 16);
;                 sum += __shfl_xor(sum, 32); sq += __shfl_xor(sq, 32);
;                 if (fq == 0) { atomicAdd(stout + 2 * (size_t)row, sum); atomicAdd(stout + 2 * (size_t)row + 1, sq); }
.LBB0_2851:
	s_or_b64 exec, exec, s[28:29]
	s_waitcnt lgkmcnt(0)
	v_or_b32_e32 v82, 48, v154
	v_ashrrev_i32_e32 v83, 31, v82
	v_lshlrev_b64 v[80:81], 3, v[82:83]
	v_lshl_add_u64 v[84:85], s[12:13], 0, v[80:81]
	flat_load_dwordx2 v[98:99], v[84:85]
	v_lshlrev_b64 v[82:83], 12, v[82:83]
	v_lshl_add_u64 v[82:83], s[46:47], 0, v[82:83]
	v_lshl_add_u64 v[100:101], v[144:145], 2, v[82:83]
	global_load_dwordx4 v[82:85], v[100:101], off
	global_load_dwordx4 v[86:89], v[150:151], off
	global_load_dwordx4 v[90:93], v[152:153], off
	global_load_dwordx4 v[94:97], v[100:101], off offset:16
	global_load_dwordx4 v[194:197], v[100:101], off offset:512
	global_load_dwordx4 v[198:201], v[100:101], off offset:528
	s_waitcnt vmcnt(0) lgkmcnt(0)
	v_pk_mul_f32 v[98:99], v[98:99], s[22:23] op_sel:[1,0] op_sel_hi:[0,0]
	v_fma_f32 v98, -v99, v99, v98
	v_max_f32_e32 v98, 0, v98
	v_add_f32_e32 v98, 0x3727c5ac, v98
	v_mul_f32_e32 v102, 0x4b800000, v98
	v_cmp_gt_f32_e32 vcc, s55, v98
	v_sub_f32_e32 v83, v83, v99
	v_sub_f32_e32 v82, v82, v99
	v_cndmask_b32_e32 v98, v98, v102, vcc
	v_rsq_f32_e32 v98, v98
	v_sub_f32_e32 v85, v85, v99
	v_sub_f32_e32 v84, v84, v99
	v_sub_f32_e32 v95, v95, v99
	v_mul_f32_e32 v102, 0x45800000, v98
	v_cndmask_b32_e32 v98, v98, v102, vcc
	v_pk_mul_f32 v[84:85], v[84:85], v[98:99] op_sel_hi:[1,0]
	v_pk_mul_f32 v[82:83], v[82:83], v[98:99] op_sel_hi:[1,0]
	v_pk_fma_f32 v[84:85], v[88:89], v[84:85], v[92:93]
	v_pk_fma_f32 v[82:83], v[86:87], v[82:83], v[90:91]
	v_pk_fma_f32 v[78:79], v[84:85], s[24:25], v[78:79] op_sel_hi:[1,0,1]
	v_pk_fma_f32 v[76:77], v[82:83], s[24:25], v[76:77] op_sel_hi:[1,0,1]
	global_store_dwordx4 v[100:101], v[76:79], off
	global_load_dwordx4 v[82:85], v[146:147], off
	global_load_dwordx4 v[86:89], v[148:149], off
	v_sub_f32_e32 v94, v94, v99
	v_sub_f32_e32 v97, v97, v99
	v_sub_f32_e32 v96, v96, v99
	v_pk_mul_f32 v[96:97], v[96:97], v[98:99] op_sel_hi:[1,0]
	v_pk_mul_f32 v[94:95], v[94:95], v[98:99] op_sel_hi:[1,0]
	s_waitcnt vmcnt(0)
	v_pk_fma_f32 v[84:85], v[84:85], v[96:97], v[88:89]
	v_pk_fma_f32 v[82:83], v[82:83], v[94:95], v[86:87]
	v_pk_fma_f32 v[74:75], v[84:85], s[24:25], v[74:75] op_sel_hi:[1,0,1]
	v_pk_fma_f32 v[72:73], v[82:83], s[24:25], v[72:73] op_sel_hi:[1,0,1]
	global_store_dwordx4 v[100:101], v[72:75], off offset:16
	global_load_dwordx4 v[82:85], v[124:125], off
	global_load_dwordx4 v[86:89], v[126:127], off
	s_waitcnt vmcnt(2)
	v_sub_f32_e32 v91, v195, v99
	v_sub_f32_e32 v90, v194, v99
	v_sub_f32_e32 v93, v197, v99
	v_sub_f32_e32 v92, v196, v99
	v_pk_mul_f32 v[92:93], v[98:99], v[92:93] op_sel_hi:[0,1]
	v_pk_mul_f32 v[90:91], v[98:99], v[90:91] op_sel_hi:[0,1]
	s_waitcnt vmcnt(0)
	v_pk_fma_f32 v[82:83], v[82:83], v[90:91], v[86:87]
	v_pk_fma_f32 v[84:85], v[84:85], v[92:93], v[88:89]
	v_pk_fma_f32 v[68:69], v[82:83], s[24:25], v[68:69] op_sel_hi:[1,0,1]
	v_pk_fma_f32 v[70:71], v[84:85], s[24:25], v[70:71] op_sel_hi:[1,0,1]
	global_store_dwordx4 v[100:101], v[68:71], off offset:512
	global_load_dwordx4 v[82:85], v[120:121], off
	global_load_dwordx4 v[86:89], v[122:123], off
	s_waitcnt vmcnt(1)
	v_sub_f32_e32 v90, v198, v99
	v_add_f32_e32 v94, v76, v77
	v_mul_f32_e32 v77, v77, v77
	v_fmac_f32_e32 v77, v76, v76
	v_add_f32_e32 v94, v78, v94
	v_fmac_f32_e32 v77, v78, v78
	v_add_f32_e32 v78, v72, v73
	v_mul_f32_e32 v73, v73, v73
	v_fmac_f32_e32 v73, v72, v72
	v_add_f32_e32 v78, v74, v78
	v_fmac_f32_e32 v73, v74, v74
	v_add_f32_e32 v74, v68, v69
	v_mul_f32_e32 v69, v69, v69
	v_add_f32_e32 v76, v79, v94
	v_fmac_f32_e32 v69, v68, v68
	v_sub_f32_e32 v91, v199, v99
	v_add_f32_e32 v76, 0, v76
	v_fmac_f32_e32 v77, v79, v79
	v_add_f32_e32 v72, v75, v78
	v_fmac_f32_e32 v73, v75, v75
	v_add_f32_e32 v74, v70, v74
	v_fmac_f32_e32 v69, v70, v70
	v_pk_mul_f32 v[90:91], v[98:99], v[90:91] op_sel_hi:[0,1]
	v_add_f32_e32 v72, v72, v76
	v_add_f32_e32 v73, v77, v73
	v_add_f32_e32 v68, v71, v74
	v_fmac_f32_e32 v69, v71, v71
	v_sub_f32_e32 v93, v201, v99
	v_sub_f32_e32 v92, v200, v99
	v_add_f32_e32 v72, v72, v68
	v_add_f32_e32 v73, v73, v69
	v_pk_mul_f32 v[92:93], v[98:99], v[92:93] op_sel_hi:[0,1]
	s_waitcnt vmcnt(0)
	v_pk_fma_f32 v[68:69], v[82:83], v[90:91], v[86:87]
	s_nop 0
	v_pk_fma_f32 v[68:69], v[68:69], s[24:25], v[64:65] op_sel_hi:[1,0,1]
	v_pk_fma_f32 v[70:71], v[84:85], v[92:93], v[88:89]
	v_mul_f32_e32 v65, v69, v69
	v_pk_fma_f32 v[70:71], v[70:71], s[24:25], v[66:67] op_sel_hi:[1,0,1]
	v_add_f32_e32 v64, v68, v69
	v_fmac_f32_e32 v65, v68, v68
	v_add_f32_e32 v64, v70, v64
	v_fmac_f32_e32 v65, v70, v70
	v_add_f32_e32 v64, v71, v64
	v_fmac_f32_e32 v65, v71, v71
	v_add_f32_e32 v64, v72, v64
	v_add_f32_e32 v65, v73, v65
	ds_bpermute_b32 v66, v116, v64
	ds_bpermute_b32 v67, v116, v65
	global_store_dwordx4 v[100:101], v[68:71], off offset:528
	s_waitcnt lgkmcnt(1)
	v_add_f32_e32 v64, v64, v66
	s_waitcnt lgkmcnt(0)
	v_add_f32_e32 v65, v65, v67
	ds_bpermute_b32 v66, v114, v64
	ds_bpermute_b32 v67, v114, v65
	s_mov_b32 s100, -1
	s_mov_b32 s101, 0
	s_mov_b32 s98, 0xffff0000
	s_mov_b32 s99, 0
	s_and_saveexec_b64 s[28:29], s[100:101]
	s_cbranch_execz .LBB0_2853
	v_lshl_add_u64 v[68:69], s[10:11], 0, v[80:81]
	s_waitcnt lgkmcnt(1)
	v_add_f32_e32 v64, v64, v66
	s_waitcnt lgkmcnt(0)
	v_add_f32_e32 v65, v65, v67
	v_cndmask_b32_e64 v64, v64, v65, s[98:99]
	v_cndmask_b32_e64 v65, 0, 4, s[98:99]
	v_or_b32_e32 v68, v68, v65
	flat_atomic_add_f32 v[68:69], v64
; DEVI unsigned pk2(float lo, float hi) { unsigned r; asm("v_cvt_pk_bf16_f32 %0, %1, %2" : "=v"(r) : "v"(lo), "v"(hi)); return r; }
;     DEVI void operator()(const f32x4 (&acc)[2][2][4][2], const pg8::Unit& u, int wr, int wc, int fr, int fq) const {
;     ...
;                 const int row = row0 + ai * 128 + m * 16; float mu, rs; row_stats(stin, row, mu, rs);
;                 float sum = 0.f, sq = 0.f;
; #pragma unroll
;                 for (int bj = 0; bj < 2; ++bj) {
;                     f32x4 z[2];
; #pragma unroll
;                     for (int n = 0; n < 2; ++n) {
;                         const int col = colb + bj * 128 + 4 * n;
;                         f32x4 xv = *(const f32x4*)(zsrc + (size_t)row * DM + col);
;                         if (stin) { const f32x4 gv = *(const f32x4*)(gin + col), bv = *(const f32x4*)(bin + col); xv = (xv - mu) * rs * gv + bv; }
;                         f32x4 zz = ALPHA * xv + acc[ai][bj][m][n];
;                         if (bias) zz += *(const f32x4*)(bias + col);
;                         *(f32x4*)(zdst + (size_t)row * DM + col) = zz;
;                         sum += zz[0] + zz[1] + zz[2] + zz[3]; sq += zz[0] * zz[0] + zz[1] * zz[1] + zz[2] * zz[2] + zz[3] * zz[3];
;                         z[n] = zz;
;                     }
;                     u32x4 o; o.x = pk2(z[0][0], z[0][1]); o.y = pk2(z[0][2], z[0][3]); o.z = pk2(z[1][0], z[1][1]); o.w = pk2(z[1][2], z[1][3]);
;                     if (zb) *(u32x4*)(zb + (size_t)row * DM + colb + bj * 128) = o;
;                 }
;                 sum += __shfl_xor(sum, 16); sq += __shfl_xor(sq, 16);
;                 sum += __shfl_xor(sum, 32); sq += __shfl_xor(sq, 32);
;                 if (fq == 0) { atomicAdd(stout + 2 * (size_t)row, sum); atomicAdd(stout + 2 * (size_t)row + 1, sq); }
.LBB0_2853:
	s_or_b64 exec, exec, s[28:29]
	s_waitcnt lgkmcnt(0)
	v_add_u32_e32 v66, 0x80, v154
	v_ashrrev_i32_e32 v67, 31, v66
	v_lshlrev_b64 v[64:65], 3, v[66:67]
	v_lshl_add_u64 v[68:69], s[12:13], 0, v[64:65]
	flat_load_dwordx2 v[82:83], v[68:69]
	v_lshlrev_b64 v[66:67], 12, v[66:67]
	v_lshl_add_u64 v[66:67], s[46:47], 0, v[66:67]
	v_lshl_add_u64 v[84:85], v[144:145], 2, v[66:67]
	global_load_dwordx4 v[66:69], v[84:85], off
	global_load_dwordx4 v[70:73], v[150:151], off
	global_load_dwordx4 v[74:77], v[152:153], off
	global_load_dwordx4 v[78:81], v[84:85], off offset:16
	global_load_dwordx4 v[194:197], v[84:85], off offset:512
	global_load_dwordx4 v[198:201], v[84:85], off offset:528
	s_waitcnt vmcnt(0) lgkmcnt(0)
	v_pk_mul_f32 v[82:83], v[82:83], s[22:23] op_sel:[1,0] op_sel_hi:[0,0]
	v_fma_f32 v82, -v83, v83, v82
	v_max_f32_e32 v82, 0, v82
	v_add_f32_e32 v82, 0x3727c5ac, v82
	v_mul_f32_e32 v86, 0x4b800000, v82
	v_cmp_gt_f32_e32 vcc, s55, v82
	v_sub_f32_e32 v67, v67, v83
	v_sub_f32_e32 v66, v66, v83
	v_cndmask_b32_e32 v82, v82, v86, vcc
	v_rsq_f32_e32 v82, v82
	v_sub_f32_e32 v69, v69, v83
	v_sub_f32_e32 v68, v68, v83
	v_sub_f32_e32 v79, v79, v83
	v_mul_f32_e32 v86, 0x45800000, v82
	v_cndmask_b32_e32 v82, v82, v86, vcc
	v_pk_mul_f32 v[68:69], v[68:69], v[82:83] op_sel_hi:[1,0]
	v_pk_mul_f32 v[66:67], v[66:67], v[82:83] op_sel_hi:[1,0]
	v_pk_fma_f32 v[68:69], v[72:73], v[68:69], v[76:77]
	v_pk_fma_f32 v[66:67], v[70:71], v[66:67], v[74:75]
	v_pk_fma_f32 v[62:63], v[68:69], s[24:25], v[62:63] op_sel_hi:[1,0,1]
	v_pk_fma_f32 v[60:61], v[66:67], s[24:25], v[60:61] op_sel_hi:[1,0,1]
	global_store_dwordx4 v[84:85], v[60:63], off
	global_load_dwordx4 v[66:69], v[146:147], off
	global_load_dwordx4 v[70:73], v[148:149], off
	v_sub_f32_e32 v78, v78, v83
	v_sub_f32_e32 v81, v81, v83
	v_sub_f32_e32 v80, v80, v83
	v_pk_mul_f32 v[80:81], v[80:81], v[82:83] op_sel_hi:[1,0]
	v_pk_mul_f32 v[78:79], v[78:79], v[82:83] op_sel_hi:[1,0]
	s_waitcnt vmcnt(0)
	v_pk_fma_f32 v[68:69], v[68:69], v[80:81], v[72:73]
	v_pk_fma_f32 v[66:67], v[66:67], v[78:79], v[70:71]
	v_pk_fma_f32 v[58:59], v[68:69], s[24:25], v[58:59] op_sel_hi:[1,0,1]
	v_pk_fma_f32 v[56:57], v[66:67], s[24:25], v[56:57] op_sel_hi:[1,0,1]
	global_store_dwordx4 v[84:85], v[56:59], off offset:16
	global_load_dwordx4 v[66:69], v[124:125], off
	global_load_dwordx4 v[70:73], v[126:127], off
	s_waitcnt vmcnt(2)
	v_sub_f32_e32 v75, v195, v83
	v_sub_f32_e32 v74, v194, v83
	v_sub_f32_e32 v77, v197, v83
	v_sub_f32_e32 v76, v196, v83
	v_pk_mul_f32 v[76:77], v[82:83], v[76:77] op_sel_hi:[0,1]
	v_pk_mul_f32 v[74:75], v[82:83], v[74:75] op_sel_hi:[0,1]
	s_waitcnt vmcnt(0)
	v_pk_fma_f32 v[66:67], v[66:67], v[74:75], v[70:71]
	v_pk_fma_f32 v[68:69], v[68:69], v[76:77], v[72:73]
	v_pk_fma_f32 v[52:53], v[66:67], s[24:25], v[52:53] op_sel_hi:[1,0,1]
	v_pk_fma_f32 v[54:55], v[68:69], s[24:25], v[54:55] op_sel_hi:[1,0,1]
	global_store_dwordx4 v[84:85], v[52:55], off offset:512
	global_load_dwordx4 v[66:69], v[120:121], off
	global_load_dwordx4 v[70:73], v[122:123], off
	s_waitcnt vmcnt(1)
	v_sub_f32_e32 v74, v198, v83
	v_add_f32_e32 v78, v60, v61
	v_mul_f32_e32 v61, v61, v61
	v_fmac_f32_e32 v61, v60, v60
	v_add_f32_e32 v78, v62, v78
	v_fmac_f32_e32 v61, v62, v62
	v_add_f32_e32 v62, v56, v57
	v_mul_f32_e32 v57, v57, v57
	v_fmac_f32_e32 v57, v56, v56
	v_add_f32_e32 v62, v58, v62
	v_fmac_f32_e32 v57, v58, v58
	v_add_f32_e32 v58, v52, v53
	v_mul_f32_e32 v53, v53, v53
	v_add_f32_e32 v60, v63, v78
	v_fmac_f32_e32 v53, v52, v52
	v_sub_f32_e32 v75, v199, v83
	v_add_f32_e32 v60, 0, v60
	v_fmac_f32_e32 v61, v63, v63
	v_add_f32_e32 v56, v59, v62
	v_fmac_f32_e32 v57, v59, v59
	v_add_f32_e32 v58, v54, v58
	v_fmac_f32_e32 v53, v54, v54
	v_pk_mul_f32 v[74:75], v[82:83], v[74:75] op_sel_hi:[0,1]
	v_add_f32_e32 v56, v56, v60
	v_add_f32_e32 v57, v61, v57
	v_add_f32_e32 v52, v55, v58
	v_fmac_f32_e32 v53, v55, v55
	v_sub_f32_e32 v77, v201, v83
	v_sub_f32_e32 v76, v200, v83
	v_add_f32_e32 v56, v56, v52
	v_add_f32_e32 v57, v57, v53
	v_pk_mul_f32 v[76:77], v[82:83], v[76:77] op_sel_hi:[0,1]
	s_waitcnt vmcnt(0)
	v_pk_fma_f32 v[52:53], v[66:67], v[74:75], v[70:71]
	s_nop 0
	v_pk_fma_f32 v[52:53], v[52:53], s[24:25], v[48:49] op_sel_hi:[1,0,1]
	v_pk_fma_f32 v[54:55], v[68:69], v[76:77], v[72:73]
	v_mul_f32_e32 v49, v53, v53
	v_pk_fma_f32 v[54:55], v[54:55], s[24:25], v[50:51] op_sel_hi:[1,0,1]
	v_add_f32_e32 v48, v52, v53
	v_fmac_f32_e32 v49, v52, v52
	v_add_f32_e32 v48, v54, v48
	v_fmac_f32_e32 v49, v54, v54
	v_add_f32_e32 v48, v55, v48
	v_fmac_f32_e32 v49, v55, v55
	v_add_f32_e32 v48, v56, v48
	v_add_f32_e32 v49, v57, v49
	ds_bpermute_b32 v50, v116, v48
	ds_bpermute_b32 v51, v116, v49
	global_store_dwordx4 v[84:85], v[52:55], off offset:528
	s_waitcnt lgkmcnt(1)
	v_add_f32_e32 v48, v48, v50
	s_waitcnt lgkmcnt(0)
	v_add_f32_e32 v49, v49, v51
	ds_bpermute_b32 v50, v114, v48
	ds_bpermute_b32 v51, v114, v49
	s_mov_b32 s100, -1
	s_mov_b32 s101, 0
	s_mov_b32 s98, 0xffff0000
	s_mov_b32 s99, 0
	s_and_saveexec_b64 s[28:29], s[100:101]
	s_cbranch_execz .LBB0_2855
	v_lshl_add_u64 v[52:53], s[10:11], 0, v[64:65]
	s_waitcnt lgkmcnt(1)
	v_add_f32_e32 v48, v48, v50
	s_waitcnt lgkmcnt(0)
	v_add_f32_e32 v49, v49, v51
	v_cndmask_b32_e64 v48, v48, v49, s[98:99]
	v_cndmask_b32_e64 v49, 0, 4, s[98:99]
	v_or_b32_e32 v52, v52, v49
	flat_atomic_add_f32 v[52:53], v48
; DEVI unsigned pk2(float lo, float hi) { unsigned r; asm("v_cvt_pk_bf16_f32 %0, %1, %2" : "=v"(r) : "v"(lo), "v"(hi)); return r; }
;     DEVI void operator()(const f32x4 (&acc)[2][2][4][2], const pg8::Unit& u, int wr, int wc, int fr, int fq) const {
;     ...
;                 const int row = row0 + ai * 128 + m * 16; float mu, rs; row_stats(stin, row, mu, rs);
;                 float sum = 0.f, sq = 0.f;
; #pragma unroll
;                 for (int bj = 0; bj < 2; ++bj) {
;                     f32x4 z[2];
; #pragma unroll
;                     for (int n = 0; n < 2; ++n) {
;                         const int col = colb + bj * 128 + 4 * n;
;                         f32x4 xv = *(const f32x4*)(zsrc + (size_t)row * DM + col);
;                         if (stin) { const f32x4 gv = *(const f32x4*)(gin + col), bv = *(const f32x4*)(bin + col); xv = (xv - mu) * rs * gv + bv; }
;                         f32x4 zz = ALPHA * xv + acc[ai][bj][m][n];
;                         if (bias) zz += *(const f32x4*)(bias + col);
;                         *(f32x4*)(zdst + (size_t)row * DM + col) = zz;
;                         sum += zz[0] + zz[1] + zz[2] + zz[3]; sq += zz[0] * zz[0] + zz[1] * zz[1] + zz[2] * zz[2] + zz[3] * zz[3];
;                         z[n] = zz;
;                     }
;                     u32x4 o; o.x = pk2(z[0][0], z[0][1]); o.y = pk2(z[0][2], z[0][3]); o.z = pk2(z[1][0], z[1][1]); o.w = pk2(z[1][2], z[1][3]);
;                     if (zb) *(u32x4*)(zb + (size_t)row * DM + colb + bj * 128) = o;
;                 }
;                 sum += __shfl_xor(sum, 16); sq += __shfl_xor(sq, 16);
;                 sum += __shfl_xor(sum, 32); sq += __shfl_xor(sq, 32);
;                 if (fq == 0) { atomicAdd(stout + 2 * (size_t)row, sum); atomicAdd(stout + 2 * (size_t)row + 1, sq); }
.LBB0_2855:
	s_or_b64 exec, exec, s[28:29]
	s_waitcnt lgkmcnt(0)
	v_add_u32_e32 v50, 0x90, v154
	v_ashrrev_i32_e32 v51, 31, v50
	v_lshlrev_b64 v[48:49], 3, v[50:51]
	v_lshl_add_u64 v[52:53], s[12:13], 0, v[48:49]
	flat_load_dwordx2 v[66:67], v[52:53]
	v_lshlrev_b64 v[50:51], 12, v[50:51]
	v_lshl_add_u64 v[50:51], s[46:47], 0, v[50:51]
	v_lshl_add_u64 v[68:69], v[144:145], 2, v[50:51]
	global_load_dwordx4 v[50:53], v[68:69], off
	global_load_dwordx4 v[54:57], v[150:151], off
	global_load_dwordx4 v[58:61], v[152:153], off
	global_load_dwordx4 v[62:65], v[68:69], off offset:16
	global_load_dwordx4 v[194:197], v[68:69], off offset:512
	global_load_dwordx4 v[198:201], v[68:69], off offset:528
	s_waitcnt vmcnt(0) lgkmcnt(0)
	v_pk_mul_f32 v[66:67], v[66:67], s[22:23] op_sel:[1,0] op_sel_hi:[0,0]
	v_fma_f32 v66, -v67, v67, v66
	v_max_f32_e32 v66, 0, v66
	v_add_f32_e32 v66, 0x3727c5ac, v66
	v_mul_f32_e32 v70, 0x4b800000, v66
	v_cmp_gt_f32_e32 vcc, s55, v66
	v_sub_f32_e32 v51, v51, v67
	v_sub_f32_e32 v50, v50, v67
	v_cndmask_b32_e32 v66, v66, v70, vcc
	v_rsq_f32_e32 v66, v66
	v_sub_f32_e32 v53, v53, v67
	v_sub_f32_e32 v52, v52, v67
	v_sub_f32_e32 v63, v63, v67
	v_mul_f32_e32 v70, 0x45800000, v66
	v_cndmask_b32_e32 v66, v66, v70, vcc
	v_pk_mul_f32 v[52:53], v[52:53], v[66:67] op_sel_hi:[1,0]
	v_pk_mul_f32 v[50:51], v[50:51], v[66:67] op_sel_hi:[1,0]
	v_pk_fma_f32 v[52:53], v[56:57], v[52:53], v[60:61]
	v_pk_fma_f32 v[50:51], v[54:55], v[50:51], v[58:59]
	v_pk_fma_f32 v[46:47], v[52:53], s[24:25], v[46:47] op_sel_hi:[1,0,1]
	v_pk_fma_f32 v[44:45], v[50:51], s[24:25], v[44:45] op_sel_hi:[1,0,1]
	global_store_dwordx4 v[68:69], v[44:47], off
	global_load_dwordx4 v[50:53], v[146:147], off
	global_load_dwordx4 v[54:57], v[148:149], off
	v_sub_f32_e32 v62, v62, v67
	v_sub_f32_e32 v65, v65, v67
	v_sub_f32_e32 v64, v64, v67
	v_pk_mul_f32 v[64:65], v[64:65], v[66:67] op_sel_hi:[1,0]
	v_pk_mul_f32 v[62:63], v[62:63], v[66:67] op_sel_hi:[1,0]
	s_waitcnt vmcnt(0)
	v_pk_fma_f32 v[52:53], v[52:53], v[64:65], v[56:57]
	v_pk_fma_f32 v[50:51], v[50:51], v[62:63], v[54:55]
	v_pk_fma_f32 v[42:43], v[52:53], s[24:25], v[42:43] op_sel_hi:[1,0,1]
	v_pk_fma_f32 v[40:41], v[50:51], s[24:25], v[40:41] op_sel_hi:[1,0,1]
	global_store_dwordx4 v[68:69], v[40:43], off offset:16
	global_load_dwordx4 v[50:53], v[124:125], off
	global_load_dwordx4 v[54:57], v[126:127], off
	s_waitcnt vmcnt(2)
	v_sub_f32_e32 v59, v195, v67
	v_sub_f32_e32 v58, v194, v67
	v_sub_f32_e32 v61, v197, v67
	v_sub_f32_e32 v60, v196, v67
	v_pk_mul_f32 v[60:61], v[66:67], v[60:61] op_sel_hi:[0,1]
	v_pk_mul_f32 v[58:59], v[66:67], v[58:59] op_sel_hi:[0,1]
	s_waitcnt vmcnt(0)
	v_pk_fma_f32 v[50:51], v[50:51], v[58:59], v[54:55]
	v_pk_fma_f32 v[52:53], v[52:53], v[60:61], v[56:57]
	v_pk_fma_f32 v[36:37], v[50:51], s[24:25], v[36:37] op_sel_hi:[1,0,1]
	v_pk_fma_f32 v[38:39], v[52:53], s[24:25], v[38:39] op_sel_hi:[1,0,1]
	global_store_dwordx4 v[68:69], v[36:39], off offset:512
	global_load_dwordx4 v[50:53], v[120:121], off
	global_load_dwordx4 v[54:57], v[122:123], off
	s_waitcnt vmcnt(1)
	v_sub_f32_e32 v58, v198, v67
	v_add_f32_e32 v62, v44, v45
	v_mul_f32_e32 v45, v45, v45
	v_fmac_f32_e32 v45, v44, v44
	v_add_f32_e32 v62, v46, v62
	v_fmac_f32_e32 v45, v46, v46
	v_add_f32_e32 v46, v40, v41
	v_mul_f32_e32 v41, v41, v41
	v_fmac_f32_e32 v41, v40, v40
	v_add_f32_e32 v46, v42, v46
	v_fmac_f32_e32 v41, v42, v42
	v_add_f32_e32 v42, v36, v37
	v_mul_f32_e32 v37, v37, v37
	v_add_f32_e32 v44, v47, v62
	v_fmac_f32_e32 v37, v36, v36
	v_sub_f32_e32 v59, v199, v67
	v_add_f32_e32 v44, 0, v44
	v_fmac_f32_e32 v45, v47, v47
	v_add_f32_e32 v40, v43, v46
	v_fmac_f32_e32 v41, v43, v43
	v_add_f32_e32 v42, v38, v42
	v_fmac_f32_e32 v37, v38, v38
	v_pk_mul_f32 v[58:59], v[66:67], v[58:59] op_sel_hi:[0,1]
	v_add_f32_e32 v40, v40, v44
	v_add_f32_e32 v41, v45, v41
	v_add_f32_e32 v36, v39, v42
	v_fmac_f32_e32 v37, v39, v39
	v_sub_f32_e32 v61, v201, v67
	v_sub_f32_e32 v60, v200, v67
	v_add_f32_e32 v40, v40, v36
	v_add_f32_e32 v41, v41, v37
	v_pk_mul_f32 v[60:61], v[66:67], v[60:61] op_sel_hi:[0,1]
	s_waitcnt vmcnt(0)
	v_pk_fma_f32 v[36:37], v[50:51], v[58:59], v[54:55]
	s_nop 0
	v_pk_fma_f32 v[36:37], v[36:37], s[24:25], v[32:33] op_sel_hi:[1,0,1]
	v_pk_fma_f32 v[38:39], v[52:53], v[60:61], v[56:57]
	v_mul_f32_e32 v33, v37, v37
	v_pk_fma_f32 v[38:39], v[38:39], s[24:25], v[34:35] op_sel_hi:[1,0,1]
	v_add_f32_e32 v32, v36, v37
	v_fmac_f32_e32 v33, v36, v36
	v_add_f32_e32 v32, v38, v32
	v_fmac_f32_e32 v33, v38, v38
	v_add_f32_e32 v32, v39, v32
	v_fmac_f32_e32 v33, v39, v39
	v_add_f32_e32 v32, v40, v32
	v_add_f32_e32 v33, v41, v33
	ds_bpermute_b32 v34, v116, v32
	ds_bpermute_b32 v35, v116, v33
	global_store_dwordx4 v[68:69], v[36:39], off offset:528
	s_waitcnt lgkmcnt(1)
	v_add_f32_e32 v32, v32, v34
	s_waitcnt lgkmcnt(0)
	v_add_f32_e32 v33, v33, v35
	ds_bpermute_b32 v34, v114, v32
	ds_bpermute_b32 v35, v114, v33
	s_mov_b32 s100, -1
	s_mov_b32 s101, 0
	s_mov_b32 s98, 0xffff0000
	s_mov_b32 s99, 0
	s_and_saveexec_b64 s[28:29], s[100:101]
	s_cbranch_execz .LBB0_2857
	v_lshl_add_u64 v[36:37], s[10:11], 0, v[48:49]
	s_waitcnt lgkmcnt(1)
	v_add_f32_e32 v32, v32, v34
	s_waitcnt lgkmcnt(0)
	v_add_f32_e32 v33, v33, v35
	v_cndmask_b32_e64 v32, v32, v33, s[98:99]
	v_cndmask_b32_e64 v33, 0, 4, s[98:99]
	v_or_b32_e32 v36, v36, v33
	flat_atomic_add_f32 v[36:37], v32
; DEVI unsigned pk2(float lo, float hi) { unsigned r; asm("v_cvt_pk_bf16_f32 %0, %1, %2" : "=v"(r) : "v"(lo), "v"(hi)); return r; }
;     DEVI void operator()(const f32x4 (&acc)[2][2][4][2], const pg8::Unit& u, int wr, int wc, int fr, int fq) const {
;     ...
;                 const int row = row0 + ai * 128 + m * 16; float mu, rs; row_stats(stin, row, mu, rs);
;                 float sum = 0.f, sq = 0.f;
; #pragma unroll
;                 for (int bj = 0; bj < 2; ++bj) {
;                     f32x4 z[2];
; #pragma unroll
;                     for (int n = 0; n < 2; ++n) {
;                         const int col = colb + bj * 128 + 4 * n;
;                         f32x4 xv = *(const f32x4*)(zsrc + (size_t)row * DM + col);
;                         if (stin) { const f32x4 gv = *(const f32x4*)(gin + col), bv = *(const f32x4*)(bin + col); xv = (xv - mu) * rs * gv + bv; }
;                         f32x4 zz = ALPHA * xv + acc[ai][bj][m][n];
;                         if (bias) zz += *(const f32x4*)(bias + col);
;                         *(f32x4*)(zdst + (size_t)row * DM + col) = zz;
;                         sum += zz[0] + zz[1] + zz[2] + zz[3]; sq += zz[0] * zz[0] + zz[1] * zz[1] + zz[2] * zz[2] + zz[3] * zz[3];
;                         z[n] = zz;
;                     }
;                     u32x4 o; o.x = pk2(z[0][0], z[0][1]); o.y = pk2(z[0][2], z[0][3]); o.z = pk2(z[1][0], z[1][1]); o.w = pk2(z[1][2], z[1][3]);
;                     if (zb) *(u32x4*)(zb + (size_t)row * DM + colb + bj * 128) = o;
;                 }
;                 sum += __shfl_xor(sum, 16); sq += __shfl_xor(sq, 16);
;                 sum += __shfl_xor(sum, 32); sq += __shfl_xor(sq, 32);
;                 if (fq == 0) { atomicAdd(stout + 2 * (size_t)row, sum); atomicAdd(stout + 2 * (size_t)row + 1, sq); }
.LBB0_2857:
	s_or_b64 exec, exec, s[28:29]
	s_waitcnt lgkmcnt(0)
	v_add_u32_e32 v34, 0xa0, v154
	v_ashrrev_i32_e32 v35, 31, v34
	v_lshlrev_b64 v[32:33], 3, v[34:35]
	v_lshl_add_u64 v[36:37], s[12:13], 0, v[32:33]
	flat_load_dwordx2 v[50:51], v[36:37]
	v_lshlrev_b64 v[34:35], 12, v[34:35]
	v_lshl_add_u64 v[34:35], s[46:47], 0, v[34:35]
	v_lshl_add_u64 v[52:53], v[144:145], 2, v[34:35]
	global_load_dwordx4 v[34:37], v[52:53], off
	global_load_dwordx4 v[38:41], v[150:151], off
	global_load_dwordx4 v[42:45], v[152:153], off
	global_load_dwordx4 v[46:49], v[52:53], off offset:16
	global_load_dwordx4 v[194:197], v[52:53], off offset:512
	global_load_dwordx4 v[198:201], v[52:53], off offset:528
	s_waitcnt vmcnt(0) lgkmcnt(0)
	v_pk_mul_f32 v[50:51], v[50:51], s[22:23] op_sel:[1,0] op_sel_hi:[0,0]
	v_fma_f32 v50, -v51, v51, v50
	v_max_f32_e32 v50, 0, v50
	v_add_f32_e32 v50, 0x3727c5ac, v50
	v_mul_f32_e32 v54, 0x4b800000, v50
	v_cmp_gt_f32_e32 vcc, s55, v50
	v_sub_f32_e32 v35, v35, v51
	v_sub_f32_e32 v34, v34, v51
	v_cndmask_b32_e32 v50, v50, v54, vcc
	v_rsq_f32_e32 v50, v50
	v_sub_f32_e32 v37, v37, v51
	v_sub_f32_e32 v36, v36, v51
	v_sub_f32_e32 v47, v47, v51
	v_mul_f32_e32 v54, 0x45800000, v50
	v_cndmask_b32_e32 v50, v50, v54, vcc
	v_pk_mul_f32 v[36:37], v[36:37], v[50:51] op_sel_hi:[1,0]
	v_pk_mul_f32 v[34:35], v[34:35], v[50:51] op_sel_hi:[1,0]
	v_pk_fma_f32 v[36:37], v[40:41], v[36:37], v[44:45]
	v_pk_fma_f32 v[34:35], v[38:39], v[34:35], v[42:43]
	v_pk_fma_f32 v[30:31], v[36:37], s[24:25], v[30:31] op_sel_hi:[1,0,1]
	v_pk_fma_f32 v[28:29], v[34:35], s[24:25], v[28:29] op_sel_hi:[1,0,1]
	global_store_dwordx4 v[52:53], v[28:31], off
	global_load_dwordx4 v[34:37], v[146:147], off
	global_load_dwordx4 v[38:41], v[148:149], off
	v_sub_f32_e32 v46, v46, v51
	v_sub_f32_e32 v49, v49, v51
	v_sub_f32_e32 v48, v48, v51
	v_pk_mul_f32 v[48:49], v[48:49], v[50:51] op_sel_hi:[1,0]
	v_pk_mul_f32 v[46:47], v[46:47], v[50:51] op_sel_hi:[1,0]
	s_waitcnt vmcnt(0)
	v_pk_fma_f32 v[36:37], v[36:37], v[48:49], v[40:41]
	v_pk_fma_f32 v[34:35], v[34:35], v[46:47], v[38:39]
	v_pk_fma_f32 v[26:27], v[36:37], s[24:25], v[26:27] op_sel_hi:[1,0,1]
	v_pk_fma_f32 v[24:25], v[34:35], s[24:25], v[24:25] op_sel_hi:[1,0,1]
	global_store_dwordx4 v[52:53], v[24:27], off offset:16
	global_load_dwordx4 v[34:37], v[124:125], off
	global_load_dwordx4 v[38:41], v[126:127], off
	s_waitcnt vmcnt(2)
	v_sub_f32_e32 v43, v195, v51
	v_sub_f32_e32 v42, v194, v51
	v_sub_f32_e32 v45, v197, v51
	v_sub_f32_e32 v44, v196, v51
	v_pk_mul_f32 v[44:45], v[50:51], v[44:45] op_sel_hi:[0,1]
	v_pk_mul_f32 v[42:43], v[50:51], v[42:43] op_sel_hi:[0,1]
	s_waitcnt vmcnt(0)
	v_pk_fma_f32 v[34:35], v[34:35], v[42:43], v[38:39]
	v_pk_fma_f32 v[36:37], v[36:37], v[44:45], v[40:41]
	v_pk_fma_f32 v[20:21], v[34:35], s[24:25], v[20:21] op_sel_hi:[1,0,1]
	v_pk_fma_f32 v[22:23], v[36:37], s[24:25], v[22:23] op_sel_hi:[1,0,1]
	global_store_dwordx4 v[52:53], v[20:23], off offset:512
	global_load_dwordx4 v[34:37], v[120:121], off
	global_load_dwordx4 v[38:41], v[122:123], off
	s_waitcnt vmcnt(1)
	v_sub_f32_e32 v42, v198, v51
	v_add_f32_e32 v46, v28, v29
	v_mul_f32_e32 v29, v29, v29
	v_fmac_f32_e32 v29, v28, v28
	v_add_f32_e32 v46, v30, v46
	v_fmac_f32_e32 v29, v30, v30
	v_add_f32_e32 v30, v24, v25
	v_mul_f32_e32 v25, v25, v25
	v_fmac_f32_e32 v25, v24, v24
	v_add_f32_e32 v30, v26, v30
	v_fmac_f32_e32 v25, v26, v26
	v_add_f32_e32 v26, v20, v21
	v_mul_f32_e32 v21, v21, v21
	v_add_f32_e32 v28, v31, v46
	v_fmac_f32_e32 v21, v20, v20
	v_sub_f32_e32 v43, v199, v51
	v_add_f32_e32 v28, 0, v28
	v_fmac_f32_e32 v29, v31, v31
	v_add_f32_e32 v24, v27, v30
	v_fmac_f32_e32 v25, v27, v27
	v_add_f32_e32 v26, v22, v26
	v_fmac_f32_e32 v21, v22, v22
	v_pk_mul_f32 v[42:43], v[50:51], v[42:43] op_sel_hi:[0,1]
	v_add_f32_e32 v24, v24, v28
	v_add_f32_e32 v25, v29, v25
	v_add_f32_e32 v20, v23, v26
	v_fmac_f32_e32 v21, v23, v23
	v_sub_f32_e32 v45, v201, v51
	v_sub_f32_e32 v44, v200, v51
	v_add_f32_e32 v24, v24, v20
	v_add_f32_e32 v25, v25, v21
	v_pk_mul_f32 v[44:45], v[50:51], v[44:45] op_sel_hi:[0,1]
	s_waitcnt vmcnt(0)
	v_pk_fma_f32 v[20:21], v[34:35], v[42:43], v[38:39]
	s_nop 0
	v_pk_fma_f32 v[20:21], v[20:21], s[24:25], v[16:17] op_sel_hi:[1,0,1]
	v_pk_fma_f32 v[22:23], v[36:37], v[44:45], v[40:41]
	v_mul_f32_e32 v17, v21, v21
	v_pk_fma_f32 v[22:23], v[22:23], s[24:25], v[18:19] op_sel_hi:[1,0,1]
	v_add_f32_e32 v16, v20, v21
	v_fmac_f32_e32 v17, v20, v20
	v_add_f32_e32 v16, v22, v16
	v_fmac_f32_e32 v17, v22, v22
	v_add_f32_e32 v16, v23, v16
	v_fmac_f32_e32 v17, v23, v23
	v_add_f32_e32 v16, v24, v16
	v_add_f32_e32 v17, v25, v17
	ds_bpermute_b32 v18, v116, v16
	ds_bpermute_b32 v19, v116, v17
	global_store_dwordx4 v[52:53], v[20:23], off offset:528
	s_waitcnt lgkmcnt(1)
	v_add_f32_e32 v16, v16, v18
	s_waitcnt lgkmcnt(0)
	v_add_f32_e32 v17, v17, v19
	ds_bpermute_b32 v18, v114, v16
	ds_bpermute_b32 v19, v114, v17
	s_mov_b32 s100, -1
	s_mov_b32 s101, 0
	s_mov_b32 s98, 0xffff0000
	s_mov_b32 s99, 0
	s_and_saveexec_b64 s[28:29], s[100:101]
	s_cbranch_execz .LBB0_2859
	v_lshl_add_u64 v[20:21], s[10:11], 0, v[32:33]
	s_waitcnt lgkmcnt(1)
	v_add_f32_e32 v16, v16, v18
	s_waitcnt lgkmcnt(0)
	v_add_f32_e32 v17, v17, v19
	v_cndmask_b32_e64 v16, v16, v17, s[98:99]
	v_cndmask_b32_e64 v17, 0, 4, s[98:99]
	v_or_b32_e32 v20, v20, v17
	flat_atomic_add_f32 v[20:21], v16
; DEVI unsigned pk2(float lo, float hi) { unsigned r; asm("v_cvt_pk_bf16_f32 %0, %1, %2" : "=v"(r) : "v"(lo), "v"(hi)); return r; }
;     DEVI void operator()(const f32x4 (&acc)[2][2][4][2], const pg8::Unit& u, int wr, int wc, int fr, int fq) const {
;     ...
;                 const int row = row0 + ai * 128 + m * 16; float mu, rs; row_stats(stin, row, mu, rs);
;                 float sum = 0.f, sq = 0.f;
; #pragma unroll
;                 for (int bj = 0; bj < 2; ++bj) {
;                     f32x4 z[2];
; #pragma unroll
;                     for (int n = 0; n < 2; ++n) {
;                         const int col = colb + bj * 128 + 4 * n;
;                         f32x4 xv = *(const f32x4*)(zsrc + (size_t)row * DM + col);
;                         if (stin) { const f32x4 gv = *(const f32x4*)(gin + col), bv = *(const f32x4*)(bin + col); xv = (xv - mu) * rs * gv + bv; }
;                         f32x4 zz = ALPHA * xv + acc[ai][bj][m][n];
;                         if (bias) zz += *(const f32x4*)(bias + col);
;                         *(f32x4*)(zdst + (size_t)row * DM + col) = zz;
;                         sum += zz[0] + zz[1] + zz[2] + zz[3]; sq += zz[0] * zz[0] + zz[1] * zz[1] + zz[2] * zz[2] + zz[3] * zz[3];
;                         z[n] = zz;
;                     }
;                     u32x4 o; o.x = pk2(z[0][0], z[0][1]); o.y = pk2(z[0][2], z[0][3]); o.z = pk2(z[1][0], z[1][1]); o.w = pk2(z[1][2], z[1][3]);
;                     if (zb) *(u32x4*)(zb + (size_t)row * DM + colb + bj * 128) = o;
;                 }
;                 sum += __shfl_xor(sum, 16); sq += __shfl_xor(sq, 16);
;                 sum += __shfl_xor(sum, 32); sq += __shfl_xor(sq, 32);
;                 if (fq == 0) { atomicAdd(stout + 2 * (size_t)row, sum); atomicAdd(stout + 2 * (size_t)row + 1, sq); }
.LBB0_2859:
	s_or_b64 exec, exec, s[28:29]
	s_waitcnt lgkmcnt(0)
	v_add_u32_e32 v18, 0xb0, v154
	v_ashrrev_i32_e32 v19, 31, v18
	v_lshlrev_b64 v[16:17], 3, v[18:19]
	v_lshl_add_u64 v[20:21], s[12:13], 0, v[16:17]
	flat_load_dwordx2 v[34:35], v[20:21]
	v_lshlrev_b64 v[18:19], 12, v[18:19]
	v_lshl_add_u64 v[18:19], s[46:47], 0, v[18:19]
	v_lshl_add_u64 v[36:37], v[144:145], 2, v[18:19]
	global_load_dwordx4 v[18:21], v[36:37], off
	global_load_dwordx4 v[22:25], v[150:151], off
	global_load_dwordx4 v[26:29], v[152:153], off
	global_load_dwordx4 v[30:33], v[36:37], off offset:16
	global_load_dwordx4 v[194:197], v[36:37], off offset:512
	global_load_dwordx4 v[198:201], v[36:37], off offset:528
	s_waitcnt vmcnt(0) lgkmcnt(0)
	v_pk_mul_f32 v[34:35], v[34:35], s[22:23] op_sel:[1,0] op_sel_hi:[0,0]
	v_fma_f32 v34, -v35, v35, v34
	v_max_f32_e32 v34, 0, v34
	v_add_f32_e32 v34, 0x3727c5ac, v34
	v_mul_f32_e32 v38, 0x4b800000, v34
	v_cmp_gt_f32_e32 vcc, s55, v34
	v_sub_f32_e32 v19, v19, v35
	v_sub_f32_e32 v18, v18, v35
	v_cndmask_b32_e32 v34, v34, v38, vcc
	v_rsq_f32_e32 v34, v34
	v_sub_f32_e32 v21, v21, v35
	v_sub_f32_e32 v20, v20, v35
	v_sub_f32_e32 v31, v31, v35
	v_mul_f32_e32 v38, 0x45800000, v34
	v_cndmask_b32_e32 v34, v34, v38, vcc
	v_pk_mul_f32 v[20:21], v[20:21], v[34:35] op_sel_hi:[1,0]
	v_pk_mul_f32 v[18:19], v[18:19], v[34:35] op_sel_hi:[1,0]
	v_pk_fma_f32 v[20:21], v[24:25], v[20:21], v[28:29]
	v_pk_fma_f32 v[18:19], v[22:23], v[18:19], v[26:27]
	v_pk_fma_f32 v[14:15], v[20:21], s[24:25], v[14:15] op_sel_hi:[1,0,1]
	v_pk_fma_f32 v[12:13], v[18:19], s[24:25], v[12:13] op_sel_hi:[1,0,1]
	global_store_dwordx4 v[36:37], v[12:15], off
	global_load_dwordx4 v[18:21], v[146:147], off
	global_load_dwordx4 v[22:25], v[148:149], off
	v_sub_f32_e32 v30, v30, v35
	v_sub_f32_e32 v33, v33, v35
	v_sub_f32_e32 v32, v32, v35
	v_pk_mul_f32 v[32:33], v[32:33], v[34:35] op_sel_hi:[1,0]
	v_pk_mul_f32 v[30:31], v[30:31], v[34:35] op_sel_hi:[1,0]
	s_waitcnt vmcnt(0)
	v_pk_fma_f32 v[20:21], v[20:21], v[32:33], v[24:25]
	v_pk_fma_f32 v[18:19], v[18:19], v[30:31], v[22:23]
	v_pk_fma_f32 v[10:11], v[20:21], s[24:25], v[10:11] op_sel_hi:[1,0,1]
	v_pk_fma_f32 v[8:9], v[18:19], s[24:25], v[8:9] op_sel_hi:[1,0,1]
	global_store_dwordx4 v[36:37], v[8:11], off offset:16
	global_load_dwordx4 v[18:21], v[124:125], off
	global_load_dwordx4 v[22:25], v[126:127], off
	s_waitcnt vmcnt(2)
	v_sub_f32_e32 v27, v195, v35
	v_sub_f32_e32 v26, v194, v35
	v_sub_f32_e32 v29, v197, v35
	v_sub_f32_e32 v28, v196, v35
	v_pk_mul_f32 v[28:29], v[34:35], v[28:29] op_sel_hi:[0,1]
	v_pk_mul_f32 v[26:27], v[34:35], v[26:27] op_sel_hi:[0,1]
	s_waitcnt vmcnt(0)
	v_pk_fma_f32 v[18:19], v[18:19], v[26:27], v[22:23]
	v_pk_fma_f32 v[20:21], v[20:21], v[28:29], v[24:25]
	v_pk_fma_f32 v[4:5], v[18:19], s[24:25], v[4:5] op_sel_hi:[1,0,1]
	v_pk_fma_f32 v[6:7], v[20:21], s[24:25], v[6:7] op_sel_hi:[1,0,1]
	global_store_dwordx4 v[36:37], v[4:7], off offset:512
	global_load_dwordx4 v[18:21], v[120:121], off
	global_load_dwordx4 v[22:25], v[122:123], off
	s_waitcnt vmcnt(1)
	v_sub_f32_e32 v26, v198, v35
	v_add_f32_e32 v30, v12, v13
	v_mul_f32_e32 v13, v13, v13
	v_fmac_f32_e32 v13, v12, v12
	v_add_f32_e32 v30, v14, v30
	v_fmac_f32_e32 v13, v14, v14
	v_add_f32_e32 v14, v8, v9
	v_mul_f32_e32 v9, v9, v9
	v_fmac_f32_e32 v9, v8, v8
	v_add_f32_e32 v14, v10, v14
	v_fmac_f32_e32 v9, v10, v10
	v_add_f32_e32 v10, v4, v5
	v_mul_f32_e32 v5, v5, v5
	v_add_f32_e32 v12, v15, v30
	v_fmac_f32_e32 v5, v4, v4
	v_sub_f32_e32 v27, v199, v35
	v_add_f32_e32 v12, 0, v12
	v_fmac_f32_e32 v13, v15, v15
	v_add_f32_e32 v8, v11, v14
	v_fmac_f32_e32 v9, v11, v11
	v_add_f32_e32 v10, v6, v10
	v_fmac_f32_e32 v5, v6, v6
	v_pk_mul_f32 v[26:27], v[34:35], v[26:27] op_sel_hi:[0,1]
	v_add_f32_e32 v8, v8, v12
	v_add_f32_e32 v9, v13, v9
	v_add_f32_e32 v4, v7, v10
	v_fmac_f32_e32 v5, v7, v7
	v_sub_f32_e32 v29, v201, v35
	v_sub_f32_e32 v28, v200, v35
	v_add_f32_e32 v8, v8, v4
	v_add_f32_e32 v9, v9, v5
	v_pk_mul_f32 v[28:29], v[34:35], v[28:29] op_sel_hi:[0,1]
	s_waitcnt vmcnt(0)
	v_pk_fma_f32 v[4:5], v[18:19], v[26:27], v[22:23]
	s_nop 0
	v_pk_fma_f32 v[4:5], v[4:5], s[24:25], v[0:1] op_sel_hi:[1,0,1]
	v_pk_fma_f32 v[6:7], v[20:21], v[28:29], v[24:25]
	v_mul_f32_e32 v1, v5, v5
	v_pk_fma_f32 v[6:7], v[6:7], s[24:25], v[2:3] op_sel_hi:[1,0,1]
	v_add_f32_e32 v0, v4, v5
	v_fmac_f32_e32 v1, v4, v4
	v_add_f32_e32 v0, v6, v0
	v_fmac_f32_e32 v1, v6, v6
	v_add_f32_e32 v0, v7, v0
	v_fmac_f32_e32 v1, v7, v7
	v_add_f32_e32 v0, v8, v0
	v_add_f32_e32 v1, v9, v1
	ds_bpermute_b32 v2, v116, v0
	ds_bpermute_b32 v3, v116, v1
	global_store_dwordx4 v[36:37], v[4:7], off offset:528
	s_waitcnt lgkmcnt(1)
	v_add_f32_e32 v0, v0, v2
	s_waitcnt lgkmcnt(0)
	v_add_f32_e32 v1, v1, v3
	ds_bpermute_b32 v2, v114, v0
	ds_bpermute_b32 v3, v114, v1
	s_mov_b32 s100, -1
	s_mov_b32 s101, 0
	s_mov_b32 s98, 0xffff0000
	s_mov_b32 s99, 0
	s_and_saveexec_b64 s[28:29], s[100:101]
	s_cbranch_execz .LBB0_2861
	v_lshl_add_u64 v[4:5], s[10:11], 0, v[16:17]
	s_waitcnt lgkmcnt(1)
	v_add_f32_e32 v0, v0, v2
	s_waitcnt lgkmcnt(0)
	v_add_f32_e32 v1, v1, v3
	v_cndmask_b32_e64 v0, v0, v1, s[98:99]
	v_cndmask_b32_e64 v1, 0, 4, s[98:99]
	v_or_b32_e32 v4, v4, v1
	flat_atomic_add_f32 v[4:5], v0
